# sc1 stores extended to P0, FFN-out, out-proj epilogues (dwordx2 included)
# speedup vs baseline: 1.0385x; 1.0005x over previous
.LBB0_85:
	s_waitcnt lgkmcnt(0)
	v_add_u32_e32 v8, 24, v10
	v_ashrrev_i32_e32 v11, 31, v8
	v_mad_u64_u32 v[8:9], s[2:3], v8, s6, 0
	v_mov_b32_e32 v10, v9
	v_mad_u64_u32 v[10:11], s[2:3], v11, s6, v[10:11]
	v_mov_b32_e32 v9, v10
	v_lshl_add_u64 v[6:7], v[8:9], 1, v[6:7]
	global_store_dwordx4 v[6:7], v[2:5], off sc1
	s_waitcnt lgkmcnt(0)
	s_add_i32 s36, s36, s37
	s_add_i32 s39, s39, s40
	s_add_i32 s42, s42, s43
	s_andn2_b64 vcc, exec, s[18:19]
	s_mov_b32 s22, s44
	v_mov_b32_e32 v18, v38
	v_mov_b32_e32 v19, v39
	v_mov_b32_e32 v20, v40
	v_mov_b32_e32 v21, v41
	v_mov_b32_e32 v2, v34
	v_mov_b32_e32 v3, v35
	v_mov_b32_e32 v4, v36
	v_mov_b32_e32 v5, v37
	v_mov_b32_e32 v22, v46
	v_mov_b32_e32 v23, v47
	v_mov_b32_e32 v24, v48
	v_mov_b32_e32 v25, v49
	v_mov_b32_e32 v6, v42
	v_mov_b32_e32 v7, v43
	v_mov_b32_e32 v8, v44
	v_mov_b32_e32 v9, v45
	v_mov_b32_e32 v26, v54
	v_mov_b32_e32 v27, v55
	v_mov_b32_e32 v28, v56
	v_mov_b32_e32 v29, v57
	v_mov_b32_e32 v14, v50
	v_mov_b32_e32 v15, v51
	v_mov_b32_e32 v16, v52
	v_mov_b32_e32 v17, v53
	v_mov_b32_e32 v30, v62
	v_mov_b32_e32 v31, v63
	v_mov_b32_e32 v32, v64
	v_mov_b32_e32 v33, v65
	v_mov_b32_e32 v10, v58
	v_mov_b32_e32 v11, v59
	v_mov_b32_e32 v12, v60
	v_mov_b32_e32 v13, v61
	s_cbranch_vccz .LBB0_8

.LBB0_145:
	s_mul_i32 s2, s35, s45
	s_add_i32 s2, s2, s36
	v_add_u32_e32 v10, s2, v72
	v_mad_u64_u32 v[8:9], s[2:3], v10, s6, 0
	v_ashrrev_i32_e32 v11, 31, v10
	v_mov_b32_e32 v12, v9
	s_ashr_i32 s21, s20, 31
	v_mad_u64_u32 v[12:13], s[2:3], v11, s6, v[12:13]
	s_waitcnt lgkmcnt(0)
	v_lshl_add_u64 v[6:7], s[20:21], 1, v[68:69]
	v_mov_b32_e32 v9, v12
	v_lshl_add_u64 v[8:9], v[8:9], 1, v[6:7]
	global_store_dwordx4 v[8:9], v[2:5], off sc1
	ds_read2_b32 v[8:9], v74 offset0:8 offset1:41
	s_andn2_b64 vcc, exec, s[14:15]
	v_cndmask_b32_e64 v2, 0, 1, s[14:15]
	v_cmp_ne_u32_e64 s[2:3], 1, v2
	s_mov_b64 s[20:21], -1
	s_cbranch_vccnz .LBB0_147
	ds_read2_b32 v[4:5], v74 offset0:74 offset1:107
	ds_read2_b32 v[12:13], v74 offset0:140 offset1:173
	ds_read2_b32 v[14:15], v74 offset0:206 offset1:239
	s_waitcnt lgkmcnt(3)
	v_cvt_pk_bf16_f32 v2, v8, v9
	s_mov_b64 s[20:21], 0
	s_waitcnt lgkmcnt(2)
	v_cvt_pk_bf16_f32 v3, v4, v5
	s_waitcnt lgkmcnt(1)
	v_cvt_pk_bf16_f32 v4, v12, v13
	s_waitcnt lgkmcnt(0)
	v_cvt_pk_bf16_f32 v5, v14, v15

.LBB0_149:
	s_waitcnt lgkmcnt(0)
	v_add_u32_e32 v8, 8, v10
	v_mad_u64_u32 v[12:13], s[20:21], v8, s6, 0
	v_ashrrev_i32_e32 v9, 31, v8
	v_mov_b32_e32 v8, v13
	v_mad_u64_u32 v[8:9], s[20:21], v9, s6, v[8:9]
	v_mov_b32_e32 v13, v8
	ds_read2_b32 v[8:9], v74 offset0:16 offset1:49
	v_lshl_add_u64 v[12:13], v[12:13], 1, v[6:7]
	s_and_b64 vcc, exec, s[2:3]
	s_mov_b64 s[20:21], -1
	global_store_dwordx4 v[12:13], v[2:5], off sc1
	s_cbranch_vccnz .LBB0_151
	ds_read2_b32 v[4:5], v74 offset0:82 offset1:115
	ds_read2_b32 v[12:13], v74 offset0:148 offset1:181
	ds_read2_b32 v[14:15], v74 offset0:214 offset1:247
	s_waitcnt lgkmcnt(3)
	v_cvt_pk_bf16_f32 v2, v8, v9
	s_mov_b64 s[20:21], 0
	s_waitcnt lgkmcnt(2)
	v_cvt_pk_bf16_f32 v3, v4, v5
	s_waitcnt lgkmcnt(1)
	v_cvt_pk_bf16_f32 v4, v12, v13
	s_waitcnt lgkmcnt(0)
	v_cvt_pk_bf16_f32 v5, v14, v15

.LBB0_153:
	s_waitcnt lgkmcnt(0)
	v_add_u32_e32 v8, 16, v10
	v_mad_u64_u32 v[12:13], s[20:21], v8, s6, 0
	v_ashrrev_i32_e32 v9, 31, v8
	v_mov_b32_e32 v8, v13
	v_mad_u64_u32 v[8:9], s[20:21], v9, s6, v[8:9]
	v_mov_b32_e32 v13, v8
	ds_read2_b32 v[8:9], v74 offset0:24 offset1:57
	v_lshl_add_u64 v[12:13], v[12:13], 1, v[6:7]
	s_and_b64 vcc, exec, s[2:3]
	s_mov_b64 s[2:3], -1
	global_store_dwordx4 v[12:13], v[2:5], off sc1
	s_cbranch_vccnz .LBB0_155
	ds_read2_b32 v[4:5], v74 offset0:90 offset1:123
	ds_read2_b32 v[12:13], v74 offset0:156 offset1:189
	ds_read2_b32 v[14:15], v74 offset0:222 offset1:255
	s_waitcnt lgkmcnt(3)
	v_cvt_pk_bf16_f32 v2, v8, v9
	s_mov_b64 s[2:3], 0
	s_waitcnt lgkmcnt(2)
	v_cvt_pk_bf16_f32 v3, v4, v5
	s_waitcnt lgkmcnt(1)
	v_cvt_pk_bf16_f32 v4, v12, v13
	s_waitcnt lgkmcnt(0)
	v_cvt_pk_bf16_f32 v5, v14, v15

.LBB0_324:
	s_waitcnt lgkmcnt(0)
	global_load_dwordx4 v[8:11], v[6:7], off offset:-3072 nt
	global_load_dwordx4 v[12:15], v[6:7], off offset:-2048 nt
	global_load_dwordx4 v[16:19], v[6:7], off offset:-1024 nt
	global_load_dwordx4 v[20:23], v[6:7], off nt
	v_mov_b32_e32 v24, 0
	v_mov_b32_e32 v25, 0
	v_mbcnt_lo_u32_b32 v24, -1, v24
	v_mbcnt_hi_u32_b32 v24, -1, v24
	v_lshlrev_b32_e32 v24, 2, v24
	v_xor_b32_e32 v24, 4, v24
	v_mov_b32_e32 v26, 0
	v_mbcnt_lo_u32_b32 v25, -1, v25
	v_mbcnt_hi_u32_b32 v25, -1, v25
	v_lshlrev_b32_e32 v25, 2, v25
	v_xor_b32_e32 v25, 8, v25
	v_mov_b32_e32 v27, 0
	v_mbcnt_lo_u32_b32 v26, -1, v26
	v_mbcnt_hi_u32_b32 v26, -1, v26
	v_lshlrev_b32_e32 v26, 2, v26
	v_xor_b32_e32 v26, 16, v26
	v_mov_b32_e32 v28, 0
	v_mbcnt_lo_u32_b32 v27, -1, v27
	v_mbcnt_hi_u32_b32 v27, -1, v27
	v_lshlrev_b32_e32 v27, 2, v27
	v_xor_b32_e32 v27, 32, v27
	v_mov_b32_e32 v29, 0
	v_mbcnt_lo_u32_b32 v28, -1, v28
	v_mbcnt_hi_u32_b32 v28, -1, v28
	v_lshlrev_b32_e32 v28, 2, v28
	v_xor_b32_e32 v28, 64, v28
	s_waitcnt vmcnt(3)
	v_mul_f32_e32 v30, v9, v9
	v_mul_f32_e32 v31, v11, v11
	s_waitcnt vmcnt(2)
	v_mul_f32_e32 v32, v13, v13
	v_mul_f32_e32 v33, v15, v15
	s_waitcnt vmcnt(1)
	v_mul_f32_e32 v34, v17, v17
	v_mul_f32_e32 v35, v19, v19
	v_fmac_f32_e32 v30, v8, v8
	v_fmac_f32_e32 v31, v10, v10
	v_fmac_f32_e32 v32, v12, v12
	v_fmac_f32_e32 v33, v14, v14
	s_waitcnt vmcnt(0)
	v_mul_f32_e32 v36, v21, v21
	v_mul_f32_e32 v37, v23, v23
	v_cvt_f16_f32_e32 v38, v8
	v_cvt_f16_f32_e32 v39, v10
	v_fmac_f32_e32 v34, v16, v16
	v_fmac_f32_e32 v35, v18, v18
	v_add_f32_e32 v8, v30, v31
	v_add_f32_e32 v10, v32, v33
	v_fmac_f32_e32 v36, v20, v20
	v_fmac_f32_e32 v37, v22, v22
	v_add_f32_e32 v30, v34, v35
	v_add_f32_e32 v8, v8, v10
	v_add_f32_e32 v31, v36, v37
	v_add_f32_e32 v8, v8, v30
	v_add_f32_e32 v8, v8, v31
	ds_bpermute_b32 v10, v24, v8
	v_cvt_f16_f32_e32 v12, v12
	v_cvt_f16_f32_sdwa v13, v13 dst_sel:WORD_1 dst_unused:UNUSED_PAD src0_sel:DWORD
	v_cvt_f16_f32_sdwa v9, v9 dst_sel:WORD_1 dst_unused:UNUSED_PAD src0_sel:DWORD
	v_cvt_f16_f32_sdwa v11, v11 dst_sel:WORD_1 dst_unused:UNUSED_PAD src0_sel:DWORD
	s_waitcnt lgkmcnt(0)
	v_add_f32_e32 v8, v8, v10
	ds_bpermute_b32 v10, v25, v8
	v_cvt_f16_f32_e32 v14, v14
	v_cvt_f16_f32_sdwa v15, v15 dst_sel:WORD_1 dst_unused:UNUSED_PAD src0_sel:DWORD
	v_mbcnt_lo_u32_b32 v29, -1, v29
	v_mbcnt_hi_u32_b32 v29, -1, v29
	s_waitcnt lgkmcnt(0)
	v_add_f32_e32 v8, v8, v10
	ds_bpermute_b32 v10, v26, v8
	v_lshlrev_b32_e32 v29, 2, v29
	v_xor_b32_e32 v29, 0x80, v29
	v_cvt_f16_f32_e32 v16, v16
	v_cvt_f16_f32_sdwa v17, v17 dst_sel:WORD_1 dst_unused:UNUSED_PAD src0_sel:DWORD
	s_waitcnt lgkmcnt(0)
	v_add_f32_e32 v24, v8, v10
	ds_bpermute_b32 v25, v27, v24
	v_or_b32_e32 v10, v13, v12
	v_or_b32_e32 v8, v9, v38
	v_or_b32_e32 v9, v11, v39
	v_or_b32_e32 v11, v15, v14
	s_waitcnt lgkmcnt(0)
	v_add_f32_e32 v13, v24, v25
	ds_bpermute_b32 v24, v28, v13
	global_store_dwordx2 v[4:5], v[8:9], off offset:-1024 sc1
	global_store_dwordx2 v[4:5], v[10:11], off offset:-512 sc1
	v_cvt_f16_f32_e32 v18, v18
	v_cvt_f16_f32_sdwa v19, v19 dst_sel:WORD_1 dst_unused:UNUSED_PAD src0_sel:DWORD
	v_cvt_f16_f32_e32 v20, v20
	s_waitcnt lgkmcnt(0)
	v_add_f32_e32 v8, v13, v24
	v_cvt_f16_f32_sdwa v21, v21 dst_sel:WORD_1 dst_unused:UNUSED_PAD src0_sel:DWORD
	v_cvt_f16_f32_e32 v22, v22
	v_cvt_f16_f32_sdwa v23, v23 dst_sel:WORD_1 dst_unused:UNUSED_PAD src0_sel:DWORD
	ds_bpermute_b32 v9, v29, v8
	v_or_b32_e32 v12, v17, v16
	v_or_b32_e32 v13, v19, v18
	v_or_b32_e32 v10, v21, v20
	v_or_b32_e32 v11, v23, v22
	global_store_dwordx2 v[4:5], v[12:13], off sc1
	global_store_dwordx2 v[4:5], v[10:11], off offset:512 sc1
	s_and_saveexec_b64 s[12:13], vcc
	s_cbranch_execz .LBB0_323
	s_waitcnt lgkmcnt(0)
	v_add_f32_e32 v8, v8, v9
	v_cndmask_b32_e64 v8, 0, v8, s[2:3]
	global_store_dword v[2:3], v8, off
	s_branch .LBB0_323

.LBB0_406:
	s_mov_b32 s7, s33
	v_lshl_or_b32 v190, s17, 7, v175
	v_mov_b32_e32 v130, s7
	ds_read2_b32 v[130:131], v130 offset1:1
	s_ashr_i32 s17, s16, 31
	s_lshl_b64 s[16:17], s[16:17], 8
	v_lshl_add_u64 v[170:171], s[16:17], 0, v[158:159]
	v_lshlrev_b64 v[132:133], 6, v[170:171]
	s_waitcnt lgkmcnt(0)
	v_readfirstlane_b32 s7, v130
	v_readfirstlane_b32 s9, v131
	v_mov_b32_e32 v174, v1
	v_mov_b32_e32 v186, s7
	s_mov_b32 s7, s33
	v_mov_b32_e32 v187, s9
	v_mov_b32_e32 v130, s7
	ds_read2_b32 v[130:131], v130 offset1:1
	v_ashrrev_i32_e32 v191, 31, v190
	v_mov_b64_e32 v[218:219], v[230:231]
	s_waitcnt lgkmcnt(0)
	v_readfirstlane_b32 s18, v130
	v_readfirstlane_b32 s19, v131
	s_nop 1
	v_lshl_add_u64 v[130:131], s[18:19], 0, v[0:1]
	v_lshl_add_u64 v[130:131], v[130:131], 0, v[132:133]
	v_add_co_u32_e32 v134, vcc, s58, v130
	s_mov_b64 s[18:19], 0x10380000
	s_nop 0
	v_addc_co_u32_e32 v135, vcc, 0, v131, vcc
	v_lshl_add_u64 v[132:133], v[130:131], 0, s[18:19]
	global_load_dwordx4 v[192:195], v[134:135], off
	global_load_dwordx4 v[196:199], v[132:133], off offset:1024
	global_load_dwordx4 v[200:203], v[132:133], off offset:2048
	global_load_dwordx4 v[146:149], v[132:133], off offset:3072
	v_add_co_u32_e32 v130, vcc, s59, v130
	s_mov_b64 s[18:19], 0xaa00000
	s_nop 0
	v_addc_co_u32_e32 v131, vcc, 0, v131, vcc
	global_load_dwordx4 v[142:145], v[130:131], off
	global_load_dwordx4 v[138:141], v[130:131], off offset:1024
	global_load_dwordx4 v[134:137], v[130:131], off offset:2048
	s_nop 0
	global_load_dwordx4 v[130:133], v[130:131], off offset:3072
	s_andn2_b64 vcc, exec, s[0:1]
	v_mbcnt_lo_u32_b32 v174, -1, v174
	v_mbcnt_hi_u32_b32 v174, -1, v174
	v_lshlrev_b32_e32 v174, 2, v174
	v_xor_b32_e32 v174, 64, v174
	s_waitcnt vmcnt(0)
	v_mov_b32_e32 v176, v193
	v_mov_b32_e32 v177, v194
	v_mov_b32_e32 v193, v195
	v_pk_add_f32 v[176:177], v[176:177], v[192:193]
	s_nop 0
	v_add_f32_e32 v172, v176, v177
	ds_bpermute_b32 v174, v174, v172
	v_mov_b32_e32 v176, v197
	v_mov_b32_e32 v177, v198
	v_mov_b32_e32 v197, v199
	v_pk_add_f32 v[176:177], v[176:177], v[196:197]
	s_waitcnt lgkmcnt(0)
	v_add_f32_e32 v172, v172, v174
	v_mov_b32_e32 v174, v1
	s_nop 0
	v_mbcnt_lo_u32_b32 v174, -1, v174
	v_mbcnt_hi_u32_b32 v174, -1, v174
	v_lshlrev_b32_e32 v174, 2, v174
	v_xor_b32_e32 v174, 0x80, v174
	ds_bpermute_b32 v174, v174, v172
	s_waitcnt lgkmcnt(0)
	v_add_f32_e32 v172, v172, v174
	v_mov_b32_e32 v174, v1
	v_fmamk_f32 v172, v172, 0x3a800000, v228
	v_mbcnt_lo_u32_b32 v174, -1, v174
	v_mbcnt_hi_u32_b32 v174, -1, v174
	v_lshlrev_b32_e32 v174, 2, v174
	v_rsq_f32_e32 v188, v172
	v_add_f32_e32 v172, v176, v177
	v_xor_b32_e32 v174, 64, v174
	ds_bpermute_b32 v174, v174, v172
	v_mov_b32_e32 v176, v201
	v_mov_b32_e32 v177, v202
	v_mov_b32_e32 v201, v203
	v_pk_add_f32 v[176:177], v[176:177], v[200:201]
	s_waitcnt lgkmcnt(0)
	v_add_f32_e32 v172, v172, v174
	v_mov_b32_e32 v174, v1
	v_pk_mul_f32 v[126:127], v[126:127], v[188:189] op_sel_hi:[1,0]
	v_mbcnt_lo_u32_b32 v174, -1, v174
	v_mbcnt_hi_u32_b32 v174, -1, v174
	v_lshlrev_b32_e32 v174, 2, v174
	v_xor_b32_e32 v174, 0x80, v174
	ds_bpermute_b32 v174, v174, v172
	v_pk_mul_f32 v[122:123], v[122:123], v[188:189] op_sel_hi:[1,0]
	v_pk_mul_f32 v[124:125], v[124:125], v[188:189] op_sel_hi:[1,0]
	v_pk_mul_f32 v[118:119], v[118:119], v[188:189] op_sel_hi:[1,0]
	v_pk_mul_f32 v[114:115], v[114:115], v[188:189] op_sel_hi:[1,0]
	s_waitcnt lgkmcnt(0)
	v_add_f32_e32 v172, v172, v174
	v_fmamk_f32 v172, v172, 0x3a800000, v228
	v_rsq_f32_e32 v174, v172
	v_add_f32_e32 v172, v176, v177
	v_mov_b32_e32 v176, v1
	v_mov_b32_e32 v177, v148
	v_mbcnt_lo_u32_b32 v176, -1, v176
	v_mbcnt_hi_u32_b32 v176, -1, v176
	v_lshlrev_b32_e32 v176, 2, v176
	v_xor_b32_e32 v176, 64, v176
	ds_bpermute_b32 v176, v176, v172
	v_mov_b32_e32 v148, v143
	v_mov_b32_e32 v143, v145
	v_mov_b32_e32 v145, v140
	v_mov_b32_e32 v140, v135
	s_waitcnt lgkmcnt(0)
	v_add_f32_e32 v172, v172, v176
	v_mov_b32_e32 v176, v1
	v_mov_b32_e32 v135, v137
	v_mbcnt_lo_u32_b32 v176, -1, v176
	v_mbcnt_hi_u32_b32 v176, -1, v176
	v_lshlrev_b32_e32 v176, 2, v176
	v_xor_b32_e32 v176, 0x80, v176
	ds_bpermute_b32 v176, v176, v172
	v_mov_b32_e32 v137, v132
	v_pk_mul_f32 v[116:117], v[116:117], v[188:189] op_sel_hi:[1,0]
	v_pk_mul_f32 v[110:111], v[110:111], v[174:175] op_sel_hi:[1,0]
	v_pk_mul_f32 v[106:107], v[106:107], v[174:175] op_sel_hi:[1,0]
	s_waitcnt lgkmcnt(0)
	v_add_f32_e32 v172, v172, v176
	v_mov_b32_e32 v176, v147
	v_mov_b32_e32 v147, v149
	v_pk_add_f32 v[146:147], v[176:177], v[146:147]
	v_mov_b32_e32 v149, v144
	v_add_f32_e32 v146, v146, v147
	v_mov_b32_e32 v147, v1
	v_pk_add_f32 v[142:143], v[148:149], v[142:143]
	v_mbcnt_lo_u32_b32 v147, -1, v147
	v_mbcnt_hi_u32_b32 v147, -1, v147
	v_lshlrev_b32_e32 v147, 2, v147
	v_xor_b32_e32 v147, 64, v147
	ds_bpermute_b32 v147, v147, v146
	v_add_f32_e32 v142, v142, v143
	v_mov_b32_e32 v143, v1
	v_mov_b32_e32 v144, v139
	v_mov_b32_e32 v139, v141
	s_waitcnt lgkmcnt(0)
	v_add_f32_e32 v146, v146, v147
	v_mov_b32_e32 v147, v1
	v_mov_b32_e32 v141, v136
	v_mbcnt_lo_u32_b32 v143, -1, v143
	v_mbcnt_hi_u32_b32 v143, -1, v143
	v_lshlrev_b32_e32 v143, 2, v143
	v_xor_b32_e32 v143, 64, v143
	ds_bpermute_b32 v143, v143, v142
	v_mov_b32_e32 v136, v131
	v_mov_b32_e32 v131, v133
	v_mul_f32_e32 v133, 0xbfb8aa3b, v126
	v_exp_f32_e32 v133, v133
	v_pk_add_f32 v[138:139], v[144:145], v[138:139]
	s_waitcnt lgkmcnt(0)
	v_add_f32_e32 v142, v142, v143
	v_mov_b32_e32 v143, v1
	v_add_f32_e32 v138, v138, v139
	v_mov_b32_e32 v139, v1
	v_add_f32_e32 v133, 1.0, v133
	v_mbcnt_lo_u32_b32 v139, -1, v139
	v_pk_add_f32 v[130:131], v[136:137], v[130:131]
	v_rcp_f32_e32 v136, v133
	v_mul_f32_e32 v133, 0xbfb8aa3b, v127
	v_mbcnt_hi_u32_b32 v139, -1, v139
	v_exp_f32_e32 v133, v133
	v_lshlrev_b32_e32 v139, 2, v139
	v_xor_b32_e32 v139, 64, v139
	ds_bpermute_b32 v139, v139, v138
	v_add_f32_e32 v133, 1.0, v133
	v_rcp_f32_e32 v137, v133
	v_pk_add_f32 v[134:135], v[140:141], v[134:135]
	v_add_f32_e32 v130, v130, v131
	s_waitcnt lgkmcnt(0)
	v_add_f32_e32 v138, v138, v139
	v_mov_b32_e32 v139, v1
	v_add_f32_e32 v134, v134, v135
	v_mov_b32_e32 v135, v1
	v_pk_mul_f32 v[126:127], v[126:127], v[136:137]
	v_mbcnt_lo_u32_b32 v135, -1, v135
	v_pk_mul_f32 v[122:123], v[122:123], v[126:127]
	v_pk_mul_f32 v[126:127], v[128:129], v[188:189] op_sel_hi:[1,0]
	v_mbcnt_hi_u32_b32 v135, -1, v135
	v_mul_f32_e32 v128, 0xbfb8aa3b, v126
	v_mul_f32_e32 v129, 0xbfb8aa3b, v127
	v_lshlrev_b32_e32 v135, 2, v135
	v_exp_f32_e32 v128, v128
	v_exp_f32_e32 v129, v129
	v_xor_b32_e32 v135, 64, v135
	ds_bpermute_b32 v135, v135, v134
	v_add_f32_e32 v128, 1.0, v128
	v_add_f32_e32 v129, 1.0, v129
	v_rcp_f32_e32 v128, v128
	v_rcp_f32_e32 v129, v129
	s_waitcnt lgkmcnt(0)
	v_add_f32_e32 v134, v134, v135
	v_mov_b32_e32 v135, v1
	v_mov_b32_e32 v131, v1
	v_pk_mul_f32 v[126:127], v[126:127], v[128:129]
	v_mbcnt_lo_u32_b32 v131, -1, v131
	v_mbcnt_hi_u32_b32 v131, -1, v131
	v_pk_mul_f32 v[124:125], v[124:125], v[126:127]
	v_mul_f32_e32 v126, 0xbfb8aa3b, v118
	v_mul_f32_e32 v127, 0xbfb8aa3b, v119
	v_lshlrev_b32_e32 v131, 2, v131
	v_exp_f32_e32 v126, v126
	v_exp_f32_e32 v127, v127
	v_xor_b32_e32 v131, 64, v131
	ds_bpermute_b32 v131, v131, v130
	v_add_f32_e32 v126, 1.0, v126
	v_add_f32_e32 v127, 1.0, v127
	v_rcp_f32_e32 v126, v126
	v_rcp_f32_e32 v127, v127
	s_waitcnt lgkmcnt(0)
	v_add_f32_e32 v130, v130, v131
	v_mov_b32_e32 v131, v1
	v_pk_mul_f32 v[118:119], v[118:119], v[126:127]
	v_mbcnt_lo_u32_b32 v131, -1, v131
	v_mbcnt_hi_u32_b32 v131, -1, v131
	v_pk_mul_f32 v[118:119], v[114:115], v[118:119]
	v_pk_mul_f32 v[114:115], v[120:121], v[188:189] op_sel_hi:[1,0]
	v_lshlrev_b32_e32 v131, 2, v131
	v_mul_f32_e32 v120, 0xbfb8aa3b, v114
	v_mul_f32_e32 v121, 0xbfb8aa3b, v115
	v_xor_b32_e32 v131, 0x80, v131
	v_exp_f32_e32 v120, v120
	v_exp_f32_e32 v121, v121
	ds_bpermute_b32 v131, v131, v130
	v_pk_mul_f32 v[108:109], v[108:109], v[174:175] op_sel_hi:[1,0]
	v_add_f32_e32 v120, 1.0, v120
	v_add_f32_e32 v121, 1.0, v121
	v_rcp_f32_e32 v120, v120
	v_rcp_f32_e32 v121, v121
	s_waitcnt lgkmcnt(0)
	v_add_f32_e32 v130, v130, v131
	v_fmamk_f32 v130, v130, 0x3a800000, v228
	v_rsq_f32_e32 v132, v130
	v_lshl_add_u64 v[130:131], v[190:191], 1, v[186:187]
	v_lshl_add_u64 v[130:131], v[130:131], 0, s[18:19]
	v_pk_mul_f32 v[114:115], v[114:115], v[120:121]
	v_pk_mul_f32 v[102:103], v[102:103], v[174:175] op_sel_hi:[1,0]
	v_pk_mul_f32 v[120:121], v[116:117], v[114:115]
	v_cvt_pk_bf16_f32 v116, v118, v119
	v_mad_u64_u32 v[118:119], s[18:19], v170, s89, v[130:131]
	v_cvt_pk_bf16_f32 v117, v120, v121
	v_mov_b32_e32 v120, v119
	v_mad_u64_u32 v[120:121], s[18:19], v171, s89, v[120:121]
	v_cvt_pk_bf16_f32 v114, v122, v123
	v_cvt_pk_bf16_f32 v115, v124, v125
	v_mov_b32_e32 v119, v120
	global_store_dwordx4 v[118:119], v[114:117], off sc1
	v_pk_mul_f32 v[98:99], v[98:99], v[174:175] op_sel_hi:[1,0]
	v_fmamk_f32 v172, v172, 0x3a800000, v228
	v_mul_f32_e32 v114, 0xbfb8aa3b, v110
	v_mul_f32_e32 v115, 0xbfb8aa3b, v111
	v_exp_f32_e32 v114, v114
	v_exp_f32_e32 v115, v115
	v_rsq_f32_e32 v172, v172
	v_pk_mul_f32 v[100:101], v[100:101], v[174:175] op_sel_hi:[1,0]
	v_add_f32_e32 v114, 1.0, v114
	v_add_f32_e32 v115, 1.0, v115
	v_rcp_f32_e32 v114, v114
	v_rcp_f32_e32 v115, v115
	v_pk_mul_f32 v[94:95], v[94:95], v[172:173] op_sel_hi:[1,0]
	v_pk_mul_f32 v[90:91], v[90:91], v[172:173] op_sel_hi:[1,0]
	v_pk_mul_f32 v[92:93], v[92:93], v[172:173] op_sel_hi:[1,0]
	v_pk_mul_f32 v[110:111], v[110:111], v[114:115]
	v_pk_mul_f32 v[86:87], v[86:87], v[172:173] op_sel_hi:[1,0]
	v_pk_mul_f32 v[106:107], v[106:107], v[110:111]
	v_pk_mul_f32 v[110:111], v[112:113], v[174:175] op_sel_hi:[1,0]
	v_pk_mul_f32 v[82:83], v[82:83], v[172:173] op_sel_hi:[1,0]
	v_mul_f32_e32 v112, 0xbfb8aa3b, v110
	v_mul_f32_e32 v113, 0xbfb8aa3b, v111
	v_exp_f32_e32 v112, v112
	v_exp_f32_e32 v113, v113
	v_mbcnt_lo_u32_b32 v147, -1, v147
	v_mbcnt_hi_u32_b32 v147, -1, v147
	v_add_f32_e32 v112, 1.0, v112
	v_add_f32_e32 v113, 1.0, v113
	v_rcp_f32_e32 v112, v112
	v_rcp_f32_e32 v113, v113
	v_lshlrev_b32_e32 v147, 2, v147
	v_xor_b32_e32 v147, 0x80, v147
	ds_bpermute_b32 v147, v147, v146
	v_pk_mul_f32 v[110:111], v[110:111], v[112:113]
	v_pk_mul_f32 v[84:85], v[84:85], v[172:173] op_sel_hi:[1,0]
	v_pk_mul_f32 v[108:109], v[108:109], v[110:111]
	v_mul_f32_e32 v110, 0xbfb8aa3b, v102
	v_mul_f32_e32 v111, 0xbfb8aa3b, v103
	v_exp_f32_e32 v110, v110
	v_exp_f32_e32 v111, v111
	s_waitcnt lgkmcnt(0)
	v_add_f32_e32 v146, v146, v147
	v_fmamk_f32 v146, v146, 0x3a800000, v228
	v_add_f32_e32 v110, 1.0, v110
	v_add_f32_e32 v111, 1.0, v111
	v_rcp_f32_e32 v110, v110
	v_rcp_f32_e32 v111, v111
	v_rsq_f32_e32 v146, v146
	v_mbcnt_lo_u32_b32 v143, -1, v143
	v_mbcnt_hi_u32_b32 v143, -1, v143
	v_pk_mul_f32 v[102:103], v[102:103], v[110:111]
	v_lshl_add_u64 v[110:111], v[160:161], 0, s[16:17]
	v_pk_mul_f32 v[102:103], v[98:99], v[102:103]
	v_pk_mul_f32 v[98:99], v[104:105], v[174:175] op_sel_hi:[1,0]
	v_pk_mul_f32 v[78:79], v[78:79], v[146:147] op_sel_hi:[1,0]
	v_mul_f32_e32 v104, 0xbfb8aa3b, v98
	v_mul_f32_e32 v105, 0xbfb8aa3b, v99
	v_exp_f32_e32 v104, v104
	v_exp_f32_e32 v105, v105
	v_pk_mul_f32 v[74:75], v[74:75], v[146:147] op_sel_hi:[1,0]
	v_pk_mul_f32 v[76:77], v[76:77], v[146:147] op_sel_hi:[1,0]
	v_add_f32_e32 v104, 1.0, v104
	v_add_f32_e32 v105, 1.0, v105
	v_rcp_f32_e32 v104, v104
	v_rcp_f32_e32 v105, v105
	v_pk_mul_f32 v[70:71], v[70:71], v[146:147] op_sel_hi:[1,0]
	v_pk_mul_f32 v[66:67], v[66:67], v[146:147] op_sel_hi:[1,0]
	v_lshlrev_b32_e32 v143, 2, v143
	v_pk_mul_f32 v[98:99], v[98:99], v[104:105]
	v_xor_b32_e32 v143, 0x80, v143
	v_pk_mul_f32 v[104:105], v[100:101], v[98:99]
	v_cvt_pk_bf16_f32 v100, v102, v103
	v_mad_u64_u32 v[102:103], s[18:19], v110, s89, v[130:131]
	v_cvt_pk_bf16_f32 v101, v104, v105
	v_mov_b32_e32 v104, v103
	v_mad_u64_u32 v[104:105], s[18:19], v111, s89, v[104:105]
	v_cvt_pk_bf16_f32 v98, v106, v107
	v_cvt_pk_bf16_f32 v99, v108, v109
	v_mov_b32_e32 v103, v104
	global_store_dwordx4 v[102:103], v[98:101], off sc1
	ds_bpermute_b32 v143, v143, v142
	v_pk_mul_f32 v[68:69], v[68:69], v[146:147] op_sel_hi:[1,0]
	v_mul_f32_e32 v98, 0xbfb8aa3b, v94
	v_mul_f32_e32 v99, 0xbfb8aa3b, v95
	v_exp_f32_e32 v98, v98
	v_exp_f32_e32 v99, v99
	s_waitcnt lgkmcnt(0)
	v_add_f32_e32 v142, v142, v143
	v_fmamk_f32 v142, v142, 0x3a800000, v228
	v_add_f32_e32 v98, 1.0, v98
	v_add_f32_e32 v99, 1.0, v99
	v_rcp_f32_e32 v98, v98
	v_rcp_f32_e32 v99, v99
	v_rsq_f32_e32 v142, v142
	v_mbcnt_lo_u32_b32 v139, -1, v139
	v_mbcnt_hi_u32_b32 v139, -1, v139
	v_pk_mul_f32 v[94:95], v[94:95], v[98:99]
	v_pk_mul_f32 v[62:63], v[62:63], v[142:143] op_sel_hi:[1,0]
	v_pk_mul_f32 v[90:91], v[90:91], v[94:95]
	v_pk_mul_f32 v[94:95], v[96:97], v[172:173] op_sel_hi:[1,0]
	v_pk_mul_f32 v[58:59], v[58:59], v[142:143] op_sel_hi:[1,0]
	v_mul_f32_e32 v96, 0xbfb8aa3b, v94
	v_mul_f32_e32 v97, 0xbfb8aa3b, v95
	v_exp_f32_e32 v96, v96
	v_exp_f32_e32 v97, v97
	v_pk_mul_f32 v[60:61], v[60:61], v[142:143] op_sel_hi:[1,0]
	v_pk_mul_f32 v[54:55], v[54:55], v[142:143] op_sel_hi:[1,0]
	v_add_f32_e32 v96, 1.0, v96
	v_add_f32_e32 v97, 1.0, v97
	v_rcp_f32_e32 v96, v96
	v_rcp_f32_e32 v97, v97
	v_pk_mul_f32 v[50:51], v[50:51], v[142:143] op_sel_hi:[1,0]
	v_lshlrev_b32_e32 v139, 2, v139
	v_xor_b32_e32 v139, 0x80, v139
	v_pk_mul_f32 v[94:95], v[94:95], v[96:97]
	ds_bpermute_b32 v139, v139, v138
	v_pk_mul_f32 v[92:93], v[92:93], v[94:95]
	v_mul_f32_e32 v94, 0xbfb8aa3b, v86
	v_mul_f32_e32 v95, 0xbfb8aa3b, v87
	v_exp_f32_e32 v94, v94
	v_exp_f32_e32 v95, v95
	s_waitcnt lgkmcnt(0)
	v_add_f32_e32 v138, v138, v139
	v_fmamk_f32 v138, v138, 0x3a800000, v228
	v_add_f32_e32 v94, 1.0, v94
	v_add_f32_e32 v95, 1.0, v95
	v_rcp_f32_e32 v94, v94
	v_rcp_f32_e32 v95, v95
	v_rsq_f32_e32 v138, v138
	v_pk_mul_f32 v[52:53], v[52:53], v[142:143] op_sel_hi:[1,0]
	v_mbcnt_lo_u32_b32 v135, -1, v135
	v_pk_mul_f32 v[86:87], v[86:87], v[94:95]
	v_lshl_add_u64 v[94:95], v[162:163], 0, s[16:17]
	v_pk_mul_f32 v[86:87], v[82:83], v[86:87]
	v_pk_mul_f32 v[82:83], v[88:89], v[172:173] op_sel_hi:[1,0]
	v_pk_mul_f32 v[46:47], v[46:47], v[138:139] op_sel_hi:[1,0]
	v_mul_f32_e32 v88, 0xbfb8aa3b, v82
	v_mul_f32_e32 v89, 0xbfb8aa3b, v83
	v_exp_f32_e32 v88, v88
	v_exp_f32_e32 v89, v89
	v_pk_mul_f32 v[42:43], v[42:43], v[138:139] op_sel_hi:[1,0]
	v_pk_mul_f32 v[44:45], v[44:45], v[138:139] op_sel_hi:[1,0]
	v_add_f32_e32 v88, 1.0, v88
	v_add_f32_e32 v89, 1.0, v89
	v_rcp_f32_e32 v88, v88
	v_rcp_f32_e32 v89, v89
	v_pk_mul_f32 v[38:39], v[38:39], v[138:139] op_sel_hi:[1,0]
	v_pk_mul_f32 v[34:35], v[34:35], v[138:139] op_sel_hi:[1,0]
	v_mbcnt_hi_u32_b32 v135, -1, v135
	v_pk_mul_f32 v[82:83], v[82:83], v[88:89]
	v_lshlrev_b32_e32 v135, 2, v135
	v_pk_mul_f32 v[88:89], v[84:85], v[82:83]
	v_cvt_pk_bf16_f32 v84, v86, v87
	v_mad_u64_u32 v[86:87], s[18:19], v94, s89, v[130:131]
	v_cvt_pk_bf16_f32 v85, v88, v89
	v_mov_b32_e32 v88, v87
	v_mad_u64_u32 v[88:89], s[18:19], v95, s89, v[88:89]
	v_cvt_pk_bf16_f32 v82, v90, v91
	v_cvt_pk_bf16_f32 v83, v92, v93
	v_mov_b32_e32 v87, v88
	global_store_dwordx4 v[86:87], v[82:85], off sc1
	v_xor_b32_e32 v135, 0x80, v135
	ds_bpermute_b32 v135, v135, v134
	v_mul_f32_e32 v82, 0xbfb8aa3b, v78
	v_mul_f32_e32 v83, 0xbfb8aa3b, v79
	v_exp_f32_e32 v82, v82
	v_exp_f32_e32 v83, v83
	s_waitcnt lgkmcnt(0)
	v_add_f32_e32 v134, v134, v135
	v_fmamk_f32 v134, v134, 0x3a800000, v228
	v_add_f32_e32 v82, 1.0, v82
	v_add_f32_e32 v83, 1.0, v83
	v_rcp_f32_e32 v82, v82
	v_rcp_f32_e32 v83, v83
	v_rsq_f32_e32 v134, v134
	v_pk_mul_f32 v[36:37], v[36:37], v[138:139] op_sel_hi:[1,0]
	v_pk_mul_f32 v[14:15], v[14:15], v[132:133] op_sel_hi:[1,0]
	v_pk_mul_f32 v[78:79], v[78:79], v[82:83]
	v_pk_mul_f32 v[30:31], v[30:31], v[134:135] op_sel_hi:[1,0]
	v_pk_mul_f32 v[74:75], v[74:75], v[78:79]
	v_pk_mul_f32 v[78:79], v[80:81], v[146:147] op_sel_hi:[1,0]
	v_pk_mul_f32 v[26:27], v[26:27], v[134:135] op_sel_hi:[1,0]
	v_mul_f32_e32 v80, 0xbfb8aa3b, v78
	v_mul_f32_e32 v81, 0xbfb8aa3b, v79
	v_exp_f32_e32 v80, v80
	v_exp_f32_e32 v81, v81
	v_pk_mul_f32 v[28:29], v[28:29], v[134:135] op_sel_hi:[1,0]
	v_pk_mul_f32 v[22:23], v[22:23], v[134:135] op_sel_hi:[1,0]
	v_add_f32_e32 v80, 1.0, v80
	v_add_f32_e32 v81, 1.0, v81
	v_rcp_f32_e32 v80, v80
	v_rcp_f32_e32 v81, v81
	v_pk_mul_f32 v[18:19], v[18:19], v[134:135] op_sel_hi:[1,0]
	v_pk_mul_f32 v[20:21], v[20:21], v[134:135] op_sel_hi:[1,0]
	v_pk_mul_f32 v[10:11], v[10:11], v[132:133] op_sel_hi:[1,0]
	v_pk_mul_f32 v[78:79], v[78:79], v[80:81]
	v_pk_mul_f32 v[12:13], v[12:13], v[132:133] op_sel_hi:[1,0]
	v_pk_mul_f32 v[76:77], v[76:77], v[78:79]
	v_mul_f32_e32 v78, 0xbfb8aa3b, v70
	v_mul_f32_e32 v79, 0xbfb8aa3b, v71
	v_exp_f32_e32 v78, v78
	v_exp_f32_e32 v79, v79
	v_pk_mul_f32 v[6:7], v[6:7], v[132:133] op_sel_hi:[1,0]
	v_pk_mul_f32 v[2:3], v[2:3], v[132:133] op_sel_hi:[1,0]
	v_add_f32_e32 v78, 1.0, v78
	v_add_f32_e32 v79, 1.0, v79
	v_rcp_f32_e32 v78, v78
	v_rcp_f32_e32 v79, v79
	v_pk_mul_f32 v[4:5], v[4:5], v[132:133] op_sel_hi:[1,0]
	v_pk_mul_f32 v[70:71], v[70:71], v[78:79]
	s_nop 0
	v_pk_mul_f32 v[70:71], v[66:67], v[70:71]
	v_pk_mul_f32 v[66:67], v[72:73], v[146:147] op_sel_hi:[1,0]
	v_lshl_add_u64 v[78:79], v[164:165], 0, s[16:17]
	v_mul_f32_e32 v72, 0xbfb8aa3b, v66
	v_mul_f32_e32 v73, 0xbfb8aa3b, v67
	v_exp_f32_e32 v72, v72
	v_exp_f32_e32 v73, v73
	v_add_f32_e32 v72, 1.0, v72
	v_add_f32_e32 v73, 1.0, v73
	v_rcp_f32_e32 v72, v72
	v_rcp_f32_e32 v73, v73
	s_nop 0
	v_pk_mul_f32 v[66:67], v[66:67], v[72:73]
	s_nop 0
	v_pk_mul_f32 v[72:73], v[68:69], v[66:67]
	v_cvt_pk_bf16_f32 v68, v70, v71
	v_mad_u64_u32 v[70:71], s[16:17], v78, s89, v[130:131]
	v_cvt_pk_bf16_f32 v69, v72, v73
	v_mov_b32_e32 v72, v71
	v_mad_u64_u32 v[72:73], s[16:17], v79, s89, v[72:73]
	v_cvt_pk_bf16_f32 v66, v74, v75
	v_cvt_pk_bf16_f32 v67, v76, v77
	v_mov_b32_e32 v71, v72
	global_store_dwordx4 v[70:71], v[66:69], off sc1
	s_nop 1
	v_mul_f32_e32 v66, 0xbfb8aa3b, v62
	v_mul_f32_e32 v67, 0xbfb8aa3b, v63
	v_exp_f32_e32 v66, v66
	v_exp_f32_e32 v67, v67
	v_add_f32_e32 v66, 1.0, v66
	v_add_f32_e32 v67, 1.0, v67
	v_rcp_f32_e32 v66, v66
	v_rcp_f32_e32 v67, v67
	s_nop 0
	v_pk_mul_f32 v[62:63], v[62:63], v[66:67]
	s_nop 0
	v_pk_mul_f32 v[58:59], v[58:59], v[62:63]
	v_pk_mul_f32 v[62:63], v[64:65], v[142:143] op_sel_hi:[1,0]
	s_nop 0
	v_mul_f32_e32 v64, 0xbfb8aa3b, v62
	v_mul_f32_e32 v65, 0xbfb8aa3b, v63
	v_exp_f32_e32 v64, v64
	v_exp_f32_e32 v65, v65
	v_add_f32_e32 v64, 1.0, v64
	v_add_f32_e32 v65, 1.0, v65
	v_rcp_f32_e32 v64, v64
	v_rcp_f32_e32 v65, v65
	s_nop 0
	v_pk_mul_f32 v[62:63], v[62:63], v[64:65]
	s_nop 0
	v_pk_mul_f32 v[60:61], v[60:61], v[62:63]
	v_mul_f32_e32 v62, 0xbfb8aa3b, v54
	v_mul_f32_e32 v63, 0xbfb8aa3b, v55
	v_exp_f32_e32 v62, v62
	v_exp_f32_e32 v63, v63
	v_add_f32_e32 v62, 1.0, v62
	v_add_f32_e32 v63, 1.0, v63
	v_rcp_f32_e32 v62, v62
	v_rcp_f32_e32 v63, v63
	s_nop 0
	v_pk_mul_f32 v[54:55], v[54:55], v[62:63]
	s_nop 0
	v_pk_mul_f32 v[54:55], v[50:51], v[54:55]
	v_pk_mul_f32 v[50:51], v[56:57], v[142:143] op_sel_hi:[1,0]
	v_lshl_add_u64 v[62:63], v[170:171], 0, s[96:97]
	v_mul_f32_e32 v56, 0xbfb8aa3b, v50
	v_mul_f32_e32 v57, 0xbfb8aa3b, v51
	v_exp_f32_e32 v56, v56
	v_exp_f32_e32 v57, v57
	v_add_f32_e32 v56, 1.0, v56
	v_add_f32_e32 v57, 1.0, v57
	v_rcp_f32_e32 v56, v56
	v_rcp_f32_e32 v57, v57
	s_nop 0
	v_pk_mul_f32 v[50:51], v[50:51], v[56:57]
	s_nop 0
	v_pk_mul_f32 v[56:57], v[52:53], v[50:51]
	v_cvt_pk_bf16_f32 v52, v54, v55
	v_mad_u64_u32 v[54:55], s[16:17], v62, s89, v[130:131]
	v_cvt_pk_bf16_f32 v53, v56, v57
	v_mov_b32_e32 v56, v55
	v_mad_u64_u32 v[56:57], s[16:17], v63, s89, v[56:57]
	v_cvt_pk_bf16_f32 v50, v58, v59
	v_cvt_pk_bf16_f32 v51, v60, v61
	v_mov_b32_e32 v55, v56
	global_store_dwordx4 v[54:55], v[50:53], off sc1
	s_mov_b64 s[16:17], 0x90
	s_nop 0
	v_mul_f32_e32 v50, 0xbfb8aa3b, v46
	v_mul_f32_e32 v51, 0xbfb8aa3b, v47
	v_exp_f32_e32 v50, v50
	v_exp_f32_e32 v51, v51
	v_add_f32_e32 v50, 1.0, v50
	v_add_f32_e32 v51, 1.0, v51
	v_rcp_f32_e32 v50, v50
	v_rcp_f32_e32 v51, v51
	s_nop 0
	v_pk_mul_f32 v[46:47], v[46:47], v[50:51]
	s_nop 0
	v_pk_mul_f32 v[42:43], v[42:43], v[46:47]
	v_pk_mul_f32 v[46:47], v[48:49], v[138:139] op_sel_hi:[1,0]
	s_nop 0
	v_mul_f32_e32 v48, 0xbfb8aa3b, v46
	v_mul_f32_e32 v49, 0xbfb8aa3b, v47
	v_exp_f32_e32 v48, v48
	v_exp_f32_e32 v49, v49
	v_add_f32_e32 v48, 1.0, v48
	v_add_f32_e32 v49, 1.0, v49
	v_rcp_f32_e32 v48, v48
	v_rcp_f32_e32 v49, v49
	s_nop 0
	v_pk_mul_f32 v[46:47], v[46:47], v[48:49]
	s_nop 0
	v_pk_mul_f32 v[44:45], v[44:45], v[46:47]
	v_mul_f32_e32 v46, 0xbfb8aa3b, v38
	v_mul_f32_e32 v47, 0xbfb8aa3b, v39
	v_exp_f32_e32 v46, v46
	v_exp_f32_e32 v47, v47
	v_add_f32_e32 v46, 1.0, v46
	v_add_f32_e32 v47, 1.0, v47
	v_rcp_f32_e32 v46, v46
	v_rcp_f32_e32 v47, v47
	s_nop 0
	v_pk_mul_f32 v[38:39], v[38:39], v[46:47]
	s_nop 0
	v_pk_mul_f32 v[38:39], v[34:35], v[38:39]
	v_pk_mul_f32 v[34:35], v[40:41], v[138:139] op_sel_hi:[1,0]
	v_lshl_add_u64 v[46:47], v[170:171], 0, s[16:17]
	v_mul_f32_e32 v40, 0xbfb8aa3b, v34
	v_mul_f32_e32 v41, 0xbfb8aa3b, v35
	v_exp_f32_e32 v40, v40
	v_exp_f32_e32 v41, v41
	v_add_f32_e32 v40, 1.0, v40
	v_add_f32_e32 v41, 1.0, v41
	v_rcp_f32_e32 v40, v40
	v_rcp_f32_e32 v41, v41
	s_nop 0
	v_pk_mul_f32 v[34:35], v[34:35], v[40:41]
	s_nop 0
	v_pk_mul_f32 v[40:41], v[36:37], v[34:35]
	v_cvt_pk_bf16_f32 v36, v38, v39
	v_mad_u64_u32 v[38:39], s[16:17], v46, s89, v[130:131]
	v_cvt_pk_bf16_f32 v37, v40, v41
	v_mov_b32_e32 v40, v39
	v_mad_u64_u32 v[40:41], s[16:17], v47, s89, v[40:41]
	v_cvt_pk_bf16_f32 v34, v42, v43
	v_cvt_pk_bf16_f32 v35, v44, v45
	v_mov_b32_e32 v39, v40
	global_store_dwordx4 v[38:39], v[34:37], off sc1
	s_mov_b64 s[16:17], 0xa0
	s_nop 0
	v_mul_f32_e32 v34, 0xbfb8aa3b, v30
	v_mul_f32_e32 v35, 0xbfb8aa3b, v31
	v_exp_f32_e32 v34, v34
	v_exp_f32_e32 v35, v35
	v_add_f32_e32 v34, 1.0, v34
	v_add_f32_e32 v35, 1.0, v35
	v_rcp_f32_e32 v34, v34
	v_rcp_f32_e32 v35, v35
	s_nop 0
	v_pk_mul_f32 v[30:31], v[30:31], v[34:35]
	s_nop 0
	v_pk_mul_f32 v[26:27], v[26:27], v[30:31]
	v_pk_mul_f32 v[30:31], v[32:33], v[134:135] op_sel_hi:[1,0]
	s_nop 0
	v_mul_f32_e32 v32, 0xbfb8aa3b, v30
	v_mul_f32_e32 v33, 0xbfb8aa3b, v31
	v_exp_f32_e32 v32, v32
	v_exp_f32_e32 v33, v33
	v_add_f32_e32 v32, 1.0, v32
	v_add_f32_e32 v33, 1.0, v33
	v_rcp_f32_e32 v32, v32
	v_rcp_f32_e32 v33, v33
	s_nop 0
	v_pk_mul_f32 v[30:31], v[30:31], v[32:33]
	s_nop 0
	v_pk_mul_f32 v[28:29], v[28:29], v[30:31]
	v_mul_f32_e32 v30, 0xbfb8aa3b, v22
	v_mul_f32_e32 v31, 0xbfb8aa3b, v23
	v_exp_f32_e32 v30, v30
	v_exp_f32_e32 v31, v31
	v_add_f32_e32 v30, 1.0, v30
	v_add_f32_e32 v31, 1.0, v31
	v_rcp_f32_e32 v30, v30
	v_rcp_f32_e32 v31, v31
	s_nop 0
	v_pk_mul_f32 v[22:23], v[22:23], v[30:31]
	s_nop 0
	v_pk_mul_f32 v[22:23], v[18:19], v[22:23]
	v_pk_mul_f32 v[18:19], v[24:25], v[134:135] op_sel_hi:[1,0]
	v_lshl_add_u64 v[30:31], v[170:171], 0, s[16:17]
	v_mul_f32_e32 v24, 0xbfb8aa3b, v18
	v_mul_f32_e32 v25, 0xbfb8aa3b, v19
	v_exp_f32_e32 v24, v24
	v_exp_f32_e32 v25, v25
	v_add_f32_e32 v24, 1.0, v24
	v_add_f32_e32 v25, 1.0, v25
	v_rcp_f32_e32 v24, v24
	v_rcp_f32_e32 v25, v25
	s_nop 0
	v_pk_mul_f32 v[18:19], v[18:19], v[24:25]
	s_nop 0
	v_pk_mul_f32 v[24:25], v[20:21], v[18:19]
	v_cvt_pk_bf16_f32 v20, v22, v23
	v_mad_u64_u32 v[22:23], s[16:17], v30, s89, v[130:131]
	v_cvt_pk_bf16_f32 v21, v24, v25
	v_mov_b32_e32 v24, v23
	v_mad_u64_u32 v[24:25], s[16:17], v31, s89, v[24:25]
	v_cvt_pk_bf16_f32 v18, v26, v27
	v_cvt_pk_bf16_f32 v19, v28, v29
	v_mov_b32_e32 v23, v24
	global_store_dwordx4 v[22:23], v[18:21], off sc1
	s_mov_b64 s[16:17], 0xb0
	s_nop 0
	v_mul_f32_e32 v18, 0xbfb8aa3b, v14
	v_mul_f32_e32 v19, 0xbfb8aa3b, v15
	v_exp_f32_e32 v18, v18
	v_exp_f32_e32 v19, v19
	v_add_f32_e32 v18, 1.0, v18
	v_add_f32_e32 v19, 1.0, v19
	v_rcp_f32_e32 v18, v18
	v_rcp_f32_e32 v19, v19
	s_nop 0
	v_pk_mul_f32 v[14:15], v[14:15], v[18:19]
	s_nop 0
	v_pk_mul_f32 v[10:11], v[10:11], v[14:15]
	v_pk_mul_f32 v[14:15], v[16:17], v[132:133] op_sel_hi:[1,0]
	s_nop 0
	v_mul_f32_e32 v16, 0xbfb8aa3b, v14
	v_mul_f32_e32 v17, 0xbfb8aa3b, v15
	v_exp_f32_e32 v16, v16
	v_exp_f32_e32 v17, v17
	v_add_f32_e32 v16, 1.0, v16
	v_add_f32_e32 v17, 1.0, v17
	v_rcp_f32_e32 v16, v16
	v_rcp_f32_e32 v17, v17
	s_nop 0
	v_pk_mul_f32 v[14:15], v[14:15], v[16:17]
	s_nop 0
	v_pk_mul_f32 v[12:13], v[12:13], v[14:15]
	v_mul_f32_e32 v14, 0xbfb8aa3b, v6
	v_mul_f32_e32 v15, 0xbfb8aa3b, v7
	v_exp_f32_e32 v14, v14
	v_exp_f32_e32 v15, v15
	v_add_f32_e32 v14, 1.0, v14
	v_add_f32_e32 v15, 1.0, v15
	v_rcp_f32_e32 v14, v14
	v_rcp_f32_e32 v15, v15
	s_nop 0
	v_pk_mul_f32 v[6:7], v[6:7], v[14:15]
	s_nop 0
	v_pk_mul_f32 v[6:7], v[2:3], v[6:7]
	v_pk_mul_f32 v[2:3], v[8:9], v[132:133] op_sel_hi:[1,0]
	v_lshl_add_u64 v[14:15], v[170:171], 0, s[16:17]
	v_mul_f32_e32 v8, 0xbfb8aa3b, v2
	v_mul_f32_e32 v9, 0xbfb8aa3b, v3
	v_exp_f32_e32 v8, v8
	v_exp_f32_e32 v9, v9
	v_add_f32_e32 v8, 1.0, v8
	v_add_f32_e32 v9, 1.0, v9
	v_rcp_f32_e32 v8, v8
	v_rcp_f32_e32 v9, v9
	s_nop 0
	v_pk_mul_f32 v[2:3], v[2:3], v[8:9]
	s_nop 0
	v_pk_mul_f32 v[8:9], v[4:5], v[2:3]
	v_cvt_pk_bf16_f32 v4, v6, v7
	v_mad_u64_u32 v[6:7], s[16:17], v14, s89, v[130:131]
	v_cvt_pk_bf16_f32 v5, v8, v9
	v_mov_b32_e32 v8, v7
	v_mad_u64_u32 v[8:9], s[16:17], v15, s89, v[8:9]
	v_cvt_pk_bf16_f32 v2, v10, v11
	v_cvt_pk_bf16_f32 v3, v12, v13
	v_mov_b32_e32 v7, v8
	s_mov_b64 s[16:17], -1
	global_store_dwordx4 v[6:7], v[2:5], off sc1
	s_cbranch_vccnz .LBB0_399
	s_andn2_b64 vcc, exec, s[2:3]
	s_cbranch_vccnz .LBB0_398
	s_barrier
	s_branch .LBB0_398

.LBB0_490:
	v_add_u32_e32 v0, 24, v0
	s_waitcnt lgkmcnt(0)
	v_mad_u64_u32 v[40:41], s[0:1], v0, s25, 0
	v_ashrrev_i32_e32 v42, 31, v0
	v_mov_b32_e32 v0, v41
	v_mad_u64_u32 v[42:43], s[0:1], v42, s25, v[0:1]
	v_mov_b32_e32 v41, v42
	v_lshl_add_u64 v[38:39], v[40:41], 1, v[38:39]
	global_store_dwordx4 v[38:39], v[34:37], off sc1
	s_waitcnt lgkmcnt(0)
	s_add_i32 s31, s31, s34
	s_add_i32 s36, s36, s37
	s_add_i32 s39, s39, s40
	s_andn2_b64 vcc, exec, s[18:19]
	s_mov_b32 s22, s41
	v_mov_b32_e32 v62, v6
	v_mov_b32_e32 v63, v7
	v_mov_b32_e32 v64, v8
	v_mov_b32_e32 v65, v9
	v_mov_b32_e32 v58, v2
	v_mov_b32_e32 v59, v3
	v_mov_b32_e32 v60, v4
	v_mov_b32_e32 v61, v5
	v_mov_b32_e32 v54, v14
	v_mov_b32_e32 v55, v15
	v_mov_b32_e32 v56, v16
	v_mov_b32_e32 v57, v17
	v_mov_b32_e32 v50, v10
	v_mov_b32_e32 v51, v11
	v_mov_b32_e32 v52, v12
	v_mov_b32_e32 v53, v13
	v_mov_b32_e32 v46, v22
	v_mov_b32_e32 v47, v23
	v_mov_b32_e32 v48, v24
	v_mov_b32_e32 v49, v25
	v_mov_b32_e32 v42, v18
	v_mov_b32_e32 v43, v19
	v_mov_b32_e32 v44, v20
	v_mov_b32_e32 v45, v21
	v_mov_b32_e32 v38, v30
	v_mov_b32_e32 v39, v31
	v_mov_b32_e32 v40, v32
	v_mov_b32_e32 v41, v33
	v_mov_b32_e32 v34, v26
	v_mov_b32_e32 v35, v27
	v_mov_b32_e32 v36, v28
	v_mov_b32_e32 v37, v29
	s_cbranch_vccz .LBB0_413

.LBB0_550:
	s_mul_i32 s0, s30, s42
	s_add_i32 s0, s0, s31
	v_add_u32_e32 v0, s0, v70
	v_mad_u64_u32 v[40:41], s[0:1], v0, s25, 0
	v_ashrrev_i32_e32 v43, 31, v0
	v_mov_b32_e32 v42, v41
	s_ashr_i32 s21, s20, 31
	v_mad_u64_u32 v[42:43], s[0:1], v43, s25, v[42:43]
	s_waitcnt lgkmcnt(0)
	v_lshl_add_u64 v[38:39], s[20:21], 1, v[66:67]
	v_mov_b32_e32 v41, v42
	v_lshl_add_u64 v[40:41], v[40:41], 1, v[38:39]
	global_store_dwordx4 v[40:41], v[34:37], off sc1
	ds_read2_b32 v[40:41], v72 offset0:8 offset1:41
	s_andn2_b64 vcc, exec, s[14:15]
	v_cndmask_b32_e64 v34, 0, 1, s[14:15]
	v_cmp_ne_u32_e64 s[0:1], 1, v34
	s_mov_b64 s[20:21], -1
	s_cbranch_vccnz .LBB0_552
	ds_read2_b32 v[36:37], v72 offset0:74 offset1:107
	ds_read2_b32 v[42:43], v72 offset0:206 offset1:239
	s_waitcnt lgkmcnt(2)
	v_cvt_pk_bf16_f32 v34, v40, v41
	s_mov_b64 s[20:21], 0
	s_waitcnt lgkmcnt(1)
	v_cvt_pk_bf16_f32 v35, v36, v37
	ds_read2_b32 v[36:37], v72 offset0:140 offset1:173
	s_waitcnt lgkmcnt(0)
	v_cvt_pk_bf16_f32 v36, v36, v37
	v_cvt_pk_bf16_f32 v37, v42, v43

.LBB0_554:
	s_waitcnt lgkmcnt(0)
	v_add_u32_e32 v40, 8, v0
	v_ashrrev_i32_e32 v43, 31, v40
	v_mad_u64_u32 v[40:41], s[20:21], v40, s25, 0
	v_mov_b32_e32 v42, v41
	v_mad_u64_u32 v[42:43], s[20:21], v43, s25, v[42:43]
	v_mov_b32_e32 v41, v42
	v_lshl_add_u64 v[40:41], v[40:41], 1, v[38:39]
	global_store_dwordx4 v[40:41], v[34:37], off sc1
	ds_read2_b32 v[40:41], v72 offset0:16 offset1:49
	s_mov_b64 s[20:21], -1
	s_and_b64 vcc, exec, s[0:1]
	s_cbranch_vccnz .LBB0_556
	ds_read2_b32 v[36:37], v72 offset0:82 offset1:115
	ds_read2_b32 v[42:43], v72 offset0:214 offset1:247
	s_waitcnt lgkmcnt(2)
	v_cvt_pk_bf16_f32 v34, v40, v41
	s_mov_b64 s[20:21], 0
	s_waitcnt lgkmcnt(1)
	v_cvt_pk_bf16_f32 v35, v36, v37
	ds_read2_b32 v[36:37], v72 offset0:148 offset1:181
	s_waitcnt lgkmcnt(0)
	v_cvt_pk_bf16_f32 v36, v36, v37
	v_cvt_pk_bf16_f32 v37, v42, v43

.LBB0_558:
	s_waitcnt lgkmcnt(0)
	v_add_u32_e32 v40, 16, v0
	v_ashrrev_i32_e32 v43, 31, v40
	v_mad_u64_u32 v[40:41], s[20:21], v40, s25, 0
	v_mov_b32_e32 v42, v41
	v_mad_u64_u32 v[42:43], s[20:21], v43, s25, v[42:43]
	v_mov_b32_e32 v41, v42
	v_lshl_add_u64 v[40:41], v[40:41], 1, v[38:39]
	global_store_dwordx4 v[40:41], v[34:37], off sc1
	ds_read2_b32 v[40:41], v72 offset0:24 offset1:57
	s_mov_b64 s[20:21], -1
	s_and_b64 vcc, exec, s[0:1]
	s_cbranch_vccnz .LBB0_560
	ds_read2_b32 v[36:37], v72 offset0:90 offset1:123
	ds_read2_b32 v[42:43], v72 offset0:222 offset1:255
	s_waitcnt lgkmcnt(2)
	v_cvt_pk_bf16_f32 v34, v40, v41
	s_mov_b64 s[20:21], 0
	s_waitcnt lgkmcnt(1)
	v_cvt_pk_bf16_f32 v35, v36, v37
	ds_read2_b32 v[36:37], v72 offset0:156 offset1:189
	s_waitcnt lgkmcnt(0)
	v_cvt_pk_bf16_f32 v36, v36, v37
	v_cvt_pk_bf16_f32 v37, v42, v43

.LBB0_646:
	v_add_u32_e32 v0, 0xffff8018, v0
	s_waitcnt lgkmcnt(0)
	v_mad_u64_u32 v[40:41], s[0:1], v0, s25, 0
	v_ashrrev_i32_e32 v42, 31, v0
	v_mov_b32_e32 v0, v41
	v_mad_u64_u32 v[42:43], s[0:1], v42, s25, v[0:1]
	v_mov_b32_e32 v41, v42
	v_lshl_add_u64 v[38:39], v[40:41], 1, v[38:39]
	global_store_dwordx4 v[38:39], v[34:37], off sc1
	s_waitcnt lgkmcnt(0)
	s_add_i32 s31, s31, 0x8000
	s_add_i32 s35, s35, 0x10000
	s_addk_i32 s37, 0x4000
	s_andn2_b64 vcc, exec, s[18:19]
	s_mov_b32 s22, s38
	v_mov_b32_e32 v62, v6
	v_mov_b32_e32 v63, v7
	v_mov_b32_e32 v64, v8
	v_mov_b32_e32 v65, v9
	v_mov_b32_e32 v58, v2
	v_mov_b32_e32 v59, v3
	v_mov_b32_e32 v60, v4
	v_mov_b32_e32 v61, v5
	v_mov_b32_e32 v54, v14
	v_mov_b32_e32 v55, v15
	v_mov_b32_e32 v56, v16
	v_mov_b32_e32 v57, v17
	v_mov_b32_e32 v50, v10
	v_mov_b32_e32 v51, v11
	v_mov_b32_e32 v52, v12
	v_mov_b32_e32 v53, v13
	v_mov_b32_e32 v46, v22
	v_mov_b32_e32 v47, v23
	v_mov_b32_e32 v48, v24
	v_mov_b32_e32 v49, v25
	v_mov_b32_e32 v42, v18
	v_mov_b32_e32 v43, v19
	v_mov_b32_e32 v44, v20
	v_mov_b32_e32 v45, v21
	v_mov_b32_e32 v38, v30
	v_mov_b32_e32 v39, v31
	v_mov_b32_e32 v40, v32
	v_mov_b32_e32 v41, v33
	v_mov_b32_e32 v34, v26
	v_mov_b32_e32 v35, v27
	v_mov_b32_e32 v36, v28
	v_mov_b32_e32 v37, v29
	s_cbranch_vccz .LBB0_569

.LBB0_706:
	s_mul_i32 s0, s30, s39
	s_add_i32 s0, s0, s31
	v_add_u32_e32 v0, s0, v70
	v_add_u32_e32 v40, 0xffff8000, v0
	v_ashrrev_i32_e32 v43, 31, v40
	v_mad_u64_u32 v[40:41], s[0:1], v40, s25, 0
	v_mov_b32_e32 v42, v41
	s_ashr_i32 s21, s20, 31
	v_mad_u64_u32 v[42:43], s[0:1], v43, s25, v[42:43]
	s_waitcnt lgkmcnt(0)
	v_lshl_add_u64 v[38:39], s[20:21], 1, v[66:67]
	v_mov_b32_e32 v41, v42
	v_lshl_add_u64 v[40:41], v[40:41], 1, v[38:39]
	global_store_dwordx4 v[40:41], v[34:37], off sc1
	ds_read2_b32 v[40:41], v72 offset0:8 offset1:41
	s_andn2_b64 vcc, exec, s[14:15]
	v_cndmask_b32_e64 v34, 0, 1, s[14:15]
	v_cmp_ne_u32_e64 s[0:1], 1, v34
	s_mov_b64 s[20:21], -1
	s_cbranch_vccnz .LBB0_708
	ds_read2_b32 v[36:37], v72 offset0:74 offset1:107
	ds_read2_b32 v[42:43], v72 offset0:206 offset1:239
	s_waitcnt lgkmcnt(2)
	v_cvt_pk_bf16_f32 v34, v40, v41
	s_mov_b64 s[20:21], 0
	s_waitcnt lgkmcnt(1)
	v_cvt_pk_bf16_f32 v35, v36, v37
	ds_read2_b32 v[36:37], v72 offset0:140 offset1:173
	s_waitcnt lgkmcnt(0)
	v_cvt_pk_bf16_f32 v36, v36, v37
	v_cvt_pk_bf16_f32 v37, v42, v43

.LBB0_710:
	s_waitcnt lgkmcnt(0)
	v_add_u32_e32 v40, 0xffff8008, v0
	v_ashrrev_i32_e32 v43, 31, v40
	v_mad_u64_u32 v[40:41], s[20:21], v40, s25, 0
	v_mov_b32_e32 v42, v41
	v_mad_u64_u32 v[42:43], s[20:21], v43, s25, v[42:43]
	v_mov_b32_e32 v41, v42
	v_lshl_add_u64 v[40:41], v[40:41], 1, v[38:39]
	global_store_dwordx4 v[40:41], v[34:37], off sc1
	ds_read2_b32 v[40:41], v72 offset0:16 offset1:49
	s_mov_b64 s[20:21], -1
	s_and_b64 vcc, exec, s[0:1]
	s_cbranch_vccnz .LBB0_712
	ds_read2_b32 v[36:37], v72 offset0:82 offset1:115
	ds_read2_b32 v[42:43], v72 offset0:214 offset1:247
	s_waitcnt lgkmcnt(2)
	v_cvt_pk_bf16_f32 v34, v40, v41
	s_mov_b64 s[20:21], 0
	s_waitcnt lgkmcnt(1)
	v_cvt_pk_bf16_f32 v35, v36, v37
	ds_read2_b32 v[36:37], v72 offset0:148 offset1:181
	s_waitcnt lgkmcnt(0)
	v_cvt_pk_bf16_f32 v36, v36, v37
	v_cvt_pk_bf16_f32 v37, v42, v43

.LBB0_714:
	s_waitcnt lgkmcnt(0)
	v_add_u32_e32 v40, 0xffff8010, v0
	v_ashrrev_i32_e32 v43, 31, v40
	v_mad_u64_u32 v[40:41], s[20:21], v40, s25, 0
	v_mov_b32_e32 v42, v41
	v_mad_u64_u32 v[42:43], s[20:21], v43, s25, v[42:43]
	v_mov_b32_e32 v41, v42
	v_lshl_add_u64 v[40:41], v[40:41], 1, v[38:39]
	global_store_dwordx4 v[40:41], v[34:37], off sc1
	ds_read2_b32 v[40:41], v72 offset0:24 offset1:57
	s_mov_b64 s[20:21], -1
	s_and_b64 vcc, exec, s[0:1]
	s_cbranch_vccnz .LBB0_716
	ds_read2_b32 v[36:37], v72 offset0:90 offset1:123
	ds_read2_b32 v[42:43], v72 offset0:222 offset1:255
	s_waitcnt lgkmcnt(2)
	v_cvt_pk_bf16_f32 v34, v40, v41
	s_mov_b64 s[20:21], 0
	s_waitcnt lgkmcnt(1)
	v_cvt_pk_bf16_f32 v35, v36, v37
	ds_read2_b32 v[36:37], v72 offset0:156 offset1:189
	s_waitcnt lgkmcnt(0)
	v_cvt_pk_bf16_f32 v36, v36, v37
	v_cvt_pk_bf16_f32 v37, v42, v43

.LBB0_801:
	s_mov_b32 s15, s93
	s_mov_b32 s18, s33
	v_mov_b32_e32 v138, s15
	ds_read2_b32 v[138:139], v138 offset1:1
	s_mov_b32 s15, s92
	s_ashr_i32 s15, s14, 31
	s_lshl_b64 s[14:15], s[14:15], 8
	s_waitcnt lgkmcnt(0)
	v_readfirstlane_b32 s16, v138
	v_lshl_or_b32 v138, s43, 8, v155
	v_lshl_add_u64 v[140:141], s[14:15], 0, v[132:133]
	v_readfirstlane_b32 s17, v139
	v_ashrrev_i32_e32 v139, 31, v138
	v_lshlrev_b64 v[144:145], 11, v[140:141]
	v_lshl_add_u64 v[142:143], s[16:17], 0, v[144:145]
	v_lshlrev_b64 v[146:147], 1, v[138:139]
	s_mov_b32 s18, s33
	v_lshl_add_u64 v[158:159], v[142:143], 0, v[146:147]
	global_load_dwordx2 v[160:161], v[158:159], off
	global_load_dwordx2 v[162:163], v[158:159], off offset:32
	global_load_dwordx2 v[164:165], v[158:159], off offset:256
	global_load_dwordx2 v[166:167], v[158:159], off offset:288
	v_mov_b32_e32 v142, s18
	ds_read2_b32 v[148:149], v142 offset1:1
	v_lshl_add_u64 v[142:143], s[16:17], 0, v[146:147]
	v_lshl_add_u64 v[144:145], v[142:143], 0, v[144:145]
	v_add_co_u32_e32 v146, vcc, s50, v144
	s_waitcnt lgkmcnt(0)
	v_readfirstlane_b32 s18, v148
	v_addc_co_u32_e32 v147, vcc, 0, v145, vcc
	v_readfirstlane_b32 s19, v149
	global_load_dwordx2 v[152:153], v[146:147], off
	global_load_dwordx2 v[150:151], v[146:147], off offset:32
	global_load_dwordx2 v[148:149], v[146:147], off offset:256
	s_nop 0
	global_load_dwordx2 v[146:147], v[146:147], off offset:288
	s_lshl_b32 s14, s43, 2
	s_ashr_i32 s15, s14, 31
	s_lshl_b64 s[14:15], s[14:15], 2
	s_add_u32 s14, s18, s14
	s_addc_u32 s15, s19, s15
	s_add_u32 s14, s14, s40
	s_addc_u32 s15, s15, 0
	s_add_u32 s14, s14, 0x10380000
	s_addc_u32 s15, s15, 0
	s_waitcnt vmcnt(0)
	v_cvt_f32_f16_e32 v168, v160
	v_cvt_f32_f16_sdwa v169, v160 dst_sel:DWORD dst_unused:UNUSED_PAD src0_sel:WORD_1
	v_cvt_f32_f16_e32 v160, v161
	v_cvt_f32_f16_sdwa v161, v161 dst_sel:DWORD dst_unused:UNUSED_PAD src0_sel:WORD_1
	v_cvt_f32_f16_e32 v170, v162
	v_cvt_f32_f16_sdwa v171, v162 dst_sel:DWORD dst_unused:UNUSED_PAD src0_sel:WORD_1
	v_cvt_f32_f16_e32 v162, v163
	v_cvt_f32_f16_sdwa v163, v163 dst_sel:DWORD dst_unused:UNUSED_PAD src0_sel:WORD_1
	v_cvt_f32_f16_e32 v172, v164
	v_cvt_f32_f16_sdwa v173, v164 dst_sel:DWORD dst_unused:UNUSED_PAD src0_sel:WORD_1
	v_cvt_f32_f16_e32 v164, v165
	v_cvt_f32_f16_sdwa v165, v165 dst_sel:DWORD dst_unused:UNUSED_PAD src0_sel:WORD_1
	v_cvt_f32_f16_e32 v174, v166
	v_cvt_f32_f16_sdwa v175, v166 dst_sel:DWORD dst_unused:UNUSED_PAD src0_sel:WORD_1
	v_cvt_f32_f16_e32 v166, v167
	v_cvt_f32_f16_sdwa v167, v167 dst_sel:DWORD dst_unused:UNUSED_PAD src0_sel:WORD_1
	v_pk_fma_f32 v[128:129], v[128:129], 0.5, v[160:161] op_sel_hi:[1,0,1]
	v_pk_fma_f32 v[126:127], v[126:127], 0.5, v[168:169] op_sel_hi:[1,0,1]
	v_pk_fma_f32 v[122:123], v[122:123], 0.5, v[170:171] op_sel_hi:[1,0,1]
	v_pk_fma_f32 v[124:125], v[124:125], 0.5, v[162:163] op_sel_hi:[1,0,1]
	v_pk_fma_f32 v[120:121], v[120:121], 0.5, v[164:165] op_sel_hi:[1,0,1]
	v_pk_fma_f32 v[118:119], v[118:119], 0.5, v[172:173] op_sel_hi:[1,0,1]
	v_cvt_f16_f32_e32 v157, v126
	v_cvt_f16_f32_sdwa v160, v127 dst_sel:WORD_1 dst_unused:UNUSED_PAD src0_sel:DWORD
	v_cvt_f16_f32_e32 v161, v128
	v_cvt_f16_f32_sdwa v162, v129 dst_sel:WORD_1 dst_unused:UNUSED_PAD src0_sel:DWORD
	v_cvt_f16_f32_e32 v163, v122
	v_cvt_f16_f32_sdwa v164, v123 dst_sel:WORD_1 dst_unused:UNUSED_PAD src0_sel:DWORD
	v_pk_fma_f32 v[116:117], v[116:117], 0.5, v[166:167] op_sel_hi:[1,0,1]
	v_mul_f32_e32 v127, v127, v127
	v_mul_f32_e32 v129, v129, v129
	v_cvt_f16_f32_e32 v165, v124
	v_cvt_f16_f32_sdwa v166, v125 dst_sel:WORD_1 dst_unused:UNUSED_PAD src0_sel:DWORD
	v_mul_f32_e32 v123, v123, v123
	v_mul_f32_e32 v125, v125, v125
	v_cvt_f16_f32_e32 v167, v118
	v_cvt_f16_f32_sdwa v168, v119 dst_sel:WORD_1 dst_unused:UNUSED_PAD src0_sel:DWORD
	v_cvt_f16_f32_e32 v169, v120
	v_cvt_f16_f32_sdwa v170, v121 dst_sel:WORD_1 dst_unused:UNUSED_PAD src0_sel:DWORD
	v_mul_f32_e32 v171, v119, v119
	v_fmac_f32_e32 v127, v126, v126
	v_fmac_f32_e32 v129, v128, v128
	v_fmac_f32_e32 v123, v122, v122
	v_fmac_f32_e32 v125, v124, v124
	v_mul_f32_e32 v172, v121, v121
	v_fmac_f32_e32 v171, v118, v118
	v_add_f32_e32 v118, v127, v129
	v_add_f32_e32 v119, v123, v125
	v_pk_fma_f32 v[114:115], v[114:115], 0.5, v[174:175] op_sel_hi:[1,0,1]
	v_fmac_f32_e32 v172, v120, v120
	v_add_f32_e32 v124, v118, v119
	v_or_b32_e32 v118, v160, v157
	v_or_b32_e32 v119, v162, v161
	v_or_b32_e32 v120, v164, v163
	v_cvt_f16_f32_e32 v173, v114
	v_cvt_f16_f32_sdwa v174, v115 dst_sel:WORD_1 dst_unused:UNUSED_PAD src0_sel:DWORD
	v_or_b32_e32 v121, v166, v165
	v_or_b32_e32 v122, v168, v167
	v_or_b32_e32 v123, v170, v169
	global_store_dwordx2 v[158:159], v[118:119], off sc1
	global_store_dwordx2 v[158:159], v[120:121], off offset:32 sc1
	global_store_dwordx2 v[158:159], v[122:123], off offset:256 sc1
	v_cvt_f16_f32_e32 v119, v116
	v_cvt_f16_f32_sdwa v120, v117 dst_sel:WORD_1 dst_unused:UNUSED_PAD src0_sel:DWORD
	v_mul_f32_e32 v115, v115, v115
	v_fmac_f32_e32 v115, v114, v114
	v_mul_f32_e32 v114, v117, v117
	v_add_f32_e32 v118, v171, v172
	v_fmac_f32_e32 v114, v116, v116
	v_add_f32_e32 v121, v124, v118
	v_or_b32_e32 v118, v174, v173
	v_or_b32_e32 v119, v120, v119
	v_add_f32_e32 v114, v115, v114
	v_mov_b32_e32 v115, v1
	global_store_dwordx2 v[158:159], v[118:119], off offset:288 sc1
	v_add_f32_e32 v114, v121, v114
	v_mbcnt_lo_u32_b32 v115, -1, v115
	v_mbcnt_hi_u32_b32 v115, -1, v115
	v_lshlrev_b32_e32 v115, 2, v115
	v_xor_b32_e32 v115, 64, v115
	ds_bpermute_b32 v115, v115, v114
	s_waitcnt lgkmcnt(0)
	v_add_f32_e32 v114, v114, v115
	v_mov_b32_e32 v115, v1
	s_nop 0
	v_mbcnt_lo_u32_b32 v115, -1, v115
	v_mbcnt_hi_u32_b32 v115, -1, v115
	v_lshlrev_b32_e32 v115, 2, v115
	v_xor_b32_e32 v115, 0x80, v115
	ds_bpermute_b32 v115, v115, v114
	s_and_saveexec_b64 s[18:19], s[0:1]
	s_cbranch_execz .LBB0_803
	v_lshlrev_b64 v[116:117], 6, v[140:141]
	v_lshl_add_u64 v[116:117], s[14:15], 0, v[116:117]
	s_waitcnt lgkmcnt(0)
	v_add_f32_e32 v114, v114, v115
	global_store_dword v[116:117], v114, off
.LBB0_803:
	s_or_b64 exec, exec, s[18:19]
	v_cvt_f32_f16_sdwa v117, v152 dst_sel:DWORD dst_unused:UNUSED_PAD src0_sel:WORD_1
	v_cvt_f32_f16_e32 v116, v152
	v_cvt_f32_f16_sdwa v119, v153 dst_sel:DWORD dst_unused:UNUSED_PAD src0_sel:WORD_1
	v_cvt_f32_f16_e32 v118, v153
	s_mov_b32 s18, 0x10000
	v_cvt_f32_f16_sdwa v129, v146 dst_sel:DWORD dst_unused:UNUSED_PAD src0_sel:WORD_1
	v_cvt_f32_f16_e32 v128, v146
	v_add_co_u32_e32 v146, vcc, s18, v144
	v_cvt_f32_f16_sdwa v125, v148 dst_sel:DWORD dst_unused:UNUSED_PAD src0_sel:WORD_1
	v_cvt_f32_f16_e32 v124, v148
	v_cvt_f32_f16_sdwa v127, v149 dst_sel:DWORD dst_unused:UNUSED_PAD src0_sel:WORD_1
	v_cvt_f32_f16_e32 v126, v149
	v_cvt_f32_f16_sdwa v149, v147 dst_sel:DWORD dst_unused:UNUSED_PAD src0_sel:WORD_1
	v_cvt_f32_f16_e32 v148, v147
	v_addc_co_u32_e32 v147, vcc, 0, v145, vcc
	v_cvt_f32_f16_sdwa v121, v150 dst_sel:DWORD dst_unused:UNUSED_PAD src0_sel:WORD_1
	v_cvt_f32_f16_e32 v120, v150
	v_cvt_f32_f16_sdwa v123, v151 dst_sel:DWORD dst_unused:UNUSED_PAD src0_sel:WORD_1
	v_cvt_f32_f16_e32 v122, v151
	v_pk_fma_f32 v[150:151], v[112:113], 0.5, v[118:119] op_sel_hi:[1,0,1]
	v_pk_fma_f32 v[152:153], v[110:111], 0.5, v[116:117] op_sel_hi:[1,0,1]
	global_load_dwordx2 v[118:119], v[146:147], off
	global_load_dwordx2 v[116:117], v[146:147], off offset:32
	global_load_dwordx2 v[112:113], v[146:147], off offset:256
	global_load_dwordx2 v[110:111], v[146:147], off offset:288
	v_cvt_f16_f32_e32 v157, v152
	v_cvt_f16_f32_sdwa v158, v153 dst_sel:WORD_1 dst_unused:UNUSED_PAD src0_sel:DWORD
	v_cvt_f16_f32_e32 v159, v150
	v_cvt_f16_f32_sdwa v160, v151 dst_sel:WORD_1 dst_unused:UNUSED_PAD src0_sel:DWORD
	v_pk_fma_f32 v[108:109], v[108:109], 0.5, v[122:123] op_sel_hi:[1,0,1]
	v_pk_fma_f32 v[106:107], v[106:107], 0.5, v[120:121] op_sel_hi:[1,0,1]
	v_cvt_f16_f32_e32 v122, v108
	v_cvt_f16_f32_e32 v120, v106
	v_cvt_f16_f32_sdwa v121, v107 dst_sel:WORD_1 dst_unused:UNUSED_PAD src0_sel:DWORD
	v_cvt_f16_f32_sdwa v123, v109 dst_sel:WORD_1 dst_unused:UNUSED_PAD src0_sel:DWORD
	v_or_b32_e32 v114, 16, v140
	s_waitcnt lgkmcnt(0)
	v_mov_b32_e32 v115, v141
	v_or_b32_e32 v146, v158, v157
	v_or_b32_e32 v147, v160, v159
	v_lshlrev_b64 v[158:159], 11, v[114:115]
	v_lshl_add_u64 v[158:159], s[16:17], 0, v[158:159]
	v_mul_f32_e32 v107, v107, v107
	v_lshl_add_u64 v[158:159], v[138:139], 1, v[158:159]
	v_or_b32_e32 v120, v121, v120
	v_or_b32_e32 v121, v123, v122
	v_fmac_f32_e32 v107, v106, v106
	v_mul_f32_e32 v106, v109, v109
	v_pk_fma_f32 v[104:105], v[104:105], 0.5, v[126:127] op_sel_hi:[1,0,1]
	v_pk_fma_f32 v[102:103], v[102:103], 0.5, v[124:125] op_sel_hi:[1,0,1]
	global_store_dwordx2 v[158:159], v[120:121], off offset:32 sc1
	v_fmac_f32_e32 v106, v108, v108
	v_cvt_f16_f32_e32 v108, v102
	v_cvt_f16_f32_sdwa v109, v103 dst_sel:WORD_1 dst_unused:UNUSED_PAD src0_sel:DWORD
	v_cvt_f16_f32_e32 v120, v104
	v_cvt_f16_f32_sdwa v121, v105 dst_sel:WORD_1 dst_unused:UNUSED_PAD src0_sel:DWORD
	global_store_dwordx2 v[158:159], v[146:147], off sc1
	v_mul_f32_e32 v146, v153, v153
	v_mul_f32_e32 v147, v151, v151
	v_fmac_f32_e32 v146, v152, v152
	v_fmac_f32_e32 v147, v150, v150
	v_add_f32_e32 v146, v146, v147
	v_add_f32_e32 v106, v107, v106
	v_mul_f32_e32 v103, v103, v103
	v_add_f32_e32 v122, v146, v106
	v_or_b32_e32 v106, v109, v108
	v_or_b32_e32 v107, v121, v120
	v_fmac_f32_e32 v103, v102, v102
	v_mul_f32_e32 v102, v105, v105
	v_pk_fma_f32 v[100:101], v[100:101], 0.5, v[148:149] op_sel_hi:[1,0,1]
	v_pk_fma_f32 v[98:99], v[98:99], 0.5, v[128:129] op_sel_hi:[1,0,1]
	global_store_dwordx2 v[158:159], v[106:107], off offset:256 sc1
	v_fmac_f32_e32 v102, v104, v104
	v_cvt_f16_f32_e32 v104, v98
	v_cvt_f16_f32_sdwa v105, v99 dst_sel:WORD_1 dst_unused:UNUSED_PAD src0_sel:DWORD
	v_cvt_f16_f32_e32 v106, v100
	v_cvt_f16_f32_sdwa v107, v101 dst_sel:WORD_1 dst_unused:UNUSED_PAD src0_sel:DWORD
	v_mul_f32_e32 v99, v99, v99
	v_fmac_f32_e32 v99, v98, v98
	v_mul_f32_e32 v98, v101, v101
	v_add_f32_e32 v102, v103, v102
	v_fmac_f32_e32 v98, v100, v100
	v_add_f32_e32 v108, v122, v102
	v_or_b32_e32 v102, v105, v104
	v_or_b32_e32 v103, v107, v106
	v_add_f32_e32 v98, v99, v98
	v_mov_b32_e32 v99, v1
	global_store_dwordx2 v[158:159], v[102:103], off offset:288 sc1
	v_add_f32_e32 v98, v108, v98
	v_mbcnt_lo_u32_b32 v99, -1, v99
	v_mbcnt_hi_u32_b32 v99, -1, v99
	v_lshlrev_b32_e32 v99, 2, v99
	v_xor_b32_e32 v99, 64, v99
	ds_bpermute_b32 v99, v99, v98
	s_waitcnt lgkmcnt(0)
	v_add_f32_e32 v98, v98, v99
	v_mov_b32_e32 v99, v1
	s_nop 0
	v_mbcnt_lo_u32_b32 v99, -1, v99
	v_mbcnt_hi_u32_b32 v99, -1, v99
	v_lshlrev_b32_e32 v99, 2, v99
	v_xor_b32_e32 v99, 0x80, v99
	ds_bpermute_b32 v99, v99, v98
	s_and_saveexec_b64 s[18:19], s[0:1]
	s_cbranch_execz .LBB0_805
	v_lshlrev_b64 v[100:101], 6, v[114:115]
	v_lshl_add_u64 v[100:101], s[14:15], 0, v[100:101]
	s_waitcnt lgkmcnt(0)
	v_add_f32_e32 v98, v98, v99
	global_store_dword v[100:101], v98, off
.LBB0_805:
	s_or_b64 exec, exec, s[18:19]
	s_waitcnt vmcnt(7)
	v_cvt_f32_f16_sdwa v101, v118 dst_sel:DWORD dst_unused:UNUSED_PAD src0_sel:WORD_1
	v_cvt_f32_f16_e32 v100, v118
	v_cvt_f32_f16_sdwa v103, v119 dst_sel:DWORD dst_unused:UNUSED_PAD src0_sel:WORD_1
	v_cvt_f32_f16_e32 v102, v119
	s_mov_b32 s18, 0x18000
	s_waitcnt vmcnt(5)
	v_cvt_f32_f16_sdwa v109, v112 dst_sel:DWORD dst_unused:UNUSED_PAD src0_sel:WORD_1
	v_cvt_f32_f16_e32 v108, v112
	v_cvt_f32_f16_sdwa v115, v113 dst_sel:DWORD dst_unused:UNUSED_PAD src0_sel:WORD_1
	v_cvt_f32_f16_e32 v114, v113
	s_waitcnt vmcnt(4)
	v_cvt_f32_f16_sdwa v113, v110 dst_sel:DWORD dst_unused:UNUSED_PAD src0_sel:WORD_1
	v_cvt_f32_f16_e32 v112, v110
	v_add_co_u32_e32 v110, vcc, s18, v144
	v_cvt_f32_f16_sdwa v105, v116 dst_sel:DWORD dst_unused:UNUSED_PAD src0_sel:WORD_1
	v_cvt_f32_f16_e32 v104, v116
	v_cvt_f32_f16_sdwa v107, v117 dst_sel:DWORD dst_unused:UNUSED_PAD src0_sel:WORD_1
	v_cvt_f32_f16_e32 v106, v117
	v_cvt_f32_f16_sdwa v117, v111 dst_sel:DWORD dst_unused:UNUSED_PAD src0_sel:WORD_1
	v_cvt_f32_f16_e32 v116, v111
	v_addc_co_u32_e32 v111, vcc, 0, v145, vcc
	v_pk_fma_f32 v[118:119], v[96:97], 0.5, v[102:103] op_sel_hi:[1,0,1]
	v_pk_fma_f32 v[120:121], v[94:95], 0.5, v[100:101] op_sel_hi:[1,0,1]
	global_load_dwordx2 v[102:103], v[110:111], off
	global_load_dwordx2 v[100:101], v[110:111], off offset:32
	global_load_dwordx2 v[96:97], v[110:111], off offset:256
	global_load_dwordx2 v[94:95], v[110:111], off offset:288
	v_cvt_f16_f32_e32 v122, v120
	v_cvt_f16_f32_sdwa v123, v121 dst_sel:WORD_1 dst_unused:UNUSED_PAD src0_sel:DWORD
	v_pk_fma_f32 v[92:93], v[92:93], 0.5, v[106:107] op_sel_hi:[1,0,1]
	v_pk_fma_f32 v[90:91], v[90:91], 0.5, v[104:105] op_sel_hi:[1,0,1]
	v_cvt_f16_f32_e32 v106, v92
	v_cvt_f16_f32_e32 v104, v90
	v_cvt_f16_f32_sdwa v105, v91 dst_sel:WORD_1 dst_unused:UNUSED_PAD src0_sel:DWORD
	v_cvt_f16_f32_sdwa v107, v93 dst_sel:WORD_1 dst_unused:UNUSED_PAD src0_sel:DWORD
	v_or_b32_e32 v98, 32, v140
	s_waitcnt lgkmcnt(0)
	v_mov_b32_e32 v99, v141
	v_cvt_f16_f32_e32 v124, v118
	v_cvt_f16_f32_sdwa v125, v119 dst_sel:WORD_1 dst_unused:UNUSED_PAD src0_sel:DWORD
	v_or_b32_e32 v110, v123, v122
	v_lshlrev_b64 v[122:123], 11, v[98:99]
	v_lshl_add_u64 v[122:123], s[16:17], 0, v[122:123]
	v_mul_f32_e32 v91, v91, v91
	v_lshl_add_u64 v[122:123], v[138:139], 1, v[122:123]
	v_or_b32_e32 v104, v105, v104
	v_or_b32_e32 v105, v107, v106
	v_fmac_f32_e32 v91, v90, v90
	v_mul_f32_e32 v90, v93, v93
	v_pk_fma_f32 v[88:89], v[88:89], 0.5, v[114:115] op_sel_hi:[1,0,1]
	v_pk_fma_f32 v[86:87], v[86:87], 0.5, v[108:109] op_sel_hi:[1,0,1]
	v_or_b32_e32 v111, v125, v124
	global_store_dwordx2 v[122:123], v[104:105], off offset:32 sc1
	v_fmac_f32_e32 v90, v92, v92
	v_cvt_f16_f32_e32 v92, v86
	v_cvt_f16_f32_sdwa v93, v87 dst_sel:WORD_1 dst_unused:UNUSED_PAD src0_sel:DWORD
	v_cvt_f16_f32_e32 v104, v88
	v_cvt_f16_f32_sdwa v105, v89 dst_sel:WORD_1 dst_unused:UNUSED_PAD src0_sel:DWORD
	global_store_dwordx2 v[122:123], v[110:111], off sc1
	v_mul_f32_e32 v110, v121, v121
	v_mul_f32_e32 v111, v119, v119
	v_fmac_f32_e32 v110, v120, v120
	v_fmac_f32_e32 v111, v118, v118
	v_add_f32_e32 v110, v110, v111
	v_add_f32_e32 v90, v91, v90
	v_mul_f32_e32 v87, v87, v87
	v_add_f32_e32 v106, v110, v90
	v_or_b32_e32 v90, v93, v92
	v_or_b32_e32 v91, v105, v104
	v_fmac_f32_e32 v87, v86, v86
	v_mul_f32_e32 v86, v89, v89
	v_pk_fma_f32 v[84:85], v[84:85], 0.5, v[116:117] op_sel_hi:[1,0,1]
	v_pk_fma_f32 v[82:83], v[82:83], 0.5, v[112:113] op_sel_hi:[1,0,1]
	global_store_dwordx2 v[122:123], v[90:91], off offset:256 sc1
	v_fmac_f32_e32 v86, v88, v88
	v_cvt_f16_f32_e32 v88, v82
	v_cvt_f16_f32_sdwa v89, v83 dst_sel:WORD_1 dst_unused:UNUSED_PAD src0_sel:DWORD
	v_cvt_f16_f32_e32 v90, v84
	v_cvt_f16_f32_sdwa v91, v85 dst_sel:WORD_1 dst_unused:UNUSED_PAD src0_sel:DWORD
	v_mul_f32_e32 v83, v83, v83
	v_fmac_f32_e32 v83, v82, v82
	v_mul_f32_e32 v82, v85, v85
	v_add_f32_e32 v86, v87, v86
	v_fmac_f32_e32 v82, v84, v84
	v_add_f32_e32 v92, v106, v86
	v_or_b32_e32 v86, v89, v88
	v_or_b32_e32 v87, v91, v90
	v_add_f32_e32 v82, v83, v82
	v_mov_b32_e32 v83, v1
	global_store_dwordx2 v[122:123], v[86:87], off offset:288 sc1
	v_add_f32_e32 v82, v92, v82
	v_mbcnt_lo_u32_b32 v83, -1, v83
	v_mbcnt_hi_u32_b32 v83, -1, v83
	v_lshlrev_b32_e32 v83, 2, v83
	v_xor_b32_e32 v83, 64, v83
	ds_bpermute_b32 v83, v83, v82
	s_waitcnt lgkmcnt(0)
	v_add_f32_e32 v82, v82, v83
	v_mov_b32_e32 v83, v1
	s_nop 0
	v_mbcnt_lo_u32_b32 v83, -1, v83
	v_mbcnt_hi_u32_b32 v83, -1, v83
	v_lshlrev_b32_e32 v83, 2, v83
	v_xor_b32_e32 v83, 0x80, v83
	ds_bpermute_b32 v83, v83, v82
	s_and_saveexec_b64 s[18:19], s[0:1]
	s_cbranch_execz .LBB0_807
	v_lshlrev_b64 v[84:85], 6, v[98:99]
	v_lshl_add_u64 v[84:85], s[14:15], 0, v[84:85]
	s_waitcnt lgkmcnt(0)
	v_add_f32_e32 v82, v82, v83
	global_store_dword v[84:85], v82, off
.LBB0_807:
	s_or_b64 exec, exec, s[18:19]
	s_waitcnt vmcnt(7)
	v_cvt_f32_f16_sdwa v85, v102 dst_sel:DWORD dst_unused:UNUSED_PAD src0_sel:WORD_1
	v_cvt_f32_f16_e32 v84, v102
	v_cvt_f32_f16_sdwa v87, v103 dst_sel:DWORD dst_unused:UNUSED_PAD src0_sel:WORD_1
	v_cvt_f32_f16_e32 v86, v103
	s_mov_b32 s18, 0x40000
	s_waitcnt vmcnt(5)
	v_cvt_f32_f16_sdwa v93, v96 dst_sel:DWORD dst_unused:UNUSED_PAD src0_sel:WORD_1
	v_cvt_f32_f16_e32 v92, v96
	v_cvt_f32_f16_sdwa v99, v97 dst_sel:DWORD dst_unused:UNUSED_PAD src0_sel:WORD_1
	v_cvt_f32_f16_e32 v98, v97
	s_waitcnt vmcnt(4)
	v_cvt_f32_f16_sdwa v97, v94 dst_sel:DWORD dst_unused:UNUSED_PAD src0_sel:WORD_1
	v_cvt_f32_f16_e32 v96, v94
	v_add_co_u32_e32 v94, vcc, s18, v144
	v_cvt_f32_f16_sdwa v89, v100 dst_sel:DWORD dst_unused:UNUSED_PAD src0_sel:WORD_1
	v_cvt_f32_f16_e32 v88, v100
	v_cvt_f32_f16_sdwa v91, v101 dst_sel:DWORD dst_unused:UNUSED_PAD src0_sel:WORD_1
	v_cvt_f32_f16_e32 v90, v101
	v_cvt_f32_f16_sdwa v101, v95 dst_sel:DWORD dst_unused:UNUSED_PAD src0_sel:WORD_1
	v_cvt_f32_f16_e32 v100, v95
	v_addc_co_u32_e32 v95, vcc, 0, v145, vcc
	v_pk_fma_f32 v[102:103], v[80:81], 0.5, v[86:87] op_sel_hi:[1,0,1]
	v_pk_fma_f32 v[104:105], v[78:79], 0.5, v[84:85] op_sel_hi:[1,0,1]
	global_load_dwordx2 v[86:87], v[94:95], off
	global_load_dwordx2 v[84:85], v[94:95], off offset:32
	global_load_dwordx2 v[80:81], v[94:95], off offset:256
	global_load_dwordx2 v[78:79], v[94:95], off offset:288
	v_cvt_f16_f32_e32 v106, v104
	v_cvt_f16_f32_sdwa v107, v105 dst_sel:WORD_1 dst_unused:UNUSED_PAD src0_sel:DWORD
	v_pk_fma_f32 v[76:77], v[76:77], 0.5, v[90:91] op_sel_hi:[1,0,1]
	v_pk_fma_f32 v[74:75], v[74:75], 0.5, v[88:89] op_sel_hi:[1,0,1]
	v_cvt_f16_f32_e32 v90, v76
	v_cvt_f16_f32_e32 v88, v74
	v_cvt_f16_f32_sdwa v89, v75 dst_sel:WORD_1 dst_unused:UNUSED_PAD src0_sel:DWORD
	v_cvt_f16_f32_sdwa v91, v77 dst_sel:WORD_1 dst_unused:UNUSED_PAD src0_sel:DWORD
	v_or_b32_e32 v82, 48, v140
	s_waitcnt lgkmcnt(0)
	v_mov_b32_e32 v83, v141
	v_cvt_f16_f32_e32 v108, v102
	v_cvt_f16_f32_sdwa v109, v103 dst_sel:WORD_1 dst_unused:UNUSED_PAD src0_sel:DWORD
	v_or_b32_e32 v94, v107, v106
	v_lshlrev_b64 v[106:107], 11, v[82:83]
	v_lshl_add_u64 v[106:107], s[16:17], 0, v[106:107]
	v_mul_f32_e32 v75, v75, v75
	v_lshl_add_u64 v[106:107], v[138:139], 1, v[106:107]
	v_or_b32_e32 v88, v89, v88
	v_or_b32_e32 v89, v91, v90
	v_fmac_f32_e32 v75, v74, v74
	v_mul_f32_e32 v74, v77, v77
	v_pk_fma_f32 v[72:73], v[72:73], 0.5, v[98:99] op_sel_hi:[1,0,1]
	v_pk_fma_f32 v[70:71], v[70:71], 0.5, v[92:93] op_sel_hi:[1,0,1]
	v_or_b32_e32 v95, v109, v108
	global_store_dwordx2 v[106:107], v[88:89], off offset:32 sc1
	v_fmac_f32_e32 v74, v76, v76
	v_cvt_f16_f32_e32 v76, v70
	v_cvt_f16_f32_sdwa v77, v71 dst_sel:WORD_1 dst_unused:UNUSED_PAD src0_sel:DWORD
	v_cvt_f16_f32_e32 v88, v72
	v_cvt_f16_f32_sdwa v89, v73 dst_sel:WORD_1 dst_unused:UNUSED_PAD src0_sel:DWORD
	global_store_dwordx2 v[106:107], v[94:95], off sc1
	v_mul_f32_e32 v94, v105, v105
	v_mul_f32_e32 v95, v103, v103
	v_fmac_f32_e32 v94, v104, v104
	v_fmac_f32_e32 v95, v102, v102
	v_add_f32_e32 v94, v94, v95
	v_add_f32_e32 v74, v75, v74
	v_mul_f32_e32 v71, v71, v71
	v_add_f32_e32 v90, v94, v74
	v_or_b32_e32 v74, v77, v76
	v_or_b32_e32 v75, v89, v88
	v_fmac_f32_e32 v71, v70, v70
	v_mul_f32_e32 v70, v73, v73
	v_pk_fma_f32 v[68:69], v[68:69], 0.5, v[100:101] op_sel_hi:[1,0,1]
	v_pk_fma_f32 v[66:67], v[66:67], 0.5, v[96:97] op_sel_hi:[1,0,1]
	global_store_dwordx2 v[106:107], v[74:75], off offset:256 sc1
	v_fmac_f32_e32 v70, v72, v72
	v_cvt_f16_f32_e32 v72, v66
	v_cvt_f16_f32_sdwa v73, v67 dst_sel:WORD_1 dst_unused:UNUSED_PAD src0_sel:DWORD
	v_cvt_f16_f32_e32 v74, v68
	v_cvt_f16_f32_sdwa v75, v69 dst_sel:WORD_1 dst_unused:UNUSED_PAD src0_sel:DWORD
	v_mul_f32_e32 v67, v67, v67
	v_fmac_f32_e32 v67, v66, v66
	v_mul_f32_e32 v66, v69, v69
	v_add_f32_e32 v70, v71, v70
	v_fmac_f32_e32 v66, v68, v68
	v_add_f32_e32 v76, v90, v70
	v_or_b32_e32 v70, v73, v72
	v_or_b32_e32 v71, v75, v74
	v_add_f32_e32 v66, v67, v66
	v_mov_b32_e32 v67, v1
	global_store_dwordx2 v[106:107], v[70:71], off offset:288 sc1
	v_add_f32_e32 v66, v76, v66
	v_mbcnt_lo_u32_b32 v67, -1, v67
	v_mbcnt_hi_u32_b32 v67, -1, v67
	v_lshlrev_b32_e32 v67, 2, v67
	v_xor_b32_e32 v67, 64, v67
	ds_bpermute_b32 v67, v67, v66
	s_waitcnt lgkmcnt(0)
	v_add_f32_e32 v66, v66, v67
	v_mov_b32_e32 v67, v1
	s_nop 0
	v_mbcnt_lo_u32_b32 v67, -1, v67
	v_mbcnt_hi_u32_b32 v67, -1, v67
	v_lshlrev_b32_e32 v67, 2, v67
	v_xor_b32_e32 v67, 0x80, v67
	ds_bpermute_b32 v67, v67, v66
	s_and_saveexec_b64 s[18:19], s[0:1]
	s_cbranch_execz .LBB0_809
	v_lshlrev_b64 v[68:69], 6, v[82:83]
	v_lshl_add_u64 v[68:69], s[14:15], 0, v[68:69]
	s_waitcnt lgkmcnt(0)
	v_add_f32_e32 v66, v66, v67
	global_store_dword v[68:69], v66, off
.LBB0_809:
	s_or_b64 exec, exec, s[18:19]
	s_waitcnt vmcnt(7)
	v_cvt_f32_f16_sdwa v71, v86 dst_sel:DWORD dst_unused:UNUSED_PAD src0_sel:WORD_1
	v_cvt_f32_f16_e32 v70, v86
	v_cvt_f32_f16_sdwa v73, v87 dst_sel:DWORD dst_unused:UNUSED_PAD src0_sel:WORD_1
	v_cvt_f32_f16_e32 v72, v87
	v_lshl_add_u64 v[68:69], v[140:141], 0, s[96:97]
	s_waitcnt lgkmcnt(0)
	v_lshlrev_b64 v[66:67], 11, v[68:69]
	v_or_b32_e32 v88, 0x8000, v66
	v_mov_b32_e32 v89, v67
	v_lshl_add_u64 v[88:89], v[142:143], 0, v[88:89]
	v_pk_fma_f32 v[90:91], v[64:65], 0.5, v[72:73] op_sel_hi:[1,0,1]
	v_pk_fma_f32 v[92:93], v[62:63], 0.5, v[70:71] op_sel_hi:[1,0,1]
	global_load_dwordx2 v[72:73], v[88:89], off
	global_load_dwordx2 v[70:71], v[88:89], off offset:32
	global_load_dwordx2 v[64:65], v[88:89], off offset:256
	global_load_dwordx2 v[62:63], v[88:89], off offset:288
	s_waitcnt vmcnt(10)
	v_cvt_f32_f16_sdwa v75, v84 dst_sel:DWORD dst_unused:UNUSED_PAD src0_sel:WORD_1
	v_cvt_f32_f16_e32 v74, v84
	v_cvt_f32_f16_sdwa v77, v85 dst_sel:DWORD dst_unused:UNUSED_PAD src0_sel:WORD_1
	v_cvt_f32_f16_e32 v76, v85
	s_waitcnt vmcnt(9)
	v_cvt_f32_f16_sdwa v83, v80 dst_sel:DWORD dst_unused:UNUSED_PAD src0_sel:WORD_1
	v_pk_fma_f32 v[58:59], v[58:59], 0.5, v[74:75] op_sel_hi:[1,0,1]
	v_cvt_f32_f16_e32 v82, v80
	v_pk_fma_f32 v[60:61], v[60:61], 0.5, v[76:77] op_sel_hi:[1,0,1]
	v_cvt_f32_f16_sdwa v85, v81 dst_sel:DWORD dst_unused:UNUSED_PAD src0_sel:WORD_1
	v_cvt_f32_f16_e32 v84, v81
	v_cvt_f16_f32_e32 v74, v58
	v_cvt_f16_f32_sdwa v75, v59 dst_sel:WORD_1 dst_unused:UNUSED_PAD src0_sel:DWORD
	v_cvt_f16_f32_e32 v76, v60
	v_cvt_f16_f32_sdwa v77, v61 dst_sel:WORD_1 dst_unused:UNUSED_PAD src0_sel:DWORD
	s_waitcnt vmcnt(8)
	v_cvt_f32_f16_sdwa v81, v78 dst_sel:DWORD dst_unused:UNUSED_PAD src0_sel:WORD_1
	v_cvt_f32_f16_e32 v80, v78
	v_cvt_f16_f32_e32 v78, v92
	v_cvt_f16_f32_sdwa v94, v93 dst_sel:WORD_1 dst_unused:UNUSED_PAD src0_sel:DWORD
	v_cvt_f16_f32_e32 v95, v90
	v_cvt_f16_f32_sdwa v96, v91 dst_sel:WORD_1 dst_unused:UNUSED_PAD src0_sel:DWORD
	v_lshl_add_u64 v[88:89], s[16:17], 0, v[66:67]
	v_mul_f32_e32 v59, v59, v59
	v_lshl_add_u64 v[88:89], v[138:139], 1, v[88:89]
	v_or_b32_e32 v74, v75, v74
	v_or_b32_e32 v75, v77, v76
	v_fmac_f32_e32 v59, v58, v58
	v_mul_f32_e32 v58, v61, v61
	v_pk_fma_f32 v[56:57], v[56:57], 0.5, v[84:85] op_sel_hi:[1,0,1]
	v_pk_fma_f32 v[54:55], v[54:55], 0.5, v[82:83] op_sel_hi:[1,0,1]
	v_cvt_f32_f16_sdwa v87, v79 dst_sel:DWORD dst_unused:UNUSED_PAD src0_sel:WORD_1
	v_cvt_f32_f16_e32 v86, v79
	v_or_b32_e32 v78, v94, v78
	v_or_b32_e32 v79, v96, v95
	global_store_dwordx2 v[88:89], v[74:75], off offset:32 sc1
	v_fmac_f32_e32 v58, v60, v60
	v_cvt_f16_f32_e32 v60, v54
	v_cvt_f16_f32_sdwa v61, v55 dst_sel:WORD_1 dst_unused:UNUSED_PAD src0_sel:DWORD
	v_cvt_f16_f32_e32 v74, v56
	v_cvt_f16_f32_sdwa v75, v57 dst_sel:WORD_1 dst_unused:UNUSED_PAD src0_sel:DWORD
	global_store_dwordx2 v[88:89], v[78:79], off sc1
	v_mul_f32_e32 v78, v93, v93
	v_mul_f32_e32 v79, v91, v91
	v_fmac_f32_e32 v78, v92, v92
	v_fmac_f32_e32 v79, v90, v90
	v_add_f32_e32 v78, v78, v79
	v_add_f32_e32 v58, v59, v58
	v_mul_f32_e32 v55, v55, v55
	v_add_f32_e32 v76, v78, v58
	v_or_b32_e32 v58, v61, v60
	v_or_b32_e32 v59, v75, v74
	v_fmac_f32_e32 v55, v54, v54
	v_mul_f32_e32 v54, v57, v57
	v_pk_fma_f32 v[52:53], v[52:53], 0.5, v[86:87] op_sel_hi:[1,0,1]
	v_pk_fma_f32 v[50:51], v[50:51], 0.5, v[80:81] op_sel_hi:[1,0,1]
	global_store_dwordx2 v[88:89], v[58:59], off offset:256 sc1
	v_fmac_f32_e32 v54, v56, v56
	v_cvt_f16_f32_e32 v56, v50
	v_cvt_f16_f32_sdwa v57, v51 dst_sel:WORD_1 dst_unused:UNUSED_PAD src0_sel:DWORD
	v_cvt_f16_f32_e32 v58, v52
	v_cvt_f16_f32_sdwa v59, v53 dst_sel:WORD_1 dst_unused:UNUSED_PAD src0_sel:DWORD
	v_mul_f32_e32 v51, v51, v51
	v_fmac_f32_e32 v51, v50, v50
	v_mul_f32_e32 v50, v53, v53
	v_add_f32_e32 v54, v55, v54
	v_fmac_f32_e32 v50, v52, v52
	v_add_f32_e32 v60, v76, v54
	v_or_b32_e32 v54, v57, v56
	v_or_b32_e32 v55, v59, v58
	v_add_f32_e32 v50, v51, v50
	v_mov_b32_e32 v51, v1
	global_store_dwordx2 v[88:89], v[54:55], off offset:288 sc1
	v_add_f32_e32 v50, v60, v50
	v_mbcnt_lo_u32_b32 v51, -1, v51
	v_mbcnt_hi_u32_b32 v51, -1, v51
	v_lshlrev_b32_e32 v51, 2, v51
	v_xor_b32_e32 v51, 64, v51
	ds_bpermute_b32 v51, v51, v50
	s_waitcnt lgkmcnt(0)
	v_add_f32_e32 v50, v50, v51
	v_mov_b32_e32 v51, v1
	s_nop 0
	v_mbcnt_lo_u32_b32 v51, -1, v51
	v_mbcnt_hi_u32_b32 v51, -1, v51
	v_lshlrev_b32_e32 v51, 2, v51
	v_xor_b32_e32 v51, 0x80, v51
	ds_bpermute_b32 v51, v51, v50
	s_and_saveexec_b64 s[18:19], s[0:1]
	s_cbranch_execz .LBB0_811
	v_lshlrev_b64 v[52:53], 6, v[68:69]
	v_lshl_add_u64 v[52:53], s[14:15], 0, v[52:53]
	s_waitcnt lgkmcnt(0)
	v_add_f32_e32 v50, v50, v51
	global_store_dword v[52:53], v50, off
.LBB0_811:
	s_or_b64 exec, exec, s[18:19]
	s_waitcnt vmcnt(7)
	v_cvt_f32_f16_sdwa v53, v72 dst_sel:DWORD dst_unused:UNUSED_PAD src0_sel:WORD_1
	v_cvt_f32_f16_e32 v52, v72
	v_cvt_f32_f16_sdwa v55, v73 dst_sel:DWORD dst_unused:UNUSED_PAD src0_sel:WORD_1
	v_cvt_f32_f16_e32 v54, v73
	s_waitcnt vmcnt(6)
	v_cvt_f32_f16_sdwa v57, v70 dst_sel:DWORD dst_unused:UNUSED_PAD src0_sel:WORD_1
	v_cvt_f32_f16_e32 v56, v70
	v_cvt_f32_f16_sdwa v59, v71 dst_sel:DWORD dst_unused:UNUSED_PAD src0_sel:WORD_1
	v_cvt_f32_f16_e32 v58, v71
	s_waitcnt vmcnt(5)
	v_cvt_f32_f16_sdwa v61, v64 dst_sel:DWORD dst_unused:UNUSED_PAD src0_sel:WORD_1
	v_cvt_f32_f16_e32 v60, v64
	v_cvt_f32_f16_sdwa v69, v65 dst_sel:DWORD dst_unused:UNUSED_PAD src0_sel:WORD_1
	v_cvt_f32_f16_e32 v68, v65
	s_waitcnt vmcnt(4)
	v_cvt_f32_f16_sdwa v65, v62 dst_sel:DWORD dst_unused:UNUSED_PAD src0_sel:WORD_1
	v_cvt_f32_f16_e32 v64, v62
	v_cvt_f32_f16_sdwa v71, v63 dst_sel:DWORD dst_unused:UNUSED_PAD src0_sel:WORD_1
	v_cvt_f32_f16_e32 v70, v63
	v_or_b32_e32 v62, 0x10000, v66
	v_mov_b32_e32 v63, v67
	v_lshl_add_u64 v[62:63], v[142:143], 0, v[62:63]
	v_pk_fma_f32 v[72:73], v[48:49], 0.5, v[54:55] op_sel_hi:[1,0,1]
	v_pk_fma_f32 v[74:75], v[46:47], 0.5, v[52:53] op_sel_hi:[1,0,1]
	global_load_dwordx2 v[54:55], v[62:63], off
	global_load_dwordx2 v[52:53], v[62:63], off offset:32
	global_load_dwordx2 v[48:49], v[62:63], off offset:256
	global_load_dwordx2 v[46:47], v[62:63], off offset:288
	v_cvt_f16_f32_e32 v76, v74
	v_cvt_f16_f32_sdwa v77, v75 dst_sel:WORD_1 dst_unused:UNUSED_PAD src0_sel:DWORD
	v_pk_fma_f32 v[44:45], v[44:45], 0.5, v[58:59] op_sel_hi:[1,0,1]
	v_pk_fma_f32 v[42:43], v[42:43], 0.5, v[56:57] op_sel_hi:[1,0,1]
	s_mov_b64 s[18:19], 0x90
	v_cvt_f16_f32_e32 v56, v42
	v_cvt_f16_f32_sdwa v57, v43 dst_sel:WORD_1 dst_unused:UNUSED_PAD src0_sel:DWORD
	v_cvt_f16_f32_e32 v58, v44
	v_cvt_f16_f32_sdwa v59, v45 dst_sel:WORD_1 dst_unused:UNUSED_PAD src0_sel:DWORD
	s_waitcnt lgkmcnt(0)
	v_lshl_add_u64 v[50:51], v[140:141], 0, s[18:19]
	v_cvt_f16_f32_e32 v78, v72
	v_cvt_f16_f32_sdwa v79, v73 dst_sel:WORD_1 dst_unused:UNUSED_PAD src0_sel:DWORD
	v_or_b32_e32 v62, v77, v76
	v_lshlrev_b64 v[76:77], 11, v[50:51]
	v_lshl_add_u64 v[76:77], s[16:17], 0, v[76:77]
	v_mul_f32_e32 v43, v43, v43
	v_lshl_add_u64 v[76:77], v[138:139], 1, v[76:77]
	v_or_b32_e32 v56, v57, v56
	v_or_b32_e32 v57, v59, v58
	v_fmac_f32_e32 v43, v42, v42
	v_mul_f32_e32 v42, v45, v45
	v_pk_fma_f32 v[40:41], v[40:41], 0.5, v[68:69] op_sel_hi:[1,0,1]
	v_pk_fma_f32 v[38:39], v[38:39], 0.5, v[60:61] op_sel_hi:[1,0,1]
	v_or_b32_e32 v63, v79, v78
	global_store_dwordx2 v[76:77], v[56:57], off offset:32 sc1
	v_fmac_f32_e32 v42, v44, v44
	v_cvt_f16_f32_e32 v44, v38
	v_cvt_f16_f32_sdwa v45, v39 dst_sel:WORD_1 dst_unused:UNUSED_PAD src0_sel:DWORD
	v_cvt_f16_f32_e32 v56, v40
	v_cvt_f16_f32_sdwa v57, v41 dst_sel:WORD_1 dst_unused:UNUSED_PAD src0_sel:DWORD
	global_store_dwordx2 v[76:77], v[62:63], off sc1
	v_mul_f32_e32 v62, v75, v75
	v_mul_f32_e32 v63, v73, v73
	v_fmac_f32_e32 v62, v74, v74
	v_fmac_f32_e32 v63, v72, v72
	v_add_f32_e32 v62, v62, v63
	v_add_f32_e32 v42, v43, v42
	v_mul_f32_e32 v39, v39, v39
	v_add_f32_e32 v58, v62, v42
	v_or_b32_e32 v42, v45, v44
	v_or_b32_e32 v43, v57, v56
	v_fmac_f32_e32 v39, v38, v38
	v_mul_f32_e32 v38, v41, v41
	v_pk_fma_f32 v[36:37], v[36:37], 0.5, v[70:71] op_sel_hi:[1,0,1]
	v_pk_fma_f32 v[34:35], v[34:35], 0.5, v[64:65] op_sel_hi:[1,0,1]
	global_store_dwordx2 v[76:77], v[42:43], off offset:256 sc1
	v_fmac_f32_e32 v38, v40, v40
	v_cvt_f16_f32_e32 v40, v34
	v_cvt_f16_f32_sdwa v41, v35 dst_sel:WORD_1 dst_unused:UNUSED_PAD src0_sel:DWORD
	v_cvt_f16_f32_e32 v42, v36
	v_cvt_f16_f32_sdwa v43, v37 dst_sel:WORD_1 dst_unused:UNUSED_PAD src0_sel:DWORD
	v_mul_f32_e32 v35, v35, v35
	v_fmac_f32_e32 v35, v34, v34
	v_mul_f32_e32 v34, v37, v37
	v_add_f32_e32 v38, v39, v38
	v_fmac_f32_e32 v34, v36, v36
	v_add_f32_e32 v44, v58, v38
	v_or_b32_e32 v38, v41, v40
	v_or_b32_e32 v39, v43, v42
	v_add_f32_e32 v34, v35, v34
	v_mov_b32_e32 v35, v1
	global_store_dwordx2 v[76:77], v[38:39], off offset:288 sc1
	v_add_f32_e32 v34, v44, v34
	v_mbcnt_lo_u32_b32 v35, -1, v35
	v_mbcnt_hi_u32_b32 v35, -1, v35
	v_lshlrev_b32_e32 v35, 2, v35
	v_xor_b32_e32 v35, 64, v35
	ds_bpermute_b32 v35, v35, v34
	s_waitcnt lgkmcnt(0)
	v_add_f32_e32 v34, v34, v35
	v_mov_b32_e32 v35, v1
	s_nop 0
	v_mbcnt_lo_u32_b32 v35, -1, v35
	v_mbcnt_hi_u32_b32 v35, -1, v35
	v_lshlrev_b32_e32 v35, 2, v35
	v_xor_b32_e32 v35, 0x80, v35
	ds_bpermute_b32 v35, v35, v34
	s_and_saveexec_b64 s[18:19], s[0:1]
	s_cbranch_execz .LBB0_813
	v_lshlrev_b64 v[36:37], 6, v[50:51]
	v_lshl_add_u64 v[36:37], s[14:15], 0, v[36:37]
	s_waitcnt lgkmcnt(0)
	v_add_f32_e32 v34, v34, v35
	global_store_dword v[36:37], v34, off
.LBB0_813:
	s_or_b64 exec, exec, s[18:19]
	s_waitcnt vmcnt(7)
	v_cvt_f32_f16_sdwa v37, v54 dst_sel:DWORD dst_unused:UNUSED_PAD src0_sel:WORD_1
	v_cvt_f32_f16_e32 v36, v54
	v_cvt_f32_f16_sdwa v39, v55 dst_sel:DWORD dst_unused:UNUSED_PAD src0_sel:WORD_1
	v_cvt_f32_f16_e32 v38, v55
	v_or_b32_e32 v66, 0x18000, v66
	s_waitcnt vmcnt(6)
	v_cvt_f32_f16_sdwa v41, v52 dst_sel:DWORD dst_unused:UNUSED_PAD src0_sel:WORD_1
	v_cvt_f32_f16_e32 v40, v52
	v_cvt_f32_f16_sdwa v43, v53 dst_sel:DWORD dst_unused:UNUSED_PAD src0_sel:WORD_1
	v_cvt_f32_f16_e32 v42, v53
	s_waitcnt vmcnt(5)
	v_cvt_f32_f16_sdwa v45, v48 dst_sel:DWORD dst_unused:UNUSED_PAD src0_sel:WORD_1
	v_cvt_f32_f16_e32 v44, v48
	v_cvt_f32_f16_sdwa v51, v49 dst_sel:DWORD dst_unused:UNUSED_PAD src0_sel:WORD_1
	v_cvt_f32_f16_e32 v50, v49
	s_waitcnt vmcnt(4)
	v_cvt_f32_f16_sdwa v49, v46 dst_sel:DWORD dst_unused:UNUSED_PAD src0_sel:WORD_1
	v_cvt_f32_f16_e32 v48, v46
	v_cvt_f32_f16_sdwa v53, v47 dst_sel:DWORD dst_unused:UNUSED_PAD src0_sel:WORD_1
	v_cvt_f32_f16_e32 v52, v47
	v_lshl_add_u64 v[46:47], v[142:143], 0, v[66:67]
	v_pk_fma_f32 v[54:55], v[32:33], 0.5, v[38:39] op_sel_hi:[1,0,1]
	v_pk_fma_f32 v[56:57], v[30:31], 0.5, v[36:37] op_sel_hi:[1,0,1]
	global_load_dwordx2 v[38:39], v[46:47], off
	global_load_dwordx2 v[36:37], v[46:47], off offset:32
	global_load_dwordx2 v[32:33], v[46:47], off offset:256
	global_load_dwordx2 v[30:31], v[46:47], off offset:288
	v_cvt_f16_f32_e32 v58, v56
	v_cvt_f16_f32_sdwa v59, v57 dst_sel:WORD_1 dst_unused:UNUSED_PAD src0_sel:DWORD
	v_pk_fma_f32 v[28:29], v[28:29], 0.5, v[42:43] op_sel_hi:[1,0,1]
	v_pk_fma_f32 v[26:27], v[26:27], 0.5, v[40:41] op_sel_hi:[1,0,1]
	s_mov_b64 s[18:19], 0xa0
	v_cvt_f16_f32_e32 v40, v26
	v_cvt_f16_f32_sdwa v41, v27 dst_sel:WORD_1 dst_unused:UNUSED_PAD src0_sel:DWORD
	v_cvt_f16_f32_e32 v42, v28
	v_cvt_f16_f32_sdwa v43, v29 dst_sel:WORD_1 dst_unused:UNUSED_PAD src0_sel:DWORD
	s_waitcnt lgkmcnt(0)
	v_lshl_add_u64 v[34:35], v[140:141], 0, s[18:19]
	v_cvt_f16_f32_e32 v60, v54
	v_cvt_f16_f32_sdwa v61, v55 dst_sel:WORD_1 dst_unused:UNUSED_PAD src0_sel:DWORD
	v_or_b32_e32 v46, v59, v58
	v_lshlrev_b64 v[58:59], 11, v[34:35]
	v_lshl_add_u64 v[58:59], s[16:17], 0, v[58:59]
	v_mul_f32_e32 v27, v27, v27
	v_lshl_add_u64 v[58:59], v[138:139], 1, v[58:59]
	v_or_b32_e32 v40, v41, v40
	v_or_b32_e32 v41, v43, v42
	v_fmac_f32_e32 v27, v26, v26
	v_mul_f32_e32 v26, v29, v29
	v_pk_fma_f32 v[24:25], v[24:25], 0.5, v[50:51] op_sel_hi:[1,0,1]
	v_pk_fma_f32 v[22:23], v[22:23], 0.5, v[44:45] op_sel_hi:[1,0,1]
	v_or_b32_e32 v47, v61, v60
	global_store_dwordx2 v[58:59], v[40:41], off offset:32 sc1
	v_fmac_f32_e32 v26, v28, v28
	v_cvt_f16_f32_e32 v28, v22
	v_cvt_f16_f32_sdwa v29, v23 dst_sel:WORD_1 dst_unused:UNUSED_PAD src0_sel:DWORD
	v_cvt_f16_f32_e32 v40, v24
	v_cvt_f16_f32_sdwa v41, v25 dst_sel:WORD_1 dst_unused:UNUSED_PAD src0_sel:DWORD
	global_store_dwordx2 v[58:59], v[46:47], off sc1
	v_mul_f32_e32 v46, v57, v57
	v_mul_f32_e32 v47, v55, v55
	v_fmac_f32_e32 v46, v56, v56
	v_fmac_f32_e32 v47, v54, v54
	v_add_f32_e32 v46, v46, v47
	v_add_f32_e32 v26, v27, v26
	v_mul_f32_e32 v23, v23, v23
	v_add_f32_e32 v42, v46, v26
	v_or_b32_e32 v26, v29, v28
	v_or_b32_e32 v27, v41, v40
	v_fmac_f32_e32 v23, v22, v22
	v_mul_f32_e32 v22, v25, v25
	v_pk_fma_f32 v[20:21], v[20:21], 0.5, v[52:53] op_sel_hi:[1,0,1]
	v_pk_fma_f32 v[18:19], v[18:19], 0.5, v[48:49] op_sel_hi:[1,0,1]
	global_store_dwordx2 v[58:59], v[26:27], off offset:256 sc1
	v_fmac_f32_e32 v22, v24, v24
	v_cvt_f16_f32_e32 v24, v18
	v_cvt_f16_f32_sdwa v25, v19 dst_sel:WORD_1 dst_unused:UNUSED_PAD src0_sel:DWORD
	v_cvt_f16_f32_e32 v26, v20
	v_cvt_f16_f32_sdwa v27, v21 dst_sel:WORD_1 dst_unused:UNUSED_PAD src0_sel:DWORD
	v_mul_f32_e32 v19, v19, v19
	v_fmac_f32_e32 v19, v18, v18
	v_mul_f32_e32 v18, v21, v21
	v_add_f32_e32 v22, v23, v22
	v_fmac_f32_e32 v18, v20, v20
	v_add_f32_e32 v28, v42, v22
	v_or_b32_e32 v22, v25, v24
	v_or_b32_e32 v23, v27, v26
	v_add_f32_e32 v18, v19, v18
	v_mov_b32_e32 v19, v1
	global_store_dwordx2 v[58:59], v[22:23], off offset:288 sc1
	v_add_f32_e32 v18, v28, v18
	v_mbcnt_lo_u32_b32 v19, -1, v19
	v_mbcnt_hi_u32_b32 v19, -1, v19
	v_lshlrev_b32_e32 v19, 2, v19
	v_xor_b32_e32 v19, 64, v19
	ds_bpermute_b32 v19, v19, v18
	s_waitcnt lgkmcnt(0)
	v_add_f32_e32 v18, v18, v19
	v_mov_b32_e32 v19, v1
	s_nop 0
	v_mbcnt_lo_u32_b32 v19, -1, v19
	v_mbcnt_hi_u32_b32 v19, -1, v19
	v_lshlrev_b32_e32 v19, 2, v19
	v_xor_b32_e32 v19, 0x80, v19
	ds_bpermute_b32 v19, v19, v18
	s_and_saveexec_b64 s[18:19], s[0:1]
	s_cbranch_execz .LBB0_815
	v_lshlrev_b64 v[20:21], 6, v[34:35]
	v_lshl_add_u64 v[20:21], s[14:15], 0, v[20:21]
	s_waitcnt lgkmcnt(0)
	v_add_f32_e32 v18, v18, v19
	global_store_dword v[20:21], v18, off
.LBB0_815:
	s_or_b64 exec, exec, s[18:19]
	s_waitcnt vmcnt(7)
	v_cvt_f32_f16_sdwa v21, v38 dst_sel:DWORD dst_unused:UNUSED_PAD src0_sel:WORD_1
	v_cvt_f32_f16_e32 v20, v38
	v_cvt_f32_f16_sdwa v23, v39 dst_sel:DWORD dst_unused:UNUSED_PAD src0_sel:WORD_1
	v_cvt_f32_f16_e32 v22, v39
	s_waitcnt vmcnt(6)
	v_cvt_f32_f16_sdwa v25, v36 dst_sel:DWORD dst_unused:UNUSED_PAD src0_sel:WORD_1
	v_cvt_f32_f16_e32 v24, v36
	v_pk_fma_f32 v[14:15], v[14:15], 0.5, v[20:21] op_sel_hi:[1,0,1]
	v_cvt_f32_f16_sdwa v27, v37 dst_sel:DWORD dst_unused:UNUSED_PAD src0_sel:WORD_1
	v_cvt_f32_f16_e32 v26, v37
	v_cvt_f16_f32_e32 v20, v14
	v_cvt_f16_f32_sdwa v21, v15 dst_sel:WORD_1 dst_unused:UNUSED_PAD src0_sel:DWORD
	v_pk_fma_f32 v[16:17], v[16:17], 0.5, v[22:23] op_sel_hi:[1,0,1]
	v_mul_f32_e32 v15, v15, v15
	v_fmac_f32_e32 v15, v14, v14
	v_mul_f32_e32 v14, v17, v17
	s_waitcnt vmcnt(5)
	v_cvt_f32_f16_sdwa v29, v32 dst_sel:DWORD dst_unused:UNUSED_PAD src0_sel:WORD_1
	v_cvt_f32_f16_e32 v28, v32
	v_fmac_f32_e32 v14, v16, v16
	v_pk_fma_f32 v[10:11], v[10:11], 0.5, v[24:25] op_sel_hi:[1,0,1]
	v_cvt_f32_f16_sdwa v35, v33 dst_sel:DWORD dst_unused:UNUSED_PAD src0_sel:WORD_1
	v_cvt_f32_f16_e32 v34, v33
	v_or_b32_e32 v20, v21, v20
	v_cvt_f16_f32_e32 v21, v16
	v_add_f32_e32 v16, v15, v14
	v_pk_fma_f32 v[12:13], v[12:13], 0.5, v[26:27] op_sel_hi:[1,0,1]
	v_cvt_f16_f32_e32 v14, v10
	v_cvt_f16_f32_sdwa v15, v11 dst_sel:WORD_1 dst_unused:UNUSED_PAD src0_sel:DWORD
	v_mul_f32_e32 v11, v11, v11
	v_fmac_f32_e32 v11, v10, v10
	v_mul_f32_e32 v10, v13, v13
	v_fmac_f32_e32 v10, v12, v12
	s_waitcnt vmcnt(4)
	v_cvt_f32_f16_sdwa v33, v30 dst_sel:DWORD dst_unused:UNUSED_PAD src0_sel:WORD_1
	v_cvt_f32_f16_e32 v32, v30
	v_add_f32_e32 v10, v11, v10
	v_pk_fma_f32 v[6:7], v[6:7], 0.5, v[28:29] op_sel_hi:[1,0,1]
	v_or_b32_e32 v14, v15, v14
	v_cvt_f16_f32_e32 v15, v12
	v_add_f32_e32 v12, v16, v10
	v_pk_fma_f32 v[8:9], v[8:9], 0.5, v[34:35] op_sel_hi:[1,0,1]
	v_cvt_f16_f32_e32 v10, v6
	v_cvt_f16_f32_sdwa v11, v7 dst_sel:WORD_1 dst_unused:UNUSED_PAD src0_sel:DWORD
	v_mul_f32_e32 v7, v7, v7
	v_fmac_f32_e32 v7, v6, v6
	v_mul_f32_e32 v6, v9, v9
	v_fmac_f32_e32 v6, v8, v8
	v_cvt_f32_f16_sdwa v37, v31 dst_sel:DWORD dst_unused:UNUSED_PAD src0_sel:WORD_1
	v_cvt_f32_f16_e32 v36, v31
	v_add_f32_e32 v6, v7, v6
	v_pk_fma_f32 v[2:3], v[2:3], 0.5, v[32:33] op_sel_hi:[1,0,1]
	v_or_b32_e32 v10, v11, v10
	v_cvt_f16_f32_e32 v11, v8
	v_add_f32_e32 v8, v12, v6
	v_cvt_f16_f32_e32 v6, v2
	v_cvt_f16_f32_sdwa v7, v3 dst_sel:WORD_1 dst_unused:UNUSED_PAD src0_sel:DWORD
	v_cvt_f16_f32_sdwa v22, v17 dst_sel:WORD_1 dst_unused:UNUSED_PAD src0_sel:DWORD
	v_pk_fma_f32 v[4:5], v[4:5], 0.5, v[36:37] op_sel_hi:[1,0,1]
	s_mov_b64 s[18:19], 0xb0
	v_cvt_f16_f32_sdwa v17, v13 dst_sel:WORD_1 dst_unused:UNUSED_PAD src0_sel:DWORD
	v_cvt_f16_f32_sdwa v13, v9 dst_sel:WORD_1 dst_unused:UNUSED_PAD src0_sel:DWORD
	v_or_b32_e32 v6, v7, v6
	v_cvt_f16_f32_e32 v7, v4
	v_cvt_f16_f32_sdwa v9, v5 dst_sel:WORD_1 dst_unused:UNUSED_PAD src0_sel:DWORD
	s_waitcnt lgkmcnt(0)
	v_lshl_add_u64 v[18:19], v[140:141], 0, s[18:19]
	v_mul_f32_e32 v3, v3, v3
	v_or_b32_e32 v21, v22, v21
	v_lshlrev_b64 v[22:23], 11, v[18:19]
	v_fmac_f32_e32 v3, v2, v2
	v_mul_f32_e32 v2, v5, v5
	v_lshl_add_u64 v[22:23], s[16:17], 0, v[22:23]
	v_fmac_f32_e32 v2, v4, v4
	v_lshl_add_u64 v[22:23], v[138:139], 1, v[22:23]
	v_or_b32_e32 v15, v17, v15
	v_or_b32_e32 v11, v13, v11
	v_or_b32_e32 v7, v9, v7
	v_add_f32_e32 v2, v3, v2
	v_mov_b32_e32 v3, v1
	global_store_dwordx2 v[22:23], v[20:21], off sc1
	global_store_dwordx2 v[22:23], v[14:15], off offset:32 sc1
	global_store_dwordx2 v[22:23], v[10:11], off offset:256 sc1
	global_store_dwordx2 v[22:23], v[6:7], off offset:288 sc1
	v_add_f32_e32 v2, v8, v2
	v_mbcnt_lo_u32_b32 v3, -1, v3
	v_mbcnt_hi_u32_b32 v3, -1, v3
	v_lshlrev_b32_e32 v3, 2, v3
	v_xor_b32_e32 v3, 64, v3
	ds_bpermute_b32 v3, v3, v2
	s_waitcnt lgkmcnt(0)
	v_add_f32_e32 v2, v2, v3
	v_mov_b32_e32 v3, v1
	s_nop 0
	v_mbcnt_lo_u32_b32 v3, -1, v3
	v_mbcnt_hi_u32_b32 v3, -1, v3
	v_lshlrev_b32_e32 v3, 2, v3
	v_xor_b32_e32 v3, 0x80, v3
	ds_bpermute_b32 v3, v3, v2
	s_and_saveexec_b64 s[16:17], s[0:1]
	s_cbranch_execz .LBB0_817
	v_lshlrev_b64 v[4:5], 6, v[18:19]
	v_lshl_add_u64 v[4:5], s[14:15], 0, v[4:5]
	s_waitcnt lgkmcnt(0)
	v_add_f32_e32 v2, v2, v3
	global_store_dword v[4:5], v2, off

.LBB0_960:
	s_or_b64 exec, exec, s[46:47]
	v_mul_f32_e32 v115, 0xbfb8aa3b, v156
	v_mul_f32_e32 v116, 0xbfb8aa3b, v157
	v_mul_f32_e32 v117, 0xbfb8aa3b, v160
	v_exp_f32_e32 v115, v115
	v_exp_f32_e32 v116, v116
	v_exp_f32_e32 v117, v117
	v_add_f32_e32 v115, 1.0, v115
	v_add_f32_e32 v116, 1.0, v116
	v_add_f32_e32 v117, 1.0, v117
	v_rcp_f32_e32 v115, v115
	v_rcp_f32_e32 v116, v116
	v_rcp_f32_e32 v117, v117
	global_store_dwordx4 v[132:133], v[114:117], off offset:12 sc1
	s_nop 1
	v_mul_f32_e32 v114, 0xbfb8aa3b, v161
	v_exp_f32_e32 v114, v114
	s_nop 0
	v_add_f32_e32 v114, 1.0, v114
	v_rcp_f32_e32 v114, v114
	global_store_dword v[132:133], v114, off offset:28
.LBB0_961:
	s_or_b64 exec, exec, s[44:45]
	s_lshl_b32 s44, s10, 8
	s_ashr_i32 s45, s44, 31
	s_lshl_b64 s[44:45], s[44:45], 1
	s_add_u32 s10, s11, s44
	s_addc_u32 s11, s27, s45
	v_add_f32_e32 v114, v193, v210
	s_add_u32 s10, s10, s77
	v_fmamk_f32 v114, v114, 0x3a800000, v228
	s_addc_u32 s11, s11, 0
	v_mov_b32_e32 v193, v1
	v_rsq_f32_e32 v140, v114
	v_lshl_add_u64 v[114:115], s[10:11], 0, v[192:193]
	s_mov_b64 s[10:11], 0xaa00000
	v_lshl_add_u64 v[114:115], v[114:115], 0, s[10:11]
	v_mad_u64_u32 v[114:115], s[10:11], v198, s89, v[114:115]
	v_mov_b32_e32 v116, v115
	v_mad_u64_u32 v[116:117], s[10:11], v199, s89, v[116:117]
	v_mov_b32_e32 v115, v116
	v_cvt_pk_bf16_f32 v136, v148, v149
	v_cvt_pk_bf16_f32 v137, v158, v159
	v_cvt_pk_bf16_f32 v138, v156, v157
	v_cvt_pk_bf16_f32 v139, v160, v161
	global_store_dwordx4 v[114:115], v[136:139], off sc1
	v_pk_mul_f32 v[110:111], v[110:111], v[140:141] op_sel_hi:[1,0]
	v_pk_mul_f32 v[116:117], v[112:113], v[140:141] op_sel_hi:[1,0]
	v_cvt_pk_bf16_f32 v136, v146, v147
	v_cvt_pk_bf16_f32 v137, v154, v155
	v_cvt_pk_bf16_f32 v138, v152, v153
	v_cvt_pk_bf16_f32 v139, v150, v151
	v_pk_mul_f32 v[112:113], v[106:107], v[140:141] op_sel_hi:[1,0]
	v_pk_mul_f32 v[132:133], v[108:109], v[140:141] op_sel_hi:[1,0]
	v_pk_mul_f32 v[102:103], v[102:103], v[140:141] op_sel_hi:[1,0]
	v_pk_mul_f32 v[106:107], v[104:105], v[140:141] op_sel_hi:[1,0]
	v_pk_mul_f32 v[104:105], v[98:99], v[140:141] op_sel_hi:[1,0]
	s_and_b64 vcc, exec, s[6:7]
	v_pk_mul_f32 v[108:109], v[100:101], v[140:141] op_sel_hi:[1,0]
	global_store_dwordx4 v[114:115], v[136:139], off offset:64 sc1
	s_cbranch_vccnz .LBB0_964
	v_mul_f32_e32 v98, 0x3d372713, v110
	v_mul_f32_e32 v99, 0x3d372713, v111
	v_mul_f32_e32 v98, v110, v98
	v_mul_f32_e32 v99, v111, v99
	v_fma_f32 v98, v110, v98, v110
	v_fma_f32 v99, v111, v99, v111
	v_mul_f32_e32 v98, 0x3f4c422a, v98
	v_mul_f32_e32 v99, 0x3f4c422a, v99
	v_mul_f32_e32 v98, 0xc038aa3b, v98
	v_mul_f32_e32 v99, 0xc038aa3b, v99
	v_exp_f32_e32 v98, v98
	v_exp_f32_e32 v99, v99
	v_add_f32_e32 v98, 1.0, v98
	v_add_f32_e32 v99, 1.0, v99
	v_rcp_f32_e32 v98, v98
	v_rcp_f32_e32 v99, v99
	s_nop 0
	v_pk_mul_f32 v[110:111], v[110:111], v[98:99]
	v_mul_f32_e32 v98, 0x3d372713, v116
	v_mul_f32_e32 v99, 0x3d372713, v117
	v_mul_f32_e32 v98, v116, v98
	v_mul_f32_e32 v99, v117, v99
	v_fma_f32 v98, v116, v98, v116
	v_fma_f32 v99, v117, v99, v117
	v_mul_f32_e32 v98, 0x3f4c422a, v98
	v_mul_f32_e32 v99, 0x3f4c422a, v99
	v_mul_f32_e32 v98, 0xc038aa3b, v98
	v_mul_f32_e32 v99, 0xc038aa3b, v99
	v_exp_f32_e32 v98, v98
	v_exp_f32_e32 v99, v99
	v_add_f32_e32 v98, 1.0, v98
	v_add_f32_e32 v99, 1.0, v99
	v_rcp_f32_e32 v98, v98
	v_rcp_f32_e32 v99, v99
	s_nop 0
	v_pk_mul_f32 v[116:117], v[116:117], v[98:99]
	v_mul_f32_e32 v98, 0x3d372713, v112
	v_mul_f32_e32 v99, 0x3d372713, v113
	v_mul_f32_e32 v98, v112, v98
	v_mul_f32_e32 v99, v113, v99
	v_fma_f32 v98, v112, v98, v112
	v_fma_f32 v99, v113, v99, v113
	v_mul_f32_e32 v98, 0x3f4c422a, v98
	v_mul_f32_e32 v99, 0x3f4c422a, v99
	v_mul_f32_e32 v98, 0xc038aa3b, v98
	v_mul_f32_e32 v99, 0xc038aa3b, v99
	v_exp_f32_e32 v98, v98
	v_exp_f32_e32 v99, v99
	v_add_f32_e32 v98, 1.0, v98
	v_add_f32_e32 v99, 1.0, v99
	v_rcp_f32_e32 v98, v98
	v_rcp_f32_e32 v99, v99
	s_nop 0
	v_pk_mul_f32 v[112:113], v[112:113], v[98:99]
	v_mul_f32_e32 v98, 0x3d372713, v132
	v_mul_f32_e32 v99, 0x3d372713, v133
	v_mul_f32_e32 v98, v132, v98
	v_mul_f32_e32 v99, v133, v99
	v_fma_f32 v98, v132, v98, v132
	v_fma_f32 v99, v133, v99, v133
	v_mul_f32_e32 v98, 0x3f4c422a, v98
	v_mul_f32_e32 v99, 0x3f4c422a, v99
	v_mul_f32_e32 v98, 0xc038aa3b, v98
	v_mul_f32_e32 v99, 0xc038aa3b, v99
	v_exp_f32_e32 v98, v98
	v_exp_f32_e32 v99, v99
	v_add_f32_e32 v98, 1.0, v98
	v_add_f32_e32 v99, 1.0, v99
	v_rcp_f32_e32 v98, v98
	v_rcp_f32_e32 v99, v99
	s_nop 0
	v_pk_mul_f32 v[132:133], v[132:133], v[98:99]
	v_mul_f32_e32 v98, 0x3d372713, v102
	v_mul_f32_e32 v99, 0x3d372713, v103
	v_mul_f32_e32 v98, v102, v98
	v_mul_f32_e32 v99, v103, v99
	v_fma_f32 v98, v102, v98, v102
	v_fma_f32 v99, v103, v99, v103
	v_mul_f32_e32 v98, 0x3f4c422a, v98
	v_mul_f32_e32 v99, 0x3f4c422a, v99
	v_mul_f32_e32 v98, 0xc038aa3b, v98
	v_mul_f32_e32 v99, 0xc038aa3b, v99
	v_exp_f32_e32 v98, v98
	v_exp_f32_e32 v99, v99
	v_add_f32_e32 v98, 1.0, v98
	v_add_f32_e32 v99, 1.0, v99
	v_rcp_f32_e32 v98, v98
	v_rcp_f32_e32 v99, v99
	s_nop 0
	v_pk_mul_f32 v[102:103], v[102:103], v[98:99]
	v_mul_f32_e32 v98, 0x3d372713, v106
	v_mul_f32_e32 v99, 0x3d372713, v107
	v_mul_f32_e32 v98, v106, v98
	v_mul_f32_e32 v99, v107, v99
	v_fma_f32 v98, v106, v98, v106
	v_fma_f32 v99, v107, v99, v107
	v_mul_f32_e32 v98, 0x3f4c422a, v98
	v_mul_f32_e32 v99, 0x3f4c422a, v99
	v_mul_f32_e32 v98, 0xc038aa3b, v98
	v_mul_f32_e32 v99, 0xc038aa3b, v99
	v_exp_f32_e32 v98, v98
	v_exp_f32_e32 v99, v99
	v_add_f32_e32 v98, 1.0, v98
	v_add_f32_e32 v99, 1.0, v99
	v_rcp_f32_e32 v98, v98
	v_rcp_f32_e32 v99, v99
	s_nop 0
	v_pk_mul_f32 v[106:107], v[106:107], v[98:99]
	v_mul_f32_e32 v98, 0x3d372713, v104
	v_mul_f32_e32 v99, 0x3d372713, v105
	v_mul_f32_e32 v98, v104, v98
	v_mul_f32_e32 v99, v105, v99
	v_fma_f32 v98, v104, v98, v104
	v_fma_f32 v99, v105, v99, v105
	v_mul_f32_e32 v98, 0x3f4c422a, v98
	v_mul_f32_e32 v99, 0x3f4c422a, v99
	v_mul_f32_e32 v98, 0xc038aa3b, v98
	v_mul_f32_e32 v99, 0xc038aa3b, v99
	v_exp_f32_e32 v98, v98
	v_exp_f32_e32 v99, v99
	v_add_f32_e32 v98, 1.0, v98
	v_add_f32_e32 v99, 1.0, v99
	v_rcp_f32_e32 v98, v98
	v_rcp_f32_e32 v99, v99
	s_nop 0
	v_pk_mul_f32 v[104:105], v[104:105], v[98:99]
	v_mul_f32_e32 v98, 0x3d372713, v108
	v_mul_f32_e32 v99, 0x3d372713, v109
	v_mul_f32_e32 v98, v108, v98
	v_mul_f32_e32 v99, v109, v99
	v_fma_f32 v98, v108, v98, v108
	v_fma_f32 v99, v109, v99, v109
	v_mul_f32_e32 v98, 0x3f4c422a, v98
	v_mul_f32_e32 v99, 0x3f4c422a, v99
	v_mul_f32_e32 v98, 0xc038aa3b, v98
	v_mul_f32_e32 v99, 0xc038aa3b, v99
	v_exp_f32_e32 v98, v98
	v_exp_f32_e32 v99, v99
	v_add_f32_e32 v98, 1.0, v98
	v_add_f32_e32 v99, 1.0, v99
	v_rcp_f32_e32 v98, v98
	v_rcp_f32_e32 v99, v99
	s_nop 0
	v_pk_mul_f32 v[108:109], v[108:109], v[98:99]
	v_cndmask_b32_e64 v98, 0, 1, s[42:43]
	s_and_b64 vcc, exec, s[8:9]
	v_cmp_ne_u32_e64 s[10:11], 1, v98
	s_cbranch_vccz .LBB0_965

.LBB0_986:
	s_or_b64 exec, exec, s[44:45]
	v_mul_f32_e32 v99, 0xbfb8aa3b, v112
	v_mul_f32_e32 v100, 0xbfb8aa3b, v113
	v_mul_f32_e32 v101, 0xbfb8aa3b, v132
	v_exp_f32_e32 v99, v99
	v_exp_f32_e32 v100, v100
	v_exp_f32_e32 v101, v101
	v_add_f32_e32 v99, 1.0, v99
	v_add_f32_e32 v100, 1.0, v100
	v_add_f32_e32 v101, 1.0, v101
	v_rcp_f32_e32 v99, v99
	v_rcp_f32_e32 v100, v100
	v_rcp_f32_e32 v101, v101
	global_store_dwordx4 v[136:137], v[98:101], off offset:12 sc1
	s_nop 1
	v_mul_f32_e32 v98, 0xbfb8aa3b, v133
	v_exp_f32_e32 v98, v98
	s_nop 0
	v_add_f32_e32 v98, 1.0, v98
	v_rcp_f32_e32 v98, v98
	global_store_dword v[136:137], v98, off offset:28
.LBB0_987:
	s_or_b64 exec, exec, s[42:43]
	v_add_f32_e32 v98, v208, v209
	v_fmamk_f32 v98, v98, 0x3a800000, v228
	v_rsq_f32_e32 v136, v98
	v_add_co_u32_e32 v100, vcc, s0, v114
	s_mov_b64 s[42:43], 0x16000
	v_cvt_pk_bf16_f32 v110, v110, v111
	v_cvt_pk_bf16_f32 v111, v116, v117
	v_cvt_pk_bf16_f32 v112, v112, v113
	v_cvt_pk_bf16_f32 v113, v132, v133
	v_addc_co_u32_e32 v101, vcc, 0, v115, vcc
	v_lshl_add_u64 v[98:99], v[114:115], 0, s[42:43]
	global_store_dwordx4 v[100:101], v[110:113], off sc1
	v_cvt_pk_bf16_f32 v100, v102, v103
	v_cvt_pk_bf16_f32 v101, v106, v107
	v_cvt_pk_bf16_f32 v102, v104, v105
	v_cvt_pk_bf16_f32 v103, v108, v109
	global_store_dwordx4 v[98:99], v[100:103], off offset:64 sc1
	v_pk_mul_f32 v[94:95], v[94:95], v[136:137] op_sel_hi:[1,0]
	v_pk_mul_f32 v[86:87], v[86:87], v[136:137] op_sel_hi:[1,0]
	v_pk_mul_f32 v[100:101], v[96:97], v[136:137] op_sel_hi:[1,0]
	v_pk_mul_f32 v[96:97], v[90:91], v[136:137] op_sel_hi:[1,0]
	v_pk_mul_f32 v[102:103], v[92:93], v[136:137] op_sel_hi:[1,0]
	v_pk_mul_f32 v[90:91], v[88:89], v[136:137] op_sel_hi:[1,0]
	v_pk_mul_f32 v[88:89], v[82:83], v[136:137] op_sel_hi:[1,0]
	s_and_b64 vcc, exec, s[6:7]
	v_pk_mul_f32 v[92:93], v[84:85], v[136:137] op_sel_hi:[1,0]
	s_cbranch_vccnz .LBB0_990
	v_mul_f32_e32 v82, 0x3d372713, v94
	v_mul_f32_e32 v83, 0x3d372713, v95
	v_mul_f32_e32 v82, v94, v82
	v_mul_f32_e32 v83, v95, v83
	v_fma_f32 v82, v94, v82, v94
	v_fma_f32 v83, v95, v83, v95
	v_mul_f32_e32 v82, 0x3f4c422a, v82
	v_mul_f32_e32 v83, 0x3f4c422a, v83
	v_mul_f32_e32 v82, 0xc038aa3b, v82
	v_mul_f32_e32 v83, 0xc038aa3b, v83
	v_exp_f32_e32 v82, v82
	v_exp_f32_e32 v83, v83
	v_add_f32_e32 v82, 1.0, v82
	v_add_f32_e32 v83, 1.0, v83
	v_rcp_f32_e32 v82, v82
	v_rcp_f32_e32 v83, v83
	s_nop 0
	v_pk_mul_f32 v[94:95], v[94:95], v[82:83]
	v_mul_f32_e32 v82, 0x3d372713, v100
	v_mul_f32_e32 v83, 0x3d372713, v101
	v_mul_f32_e32 v82, v100, v82
	v_mul_f32_e32 v83, v101, v83
	v_fma_f32 v82, v100, v82, v100
	v_fma_f32 v83, v101, v83, v101
	v_mul_f32_e32 v82, 0x3f4c422a, v82
	v_mul_f32_e32 v83, 0x3f4c422a, v83
	v_mul_f32_e32 v82, 0xc038aa3b, v82
	v_mul_f32_e32 v83, 0xc038aa3b, v83
	v_exp_f32_e32 v82, v82
	v_exp_f32_e32 v83, v83
	v_add_f32_e32 v82, 1.0, v82
	v_add_f32_e32 v83, 1.0, v83
	v_rcp_f32_e32 v82, v82
	v_rcp_f32_e32 v83, v83
	s_nop 0
	v_pk_mul_f32 v[100:101], v[100:101], v[82:83]
	v_mul_f32_e32 v82, 0x3d372713, v96
	v_mul_f32_e32 v83, 0x3d372713, v97
	v_mul_f32_e32 v82, v96, v82
	v_mul_f32_e32 v83, v97, v83
	v_fma_f32 v82, v96, v82, v96
	v_fma_f32 v83, v97, v83, v97
	v_mul_f32_e32 v82, 0x3f4c422a, v82
	v_mul_f32_e32 v83, 0x3f4c422a, v83
	v_mul_f32_e32 v82, 0xc038aa3b, v82
	v_mul_f32_e32 v83, 0xc038aa3b, v83
	v_exp_f32_e32 v82, v82
	v_exp_f32_e32 v83, v83
	v_add_f32_e32 v82, 1.0, v82
	v_add_f32_e32 v83, 1.0, v83
	v_rcp_f32_e32 v82, v82
	v_rcp_f32_e32 v83, v83
	s_nop 0
	v_pk_mul_f32 v[96:97], v[96:97], v[82:83]
	v_mul_f32_e32 v82, 0x3d372713, v102
	v_mul_f32_e32 v83, 0x3d372713, v103
	v_mul_f32_e32 v82, v102, v82
	v_mul_f32_e32 v83, v103, v83
	v_fma_f32 v82, v102, v82, v102
	v_fma_f32 v83, v103, v83, v103
	v_mul_f32_e32 v82, 0x3f4c422a, v82
	v_mul_f32_e32 v83, 0x3f4c422a, v83
	v_mul_f32_e32 v82, 0xc038aa3b, v82
	v_mul_f32_e32 v83, 0xc038aa3b, v83
	v_exp_f32_e32 v82, v82
	v_exp_f32_e32 v83, v83
	v_add_f32_e32 v82, 1.0, v82
	v_add_f32_e32 v83, 1.0, v83
	v_rcp_f32_e32 v82, v82
	v_rcp_f32_e32 v83, v83
	s_nop 0
	v_pk_mul_f32 v[102:103], v[102:103], v[82:83]
	v_mul_f32_e32 v82, 0x3d372713, v86
	v_mul_f32_e32 v83, 0x3d372713, v87
	v_mul_f32_e32 v82, v86, v82
	v_mul_f32_e32 v83, v87, v83
	v_fma_f32 v82, v86, v82, v86
	v_fma_f32 v83, v87, v83, v87
	v_mul_f32_e32 v82, 0x3f4c422a, v82
	v_mul_f32_e32 v83, 0x3f4c422a, v83
	v_mul_f32_e32 v82, 0xc038aa3b, v82
	v_mul_f32_e32 v83, 0xc038aa3b, v83
	v_exp_f32_e32 v82, v82
	v_exp_f32_e32 v83, v83
	v_add_f32_e32 v82, 1.0, v82
	v_add_f32_e32 v83, 1.0, v83
	v_rcp_f32_e32 v82, v82
	v_rcp_f32_e32 v83, v83
	s_nop 0
	v_pk_mul_f32 v[86:87], v[86:87], v[82:83]
	v_mul_f32_e32 v82, 0x3d372713, v90
	v_mul_f32_e32 v83, 0x3d372713, v91
	v_mul_f32_e32 v82, v90, v82
	v_mul_f32_e32 v83, v91, v83
	v_fma_f32 v82, v90, v82, v90
	v_fma_f32 v83, v91, v83, v91
	v_mul_f32_e32 v82, 0x3f4c422a, v82
	v_mul_f32_e32 v83, 0x3f4c422a, v83
	v_mul_f32_e32 v82, 0xc038aa3b, v82
	v_mul_f32_e32 v83, 0xc038aa3b, v83
	v_exp_f32_e32 v82, v82
	v_exp_f32_e32 v83, v83
	v_add_f32_e32 v82, 1.0, v82
	v_add_f32_e32 v83, 1.0, v83
	v_rcp_f32_e32 v82, v82
	v_rcp_f32_e32 v83, v83
	s_nop 0
	v_pk_mul_f32 v[90:91], v[90:91], v[82:83]
	v_mul_f32_e32 v82, 0x3d372713, v88
	v_mul_f32_e32 v83, 0x3d372713, v89
	v_mul_f32_e32 v82, v88, v82
	v_mul_f32_e32 v83, v89, v83
	v_fma_f32 v82, v88, v82, v88
	v_fma_f32 v83, v89, v83, v89
	v_mul_f32_e32 v82, 0x3f4c422a, v82
	v_mul_f32_e32 v83, 0x3f4c422a, v83
	v_mul_f32_e32 v82, 0xc038aa3b, v82
	v_mul_f32_e32 v83, 0xc038aa3b, v83
	v_exp_f32_e32 v82, v82
	v_exp_f32_e32 v83, v83
	v_add_f32_e32 v82, 1.0, v82
	v_add_f32_e32 v83, 1.0, v83
	v_rcp_f32_e32 v82, v82
	v_rcp_f32_e32 v83, v83
	s_nop 0
	v_pk_mul_f32 v[88:89], v[88:89], v[82:83]
	v_mul_f32_e32 v82, 0x3d372713, v92
	v_mul_f32_e32 v83, 0x3d372713, v93
	v_mul_f32_e32 v82, v92, v82
	v_mul_f32_e32 v83, v93, v83
	v_fma_f32 v82, v92, v82, v92
	v_fma_f32 v83, v93, v83, v93
	v_mul_f32_e32 v82, 0x3f4c422a, v82
	v_mul_f32_e32 v83, 0x3f4c422a, v83
	v_mul_f32_e32 v82, 0xc038aa3b, v82
	v_mul_f32_e32 v83, 0xc038aa3b, v83
	v_exp_f32_e32 v82, v82
	v_exp_f32_e32 v83, v83
	v_add_f32_e32 v82, 1.0, v82
	v_add_f32_e32 v83, 1.0, v83
	v_rcp_f32_e32 v82, v82
	v_rcp_f32_e32 v83, v83
	s_nop 0
	v_pk_mul_f32 v[92:93], v[92:93], v[82:83]
	s_and_b64 vcc, exec, s[8:9]
	s_cbranch_vccz .LBB0_991

.LBB0_1012:
	s_or_b64 exec, exec, s[44:45]
	v_mul_f32_e32 v83, 0xbfb8aa3b, v96
	v_mul_f32_e32 v84, 0xbfb8aa3b, v97
	v_mul_f32_e32 v85, 0xbfb8aa3b, v102
	v_exp_f32_e32 v83, v83
	v_exp_f32_e32 v84, v84
	v_exp_f32_e32 v85, v85
	v_add_f32_e32 v83, 1.0, v83
	v_add_f32_e32 v84, 1.0, v84
	v_add_f32_e32 v85, 1.0, v85
	v_rcp_f32_e32 v83, v83
	v_rcp_f32_e32 v84, v84
	v_rcp_f32_e32 v85, v85
	global_store_dwordx4 v[104:105], v[82:85], off offset:12 sc1
	s_nop 1
	v_mul_f32_e32 v82, 0xbfb8aa3b, v103
	v_exp_f32_e32 v82, v82
	s_nop 0
	v_add_f32_e32 v82, 1.0, v82
	v_rcp_f32_e32 v82, v82
	global_store_dword v[104:105], v82, off offset:28
.LBB0_1013:
	s_or_b64 exec, exec, s[42:43]
	v_add_f32_e32 v82, v206, v207
	v_fmamk_f32 v82, v82, 0x3a800000, v228
	v_rsq_f32_e32 v104, v82
	v_add_co_u32_e32 v84, vcc, s0, v98
	s_mov_b64 s[42:43], 0x16000
	v_cvt_pk_bf16_f32 v94, v94, v95
	v_cvt_pk_bf16_f32 v95, v100, v101
	v_cvt_pk_bf16_f32 v96, v96, v97
	v_cvt_pk_bf16_f32 v97, v102, v103
	v_addc_co_u32_e32 v85, vcc, 0, v99, vcc
	v_lshl_add_u64 v[82:83], v[98:99], 0, s[42:43]
	global_store_dwordx4 v[84:85], v[94:97], off sc1
	v_cvt_pk_bf16_f32 v84, v86, v87
	v_cvt_pk_bf16_f32 v85, v90, v91
	v_cvt_pk_bf16_f32 v86, v88, v89
	v_cvt_pk_bf16_f32 v87, v92, v93
	global_store_dwordx4 v[82:83], v[84:87], off offset:64 sc1
	v_pk_mul_f32 v[78:79], v[78:79], v[104:105] op_sel_hi:[1,0]
	v_pk_mul_f32 v[70:71], v[70:71], v[104:105] op_sel_hi:[1,0]
	v_pk_mul_f32 v[84:85], v[80:81], v[104:105] op_sel_hi:[1,0]
	v_pk_mul_f32 v[80:81], v[74:75], v[104:105] op_sel_hi:[1,0]
	v_pk_mul_f32 v[86:87], v[76:77], v[104:105] op_sel_hi:[1,0]
	v_pk_mul_f32 v[74:75], v[72:73], v[104:105] op_sel_hi:[1,0]
	v_pk_mul_f32 v[72:73], v[66:67], v[104:105] op_sel_hi:[1,0]
	s_and_b64 vcc, exec, s[6:7]
	v_pk_mul_f32 v[76:77], v[68:69], v[104:105] op_sel_hi:[1,0]
	s_cbranch_vccnz .LBB0_1016
	v_mul_f32_e32 v66, 0x3d372713, v78
	v_mul_f32_e32 v67, 0x3d372713, v79
	v_mul_f32_e32 v66, v78, v66
	v_mul_f32_e32 v67, v79, v67
	v_fma_f32 v66, v78, v66, v78
	v_fma_f32 v67, v79, v67, v79
	v_mul_f32_e32 v66, 0x3f4c422a, v66
	v_mul_f32_e32 v67, 0x3f4c422a, v67
	v_mul_f32_e32 v66, 0xc038aa3b, v66
	v_mul_f32_e32 v67, 0xc038aa3b, v67
	v_exp_f32_e32 v66, v66
	v_exp_f32_e32 v67, v67
	v_add_f32_e32 v66, 1.0, v66
	v_add_f32_e32 v67, 1.0, v67
	v_rcp_f32_e32 v66, v66
	v_rcp_f32_e32 v67, v67
	s_nop 0
	v_pk_mul_f32 v[78:79], v[78:79], v[66:67]
	v_mul_f32_e32 v66, 0x3d372713, v84
	v_mul_f32_e32 v67, 0x3d372713, v85
	v_mul_f32_e32 v66, v84, v66
	v_mul_f32_e32 v67, v85, v67
	v_fma_f32 v66, v84, v66, v84
	v_fma_f32 v67, v85, v67, v85
	v_mul_f32_e32 v66, 0x3f4c422a, v66
	v_mul_f32_e32 v67, 0x3f4c422a, v67
	v_mul_f32_e32 v66, 0xc038aa3b, v66
	v_mul_f32_e32 v67, 0xc038aa3b, v67
	v_exp_f32_e32 v66, v66
	v_exp_f32_e32 v67, v67
	v_add_f32_e32 v66, 1.0, v66
	v_add_f32_e32 v67, 1.0, v67
	v_rcp_f32_e32 v66, v66
	v_rcp_f32_e32 v67, v67
	s_nop 0
	v_pk_mul_f32 v[84:85], v[84:85], v[66:67]
	v_mul_f32_e32 v66, 0x3d372713, v80
	v_mul_f32_e32 v67, 0x3d372713, v81
	v_mul_f32_e32 v66, v80, v66
	v_mul_f32_e32 v67, v81, v67
	v_fma_f32 v66, v80, v66, v80
	v_fma_f32 v67, v81, v67, v81
	v_mul_f32_e32 v66, 0x3f4c422a, v66
	v_mul_f32_e32 v67, 0x3f4c422a, v67
	v_mul_f32_e32 v66, 0xc038aa3b, v66
	v_mul_f32_e32 v67, 0xc038aa3b, v67
	v_exp_f32_e32 v66, v66
	v_exp_f32_e32 v67, v67
	v_add_f32_e32 v66, 1.0, v66
	v_add_f32_e32 v67, 1.0, v67
	v_rcp_f32_e32 v66, v66
	v_rcp_f32_e32 v67, v67
	s_nop 0
	v_pk_mul_f32 v[80:81], v[80:81], v[66:67]
	v_mul_f32_e32 v66, 0x3d372713, v86
	v_mul_f32_e32 v67, 0x3d372713, v87
	v_mul_f32_e32 v66, v86, v66
	v_mul_f32_e32 v67, v87, v67
	v_fma_f32 v66, v86, v66, v86
	v_fma_f32 v67, v87, v67, v87
	v_mul_f32_e32 v66, 0x3f4c422a, v66
	v_mul_f32_e32 v67, 0x3f4c422a, v67
	v_mul_f32_e32 v66, 0xc038aa3b, v66
	v_mul_f32_e32 v67, 0xc038aa3b, v67
	v_exp_f32_e32 v66, v66
	v_exp_f32_e32 v67, v67
	v_add_f32_e32 v66, 1.0, v66
	v_add_f32_e32 v67, 1.0, v67
	v_rcp_f32_e32 v66, v66
	v_rcp_f32_e32 v67, v67
	s_nop 0
	v_pk_mul_f32 v[86:87], v[86:87], v[66:67]
	v_mul_f32_e32 v66, 0x3d372713, v70
	v_mul_f32_e32 v67, 0x3d372713, v71
	v_mul_f32_e32 v66, v70, v66
	v_mul_f32_e32 v67, v71, v67
	v_fma_f32 v66, v70, v66, v70
	v_fma_f32 v67, v71, v67, v71
	v_mul_f32_e32 v66, 0x3f4c422a, v66
	v_mul_f32_e32 v67, 0x3f4c422a, v67
	v_mul_f32_e32 v66, 0xc038aa3b, v66
	v_mul_f32_e32 v67, 0xc038aa3b, v67
	v_exp_f32_e32 v66, v66
	v_exp_f32_e32 v67, v67
	v_add_f32_e32 v66, 1.0, v66
	v_add_f32_e32 v67, 1.0, v67
	v_rcp_f32_e32 v66, v66
	v_rcp_f32_e32 v67, v67
	s_nop 0
	v_pk_mul_f32 v[70:71], v[70:71], v[66:67]
	v_mul_f32_e32 v66, 0x3d372713, v74
	v_mul_f32_e32 v67, 0x3d372713, v75
	v_mul_f32_e32 v66, v74, v66
	v_mul_f32_e32 v67, v75, v67
	v_fma_f32 v66, v74, v66, v74
	v_fma_f32 v67, v75, v67, v75
	v_mul_f32_e32 v66, 0x3f4c422a, v66
	v_mul_f32_e32 v67, 0x3f4c422a, v67
	v_mul_f32_e32 v66, 0xc038aa3b, v66
	v_mul_f32_e32 v67, 0xc038aa3b, v67
	v_exp_f32_e32 v66, v66
	v_exp_f32_e32 v67, v67
	v_add_f32_e32 v66, 1.0, v66
	v_add_f32_e32 v67, 1.0, v67
	v_rcp_f32_e32 v66, v66
	v_rcp_f32_e32 v67, v67
	s_nop 0
	v_pk_mul_f32 v[74:75], v[74:75], v[66:67]
	v_mul_f32_e32 v66, 0x3d372713, v72
	v_mul_f32_e32 v67, 0x3d372713, v73
	v_mul_f32_e32 v66, v72, v66
	v_mul_f32_e32 v67, v73, v67
	v_fma_f32 v66, v72, v66, v72
	v_fma_f32 v67, v73, v67, v73
	v_mul_f32_e32 v66, 0x3f4c422a, v66
	v_mul_f32_e32 v67, 0x3f4c422a, v67
	v_mul_f32_e32 v66, 0xc038aa3b, v66
	v_mul_f32_e32 v67, 0xc038aa3b, v67
	v_exp_f32_e32 v66, v66
	v_exp_f32_e32 v67, v67
	v_add_f32_e32 v66, 1.0, v66
	v_add_f32_e32 v67, 1.0, v67
	v_rcp_f32_e32 v66, v66
	v_rcp_f32_e32 v67, v67
	s_nop 0
	v_pk_mul_f32 v[72:73], v[72:73], v[66:67]
	v_mul_f32_e32 v66, 0x3d372713, v76
	v_mul_f32_e32 v67, 0x3d372713, v77
	v_mul_f32_e32 v66, v76, v66
	v_mul_f32_e32 v67, v77, v67
	v_fma_f32 v66, v76, v66, v76
	v_fma_f32 v67, v77, v67, v77
	v_mul_f32_e32 v66, 0x3f4c422a, v66
	v_mul_f32_e32 v67, 0x3f4c422a, v67
	v_mul_f32_e32 v66, 0xc038aa3b, v66
	v_mul_f32_e32 v67, 0xc038aa3b, v67
	v_exp_f32_e32 v66, v66
	v_exp_f32_e32 v67, v67
	v_add_f32_e32 v66, 1.0, v66
	v_add_f32_e32 v67, 1.0, v67
	v_rcp_f32_e32 v66, v66
	v_rcp_f32_e32 v67, v67
	s_nop 0
	v_pk_mul_f32 v[76:77], v[76:77], v[66:67]
	s_and_b64 vcc, exec, s[8:9]
	s_cbranch_vccz .LBB0_1017

.LBB0_1038:
	s_or_b64 exec, exec, s[44:45]
	v_mul_f32_e32 v67, 0xbfb8aa3b, v80
	v_mul_f32_e32 v68, 0xbfb8aa3b, v81
	v_mul_f32_e32 v69, 0xbfb8aa3b, v86
	v_exp_f32_e32 v67, v67
	v_exp_f32_e32 v68, v68
	v_exp_f32_e32 v69, v69
	v_add_f32_e32 v67, 1.0, v67
	v_add_f32_e32 v68, 1.0, v68
	v_add_f32_e32 v69, 1.0, v69
	v_rcp_f32_e32 v67, v67
	v_rcp_f32_e32 v68, v68
	v_rcp_f32_e32 v69, v69
	global_store_dwordx4 v[88:89], v[66:69], off offset:12 sc1
	s_nop 1
	v_mul_f32_e32 v66, 0xbfb8aa3b, v87
	v_exp_f32_e32 v66, v66
	s_nop 0
	v_add_f32_e32 v66, 1.0, v66
	v_rcp_f32_e32 v66, v66
	global_store_dword v[88:89], v66, off offset:28
.LBB0_1039:
	s_or_b64 exec, exec, s[42:43]
	v_add_f32_e32 v66, v204, v205
	v_fmamk_f32 v66, v66, 0x3a800000, v228
	v_rsq_f32_e32 v88, v66
	v_add_co_u32_e32 v68, vcc, s0, v82
	s_mov_b64 s[42:43], 0x16000
	v_cvt_pk_bf16_f32 v78, v78, v79
	v_cvt_pk_bf16_f32 v79, v84, v85
	v_cvt_pk_bf16_f32 v80, v80, v81
	v_cvt_pk_bf16_f32 v81, v86, v87
	v_addc_co_u32_e32 v69, vcc, 0, v83, vcc
	v_lshl_add_u64 v[66:67], v[82:83], 0, s[42:43]
	global_store_dwordx4 v[68:69], v[78:81], off sc1
	v_cvt_pk_bf16_f32 v68, v70, v71
	v_cvt_pk_bf16_f32 v69, v74, v75
	v_cvt_pk_bf16_f32 v70, v72, v73
	v_cvt_pk_bf16_f32 v71, v76, v77
	global_store_dwordx4 v[66:67], v[68:71], off offset:64 sc1
	v_pk_mul_f32 v[62:63], v[62:63], v[88:89] op_sel_hi:[1,0]
	v_pk_mul_f32 v[54:55], v[54:55], v[88:89] op_sel_hi:[1,0]
	v_pk_mul_f32 v[68:69], v[64:65], v[88:89] op_sel_hi:[1,0]
	v_pk_mul_f32 v[64:65], v[58:59], v[88:89] op_sel_hi:[1,0]
	v_pk_mul_f32 v[70:71], v[60:61], v[88:89] op_sel_hi:[1,0]
	v_pk_mul_f32 v[58:59], v[56:57], v[88:89] op_sel_hi:[1,0]
	v_pk_mul_f32 v[56:57], v[50:51], v[88:89] op_sel_hi:[1,0]
	s_and_b64 vcc, exec, s[6:7]
	v_pk_mul_f32 v[60:61], v[52:53], v[88:89] op_sel_hi:[1,0]
	s_cbranch_vccnz .LBB0_1042
	v_mul_f32_e32 v50, 0x3d372713, v62
	v_mul_f32_e32 v51, 0x3d372713, v63
	v_mul_f32_e32 v50, v62, v50
	v_mul_f32_e32 v51, v63, v51
	v_fma_f32 v50, v62, v50, v62
	v_fma_f32 v51, v63, v51, v63
	v_mul_f32_e32 v50, 0x3f4c422a, v50
	v_mul_f32_e32 v51, 0x3f4c422a, v51
	v_mul_f32_e32 v50, 0xc038aa3b, v50
	v_mul_f32_e32 v51, 0xc038aa3b, v51
	v_exp_f32_e32 v50, v50
	v_exp_f32_e32 v51, v51
	v_add_f32_e32 v50, 1.0, v50
	v_add_f32_e32 v51, 1.0, v51
	v_rcp_f32_e32 v50, v50
	v_rcp_f32_e32 v51, v51
	s_nop 0
	v_pk_mul_f32 v[62:63], v[62:63], v[50:51]
	v_mul_f32_e32 v50, 0x3d372713, v68
	v_mul_f32_e32 v51, 0x3d372713, v69
	v_mul_f32_e32 v50, v68, v50
	v_mul_f32_e32 v51, v69, v51
	v_fma_f32 v50, v68, v50, v68
	v_fma_f32 v51, v69, v51, v69
	v_mul_f32_e32 v50, 0x3f4c422a, v50
	v_mul_f32_e32 v51, 0x3f4c422a, v51
	v_mul_f32_e32 v50, 0xc038aa3b, v50
	v_mul_f32_e32 v51, 0xc038aa3b, v51
	v_exp_f32_e32 v50, v50
	v_exp_f32_e32 v51, v51
	v_add_f32_e32 v50, 1.0, v50
	v_add_f32_e32 v51, 1.0, v51
	v_rcp_f32_e32 v50, v50
	v_rcp_f32_e32 v51, v51
	s_nop 0
	v_pk_mul_f32 v[68:69], v[68:69], v[50:51]
	v_mul_f32_e32 v50, 0x3d372713, v64
	v_mul_f32_e32 v51, 0x3d372713, v65
	v_mul_f32_e32 v50, v64, v50
	v_mul_f32_e32 v51, v65, v51
	v_fma_f32 v50, v64, v50, v64
	v_fma_f32 v51, v65, v51, v65
	v_mul_f32_e32 v50, 0x3f4c422a, v50
	v_mul_f32_e32 v51, 0x3f4c422a, v51
	v_mul_f32_e32 v50, 0xc038aa3b, v50
	v_mul_f32_e32 v51, 0xc038aa3b, v51
	v_exp_f32_e32 v50, v50
	v_exp_f32_e32 v51, v51
	v_add_f32_e32 v50, 1.0, v50
	v_add_f32_e32 v51, 1.0, v51
	v_rcp_f32_e32 v50, v50
	v_rcp_f32_e32 v51, v51
	s_nop 0
	v_pk_mul_f32 v[64:65], v[64:65], v[50:51]
	v_mul_f32_e32 v50, 0x3d372713, v70
	v_mul_f32_e32 v51, 0x3d372713, v71
	v_mul_f32_e32 v50, v70, v50
	v_mul_f32_e32 v51, v71, v51
	v_fma_f32 v50, v70, v50, v70
	v_fma_f32 v51, v71, v51, v71
	v_mul_f32_e32 v50, 0x3f4c422a, v50
	v_mul_f32_e32 v51, 0x3f4c422a, v51
	v_mul_f32_e32 v50, 0xc038aa3b, v50
	v_mul_f32_e32 v51, 0xc038aa3b, v51
	v_exp_f32_e32 v50, v50
	v_exp_f32_e32 v51, v51
	v_add_f32_e32 v50, 1.0, v50
	v_add_f32_e32 v51, 1.0, v51
	v_rcp_f32_e32 v50, v50
	v_rcp_f32_e32 v51, v51
	s_nop 0
	v_pk_mul_f32 v[70:71], v[70:71], v[50:51]
	v_mul_f32_e32 v50, 0x3d372713, v54
	v_mul_f32_e32 v51, 0x3d372713, v55
	v_mul_f32_e32 v50, v54, v50
	v_mul_f32_e32 v51, v55, v51
	v_fma_f32 v50, v54, v50, v54
	v_fma_f32 v51, v55, v51, v55
	v_mul_f32_e32 v50, 0x3f4c422a, v50
	v_mul_f32_e32 v51, 0x3f4c422a, v51
	v_mul_f32_e32 v50, 0xc038aa3b, v50
	v_mul_f32_e32 v51, 0xc038aa3b, v51
	v_exp_f32_e32 v50, v50
	v_exp_f32_e32 v51, v51
	v_add_f32_e32 v50, 1.0, v50
	v_add_f32_e32 v51, 1.0, v51
	v_rcp_f32_e32 v50, v50
	v_rcp_f32_e32 v51, v51
	s_nop 0
	v_pk_mul_f32 v[54:55], v[54:55], v[50:51]
	v_mul_f32_e32 v50, 0x3d372713, v58
	v_mul_f32_e32 v51, 0x3d372713, v59
	v_mul_f32_e32 v50, v58, v50
	v_mul_f32_e32 v51, v59, v51
	v_fma_f32 v50, v58, v50, v58
	v_fma_f32 v51, v59, v51, v59
	v_mul_f32_e32 v50, 0x3f4c422a, v50
	v_mul_f32_e32 v51, 0x3f4c422a, v51
	v_mul_f32_e32 v50, 0xc038aa3b, v50
	v_mul_f32_e32 v51, 0xc038aa3b, v51
	v_exp_f32_e32 v50, v50
	v_exp_f32_e32 v51, v51
	v_add_f32_e32 v50, 1.0, v50
	v_add_f32_e32 v51, 1.0, v51
	v_rcp_f32_e32 v50, v50
	v_rcp_f32_e32 v51, v51
	s_nop 0
	v_pk_mul_f32 v[58:59], v[58:59], v[50:51]
	v_mul_f32_e32 v50, 0x3d372713, v56
	v_mul_f32_e32 v51, 0x3d372713, v57
	v_mul_f32_e32 v50, v56, v50
	v_mul_f32_e32 v51, v57, v51
	v_fma_f32 v50, v56, v50, v56
	v_fma_f32 v51, v57, v51, v57
	v_mul_f32_e32 v50, 0x3f4c422a, v50
	v_mul_f32_e32 v51, 0x3f4c422a, v51
	v_mul_f32_e32 v50, 0xc038aa3b, v50
	v_mul_f32_e32 v51, 0xc038aa3b, v51
	v_exp_f32_e32 v50, v50
	v_exp_f32_e32 v51, v51
	v_add_f32_e32 v50, 1.0, v50
	v_add_f32_e32 v51, 1.0, v51
	v_rcp_f32_e32 v50, v50
	v_rcp_f32_e32 v51, v51
	s_nop 0
	v_pk_mul_f32 v[56:57], v[56:57], v[50:51]
	v_mul_f32_e32 v50, 0x3d372713, v60
	v_mul_f32_e32 v51, 0x3d372713, v61
	v_mul_f32_e32 v50, v60, v50
	v_mul_f32_e32 v51, v61, v51
	v_fma_f32 v50, v60, v50, v60
	v_fma_f32 v51, v61, v51, v61
	v_mul_f32_e32 v50, 0x3f4c422a, v50
	v_mul_f32_e32 v51, 0x3f4c422a, v51
	v_mul_f32_e32 v50, 0xc038aa3b, v50
	v_mul_f32_e32 v51, 0xc038aa3b, v51
	v_exp_f32_e32 v50, v50
	v_exp_f32_e32 v51, v51
	v_add_f32_e32 v50, 1.0, v50
	v_add_f32_e32 v51, 1.0, v51
	v_rcp_f32_e32 v50, v50
	v_rcp_f32_e32 v51, v51
	s_nop 0
	v_pk_mul_f32 v[60:61], v[60:61], v[50:51]
	s_and_b64 vcc, exec, s[8:9]
	s_cbranch_vccz .LBB0_1043

.LBB0_1064:
	s_or_b64 exec, exec, s[44:45]
	v_mul_f32_e32 v51, 0xbfb8aa3b, v64
	v_mul_f32_e32 v52, 0xbfb8aa3b, v65
	v_mul_f32_e32 v53, 0xbfb8aa3b, v70
	v_exp_f32_e32 v51, v51
	v_exp_f32_e32 v52, v52
	v_exp_f32_e32 v53, v53
	v_add_f32_e32 v51, 1.0, v51
	v_add_f32_e32 v52, 1.0, v52
	v_add_f32_e32 v53, 1.0, v53
	v_rcp_f32_e32 v51, v51
	v_rcp_f32_e32 v52, v52
	v_rcp_f32_e32 v53, v53
	global_store_dwordx4 v[72:73], v[50:53], off offset:12 sc1
	s_nop 1
	v_mul_f32_e32 v50, 0xbfb8aa3b, v71
	v_exp_f32_e32 v50, v50
	s_nop 0
	v_add_f32_e32 v50, 1.0, v50
	v_rcp_f32_e32 v50, v50
	global_store_dword v[72:73], v50, off offset:28
.LBB0_1065:
	s_or_b64 exec, exec, s[42:43]
	v_add_f32_e32 v50, v202, v203
	v_fmamk_f32 v50, v50, 0x3a800000, v228
	v_rsq_f32_e32 v72, v50
	s_mov_b32 s27, 0x6e000
	v_add_co_u32_e32 v52, vcc, s27, v66
	s_mov_b64 s[42:43], 0x6e000
	v_cvt_pk_bf16_f32 v62, v62, v63
	v_cvt_pk_bf16_f32 v63, v68, v69
	v_cvt_pk_bf16_f32 v64, v64, v65
	v_cvt_pk_bf16_f32 v65, v70, v71
	v_addc_co_u32_e32 v53, vcc, 0, v67, vcc
	v_lshl_add_u64 v[50:51], v[66:67], 0, s[42:43]
	global_store_dwordx4 v[52:53], v[62:65], off sc1
	v_cvt_pk_bf16_f32 v52, v54, v55
	v_cvt_pk_bf16_f32 v53, v58, v59
	v_cvt_pk_bf16_f32 v54, v56, v57
	v_cvt_pk_bf16_f32 v55, v60, v61
	global_store_dwordx4 v[50:51], v[52:55], off offset:64 sc1
	v_pk_mul_f32 v[46:47], v[46:47], v[72:73] op_sel_hi:[1,0]
	v_pk_mul_f32 v[38:39], v[38:39], v[72:73] op_sel_hi:[1,0]
	v_pk_mul_f32 v[52:53], v[48:49], v[72:73] op_sel_hi:[1,0]
	v_pk_mul_f32 v[48:49], v[42:43], v[72:73] op_sel_hi:[1,0]
	v_pk_mul_f32 v[54:55], v[44:45], v[72:73] op_sel_hi:[1,0]
	v_pk_mul_f32 v[42:43], v[40:41], v[72:73] op_sel_hi:[1,0]
	v_pk_mul_f32 v[40:41], v[34:35], v[72:73] op_sel_hi:[1,0]
	s_and_b64 vcc, exec, s[6:7]
	v_pk_mul_f32 v[44:45], v[36:37], v[72:73] op_sel_hi:[1,0]
	s_cbranch_vccnz .LBB0_1068
	v_mul_f32_e32 v34, 0x3d372713, v46
	v_mul_f32_e32 v35, 0x3d372713, v47
	v_mul_f32_e32 v34, v46, v34
	v_mul_f32_e32 v35, v47, v35
	v_fma_f32 v34, v46, v34, v46
	v_fma_f32 v35, v47, v35, v47
	v_mul_f32_e32 v34, 0x3f4c422a, v34
	v_mul_f32_e32 v35, 0x3f4c422a, v35
	v_mul_f32_e32 v34, 0xc038aa3b, v34
	v_mul_f32_e32 v35, 0xc038aa3b, v35
	v_exp_f32_e32 v34, v34
	v_exp_f32_e32 v35, v35
	v_add_f32_e32 v34, 1.0, v34
	v_add_f32_e32 v35, 1.0, v35
	v_rcp_f32_e32 v34, v34
	v_rcp_f32_e32 v35, v35
	s_nop 0
	v_pk_mul_f32 v[46:47], v[46:47], v[34:35]
	v_mul_f32_e32 v34, 0x3d372713, v52
	v_mul_f32_e32 v35, 0x3d372713, v53
	v_mul_f32_e32 v34, v52, v34
	v_mul_f32_e32 v35, v53, v35
	v_fma_f32 v34, v52, v34, v52
	v_fma_f32 v35, v53, v35, v53
	v_mul_f32_e32 v34, 0x3f4c422a, v34
	v_mul_f32_e32 v35, 0x3f4c422a, v35
	v_mul_f32_e32 v34, 0xc038aa3b, v34
	v_mul_f32_e32 v35, 0xc038aa3b, v35
	v_exp_f32_e32 v34, v34
	v_exp_f32_e32 v35, v35
	v_add_f32_e32 v34, 1.0, v34
	v_add_f32_e32 v35, 1.0, v35
	v_rcp_f32_e32 v34, v34
	v_rcp_f32_e32 v35, v35
	s_nop 0
	v_pk_mul_f32 v[52:53], v[52:53], v[34:35]
	v_mul_f32_e32 v34, 0x3d372713, v48
	v_mul_f32_e32 v35, 0x3d372713, v49
	v_mul_f32_e32 v34, v48, v34
	v_mul_f32_e32 v35, v49, v35
	v_fma_f32 v34, v48, v34, v48
	v_fma_f32 v35, v49, v35, v49
	v_mul_f32_e32 v34, 0x3f4c422a, v34
	v_mul_f32_e32 v35, 0x3f4c422a, v35
	v_mul_f32_e32 v34, 0xc038aa3b, v34
	v_mul_f32_e32 v35, 0xc038aa3b, v35
	v_exp_f32_e32 v34, v34
	v_exp_f32_e32 v35, v35
	v_add_f32_e32 v34, 1.0, v34
	v_add_f32_e32 v35, 1.0, v35
	v_rcp_f32_e32 v34, v34
	v_rcp_f32_e32 v35, v35
	s_nop 0
	v_pk_mul_f32 v[48:49], v[48:49], v[34:35]
	v_mul_f32_e32 v34, 0x3d372713, v54
	v_mul_f32_e32 v35, 0x3d372713, v55
	v_mul_f32_e32 v34, v54, v34
	v_mul_f32_e32 v35, v55, v35
	v_fma_f32 v34, v54, v34, v54
	v_fma_f32 v35, v55, v35, v55
	v_mul_f32_e32 v34, 0x3f4c422a, v34
	v_mul_f32_e32 v35, 0x3f4c422a, v35
	v_mul_f32_e32 v34, 0xc038aa3b, v34
	v_mul_f32_e32 v35, 0xc038aa3b, v35
	v_exp_f32_e32 v34, v34
	v_exp_f32_e32 v35, v35
	v_add_f32_e32 v34, 1.0, v34
	v_add_f32_e32 v35, 1.0, v35
	v_rcp_f32_e32 v34, v34
	v_rcp_f32_e32 v35, v35
	s_nop 0
	v_pk_mul_f32 v[54:55], v[54:55], v[34:35]
	v_mul_f32_e32 v34, 0x3d372713, v38
	v_mul_f32_e32 v35, 0x3d372713, v39
	v_mul_f32_e32 v34, v38, v34
	v_mul_f32_e32 v35, v39, v35
	v_fma_f32 v34, v38, v34, v38
	v_fma_f32 v35, v39, v35, v39
	v_mul_f32_e32 v34, 0x3f4c422a, v34
	v_mul_f32_e32 v35, 0x3f4c422a, v35
	v_mul_f32_e32 v34, 0xc038aa3b, v34
	v_mul_f32_e32 v35, 0xc038aa3b, v35
	v_exp_f32_e32 v34, v34
	v_exp_f32_e32 v35, v35
	v_add_f32_e32 v34, 1.0, v34
	v_add_f32_e32 v35, 1.0, v35
	v_rcp_f32_e32 v34, v34
	v_rcp_f32_e32 v35, v35
	s_nop 0
	v_pk_mul_f32 v[38:39], v[38:39], v[34:35]
	v_mul_f32_e32 v34, 0x3d372713, v42
	v_mul_f32_e32 v35, 0x3d372713, v43
	v_mul_f32_e32 v34, v42, v34
	v_mul_f32_e32 v35, v43, v35
	v_fma_f32 v34, v42, v34, v42
	v_fma_f32 v35, v43, v35, v43
	v_mul_f32_e32 v34, 0x3f4c422a, v34
	v_mul_f32_e32 v35, 0x3f4c422a, v35
	v_mul_f32_e32 v34, 0xc038aa3b, v34
	v_mul_f32_e32 v35, 0xc038aa3b, v35
	v_exp_f32_e32 v34, v34
	v_exp_f32_e32 v35, v35
	v_add_f32_e32 v34, 1.0, v34
	v_add_f32_e32 v35, 1.0, v35
	v_rcp_f32_e32 v34, v34
	v_rcp_f32_e32 v35, v35
	s_nop 0
	v_pk_mul_f32 v[42:43], v[42:43], v[34:35]
	v_mul_f32_e32 v34, 0x3d372713, v40
	v_mul_f32_e32 v35, 0x3d372713, v41
	v_mul_f32_e32 v34, v40, v34
	v_mul_f32_e32 v35, v41, v35
	v_fma_f32 v34, v40, v34, v40
	v_fma_f32 v35, v41, v35, v41
	v_mul_f32_e32 v34, 0x3f4c422a, v34
	v_mul_f32_e32 v35, 0x3f4c422a, v35
	v_mul_f32_e32 v34, 0xc038aa3b, v34
	v_mul_f32_e32 v35, 0xc038aa3b, v35
	v_exp_f32_e32 v34, v34
	v_exp_f32_e32 v35, v35
	v_add_f32_e32 v34, 1.0, v34
	v_add_f32_e32 v35, 1.0, v35
	v_rcp_f32_e32 v34, v34
	v_rcp_f32_e32 v35, v35
	s_nop 0
	v_pk_mul_f32 v[40:41], v[40:41], v[34:35]
	v_mul_f32_e32 v34, 0x3d372713, v44
	v_mul_f32_e32 v35, 0x3d372713, v45
	v_mul_f32_e32 v34, v44, v34
	v_mul_f32_e32 v35, v45, v35
	v_fma_f32 v34, v44, v34, v44
	v_fma_f32 v35, v45, v35, v45
	v_mul_f32_e32 v34, 0x3f4c422a, v34
	v_mul_f32_e32 v35, 0x3f4c422a, v35
	v_mul_f32_e32 v34, 0xc038aa3b, v34
	v_mul_f32_e32 v35, 0xc038aa3b, v35
	v_exp_f32_e32 v34, v34
	v_exp_f32_e32 v35, v35
	v_add_f32_e32 v34, 1.0, v34
	v_add_f32_e32 v35, 1.0, v35
	v_rcp_f32_e32 v34, v34
	v_rcp_f32_e32 v35, v35
	s_nop 0
	v_pk_mul_f32 v[44:45], v[44:45], v[34:35]
	s_and_b64 vcc, exec, s[8:9]
	s_cbranch_vccz .LBB0_1069

.LBB0_1090:
	s_or_b64 exec, exec, s[44:45]
	v_mul_f32_e32 v35, 0xbfb8aa3b, v48
	v_mul_f32_e32 v36, 0xbfb8aa3b, v49
	v_mul_f32_e32 v37, 0xbfb8aa3b, v54
	v_exp_f32_e32 v35, v35
	v_exp_f32_e32 v36, v36
	v_exp_f32_e32 v37, v37
	v_add_f32_e32 v35, 1.0, v35
	v_add_f32_e32 v36, 1.0, v36
	v_add_f32_e32 v37, 1.0, v37
	v_rcp_f32_e32 v35, v35
	v_rcp_f32_e32 v36, v36
	v_rcp_f32_e32 v37, v37
	global_store_dwordx4 v[56:57], v[34:37], off offset:12 sc1
	s_nop 1
	v_mul_f32_e32 v34, 0xbfb8aa3b, v55
	v_exp_f32_e32 v34, v34
	s_nop 0
	v_add_f32_e32 v34, 1.0, v34
	v_rcp_f32_e32 v34, v34
	global_store_dword v[56:57], v34, off offset:28
.LBB0_1091:
	s_or_b64 exec, exec, s[42:43]
	s_waitcnt lgkmcnt(1)
	v_add_f32_e32 v34, v164, v165
	v_fmamk_f32 v34, v34, 0x3a800000, v228
	v_rsq_f32_e32 v56, v34
	v_add_co_u32_e32 v36, vcc, s0, v50
	s_mov_b64 s[42:43], 0x16000
	v_cvt_pk_bf16_f32 v46, v46, v47
	v_cvt_pk_bf16_f32 v47, v52, v53
	v_cvt_pk_bf16_f32 v48, v48, v49
	v_cvt_pk_bf16_f32 v49, v54, v55
	v_addc_co_u32_e32 v37, vcc, 0, v51, vcc
	v_lshl_add_u64 v[34:35], v[50:51], 0, s[42:43]
	global_store_dwordx4 v[36:37], v[46:49], off sc1
	v_cvt_pk_bf16_f32 v36, v38, v39
	v_cvt_pk_bf16_f32 v37, v42, v43
	v_cvt_pk_bf16_f32 v38, v40, v41
	v_cvt_pk_bf16_f32 v39, v44, v45
	global_store_dwordx4 v[34:35], v[36:39], off offset:64 sc1
	v_pk_mul_f32 v[30:31], v[30:31], v[56:57] op_sel_hi:[1,0]
	v_pk_mul_f32 v[22:23], v[22:23], v[56:57] op_sel_hi:[1,0]
	v_pk_mul_f32 v[36:37], v[32:33], v[56:57] op_sel_hi:[1,0]
	v_pk_mul_f32 v[32:33], v[26:27], v[56:57] op_sel_hi:[1,0]
	v_pk_mul_f32 v[38:39], v[28:29], v[56:57] op_sel_hi:[1,0]
	v_pk_mul_f32 v[26:27], v[24:25], v[56:57] op_sel_hi:[1,0]
	v_pk_mul_f32 v[24:25], v[18:19], v[56:57] op_sel_hi:[1,0]
	s_and_b64 vcc, exec, s[6:7]
	v_pk_mul_f32 v[28:29], v[20:21], v[56:57] op_sel_hi:[1,0]
	s_cbranch_vccnz .LBB0_1094
	v_mul_f32_e32 v18, 0x3d372713, v30
	v_mul_f32_e32 v19, 0x3d372713, v31
	v_mul_f32_e32 v18, v30, v18
	v_mul_f32_e32 v19, v31, v19
	v_fma_f32 v18, v30, v18, v30
	v_fma_f32 v19, v31, v19, v31
	v_mul_f32_e32 v18, 0x3f4c422a, v18
	v_mul_f32_e32 v19, 0x3f4c422a, v19
	v_mul_f32_e32 v18, 0xc038aa3b, v18
	v_mul_f32_e32 v19, 0xc038aa3b, v19
	v_exp_f32_e32 v18, v18
	v_exp_f32_e32 v19, v19
	v_add_f32_e32 v18, 1.0, v18
	v_add_f32_e32 v19, 1.0, v19
	v_rcp_f32_e32 v18, v18
	v_rcp_f32_e32 v19, v19
	s_nop 0
	v_pk_mul_f32 v[30:31], v[30:31], v[18:19]
	v_mul_f32_e32 v18, 0x3d372713, v36
	v_mul_f32_e32 v19, 0x3d372713, v37
	v_mul_f32_e32 v18, v36, v18
	v_mul_f32_e32 v19, v37, v19
	v_fma_f32 v18, v36, v18, v36
	v_fma_f32 v19, v37, v19, v37
	v_mul_f32_e32 v18, 0x3f4c422a, v18
	v_mul_f32_e32 v19, 0x3f4c422a, v19
	v_mul_f32_e32 v18, 0xc038aa3b, v18
	v_mul_f32_e32 v19, 0xc038aa3b, v19
	v_exp_f32_e32 v18, v18
	v_exp_f32_e32 v19, v19
	v_add_f32_e32 v18, 1.0, v18
	v_add_f32_e32 v19, 1.0, v19
	v_rcp_f32_e32 v18, v18
	v_rcp_f32_e32 v19, v19
	s_nop 0
	v_pk_mul_f32 v[36:37], v[36:37], v[18:19]
	v_mul_f32_e32 v18, 0x3d372713, v32
	v_mul_f32_e32 v19, 0x3d372713, v33
	v_mul_f32_e32 v18, v32, v18
	v_mul_f32_e32 v19, v33, v19
	v_fma_f32 v18, v32, v18, v32
	v_fma_f32 v19, v33, v19, v33
	v_mul_f32_e32 v18, 0x3f4c422a, v18
	v_mul_f32_e32 v19, 0x3f4c422a, v19
	v_mul_f32_e32 v18, 0xc038aa3b, v18
	v_mul_f32_e32 v19, 0xc038aa3b, v19
	v_exp_f32_e32 v18, v18
	v_exp_f32_e32 v19, v19
	v_add_f32_e32 v18, 1.0, v18
	v_add_f32_e32 v19, 1.0, v19
	v_rcp_f32_e32 v18, v18
	v_rcp_f32_e32 v19, v19
	s_nop 0
	v_pk_mul_f32 v[32:33], v[32:33], v[18:19]
	v_mul_f32_e32 v18, 0x3d372713, v38
	v_mul_f32_e32 v19, 0x3d372713, v39
	v_mul_f32_e32 v18, v38, v18
	v_mul_f32_e32 v19, v39, v19
	v_fma_f32 v18, v38, v18, v38
	v_fma_f32 v19, v39, v19, v39
	v_mul_f32_e32 v18, 0x3f4c422a, v18
	v_mul_f32_e32 v19, 0x3f4c422a, v19
	v_mul_f32_e32 v18, 0xc038aa3b, v18
	v_mul_f32_e32 v19, 0xc038aa3b, v19
	v_exp_f32_e32 v18, v18
	v_exp_f32_e32 v19, v19
	v_add_f32_e32 v18, 1.0, v18
	v_add_f32_e32 v19, 1.0, v19
	v_rcp_f32_e32 v18, v18
	v_rcp_f32_e32 v19, v19
	s_nop 0
	v_pk_mul_f32 v[38:39], v[38:39], v[18:19]
	v_mul_f32_e32 v18, 0x3d372713, v22
	v_mul_f32_e32 v19, 0x3d372713, v23
	v_mul_f32_e32 v18, v22, v18
	v_mul_f32_e32 v19, v23, v19
	v_fma_f32 v18, v22, v18, v22
	v_fma_f32 v19, v23, v19, v23
	v_mul_f32_e32 v18, 0x3f4c422a, v18
	v_mul_f32_e32 v19, 0x3f4c422a, v19
	v_mul_f32_e32 v18, 0xc038aa3b, v18
	v_mul_f32_e32 v19, 0xc038aa3b, v19
	v_exp_f32_e32 v18, v18
	v_exp_f32_e32 v19, v19
	v_add_f32_e32 v18, 1.0, v18
	v_add_f32_e32 v19, 1.0, v19
	v_rcp_f32_e32 v18, v18
	v_rcp_f32_e32 v19, v19
	s_nop 0
	v_pk_mul_f32 v[22:23], v[22:23], v[18:19]
	v_mul_f32_e32 v18, 0x3d372713, v26
	v_mul_f32_e32 v19, 0x3d372713, v27
	v_mul_f32_e32 v18, v26, v18
	v_mul_f32_e32 v19, v27, v19
	v_fma_f32 v18, v26, v18, v26
	v_fma_f32 v19, v27, v19, v27
	v_mul_f32_e32 v18, 0x3f4c422a, v18
	v_mul_f32_e32 v19, 0x3f4c422a, v19
	v_mul_f32_e32 v18, 0xc038aa3b, v18
	v_mul_f32_e32 v19, 0xc038aa3b, v19
	v_exp_f32_e32 v18, v18
	v_exp_f32_e32 v19, v19
	v_add_f32_e32 v18, 1.0, v18
	v_add_f32_e32 v19, 1.0, v19
	v_rcp_f32_e32 v18, v18
	v_rcp_f32_e32 v19, v19
	s_nop 0
	v_pk_mul_f32 v[26:27], v[26:27], v[18:19]
	v_mul_f32_e32 v18, 0x3d372713, v24
	v_mul_f32_e32 v19, 0x3d372713, v25
	v_mul_f32_e32 v18, v24, v18
	v_mul_f32_e32 v19, v25, v19
	v_fma_f32 v18, v24, v18, v24
	v_fma_f32 v19, v25, v19, v25
	v_mul_f32_e32 v18, 0x3f4c422a, v18
	v_mul_f32_e32 v19, 0x3f4c422a, v19
	v_mul_f32_e32 v18, 0xc038aa3b, v18
	v_mul_f32_e32 v19, 0xc038aa3b, v19
	v_exp_f32_e32 v18, v18
	v_exp_f32_e32 v19, v19
	v_add_f32_e32 v18, 1.0, v18
	v_add_f32_e32 v19, 1.0, v19
	v_rcp_f32_e32 v18, v18
	v_rcp_f32_e32 v19, v19
	s_nop 0
	v_pk_mul_f32 v[24:25], v[24:25], v[18:19]
	v_mul_f32_e32 v18, 0x3d372713, v28
	v_mul_f32_e32 v19, 0x3d372713, v29
	v_mul_f32_e32 v18, v28, v18
	v_mul_f32_e32 v19, v29, v19
	v_fma_f32 v18, v28, v18, v28
	v_fma_f32 v19, v29, v19, v29
	v_mul_f32_e32 v18, 0x3f4c422a, v18
	v_mul_f32_e32 v19, 0x3f4c422a, v19
	v_mul_f32_e32 v18, 0xc038aa3b, v18
	v_mul_f32_e32 v19, 0xc038aa3b, v19
	v_exp_f32_e32 v18, v18
	v_exp_f32_e32 v19, v19
	v_add_f32_e32 v18, 1.0, v18
	v_add_f32_e32 v19, 1.0, v19
	v_rcp_f32_e32 v18, v18
	v_rcp_f32_e32 v19, v19
	s_nop 0
	v_pk_mul_f32 v[28:29], v[28:29], v[18:19]
	s_and_b64 vcc, exec, s[8:9]
	s_cbranch_vccz .LBB0_1095

.LBB0_1116:
	s_or_b64 exec, exec, s[44:45]
	v_mul_f32_e32 v19, 0xbfb8aa3b, v32
	v_mul_f32_e32 v20, 0xbfb8aa3b, v33
	v_mul_f32_e32 v21, 0xbfb8aa3b, v38
	v_exp_f32_e32 v19, v19
	v_exp_f32_e32 v20, v20
	v_exp_f32_e32 v21, v21
	v_add_f32_e32 v19, 1.0, v19
	v_add_f32_e32 v20, 1.0, v20
	v_add_f32_e32 v21, 1.0, v21
	v_rcp_f32_e32 v19, v19
	v_rcp_f32_e32 v20, v20
	v_rcp_f32_e32 v21, v21
	global_store_dwordx4 v[40:41], v[18:21], off offset:12 sc1
	s_nop 1
	v_mul_f32_e32 v18, 0xbfb8aa3b, v39
	v_exp_f32_e32 v18, v18
	s_nop 0
	v_add_f32_e32 v18, 1.0, v18
	v_rcp_f32_e32 v18, v18
	global_store_dword v[40:41], v18, off offset:28
.LBB0_1117:
	s_or_b64 exec, exec, s[42:43]
	s_waitcnt lgkmcnt(0)
	v_add_f32_e32 v18, v162, v163
	v_fmamk_f32 v18, v18, 0x3a800000, v228
	v_rsq_f32_e32 v40, v18
	v_add_co_u32_e32 v20, vcc, s0, v34
	s_mov_b64 s[42:43], 0x16000
	v_cvt_pk_bf16_f32 v30, v30, v31
	v_cvt_pk_bf16_f32 v31, v36, v37
	v_cvt_pk_bf16_f32 v32, v32, v33
	v_cvt_pk_bf16_f32 v33, v38, v39
	v_addc_co_u32_e32 v21, vcc, 0, v35, vcc
	v_lshl_add_u64 v[18:19], v[34:35], 0, s[42:43]
	global_store_dwordx4 v[20:21], v[30:33], off sc1
	v_cvt_pk_bf16_f32 v20, v22, v23
	v_cvt_pk_bf16_f32 v21, v26, v27
	v_cvt_pk_bf16_f32 v22, v24, v25
	v_cvt_pk_bf16_f32 v23, v28, v29
	global_store_dwordx4 v[18:19], v[20:23], off offset:64 sc1
	v_pk_mul_f32 v[14:15], v[14:15], v[40:41] op_sel_hi:[1,0]
	v_pk_mul_f32 v[6:7], v[6:7], v[40:41] op_sel_hi:[1,0]
	v_pk_mul_f32 v[20:21], v[16:17], v[40:41] op_sel_hi:[1,0]
	v_pk_mul_f32 v[16:17], v[10:11], v[40:41] op_sel_hi:[1,0]
	v_pk_mul_f32 v[22:23], v[12:13], v[40:41] op_sel_hi:[1,0]
	v_pk_mul_f32 v[10:11], v[8:9], v[40:41] op_sel_hi:[1,0]
	v_pk_mul_f32 v[8:9], v[2:3], v[40:41] op_sel_hi:[1,0]
	s_and_b64 vcc, exec, s[6:7]
	v_pk_mul_f32 v[12:13], v[4:5], v[40:41] op_sel_hi:[1,0]
	s_cbranch_vccnz .LBB0_1120
	v_mul_f32_e32 v2, 0x3d372713, v14
	v_mul_f32_e32 v3, 0x3d372713, v15
	v_mul_f32_e32 v2, v14, v2
	v_mul_f32_e32 v3, v15, v3
	v_fma_f32 v2, v14, v2, v14
	v_fma_f32 v3, v15, v3, v15
	v_mul_f32_e32 v2, 0x3f4c422a, v2
	v_mul_f32_e32 v3, 0x3f4c422a, v3
	v_mul_f32_e32 v2, 0xc038aa3b, v2
	v_mul_f32_e32 v3, 0xc038aa3b, v3
	v_exp_f32_e32 v2, v2
	v_exp_f32_e32 v3, v3
	v_add_f32_e32 v2, 1.0, v2
	v_add_f32_e32 v3, 1.0, v3
	v_rcp_f32_e32 v2, v2
	v_rcp_f32_e32 v3, v3
	s_nop 0
	v_pk_mul_f32 v[14:15], v[14:15], v[2:3]
	v_mul_f32_e32 v2, 0x3d372713, v20
	v_mul_f32_e32 v3, 0x3d372713, v21
	v_mul_f32_e32 v2, v20, v2
	v_mul_f32_e32 v3, v21, v3
	v_fma_f32 v2, v20, v2, v20
	v_fma_f32 v3, v21, v3, v21
	v_mul_f32_e32 v2, 0x3f4c422a, v2
	v_mul_f32_e32 v3, 0x3f4c422a, v3
	v_mul_f32_e32 v2, 0xc038aa3b, v2
	v_mul_f32_e32 v3, 0xc038aa3b, v3
	v_exp_f32_e32 v2, v2
	v_exp_f32_e32 v3, v3
	v_add_f32_e32 v2, 1.0, v2
	v_add_f32_e32 v3, 1.0, v3
	v_rcp_f32_e32 v2, v2
	v_rcp_f32_e32 v3, v3
	s_nop 0
	v_pk_mul_f32 v[20:21], v[20:21], v[2:3]
	v_mul_f32_e32 v2, 0x3d372713, v16
	v_mul_f32_e32 v3, 0x3d372713, v17
	v_mul_f32_e32 v2, v16, v2
	v_mul_f32_e32 v3, v17, v3
	v_fma_f32 v2, v16, v2, v16
	v_fma_f32 v3, v17, v3, v17
	v_mul_f32_e32 v2, 0x3f4c422a, v2
	v_mul_f32_e32 v3, 0x3f4c422a, v3
	v_mul_f32_e32 v2, 0xc038aa3b, v2
	v_mul_f32_e32 v3, 0xc038aa3b, v3
	v_exp_f32_e32 v2, v2
	v_exp_f32_e32 v3, v3
	v_add_f32_e32 v2, 1.0, v2
	v_add_f32_e32 v3, 1.0, v3
	v_rcp_f32_e32 v2, v2
	v_rcp_f32_e32 v3, v3
	s_nop 0
	v_pk_mul_f32 v[16:17], v[16:17], v[2:3]
	v_mul_f32_e32 v2, 0x3d372713, v22
	v_mul_f32_e32 v3, 0x3d372713, v23
	v_mul_f32_e32 v2, v22, v2
	v_mul_f32_e32 v3, v23, v3
	v_fma_f32 v2, v22, v2, v22
	v_fma_f32 v3, v23, v3, v23
	v_mul_f32_e32 v2, 0x3f4c422a, v2
	v_mul_f32_e32 v3, 0x3f4c422a, v3
	v_mul_f32_e32 v2, 0xc038aa3b, v2
	v_mul_f32_e32 v3, 0xc038aa3b, v3
	v_exp_f32_e32 v2, v2
	v_exp_f32_e32 v3, v3
	v_add_f32_e32 v2, 1.0, v2
	v_add_f32_e32 v3, 1.0, v3
	v_rcp_f32_e32 v2, v2
	v_rcp_f32_e32 v3, v3
	s_nop 0
	v_pk_mul_f32 v[22:23], v[22:23], v[2:3]
	v_mul_f32_e32 v2, 0x3d372713, v6
	v_mul_f32_e32 v3, 0x3d372713, v7
	v_mul_f32_e32 v2, v6, v2
	v_mul_f32_e32 v3, v7, v3
	v_fma_f32 v2, v6, v2, v6
	v_fma_f32 v3, v7, v3, v7
	v_mul_f32_e32 v2, 0x3f4c422a, v2
	v_mul_f32_e32 v3, 0x3f4c422a, v3
	v_mul_f32_e32 v2, 0xc038aa3b, v2
	v_mul_f32_e32 v3, 0xc038aa3b, v3
	v_exp_f32_e32 v2, v2
	v_exp_f32_e32 v3, v3
	v_add_f32_e32 v2, 1.0, v2
	v_add_f32_e32 v3, 1.0, v3
	v_rcp_f32_e32 v2, v2
	v_rcp_f32_e32 v3, v3
	s_nop 0
	v_pk_mul_f32 v[6:7], v[6:7], v[2:3]
	v_mul_f32_e32 v2, 0x3d372713, v10
	v_mul_f32_e32 v3, 0x3d372713, v11
	v_mul_f32_e32 v2, v10, v2
	v_mul_f32_e32 v3, v11, v3
	v_fma_f32 v2, v10, v2, v10
	v_fma_f32 v3, v11, v3, v11
	v_mul_f32_e32 v2, 0x3f4c422a, v2
	v_mul_f32_e32 v3, 0x3f4c422a, v3
	v_mul_f32_e32 v2, 0xc038aa3b, v2
	v_mul_f32_e32 v3, 0xc038aa3b, v3
	v_exp_f32_e32 v2, v2
	v_exp_f32_e32 v3, v3
	v_add_f32_e32 v2, 1.0, v2
	v_add_f32_e32 v3, 1.0, v3
	v_rcp_f32_e32 v2, v2
	v_rcp_f32_e32 v3, v3
	s_nop 0
	v_pk_mul_f32 v[10:11], v[10:11], v[2:3]
	v_mul_f32_e32 v2, 0x3d372713, v8
	v_mul_f32_e32 v3, 0x3d372713, v9
	v_mul_f32_e32 v2, v8, v2
	v_mul_f32_e32 v3, v9, v3
	v_fma_f32 v2, v8, v2, v8
	v_fma_f32 v3, v9, v3, v9
	v_mul_f32_e32 v2, 0x3f4c422a, v2
	v_mul_f32_e32 v3, 0x3f4c422a, v3
	v_mul_f32_e32 v2, 0xc038aa3b, v2
	v_mul_f32_e32 v3, 0xc038aa3b, v3
	v_exp_f32_e32 v2, v2
	v_exp_f32_e32 v3, v3
	v_add_f32_e32 v2, 1.0, v2
	v_add_f32_e32 v3, 1.0, v3
	v_rcp_f32_e32 v2, v2
	v_rcp_f32_e32 v3, v3
	s_nop 0
	v_pk_mul_f32 v[8:9], v[8:9], v[2:3]
	v_mul_f32_e32 v2, 0x3d372713, v12
	v_mul_f32_e32 v3, 0x3d372713, v13
	v_mul_f32_e32 v2, v12, v2
	v_mul_f32_e32 v3, v13, v3
	v_fma_f32 v2, v12, v2, v12
	v_fma_f32 v3, v13, v3, v13
	v_mul_f32_e32 v2, 0x3f4c422a, v2
	v_mul_f32_e32 v3, 0x3f4c422a, v3
	v_mul_f32_e32 v2, 0xc038aa3b, v2
	v_mul_f32_e32 v3, 0xc038aa3b, v3
	v_exp_f32_e32 v2, v2
	v_exp_f32_e32 v3, v3
	v_add_f32_e32 v2, 1.0, v2
	v_add_f32_e32 v3, 1.0, v3
	v_rcp_f32_e32 v2, v2
	v_rcp_f32_e32 v3, v3
	s_nop 0
	v_pk_mul_f32 v[12:13], v[12:13], v[2:3]
	s_and_b64 vcc, exec, s[8:9]
	s_cbranch_vccz .LBB0_1121

.LBB0_1142:
	s_or_b64 exec, exec, s[8:9]
	v_mul_f32_e32 v3, 0xbfb8aa3b, v16
	v_mul_f32_e32 v4, 0xbfb8aa3b, v17
	v_mul_f32_e32 v5, 0xbfb8aa3b, v22
	v_exp_f32_e32 v3, v3
	v_exp_f32_e32 v4, v4
	v_exp_f32_e32 v5, v5
	v_add_f32_e32 v3, 1.0, v3
	v_add_f32_e32 v4, 1.0, v4
	v_add_f32_e32 v5, 1.0, v5
	v_rcp_f32_e32 v3, v3
	v_rcp_f32_e32 v4, v4
	v_rcp_f32_e32 v5, v5
	global_store_dwordx4 v[24:25], v[2:5], off offset:12 sc1
	s_nop 1
	v_mul_f32_e32 v2, 0xbfb8aa3b, v23
	v_exp_f32_e32 v2, v2
	s_nop 0
	v_add_f32_e32 v2, 1.0, v2
	v_rcp_f32_e32 v2, v2
	global_store_dword v[24:25], v2, off offset:28
.LBB0_1143:
	s_or_b64 exec, exec, s[6:7]
	v_cvt_pk_bf16_f32 v2, v14, v15
	v_add_co_u32_e32 v14, vcc, 0x16000, v18
	s_mov_b64 s[6:7], 0x16000
	v_cvt_pk_bf16_f32 v3, v20, v21
	v_cvt_pk_bf16_f32 v4, v16, v17
	v_cvt_pk_bf16_f32 v5, v22, v23
	v_addc_co_u32_e32 v15, vcc, 0, v19, vcc
	v_lshl_add_u64 v[24:25], v[18:19], 0, s[6:7]
	global_store_dwordx4 v[14:15], v[2:5], off sc1
	s_andn2_b64 vcc, exec, s[4:5]
	s_mov_b64 s[4:5], -1
	v_cvt_pk_bf16_f32 v2, v6, v7
	v_cvt_pk_bf16_f32 v3, v10, v11
	v_cvt_pk_bf16_f32 v4, v8, v9
	v_cvt_pk_bf16_f32 v5, v12, v13
	global_store_dwordx4 v[24:25], v[2:5], off offset:64 sc1
	s_cbranch_vccnz .LBB0_880
	s_andn2_b64 vcc, exec, s[14:15]
	s_cbranch_vccnz .LBB0_879
	s_barrier
	s_branch .LBB0_879

.LBB0_1385:
	v_add_u32_e32 v0, 0xffffc018, v0
	s_waitcnt lgkmcnt(0)
	v_mad_u64_u32 v[40:41], s[0:1], v0, s24, 0
	v_ashrrev_i32_e32 v42, 31, v0
	v_mov_b32_e32 v0, v41
	v_mad_u64_u32 v[42:43], s[0:1], v42, s24, v[0:1]
	v_mov_b32_e32 v41, v42
	v_lshl_add_u64 v[38:39], v[40:41], 1, v[38:39]
	global_store_dwordx4 v[38:39], v[34:37], off sc1
	s_waitcnt lgkmcnt(0)
	s_addk_i32 s30, 0x4000
	s_add_i32 s34, s34, 0x8000
	s_addk_i32 s36, 0x2000
	s_andn2_b64 vcc, exec, s[18:19]
	s_mov_b32 s22, s37
	v_mov_b32_e32 v62, v6
	v_mov_b32_e32 v63, v7
	v_mov_b32_e32 v64, v8
	v_mov_b32_e32 v65, v9
	v_mov_b32_e32 v58, v2
	v_mov_b32_e32 v59, v3
	v_mov_b32_e32 v60, v4
	v_mov_b32_e32 v61, v5
	v_mov_b32_e32 v54, v14
	v_mov_b32_e32 v55, v15
	v_mov_b32_e32 v56, v16
	v_mov_b32_e32 v57, v17
	v_mov_b32_e32 v50, v10
	v_mov_b32_e32 v51, v11
	v_mov_b32_e32 v52, v12
	v_mov_b32_e32 v53, v13
	v_mov_b32_e32 v46, v22
	v_mov_b32_e32 v47, v23
	v_mov_b32_e32 v48, v24
	v_mov_b32_e32 v49, v25
	v_mov_b32_e32 v42, v18
	v_mov_b32_e32 v43, v19
	v_mov_b32_e32 v44, v20
	v_mov_b32_e32 v45, v21
	v_mov_b32_e32 v38, v30
	v_mov_b32_e32 v39, v31
	v_mov_b32_e32 v40, v32
	v_mov_b32_e32 v41, v33
	v_mov_b32_e32 v34, v26
	v_mov_b32_e32 v35, v27
	v_mov_b32_e32 v36, v28
	v_mov_b32_e32 v37, v29
	s_cbranch_vccz .LBB0_1307

.LBB0_1445:
	s_mul_i32 s0, s29, s38
	s_add_i32 s0, s0, s30
	v_add_u32_e32 v0, s0, v70
	v_add_u32_e32 v40, 0xffffc000, v0
	v_ashrrev_i32_e32 v43, 31, v40
	v_mad_u64_u32 v[40:41], s[0:1], v40, s24, 0
	v_mov_b32_e32 v42, v41
	s_ashr_i32 s21, s20, 31
	v_mad_u64_u32 v[42:43], s[0:1], v43, s24, v[42:43]
	s_waitcnt lgkmcnt(0)
	v_lshl_add_u64 v[38:39], s[20:21], 1, v[66:67]
	v_mov_b32_e32 v41, v42
	v_lshl_add_u64 v[40:41], v[40:41], 1, v[38:39]
	global_store_dwordx4 v[40:41], v[34:37], off sc1
	ds_read2_b32 v[40:41], v72 offset0:8 offset1:41
	s_andn2_b64 vcc, exec, s[14:15]
	v_cndmask_b32_e64 v34, 0, 1, s[14:15]
	v_cmp_ne_u32_e64 s[0:1], 1, v34
	s_mov_b64 s[20:21], -1
	s_cbranch_vccnz .LBB0_1447
	ds_read2_b32 v[36:37], v72 offset0:74 offset1:107
	ds_read2_b32 v[42:43], v72 offset0:206 offset1:239
	s_waitcnt lgkmcnt(2)
	v_cvt_pk_bf16_f32 v34, v40, v41
	s_mov_b64 s[20:21], 0
	s_waitcnt lgkmcnt(1)
	v_cvt_pk_bf16_f32 v35, v36, v37
	ds_read2_b32 v[36:37], v72 offset0:140 offset1:173
	s_waitcnt lgkmcnt(0)
	v_cvt_pk_bf16_f32 v36, v36, v37
	v_cvt_pk_bf16_f32 v37, v42, v43

.LBB0_1449:
	s_waitcnt lgkmcnt(0)
	v_add_u32_e32 v40, 0xffffc008, v0
	v_ashrrev_i32_e32 v43, 31, v40
	v_mad_u64_u32 v[40:41], s[20:21], v40, s24, 0
	v_mov_b32_e32 v42, v41
	v_mad_u64_u32 v[42:43], s[20:21], v43, s24, v[42:43]
	v_mov_b32_e32 v41, v42
	v_lshl_add_u64 v[40:41], v[40:41], 1, v[38:39]
	global_store_dwordx4 v[40:41], v[34:37], off sc1
	ds_read2_b32 v[40:41], v72 offset0:16 offset1:49
	s_mov_b64 s[20:21], -1
	s_and_b64 vcc, exec, s[0:1]
	s_cbranch_vccnz .LBB0_1451
	ds_read2_b32 v[36:37], v72 offset0:82 offset1:115
	ds_read2_b32 v[42:43], v72 offset0:214 offset1:247
	s_waitcnt lgkmcnt(2)
	v_cvt_pk_bf16_f32 v34, v40, v41
	s_mov_b64 s[20:21], 0
	s_waitcnt lgkmcnt(1)
	v_cvt_pk_bf16_f32 v35, v36, v37
	ds_read2_b32 v[36:37], v72 offset0:148 offset1:181
	s_waitcnt lgkmcnt(0)
	v_cvt_pk_bf16_f32 v36, v36, v37
	v_cvt_pk_bf16_f32 v37, v42, v43

.LBB0_1453:
	s_waitcnt lgkmcnt(0)
	v_add_u32_e32 v40, 0xffffc010, v0
	v_ashrrev_i32_e32 v43, 31, v40
	v_mad_u64_u32 v[40:41], s[20:21], v40, s24, 0
	v_mov_b32_e32 v42, v41
	v_mad_u64_u32 v[42:43], s[20:21], v43, s24, v[42:43]
	v_mov_b32_e32 v41, v42
	v_lshl_add_u64 v[40:41], v[40:41], 1, v[38:39]
	global_store_dwordx4 v[40:41], v[34:37], off sc1
	ds_read2_b32 v[40:41], v72 offset0:24 offset1:57
	s_mov_b64 s[20:21], -1
	s_and_b64 vcc, exec, s[0:1]
	s_cbranch_vccnz .LBB0_1455
	ds_read2_b32 v[36:37], v72 offset0:90 offset1:123
	ds_read2_b32 v[42:43], v72 offset0:222 offset1:255
	s_waitcnt lgkmcnt(2)
	v_cvt_pk_bf16_f32 v34, v40, v41
	s_mov_b64 s[20:21], 0
	s_waitcnt lgkmcnt(1)
	v_cvt_pk_bf16_f32 v35, v36, v37
	ds_read2_b32 v[36:37], v72 offset0:156 offset1:189
	s_waitcnt lgkmcnt(0)
	v_cvt_pk_bf16_f32 v36, v36, v37
	v_cvt_pk_bf16_f32 v37, v42, v43

.LBB0_1990:
	s_ashr_i32 s23, s22, 31
	s_lshl_b64 s[22:23], s[22:23], 8
	v_lshl_or_b32 v138, s20, 8, v155
	v_lshl_add_u64 v[140:141], s[22:23], 0, v[132:133]
	s_mov_b32 s13, s33
	v_ashrrev_i32_e32 v139, 31, v138
	v_lshlrev_b64 v[146:147], 11, v[140:141]
	v_lshl_add_u64 v[142:143], s[26:27], 0, v[146:147]
	v_lshlrev_b64 v[148:149], 1, v[138:139]
	s_mov_b32 s13, s33
	v_lshl_add_u64 v[142:143], v[142:143], 0, v[148:149]
	global_load_dwordx2 v[158:159], v[142:143], off
	global_load_dwordx2 v[160:161], v[142:143], off offset:32
	global_load_dwordx2 v[162:163], v[142:143], off offset:256
	global_load_dwordx2 v[164:165], v[142:143], off offset:288
	v_mov_b32_e32 v142, s13
	ds_read2_b32 v[166:167], v142 offset1:1
	v_lshl_add_u64 v[142:143], s[26:27], 0, v[148:149]
	v_lshl_add_u64 v[144:145], v[142:143], 0, v[146:147]
	v_add_co_u32_e32 v168, vcc, s54, v144
	v_lshl_add_u64 v[146:147], s[24:25], 0, v[146:147]
	s_nop 0
	v_addc_co_u32_e32 v169, vcc, 0, v145, vcc
	v_lshl_add_u64 v[170:171], v[146:147], 0, v[148:149]
	global_load_dwordx2 v[152:153], v[168:169], off
	global_load_dwordx2 v[150:151], v[168:169], off offset:32
	global_load_dwordx2 v[148:149], v[168:169], off offset:256
	global_load_dwordx2 v[146:147], v[168:169], off offset:288
	s_waitcnt lgkmcnt(0)
	v_readfirstlane_b32 s13, v166
	v_readfirstlane_b32 s15, v167
	s_lshl_b32 s20, s20, 2
	s_ashr_i32 s21, s20, 31
	s_lshl_b64 s[20:21], s[20:21], 2
	s_add_u32 s13, s13, s20
	s_addc_u32 s15, s15, s21
	s_add_u32 s13, s13, s48
	s_addc_u32 s15, s15, 0
	s_add_u32 s20, s13, 0x10380000
	s_addc_u32 s21, s15, 0
	s_waitcnt vmcnt(0)
	v_cvt_f32_f16_e32 v166, v158
	v_cvt_f32_f16_sdwa v167, v158 dst_sel:DWORD dst_unused:UNUSED_PAD src0_sel:WORD_1
	v_cvt_f32_f16_e32 v158, v159
	v_cvt_f32_f16_sdwa v159, v159 dst_sel:DWORD dst_unused:UNUSED_PAD src0_sel:WORD_1
	v_cvt_f32_f16_e32 v168, v160
	v_cvt_f32_f16_sdwa v169, v160 dst_sel:DWORD dst_unused:UNUSED_PAD src0_sel:WORD_1
	v_cvt_f32_f16_e32 v160, v161
	v_cvt_f32_f16_sdwa v161, v161 dst_sel:DWORD dst_unused:UNUSED_PAD src0_sel:WORD_1
	v_cvt_f32_f16_e32 v172, v162
	v_cvt_f32_f16_sdwa v173, v162 dst_sel:DWORD dst_unused:UNUSED_PAD src0_sel:WORD_1
	v_cvt_f32_f16_e32 v162, v163
	v_cvt_f32_f16_sdwa v163, v163 dst_sel:DWORD dst_unused:UNUSED_PAD src0_sel:WORD_1
	v_cvt_f32_f16_e32 v174, v164
	v_cvt_f32_f16_sdwa v175, v164 dst_sel:DWORD dst_unused:UNUSED_PAD src0_sel:WORD_1
	v_cvt_f32_f16_e32 v164, v165
	v_cvt_f32_f16_sdwa v165, v165 dst_sel:DWORD dst_unused:UNUSED_PAD src0_sel:WORD_1
	v_pk_add_f32 v[128:129], v[128:129], v[158:159]
	v_pk_add_f32 v[126:127], v[126:127], v[166:167]
	v_pk_add_f32 v[124:125], v[124:125], v[160:161]
	v_pk_add_f32 v[122:123], v[122:123], v[168:169]
	v_pk_add_f32 v[120:121], v[120:121], v[162:163]
	v_pk_add_f32 v[118:119], v[118:119], v[172:173]
	v_cvt_f16_f32_e32 v157, v126
	v_cvt_f16_f32_sdwa v158, v127 dst_sel:WORD_1 dst_unused:UNUSED_PAD src0_sel:DWORD
	v_cvt_f16_f32_e32 v159, v128
	v_cvt_f16_f32_sdwa v160, v129 dst_sel:WORD_1 dst_unused:UNUSED_PAD src0_sel:DWORD
	v_pk_add_f32 v[116:117], v[116:117], v[164:165]
	v_mul_f32_e32 v127, v127, v127
	v_mul_f32_e32 v129, v129, v129
	v_cvt_f16_f32_e32 v161, v122
	v_cvt_f16_f32_sdwa v162, v123 dst_sel:WORD_1 dst_unused:UNUSED_PAD src0_sel:DWORD
	v_cvt_f16_f32_e32 v163, v124
	v_cvt_f16_f32_sdwa v164, v125 dst_sel:WORD_1 dst_unused:UNUSED_PAD src0_sel:DWORD
	v_mul_f32_e32 v123, v123, v123
	v_mul_f32_e32 v125, v125, v125
	v_cvt_f16_f32_e32 v165, v118
	v_cvt_f16_f32_sdwa v166, v119 dst_sel:WORD_1 dst_unused:UNUSED_PAD src0_sel:DWORD
	v_cvt_f16_f32_e32 v167, v120
	v_cvt_f16_f32_sdwa v168, v121 dst_sel:WORD_1 dst_unused:UNUSED_PAD src0_sel:DWORD
	v_mul_f32_e32 v169, v119, v119
	v_fmac_f32_e32 v127, v126, v126
	v_fmac_f32_e32 v129, v128, v128
	v_fmac_f32_e32 v123, v122, v122
	v_fmac_f32_e32 v125, v124, v124
	v_fmac_f32_e32 v169, v118, v118
	v_add_f32_e32 v118, v127, v129
	v_add_f32_e32 v119, v123, v125
	v_pk_add_f32 v[114:115], v[114:115], v[174:175]
	v_mul_f32_e32 v172, v121, v121
	v_add_f32_e32 v124, v118, v119
	v_or_b32_e32 v118, v158, v157
	v_or_b32_e32 v119, v160, v159
	v_cvt_f16_f32_e32 v173, v114
	v_cvt_f16_f32_sdwa v174, v115 dst_sel:WORD_1 dst_unused:UNUSED_PAD src0_sel:DWORD
	v_cvt_f16_f32_e32 v175, v116
	v_fmac_f32_e32 v172, v120, v120
	v_or_b32_e32 v120, v162, v161
	v_or_b32_e32 v121, v164, v163
	v_or_b32_e32 v122, v166, v165
	v_or_b32_e32 v123, v168, v167
	global_store_dwordx2 v[170:171], v[118:119], off sc1
	global_store_dwordx2 v[170:171], v[120:121], off offset:32 sc1
	global_store_dwordx2 v[170:171], v[122:123], off offset:256 sc1
	v_cvt_f16_f32_sdwa v119, v117 dst_sel:WORD_1 dst_unused:UNUSED_PAD src0_sel:DWORD
	v_mul_f32_e32 v115, v115, v115
	v_fmac_f32_e32 v115, v114, v114
	v_mul_f32_e32 v114, v117, v117
	v_add_f32_e32 v118, v169, v172
	v_fmac_f32_e32 v114, v116, v116
	v_add_f32_e32 v120, v124, v118
	v_or_b32_e32 v118, v174, v173
	v_or_b32_e32 v119, v119, v175
	v_add_f32_e32 v114, v115, v114
	v_mov_b32_e32 v115, v1
	global_store_dwordx2 v[170:171], v[118:119], off offset:288 sc1
	v_add_f32_e32 v114, v120, v114
	v_mbcnt_lo_u32_b32 v115, -1, v115
	v_mbcnt_hi_u32_b32 v115, -1, v115
	v_lshlrev_b32_e32 v115, 2, v115
	v_xor_b32_e32 v115, 64, v115
	ds_bpermute_b32 v115, v115, v114
	s_waitcnt lgkmcnt(0)
	v_add_f32_e32 v114, v114, v115
	v_mov_b32_e32 v115, v1
	s_nop 0
	v_mbcnt_lo_u32_b32 v115, -1, v115
	v_mbcnt_hi_u32_b32 v115, -1, v115
	v_lshlrev_b32_e32 v115, 2, v115
	v_xor_b32_e32 v115, 0x80, v115
	ds_bpermute_b32 v115, v115, v114
	s_and_saveexec_b64 s[22:23], s[0:1]
	s_cbranch_execz .LBB0_1992
	v_lshlrev_b64 v[116:117], 6, v[140:141]
	v_lshl_add_u64 v[116:117], s[20:21], 0, v[116:117]
	s_waitcnt lgkmcnt(0)
	v_add_f32_e32 v114, v114, v115
	global_store_dword v[116:117], v114, off
.LBB0_1992:
	s_or_b64 exec, exec, s[22:23]
	v_cvt_f32_f16_sdwa v117, v152 dst_sel:DWORD dst_unused:UNUSED_PAD src0_sel:WORD_1
	v_cvt_f32_f16_e32 v116, v152
	v_cvt_f32_f16_sdwa v119, v153 dst_sel:DWORD dst_unused:UNUSED_PAD src0_sel:WORD_1
	v_cvt_f32_f16_e32 v118, v153
	s_mov_b32 s13, 0x10000
	v_cvt_f32_f16_sdwa v129, v146 dst_sel:DWORD dst_unused:UNUSED_PAD src0_sel:WORD_1
	v_cvt_f32_f16_e32 v128, v146
	v_add_co_u32_e32 v146, vcc, s13, v144
	v_cvt_f32_f16_sdwa v125, v148 dst_sel:DWORD dst_unused:UNUSED_PAD src0_sel:WORD_1
	v_cvt_f32_f16_e32 v124, v148
	v_cvt_f32_f16_sdwa v127, v149 dst_sel:DWORD dst_unused:UNUSED_PAD src0_sel:WORD_1
	v_cvt_f32_f16_e32 v126, v149
	v_cvt_f32_f16_sdwa v149, v147 dst_sel:DWORD dst_unused:UNUSED_PAD src0_sel:WORD_1
	v_cvt_f32_f16_e32 v148, v147
	v_addc_co_u32_e32 v147, vcc, 0, v145, vcc
	v_cvt_f32_f16_sdwa v121, v150 dst_sel:DWORD dst_unused:UNUSED_PAD src0_sel:WORD_1
	v_cvt_f32_f16_e32 v120, v150
	v_cvt_f32_f16_sdwa v123, v151 dst_sel:DWORD dst_unused:UNUSED_PAD src0_sel:WORD_1
	v_cvt_f32_f16_e32 v122, v151
	v_pk_add_f32 v[150:151], v[112:113], v[118:119]
	v_pk_add_f32 v[152:153], v[110:111], v[116:117]
	global_load_dwordx2 v[118:119], v[146:147], off
	global_load_dwordx2 v[116:117], v[146:147], off offset:32
	global_load_dwordx2 v[112:113], v[146:147], off offset:256
	global_load_dwordx2 v[110:111], v[146:147], off offset:288
	v_cvt_f16_f32_e32 v157, v152
	v_cvt_f16_f32_sdwa v158, v153 dst_sel:WORD_1 dst_unused:UNUSED_PAD src0_sel:DWORD
	v_cvt_f16_f32_e32 v159, v150
	v_cvt_f16_f32_sdwa v160, v151 dst_sel:WORD_1 dst_unused:UNUSED_PAD src0_sel:DWORD
	v_pk_add_f32 v[108:109], v[108:109], v[122:123]
	v_pk_add_f32 v[106:107], v[106:107], v[120:121]
	v_cvt_f16_f32_e32 v122, v108
	v_cvt_f16_f32_e32 v120, v106
	v_cvt_f16_f32_sdwa v121, v107 dst_sel:WORD_1 dst_unused:UNUSED_PAD src0_sel:DWORD
	v_cvt_f16_f32_sdwa v123, v109 dst_sel:WORD_1 dst_unused:UNUSED_PAD src0_sel:DWORD
	v_or_b32_e32 v114, 16, v140
	s_waitcnt lgkmcnt(0)
	v_mov_b32_e32 v115, v141
	v_or_b32_e32 v146, v158, v157
	v_or_b32_e32 v147, v160, v159
	v_lshlrev_b64 v[158:159], 11, v[114:115]
	v_lshl_add_u64 v[158:159], s[24:25], 0, v[158:159]
	v_mul_f32_e32 v107, v107, v107
	v_lshl_add_u64 v[158:159], v[138:139], 1, v[158:159]
	v_or_b32_e32 v120, v121, v120
	v_or_b32_e32 v121, v123, v122
	v_fmac_f32_e32 v107, v106, v106
	v_mul_f32_e32 v106, v109, v109
	v_pk_add_f32 v[104:105], v[104:105], v[126:127]
	v_pk_add_f32 v[102:103], v[102:103], v[124:125]
	global_store_dwordx2 v[158:159], v[120:121], off offset:32 sc1
	v_fmac_f32_e32 v106, v108, v108
	v_cvt_f16_f32_e32 v108, v102
	v_cvt_f16_f32_sdwa v109, v103 dst_sel:WORD_1 dst_unused:UNUSED_PAD src0_sel:DWORD
	v_cvt_f16_f32_e32 v120, v104
	v_cvt_f16_f32_sdwa v121, v105 dst_sel:WORD_1 dst_unused:UNUSED_PAD src0_sel:DWORD
	global_store_dwordx2 v[158:159], v[146:147], off sc1
	v_mul_f32_e32 v146, v153, v153
	v_mul_f32_e32 v147, v151, v151
	v_fmac_f32_e32 v146, v152, v152
	v_fmac_f32_e32 v147, v150, v150
	v_add_f32_e32 v146, v146, v147
	v_add_f32_e32 v106, v107, v106
	v_mul_f32_e32 v103, v103, v103
	v_add_f32_e32 v122, v146, v106
	v_or_b32_e32 v106, v109, v108
	v_or_b32_e32 v107, v121, v120
	v_fmac_f32_e32 v103, v102, v102
	v_mul_f32_e32 v102, v105, v105
	v_pk_add_f32 v[100:101], v[100:101], v[148:149]
	v_pk_add_f32 v[98:99], v[98:99], v[128:129]
	global_store_dwordx2 v[158:159], v[106:107], off offset:256 sc1
	v_fmac_f32_e32 v102, v104, v104
	v_cvt_f16_f32_e32 v104, v98
	v_cvt_f16_f32_sdwa v105, v99 dst_sel:WORD_1 dst_unused:UNUSED_PAD src0_sel:DWORD
	v_cvt_f16_f32_e32 v106, v100
	v_cvt_f16_f32_sdwa v107, v101 dst_sel:WORD_1 dst_unused:UNUSED_PAD src0_sel:DWORD
	v_mul_f32_e32 v99, v99, v99
	v_fmac_f32_e32 v99, v98, v98
	v_mul_f32_e32 v98, v101, v101
	v_add_f32_e32 v102, v103, v102
	v_fmac_f32_e32 v98, v100, v100
	v_add_f32_e32 v108, v122, v102
	v_or_b32_e32 v102, v105, v104
	v_or_b32_e32 v103, v107, v106
	v_add_f32_e32 v98, v99, v98
	v_mov_b32_e32 v99, v1
	global_store_dwordx2 v[158:159], v[102:103], off offset:288 sc1
	v_add_f32_e32 v98, v108, v98
	v_mbcnt_lo_u32_b32 v99, -1, v99
	v_mbcnt_hi_u32_b32 v99, -1, v99
	v_lshlrev_b32_e32 v99, 2, v99
	v_xor_b32_e32 v99, 64, v99
	ds_bpermute_b32 v99, v99, v98
	s_waitcnt lgkmcnt(0)
	v_add_f32_e32 v98, v98, v99
	v_mov_b32_e32 v99, v1
	s_nop 0
	v_mbcnt_lo_u32_b32 v99, -1, v99
	v_mbcnt_hi_u32_b32 v99, -1, v99
	v_lshlrev_b32_e32 v99, 2, v99
	v_xor_b32_e32 v99, 0x80, v99
	ds_bpermute_b32 v99, v99, v98
	s_and_saveexec_b64 s[22:23], s[0:1]
	s_movk_i32 s53, 0x5ff
	s_cbranch_execz .LBB0_1994
	v_lshlrev_b64 v[100:101], 6, v[114:115]
	v_lshl_add_u64 v[100:101], s[20:21], 0, v[100:101]
	s_waitcnt lgkmcnt(0)
	v_add_f32_e32 v98, v98, v99
	global_store_dword v[100:101], v98, off
.LBB0_1994:
	s_or_b64 exec, exec, s[22:23]
	s_waitcnt vmcnt(7)
	v_cvt_f32_f16_sdwa v101, v118 dst_sel:DWORD dst_unused:UNUSED_PAD src0_sel:WORD_1
	v_cvt_f32_f16_e32 v100, v118
	v_cvt_f32_f16_sdwa v103, v119 dst_sel:DWORD dst_unused:UNUSED_PAD src0_sel:WORD_1
	v_cvt_f32_f16_e32 v102, v119
	s_mov_b32 s13, 0x18000
	s_waitcnt vmcnt(5)
	v_cvt_f32_f16_sdwa v109, v112 dst_sel:DWORD dst_unused:UNUSED_PAD src0_sel:WORD_1
	v_cvt_f32_f16_e32 v108, v112
	v_cvt_f32_f16_sdwa v115, v113 dst_sel:DWORD dst_unused:UNUSED_PAD src0_sel:WORD_1
	v_cvt_f32_f16_e32 v114, v113
	s_waitcnt vmcnt(4)
	v_cvt_f32_f16_sdwa v113, v110 dst_sel:DWORD dst_unused:UNUSED_PAD src0_sel:WORD_1
	v_cvt_f32_f16_e32 v112, v110
	v_add_co_u32_e32 v110, vcc, s13, v144
	v_cvt_f32_f16_sdwa v105, v116 dst_sel:DWORD dst_unused:UNUSED_PAD src0_sel:WORD_1
	v_cvt_f32_f16_e32 v104, v116
	v_cvt_f32_f16_sdwa v107, v117 dst_sel:DWORD dst_unused:UNUSED_PAD src0_sel:WORD_1
	v_cvt_f32_f16_e32 v106, v117
	v_cvt_f32_f16_sdwa v117, v111 dst_sel:DWORD dst_unused:UNUSED_PAD src0_sel:WORD_1
	v_cvt_f32_f16_e32 v116, v111
	v_addc_co_u32_e32 v111, vcc, 0, v145, vcc
	v_pk_add_f32 v[118:119], v[96:97], v[102:103]
	v_pk_add_f32 v[120:121], v[94:95], v[100:101]
	global_load_dwordx2 v[102:103], v[110:111], off
	global_load_dwordx2 v[100:101], v[110:111], off offset:32
	global_load_dwordx2 v[96:97], v[110:111], off offset:256
	global_load_dwordx2 v[94:95], v[110:111], off offset:288
	v_cvt_f16_f32_e32 v122, v120
	v_cvt_f16_f32_sdwa v123, v121 dst_sel:WORD_1 dst_unused:UNUSED_PAD src0_sel:DWORD
	v_pk_add_f32 v[92:93], v[92:93], v[106:107]
	v_pk_add_f32 v[90:91], v[90:91], v[104:105]
	v_cvt_f16_f32_e32 v106, v92
	v_cvt_f16_f32_e32 v104, v90
	v_cvt_f16_f32_sdwa v105, v91 dst_sel:WORD_1 dst_unused:UNUSED_PAD src0_sel:DWORD
	v_cvt_f16_f32_sdwa v107, v93 dst_sel:WORD_1 dst_unused:UNUSED_PAD src0_sel:DWORD
	v_or_b32_e32 v98, 32, v140
	s_waitcnt lgkmcnt(0)
	v_mov_b32_e32 v99, v141
	v_cvt_f16_f32_e32 v124, v118
	v_cvt_f16_f32_sdwa v125, v119 dst_sel:WORD_1 dst_unused:UNUSED_PAD src0_sel:DWORD
	v_or_b32_e32 v110, v123, v122
	v_lshlrev_b64 v[122:123], 11, v[98:99]
	v_lshl_add_u64 v[122:123], s[24:25], 0, v[122:123]
	v_mul_f32_e32 v91, v91, v91
	v_lshl_add_u64 v[122:123], v[138:139], 1, v[122:123]
	v_or_b32_e32 v104, v105, v104
	v_or_b32_e32 v105, v107, v106
	v_fmac_f32_e32 v91, v90, v90
	v_mul_f32_e32 v90, v93, v93
	v_pk_add_f32 v[88:89], v[88:89], v[114:115]
	v_pk_add_f32 v[86:87], v[86:87], v[108:109]
	v_or_b32_e32 v111, v125, v124
	global_store_dwordx2 v[122:123], v[104:105], off offset:32 sc1
	v_fmac_f32_e32 v90, v92, v92
	v_cvt_f16_f32_e32 v92, v86
	v_cvt_f16_f32_sdwa v93, v87 dst_sel:WORD_1 dst_unused:UNUSED_PAD src0_sel:DWORD
	v_cvt_f16_f32_e32 v104, v88
	v_cvt_f16_f32_sdwa v105, v89 dst_sel:WORD_1 dst_unused:UNUSED_PAD src0_sel:DWORD
	global_store_dwordx2 v[122:123], v[110:111], off sc1
	v_mul_f32_e32 v110, v121, v121
	v_mul_f32_e32 v111, v119, v119
	v_fmac_f32_e32 v110, v120, v120
	v_fmac_f32_e32 v111, v118, v118
	v_add_f32_e32 v110, v110, v111
	v_add_f32_e32 v90, v91, v90
	v_mul_f32_e32 v87, v87, v87
	v_add_f32_e32 v106, v110, v90
	v_or_b32_e32 v90, v93, v92
	v_or_b32_e32 v91, v105, v104
	v_fmac_f32_e32 v87, v86, v86
	v_mul_f32_e32 v86, v89, v89
	v_pk_add_f32 v[84:85], v[84:85], v[116:117]
	v_pk_add_f32 v[82:83], v[82:83], v[112:113]
	global_store_dwordx2 v[122:123], v[90:91], off offset:256 sc1
	v_fmac_f32_e32 v86, v88, v88
	v_cvt_f16_f32_e32 v88, v82
	v_cvt_f16_f32_sdwa v89, v83 dst_sel:WORD_1 dst_unused:UNUSED_PAD src0_sel:DWORD
	v_cvt_f16_f32_e32 v90, v84
	v_cvt_f16_f32_sdwa v91, v85 dst_sel:WORD_1 dst_unused:UNUSED_PAD src0_sel:DWORD
	v_mul_f32_e32 v83, v83, v83
	v_fmac_f32_e32 v83, v82, v82
	v_mul_f32_e32 v82, v85, v85
	v_add_f32_e32 v86, v87, v86
	v_fmac_f32_e32 v82, v84, v84
	v_add_f32_e32 v92, v106, v86
	v_or_b32_e32 v86, v89, v88
	v_or_b32_e32 v87, v91, v90
	v_add_f32_e32 v82, v83, v82
	v_mov_b32_e32 v83, v1
	global_store_dwordx2 v[122:123], v[86:87], off offset:288 sc1
	v_add_f32_e32 v82, v92, v82
	v_mbcnt_lo_u32_b32 v83, -1, v83
	v_mbcnt_hi_u32_b32 v83, -1, v83
	v_lshlrev_b32_e32 v83, 2, v83
	v_xor_b32_e32 v83, 64, v83
	ds_bpermute_b32 v83, v83, v82
	s_waitcnt lgkmcnt(0)
	v_add_f32_e32 v82, v82, v83
	v_mov_b32_e32 v83, v1
	s_nop 0
	v_mbcnt_lo_u32_b32 v83, -1, v83
	v_mbcnt_hi_u32_b32 v83, -1, v83
	v_lshlrev_b32_e32 v83, 2, v83
	v_xor_b32_e32 v83, 0x80, v83
	ds_bpermute_b32 v83, v83, v82
	s_and_saveexec_b64 s[22:23], s[0:1]
	s_cbranch_execz .LBB0_1996
	v_lshlrev_b64 v[84:85], 6, v[98:99]
	v_lshl_add_u64 v[84:85], s[20:21], 0, v[84:85]
	s_waitcnt lgkmcnt(0)
	v_add_f32_e32 v82, v82, v83
	global_store_dword v[84:85], v82, off
.LBB0_1996:
	s_or_b64 exec, exec, s[22:23]
	s_waitcnt vmcnt(7)
	v_cvt_f32_f16_sdwa v85, v102 dst_sel:DWORD dst_unused:UNUSED_PAD src0_sel:WORD_1
	v_cvt_f32_f16_e32 v84, v102
	v_cvt_f32_f16_sdwa v87, v103 dst_sel:DWORD dst_unused:UNUSED_PAD src0_sel:WORD_1
	v_cvt_f32_f16_e32 v86, v103
	s_mov_b32 s13, 0x40000
	s_waitcnt vmcnt(5)
	v_cvt_f32_f16_sdwa v93, v96 dst_sel:DWORD dst_unused:UNUSED_PAD src0_sel:WORD_1
	v_cvt_f32_f16_e32 v92, v96
	v_cvt_f32_f16_sdwa v99, v97 dst_sel:DWORD dst_unused:UNUSED_PAD src0_sel:WORD_1
	v_cvt_f32_f16_e32 v98, v97
	s_waitcnt vmcnt(4)
	v_cvt_f32_f16_sdwa v97, v94 dst_sel:DWORD dst_unused:UNUSED_PAD src0_sel:WORD_1
	v_cvt_f32_f16_e32 v96, v94
	v_add_co_u32_e32 v94, vcc, s13, v144
	v_cvt_f32_f16_sdwa v89, v100 dst_sel:DWORD dst_unused:UNUSED_PAD src0_sel:WORD_1
	v_cvt_f32_f16_e32 v88, v100
	v_cvt_f32_f16_sdwa v91, v101 dst_sel:DWORD dst_unused:UNUSED_PAD src0_sel:WORD_1
	v_cvt_f32_f16_e32 v90, v101
	v_cvt_f32_f16_sdwa v101, v95 dst_sel:DWORD dst_unused:UNUSED_PAD src0_sel:WORD_1
	v_cvt_f32_f16_e32 v100, v95
	v_addc_co_u32_e32 v95, vcc, 0, v145, vcc
	v_pk_add_f32 v[102:103], v[80:81], v[86:87]
	v_pk_add_f32 v[104:105], v[78:79], v[84:85]
	global_load_dwordx2 v[86:87], v[94:95], off
	global_load_dwordx2 v[84:85], v[94:95], off offset:32
	global_load_dwordx2 v[80:81], v[94:95], off offset:256
	global_load_dwordx2 v[78:79], v[94:95], off offset:288
	v_cvt_f16_f32_e32 v106, v104
	v_cvt_f16_f32_sdwa v107, v105 dst_sel:WORD_1 dst_unused:UNUSED_PAD src0_sel:DWORD
	v_pk_add_f32 v[76:77], v[76:77], v[90:91]
	v_pk_add_f32 v[74:75], v[74:75], v[88:89]
	v_cvt_f16_f32_e32 v90, v76
	v_cvt_f16_f32_e32 v88, v74
	v_cvt_f16_f32_sdwa v89, v75 dst_sel:WORD_1 dst_unused:UNUSED_PAD src0_sel:DWORD
	v_cvt_f16_f32_sdwa v91, v77 dst_sel:WORD_1 dst_unused:UNUSED_PAD src0_sel:DWORD
	v_or_b32_e32 v82, 48, v140
	s_waitcnt lgkmcnt(0)
	v_mov_b32_e32 v83, v141
	v_cvt_f16_f32_e32 v108, v102
	v_cvt_f16_f32_sdwa v109, v103 dst_sel:WORD_1 dst_unused:UNUSED_PAD src0_sel:DWORD
	v_or_b32_e32 v94, v107, v106
	v_lshlrev_b64 v[106:107], 11, v[82:83]
	v_lshl_add_u64 v[106:107], s[24:25], 0, v[106:107]
	v_mul_f32_e32 v75, v75, v75
	v_lshl_add_u64 v[106:107], v[138:139], 1, v[106:107]
	v_or_b32_e32 v88, v89, v88
	v_or_b32_e32 v89, v91, v90
	v_fmac_f32_e32 v75, v74, v74
	v_mul_f32_e32 v74, v77, v77
	v_pk_add_f32 v[72:73], v[72:73], v[98:99]
	v_pk_add_f32 v[70:71], v[70:71], v[92:93]
	v_or_b32_e32 v95, v109, v108
	global_store_dwordx2 v[106:107], v[88:89], off offset:32 sc1
	v_fmac_f32_e32 v74, v76, v76
	v_cvt_f16_f32_e32 v76, v70
	v_cvt_f16_f32_sdwa v77, v71 dst_sel:WORD_1 dst_unused:UNUSED_PAD src0_sel:DWORD
	v_cvt_f16_f32_e32 v88, v72
	v_cvt_f16_f32_sdwa v89, v73 dst_sel:WORD_1 dst_unused:UNUSED_PAD src0_sel:DWORD
	global_store_dwordx2 v[106:107], v[94:95], off sc1
	v_mul_f32_e32 v94, v105, v105
	v_mul_f32_e32 v95, v103, v103
	v_fmac_f32_e32 v94, v104, v104
	v_fmac_f32_e32 v95, v102, v102
	v_add_f32_e32 v94, v94, v95
	v_add_f32_e32 v74, v75, v74
	v_mul_f32_e32 v71, v71, v71
	v_add_f32_e32 v90, v94, v74
	v_or_b32_e32 v74, v77, v76
	v_or_b32_e32 v75, v89, v88
	v_fmac_f32_e32 v71, v70, v70
	v_mul_f32_e32 v70, v73, v73
	v_pk_add_f32 v[68:69], v[68:69], v[100:101]
	v_pk_add_f32 v[66:67], v[66:67], v[96:97]
	global_store_dwordx2 v[106:107], v[74:75], off offset:256 sc1
	v_fmac_f32_e32 v70, v72, v72
	v_cvt_f16_f32_e32 v72, v66
	v_cvt_f16_f32_sdwa v73, v67 dst_sel:WORD_1 dst_unused:UNUSED_PAD src0_sel:DWORD
	v_cvt_f16_f32_e32 v74, v68
	v_cvt_f16_f32_sdwa v75, v69 dst_sel:WORD_1 dst_unused:UNUSED_PAD src0_sel:DWORD
	v_mul_f32_e32 v67, v67, v67
	v_fmac_f32_e32 v67, v66, v66
	v_mul_f32_e32 v66, v69, v69
	v_add_f32_e32 v70, v71, v70
	v_fmac_f32_e32 v66, v68, v68
	v_add_f32_e32 v76, v90, v70
	v_or_b32_e32 v70, v73, v72
	v_or_b32_e32 v71, v75, v74
	v_add_f32_e32 v66, v67, v66
	v_mov_b32_e32 v67, v1
	global_store_dwordx2 v[106:107], v[70:71], off offset:288 sc1
	v_add_f32_e32 v66, v76, v66
	v_mbcnt_lo_u32_b32 v67, -1, v67
	v_mbcnt_hi_u32_b32 v67, -1, v67
	v_lshlrev_b32_e32 v67, 2, v67
	v_xor_b32_e32 v67, 64, v67
	ds_bpermute_b32 v67, v67, v66
	s_waitcnt lgkmcnt(0)
	v_add_f32_e32 v66, v66, v67
	v_mov_b32_e32 v67, v1
	s_nop 0
	v_mbcnt_lo_u32_b32 v67, -1, v67
	v_mbcnt_hi_u32_b32 v67, -1, v67
	v_lshlrev_b32_e32 v67, 2, v67
	v_xor_b32_e32 v67, 0x80, v67
	ds_bpermute_b32 v67, v67, v66
	s_and_saveexec_b64 s[22:23], s[0:1]
	s_cbranch_execz .LBB0_1998
	v_lshlrev_b64 v[68:69], 6, v[82:83]
	v_lshl_add_u64 v[68:69], s[20:21], 0, v[68:69]
	s_waitcnt lgkmcnt(0)
	v_add_f32_e32 v66, v66, v67
	global_store_dword v[68:69], v66, off
.LBB0_1998:
	s_or_b64 exec, exec, s[22:23]
	s_waitcnt vmcnt(7)
	v_cvt_f32_f16_sdwa v71, v86 dst_sel:DWORD dst_unused:UNUSED_PAD src0_sel:WORD_1
	v_cvt_f32_f16_e32 v70, v86
	v_cvt_f32_f16_sdwa v73, v87 dst_sel:DWORD dst_unused:UNUSED_PAD src0_sel:WORD_1
	v_cvt_f32_f16_e32 v72, v87
	v_lshl_add_u64 v[68:69], v[140:141], 0, s[96:97]
	s_waitcnt lgkmcnt(0)
	v_lshlrev_b64 v[66:67], 11, v[68:69]
	v_or_b32_e32 v88, 0x8000, v66
	v_mov_b32_e32 v89, v67
	v_lshl_add_u64 v[88:89], v[142:143], 0, v[88:89]
	v_pk_add_f32 v[90:91], v[64:65], v[72:73]
	v_pk_add_f32 v[92:93], v[62:63], v[70:71]
	global_load_dwordx2 v[72:73], v[88:89], off
	global_load_dwordx2 v[70:71], v[88:89], off offset:32
	global_load_dwordx2 v[64:65], v[88:89], off offset:256
	global_load_dwordx2 v[62:63], v[88:89], off offset:288
	s_waitcnt vmcnt(10)
	v_cvt_f32_f16_sdwa v75, v84 dst_sel:DWORD dst_unused:UNUSED_PAD src0_sel:WORD_1
	v_cvt_f32_f16_e32 v74, v84
	v_cvt_f32_f16_sdwa v77, v85 dst_sel:DWORD dst_unused:UNUSED_PAD src0_sel:WORD_1
	v_cvt_f32_f16_e32 v76, v85
	s_waitcnt vmcnt(9)
	v_cvt_f32_f16_sdwa v83, v80 dst_sel:DWORD dst_unused:UNUSED_PAD src0_sel:WORD_1
	v_pk_add_f32 v[58:59], v[58:59], v[74:75]
	v_cvt_f32_f16_e32 v82, v80
	v_pk_add_f32 v[60:61], v[60:61], v[76:77]
	v_cvt_f32_f16_sdwa v85, v81 dst_sel:DWORD dst_unused:UNUSED_PAD src0_sel:WORD_1
	v_cvt_f32_f16_e32 v84, v81
	v_cvt_f16_f32_e32 v74, v58
	v_cvt_f16_f32_sdwa v75, v59 dst_sel:WORD_1 dst_unused:UNUSED_PAD src0_sel:DWORD
	v_cvt_f16_f32_e32 v76, v60
	v_cvt_f16_f32_sdwa v77, v61 dst_sel:WORD_1 dst_unused:UNUSED_PAD src0_sel:DWORD
	s_waitcnt vmcnt(8)
	v_cvt_f32_f16_sdwa v81, v78 dst_sel:DWORD dst_unused:UNUSED_PAD src0_sel:WORD_1
	v_cvt_f32_f16_e32 v80, v78
	v_cvt_f16_f32_e32 v78, v92
	v_cvt_f16_f32_sdwa v94, v93 dst_sel:WORD_1 dst_unused:UNUSED_PAD src0_sel:DWORD
	v_cvt_f16_f32_e32 v95, v90
	v_cvt_f16_f32_sdwa v96, v91 dst_sel:WORD_1 dst_unused:UNUSED_PAD src0_sel:DWORD
	v_lshl_add_u64 v[88:89], s[24:25], 0, v[66:67]
	v_mul_f32_e32 v59, v59, v59
	v_lshl_add_u64 v[88:89], v[138:139], 1, v[88:89]
	v_or_b32_e32 v74, v75, v74
	v_or_b32_e32 v75, v77, v76
	v_fmac_f32_e32 v59, v58, v58
	v_mul_f32_e32 v58, v61, v61
	v_pk_add_f32 v[56:57], v[56:57], v[84:85]
	v_pk_add_f32 v[54:55], v[54:55], v[82:83]
	v_cvt_f32_f16_sdwa v87, v79 dst_sel:DWORD dst_unused:UNUSED_PAD src0_sel:WORD_1
	v_cvt_f32_f16_e32 v86, v79
	v_or_b32_e32 v78, v94, v78
	v_or_b32_e32 v79, v96, v95
	global_store_dwordx2 v[88:89], v[74:75], off offset:32 sc1
	v_fmac_f32_e32 v58, v60, v60
	v_cvt_f16_f32_e32 v60, v54
	v_cvt_f16_f32_sdwa v61, v55 dst_sel:WORD_1 dst_unused:UNUSED_PAD src0_sel:DWORD
	v_cvt_f16_f32_e32 v74, v56
	v_cvt_f16_f32_sdwa v75, v57 dst_sel:WORD_1 dst_unused:UNUSED_PAD src0_sel:DWORD
	global_store_dwordx2 v[88:89], v[78:79], off sc1
	v_mul_f32_e32 v78, v93, v93
	v_mul_f32_e32 v79, v91, v91
	v_fmac_f32_e32 v78, v92, v92
	v_fmac_f32_e32 v79, v90, v90
	v_add_f32_e32 v78, v78, v79
	v_add_f32_e32 v58, v59, v58
	v_mul_f32_e32 v55, v55, v55
	v_add_f32_e32 v76, v78, v58
	v_or_b32_e32 v58, v61, v60
	v_or_b32_e32 v59, v75, v74
	v_fmac_f32_e32 v55, v54, v54
	v_mul_f32_e32 v54, v57, v57
	v_pk_add_f32 v[52:53], v[52:53], v[86:87]
	v_pk_add_f32 v[50:51], v[50:51], v[80:81]
	global_store_dwordx2 v[88:89], v[58:59], off offset:256 sc1
	v_fmac_f32_e32 v54, v56, v56
	v_cvt_f16_f32_e32 v56, v50
	v_cvt_f16_f32_sdwa v57, v51 dst_sel:WORD_1 dst_unused:UNUSED_PAD src0_sel:DWORD
	v_cvt_f16_f32_e32 v58, v52
	v_cvt_f16_f32_sdwa v59, v53 dst_sel:WORD_1 dst_unused:UNUSED_PAD src0_sel:DWORD
	v_mul_f32_e32 v51, v51, v51
	v_fmac_f32_e32 v51, v50, v50
	v_mul_f32_e32 v50, v53, v53
	v_add_f32_e32 v54, v55, v54
	v_fmac_f32_e32 v50, v52, v52
	v_add_f32_e32 v60, v76, v54
	v_or_b32_e32 v54, v57, v56
	v_or_b32_e32 v55, v59, v58
	v_add_f32_e32 v50, v51, v50
	v_mov_b32_e32 v51, v1
	global_store_dwordx2 v[88:89], v[54:55], off offset:288 sc1
	v_add_f32_e32 v50, v60, v50
	v_mbcnt_lo_u32_b32 v51, -1, v51
	v_mbcnt_hi_u32_b32 v51, -1, v51
	v_lshlrev_b32_e32 v51, 2, v51
	v_xor_b32_e32 v51, 64, v51
	ds_bpermute_b32 v51, v51, v50
	s_waitcnt lgkmcnt(0)
	v_add_f32_e32 v50, v50, v51
	v_mov_b32_e32 v51, v1
	s_nop 0
	v_mbcnt_lo_u32_b32 v51, -1, v51
	v_mbcnt_hi_u32_b32 v51, -1, v51
	v_lshlrev_b32_e32 v51, 2, v51
	v_xor_b32_e32 v51, 0x80, v51
	ds_bpermute_b32 v51, v51, v50
	s_and_saveexec_b64 s[22:23], s[0:1]
	s_cbranch_execz .LBB0_2000
	v_lshlrev_b64 v[52:53], 6, v[68:69]
	v_lshl_add_u64 v[52:53], s[20:21], 0, v[52:53]
	s_waitcnt lgkmcnt(0)
	v_add_f32_e32 v50, v50, v51
	global_store_dword v[52:53], v50, off
.LBB0_2000:
	s_or_b64 exec, exec, s[22:23]
	s_waitcnt vmcnt(7)
	v_cvt_f32_f16_sdwa v53, v72 dst_sel:DWORD dst_unused:UNUSED_PAD src0_sel:WORD_1
	v_cvt_f32_f16_e32 v52, v72
	v_cvt_f32_f16_sdwa v55, v73 dst_sel:DWORD dst_unused:UNUSED_PAD src0_sel:WORD_1
	v_cvt_f32_f16_e32 v54, v73
	s_waitcnt vmcnt(6)
	v_cvt_f32_f16_sdwa v57, v70 dst_sel:DWORD dst_unused:UNUSED_PAD src0_sel:WORD_1
	v_cvt_f32_f16_e32 v56, v70
	v_cvt_f32_f16_sdwa v59, v71 dst_sel:DWORD dst_unused:UNUSED_PAD src0_sel:WORD_1
	v_cvt_f32_f16_e32 v58, v71
	s_waitcnt vmcnt(5)
	v_cvt_f32_f16_sdwa v61, v64 dst_sel:DWORD dst_unused:UNUSED_PAD src0_sel:WORD_1
	v_cvt_f32_f16_e32 v60, v64
	v_cvt_f32_f16_sdwa v69, v65 dst_sel:DWORD dst_unused:UNUSED_PAD src0_sel:WORD_1
	v_cvt_f32_f16_e32 v68, v65
	s_waitcnt vmcnt(4)
	v_cvt_f32_f16_sdwa v65, v62 dst_sel:DWORD dst_unused:UNUSED_PAD src0_sel:WORD_1
	v_cvt_f32_f16_e32 v64, v62
	v_cvt_f32_f16_sdwa v71, v63 dst_sel:DWORD dst_unused:UNUSED_PAD src0_sel:WORD_1
	v_cvt_f32_f16_e32 v70, v63
	v_or_b32_e32 v62, 0x10000, v66
	v_mov_b32_e32 v63, v67
	v_lshl_add_u64 v[62:63], v[142:143], 0, v[62:63]
	v_pk_add_f32 v[72:73], v[48:49], v[54:55]
	v_pk_add_f32 v[74:75], v[46:47], v[52:53]
	global_load_dwordx2 v[54:55], v[62:63], off
	global_load_dwordx2 v[52:53], v[62:63], off offset:32
	global_load_dwordx2 v[48:49], v[62:63], off offset:256
	global_load_dwordx2 v[46:47], v[62:63], off offset:288
	v_cvt_f16_f32_e32 v76, v74
	v_cvt_f16_f32_sdwa v77, v75 dst_sel:WORD_1 dst_unused:UNUSED_PAD src0_sel:DWORD
	v_pk_add_f32 v[44:45], v[44:45], v[58:59]
	v_pk_add_f32 v[42:43], v[42:43], v[56:57]
	s_mov_b64 s[22:23], 0x90
	v_cvt_f16_f32_e32 v56, v42
	v_cvt_f16_f32_sdwa v57, v43 dst_sel:WORD_1 dst_unused:UNUSED_PAD src0_sel:DWORD
	v_cvt_f16_f32_e32 v58, v44
	v_cvt_f16_f32_sdwa v59, v45 dst_sel:WORD_1 dst_unused:UNUSED_PAD src0_sel:DWORD
	s_waitcnt lgkmcnt(0)
	v_lshl_add_u64 v[50:51], v[140:141], 0, s[22:23]
	v_cvt_f16_f32_e32 v78, v72
	v_cvt_f16_f32_sdwa v79, v73 dst_sel:WORD_1 dst_unused:UNUSED_PAD src0_sel:DWORD
	v_or_b32_e32 v62, v77, v76
	v_lshlrev_b64 v[76:77], 11, v[50:51]
	v_lshl_add_u64 v[76:77], s[24:25], 0, v[76:77]
	v_mul_f32_e32 v43, v43, v43
	v_lshl_add_u64 v[76:77], v[138:139], 1, v[76:77]
	v_or_b32_e32 v56, v57, v56
	v_or_b32_e32 v57, v59, v58
	v_fmac_f32_e32 v43, v42, v42
	v_mul_f32_e32 v42, v45, v45
	v_pk_add_f32 v[40:41], v[40:41], v[68:69]
	v_pk_add_f32 v[38:39], v[38:39], v[60:61]
	v_or_b32_e32 v63, v79, v78
	global_store_dwordx2 v[76:77], v[56:57], off offset:32 sc1
	v_fmac_f32_e32 v42, v44, v44
	v_cvt_f16_f32_e32 v44, v38
	v_cvt_f16_f32_sdwa v45, v39 dst_sel:WORD_1 dst_unused:UNUSED_PAD src0_sel:DWORD
	v_cvt_f16_f32_e32 v56, v40
	v_cvt_f16_f32_sdwa v57, v41 dst_sel:WORD_1 dst_unused:UNUSED_PAD src0_sel:DWORD
	global_store_dwordx2 v[76:77], v[62:63], off sc1
	v_mul_f32_e32 v62, v75, v75
	v_mul_f32_e32 v63, v73, v73
	v_fmac_f32_e32 v62, v74, v74
	v_fmac_f32_e32 v63, v72, v72
	v_add_f32_e32 v62, v62, v63
	v_add_f32_e32 v42, v43, v42
	v_mul_f32_e32 v39, v39, v39
	v_add_f32_e32 v58, v62, v42
	v_or_b32_e32 v42, v45, v44
	v_or_b32_e32 v43, v57, v56
	v_fmac_f32_e32 v39, v38, v38
	v_mul_f32_e32 v38, v41, v41
	v_pk_add_f32 v[36:37], v[36:37], v[70:71]
	v_pk_add_f32 v[34:35], v[34:35], v[64:65]
	global_store_dwordx2 v[76:77], v[42:43], off offset:256 sc1
	v_fmac_f32_e32 v38, v40, v40
	v_cvt_f16_f32_e32 v40, v34
	v_cvt_f16_f32_sdwa v41, v35 dst_sel:WORD_1 dst_unused:UNUSED_PAD src0_sel:DWORD
	v_cvt_f16_f32_e32 v42, v36
	v_cvt_f16_f32_sdwa v43, v37 dst_sel:WORD_1 dst_unused:UNUSED_PAD src0_sel:DWORD
	v_mul_f32_e32 v35, v35, v35
	v_fmac_f32_e32 v35, v34, v34
	v_mul_f32_e32 v34, v37, v37
	v_add_f32_e32 v38, v39, v38
	v_fmac_f32_e32 v34, v36, v36
	v_add_f32_e32 v44, v58, v38
	v_or_b32_e32 v38, v41, v40
	v_or_b32_e32 v39, v43, v42
	v_add_f32_e32 v34, v35, v34
	v_mov_b32_e32 v35, v1
	global_store_dwordx2 v[76:77], v[38:39], off offset:288 sc1
	v_add_f32_e32 v34, v44, v34
	v_mbcnt_lo_u32_b32 v35, -1, v35
	v_mbcnt_hi_u32_b32 v35, -1, v35
	v_lshlrev_b32_e32 v35, 2, v35
	v_xor_b32_e32 v35, 64, v35
	ds_bpermute_b32 v35, v35, v34
	s_waitcnt lgkmcnt(0)
	v_add_f32_e32 v34, v34, v35
	v_mov_b32_e32 v35, v1
	s_nop 0
	v_mbcnt_lo_u32_b32 v35, -1, v35
	v_mbcnt_hi_u32_b32 v35, -1, v35
	v_lshlrev_b32_e32 v35, 2, v35
	v_xor_b32_e32 v35, 0x80, v35
	ds_bpermute_b32 v35, v35, v34
	s_and_saveexec_b64 s[22:23], s[0:1]
	s_cbranch_execz .LBB0_2002
	v_lshlrev_b64 v[36:37], 6, v[50:51]
	v_lshl_add_u64 v[36:37], s[20:21], 0, v[36:37]
	s_waitcnt lgkmcnt(0)
	v_add_f32_e32 v34, v34, v35
	global_store_dword v[36:37], v34, off
.LBB0_2002:
	s_or_b64 exec, exec, s[22:23]
	s_waitcnt vmcnt(7)
	v_cvt_f32_f16_sdwa v37, v54 dst_sel:DWORD dst_unused:UNUSED_PAD src0_sel:WORD_1
	v_cvt_f32_f16_e32 v36, v54
	v_cvt_f32_f16_sdwa v39, v55 dst_sel:DWORD dst_unused:UNUSED_PAD src0_sel:WORD_1
	v_cvt_f32_f16_e32 v38, v55
	v_or_b32_e32 v66, 0x18000, v66
	s_waitcnt vmcnt(6)
	v_cvt_f32_f16_sdwa v41, v52 dst_sel:DWORD dst_unused:UNUSED_PAD src0_sel:WORD_1
	v_cvt_f32_f16_e32 v40, v52
	v_cvt_f32_f16_sdwa v43, v53 dst_sel:DWORD dst_unused:UNUSED_PAD src0_sel:WORD_1
	v_cvt_f32_f16_e32 v42, v53
	s_waitcnt vmcnt(5)
	v_cvt_f32_f16_sdwa v45, v48 dst_sel:DWORD dst_unused:UNUSED_PAD src0_sel:WORD_1
	v_cvt_f32_f16_e32 v44, v48
	v_cvt_f32_f16_sdwa v51, v49 dst_sel:DWORD dst_unused:UNUSED_PAD src0_sel:WORD_1
	v_cvt_f32_f16_e32 v50, v49
	s_waitcnt vmcnt(4)
	v_cvt_f32_f16_sdwa v49, v46 dst_sel:DWORD dst_unused:UNUSED_PAD src0_sel:WORD_1
	v_cvt_f32_f16_e32 v48, v46
	v_cvt_f32_f16_sdwa v53, v47 dst_sel:DWORD dst_unused:UNUSED_PAD src0_sel:WORD_1
	v_cvt_f32_f16_e32 v52, v47
	v_lshl_add_u64 v[46:47], v[142:143], 0, v[66:67]
	v_pk_add_f32 v[54:55], v[32:33], v[38:39]
	v_pk_add_f32 v[56:57], v[30:31], v[36:37]
	global_load_dwordx2 v[38:39], v[46:47], off
	global_load_dwordx2 v[36:37], v[46:47], off offset:32
	global_load_dwordx2 v[32:33], v[46:47], off offset:256
	global_load_dwordx2 v[30:31], v[46:47], off offset:288
	v_cvt_f16_f32_e32 v58, v56
	v_cvt_f16_f32_sdwa v59, v57 dst_sel:WORD_1 dst_unused:UNUSED_PAD src0_sel:DWORD
	v_pk_add_f32 v[28:29], v[28:29], v[42:43]
	v_pk_add_f32 v[26:27], v[26:27], v[40:41]
	s_mov_b64 s[22:23], 0xa0
	v_cvt_f16_f32_e32 v40, v26
	v_cvt_f16_f32_sdwa v41, v27 dst_sel:WORD_1 dst_unused:UNUSED_PAD src0_sel:DWORD
	v_cvt_f16_f32_e32 v42, v28
	v_cvt_f16_f32_sdwa v43, v29 dst_sel:WORD_1 dst_unused:UNUSED_PAD src0_sel:DWORD
	s_waitcnt lgkmcnt(0)
	v_lshl_add_u64 v[34:35], v[140:141], 0, s[22:23]
	v_cvt_f16_f32_e32 v60, v54
	v_cvt_f16_f32_sdwa v61, v55 dst_sel:WORD_1 dst_unused:UNUSED_PAD src0_sel:DWORD
	v_or_b32_e32 v46, v59, v58
	v_lshlrev_b64 v[58:59], 11, v[34:35]
	v_lshl_add_u64 v[58:59], s[24:25], 0, v[58:59]
	v_mul_f32_e32 v27, v27, v27
	v_lshl_add_u64 v[58:59], v[138:139], 1, v[58:59]
	v_or_b32_e32 v40, v41, v40
	v_or_b32_e32 v41, v43, v42
	v_fmac_f32_e32 v27, v26, v26
	v_mul_f32_e32 v26, v29, v29
	v_pk_add_f32 v[24:25], v[24:25], v[50:51]
	v_pk_add_f32 v[22:23], v[22:23], v[44:45]
	v_or_b32_e32 v47, v61, v60
	global_store_dwordx2 v[58:59], v[40:41], off offset:32 sc1
	v_fmac_f32_e32 v26, v28, v28
	v_cvt_f16_f32_e32 v28, v22
	v_cvt_f16_f32_sdwa v29, v23 dst_sel:WORD_1 dst_unused:UNUSED_PAD src0_sel:DWORD
	v_cvt_f16_f32_e32 v40, v24
	v_cvt_f16_f32_sdwa v41, v25 dst_sel:WORD_1 dst_unused:UNUSED_PAD src0_sel:DWORD
	global_store_dwordx2 v[58:59], v[46:47], off sc1
	v_mul_f32_e32 v46, v57, v57
	v_mul_f32_e32 v47, v55, v55
	v_fmac_f32_e32 v46, v56, v56
	v_fmac_f32_e32 v47, v54, v54
	v_add_f32_e32 v46, v46, v47
	v_add_f32_e32 v26, v27, v26
	v_mul_f32_e32 v23, v23, v23
	v_add_f32_e32 v42, v46, v26
	v_or_b32_e32 v26, v29, v28
	v_or_b32_e32 v27, v41, v40
	v_fmac_f32_e32 v23, v22, v22
	v_mul_f32_e32 v22, v25, v25
	v_pk_add_f32 v[20:21], v[20:21], v[52:53]
	v_pk_add_f32 v[18:19], v[18:19], v[48:49]
	global_store_dwordx2 v[58:59], v[26:27], off offset:256 sc1
	v_fmac_f32_e32 v22, v24, v24
	v_cvt_f16_f32_e32 v24, v18
	v_cvt_f16_f32_sdwa v25, v19 dst_sel:WORD_1 dst_unused:UNUSED_PAD src0_sel:DWORD
	v_cvt_f16_f32_e32 v26, v20
	v_cvt_f16_f32_sdwa v27, v21 dst_sel:WORD_1 dst_unused:UNUSED_PAD src0_sel:DWORD
	v_mul_f32_e32 v19, v19, v19
	v_fmac_f32_e32 v19, v18, v18
	v_mul_f32_e32 v18, v21, v21
	v_add_f32_e32 v22, v23, v22
	v_fmac_f32_e32 v18, v20, v20
	v_add_f32_e32 v28, v42, v22
	v_or_b32_e32 v22, v25, v24
	v_or_b32_e32 v23, v27, v26
	v_add_f32_e32 v18, v19, v18
	v_mov_b32_e32 v19, v1
	global_store_dwordx2 v[58:59], v[22:23], off offset:288 sc1
	v_add_f32_e32 v18, v28, v18
	v_mbcnt_lo_u32_b32 v19, -1, v19
	v_mbcnt_hi_u32_b32 v19, -1, v19
	v_lshlrev_b32_e32 v19, 2, v19
	v_xor_b32_e32 v19, 64, v19
	ds_bpermute_b32 v19, v19, v18
	s_waitcnt lgkmcnt(0)
	v_add_f32_e32 v18, v18, v19
	v_mov_b32_e32 v19, v1
	s_nop 0
	v_mbcnt_lo_u32_b32 v19, -1, v19
	v_mbcnt_hi_u32_b32 v19, -1, v19
	v_lshlrev_b32_e32 v19, 2, v19
	v_xor_b32_e32 v19, 0x80, v19
	ds_bpermute_b32 v19, v19, v18
	s_and_saveexec_b64 s[22:23], s[0:1]
	s_cbranch_execz .LBB0_2004
	v_lshlrev_b64 v[20:21], 6, v[34:35]
	v_lshl_add_u64 v[20:21], s[20:21], 0, v[20:21]
	s_waitcnt lgkmcnt(0)
	v_add_f32_e32 v18, v18, v19
	global_store_dword v[20:21], v18, off
.LBB0_2004:
	s_or_b64 exec, exec, s[22:23]
	s_waitcnt vmcnt(7)
	v_cvt_f32_f16_sdwa v21, v38 dst_sel:DWORD dst_unused:UNUSED_PAD src0_sel:WORD_1
	v_cvt_f32_f16_e32 v20, v38
	v_cvt_f32_f16_sdwa v23, v39 dst_sel:DWORD dst_unused:UNUSED_PAD src0_sel:WORD_1
	v_cvt_f32_f16_e32 v22, v39
	s_waitcnt vmcnt(6)
	v_cvt_f32_f16_sdwa v25, v36 dst_sel:DWORD dst_unused:UNUSED_PAD src0_sel:WORD_1
	v_cvt_f32_f16_e32 v24, v36
	v_pk_add_f32 v[14:15], v[14:15], v[20:21]
	v_cvt_f32_f16_sdwa v27, v37 dst_sel:DWORD dst_unused:UNUSED_PAD src0_sel:WORD_1
	v_cvt_f32_f16_e32 v26, v37
	v_cvt_f16_f32_e32 v20, v14
	v_cvt_f16_f32_sdwa v21, v15 dst_sel:WORD_1 dst_unused:UNUSED_PAD src0_sel:DWORD
	v_pk_add_f32 v[16:17], v[16:17], v[22:23]
	v_mul_f32_e32 v15, v15, v15
	v_fmac_f32_e32 v15, v14, v14
	v_mul_f32_e32 v14, v17, v17
	s_waitcnt vmcnt(5)
	v_cvt_f32_f16_sdwa v29, v32 dst_sel:DWORD dst_unused:UNUSED_PAD src0_sel:WORD_1
	v_cvt_f32_f16_e32 v28, v32
	v_fmac_f32_e32 v14, v16, v16
	v_pk_add_f32 v[10:11], v[10:11], v[24:25]
	v_cvt_f32_f16_sdwa v35, v33 dst_sel:DWORD dst_unused:UNUSED_PAD src0_sel:WORD_1
	v_cvt_f32_f16_e32 v34, v33
	v_or_b32_e32 v20, v21, v20
	v_cvt_f16_f32_e32 v21, v16
	v_add_f32_e32 v16, v15, v14
	v_pk_add_f32 v[12:13], v[12:13], v[26:27]
	v_cvt_f16_f32_e32 v14, v10
	v_cvt_f16_f32_sdwa v15, v11 dst_sel:WORD_1 dst_unused:UNUSED_PAD src0_sel:DWORD
	v_mul_f32_e32 v11, v11, v11
	v_fmac_f32_e32 v11, v10, v10
	v_mul_f32_e32 v10, v13, v13
	v_fmac_f32_e32 v10, v12, v12
	s_waitcnt vmcnt(4)
	v_cvt_f32_f16_sdwa v33, v30 dst_sel:DWORD dst_unused:UNUSED_PAD src0_sel:WORD_1
	v_cvt_f32_f16_e32 v32, v30
	v_add_f32_e32 v10, v11, v10
	v_pk_add_f32 v[6:7], v[6:7], v[28:29]
	v_or_b32_e32 v14, v15, v14
	v_cvt_f16_f32_e32 v15, v12
	v_add_f32_e32 v12, v16, v10
	v_pk_add_f32 v[8:9], v[8:9], v[34:35]
	v_cvt_f16_f32_e32 v10, v6
	v_cvt_f16_f32_sdwa v11, v7 dst_sel:WORD_1 dst_unused:UNUSED_PAD src0_sel:DWORD
	v_mul_f32_e32 v7, v7, v7
	v_fmac_f32_e32 v7, v6, v6
	v_mul_f32_e32 v6, v9, v9
	v_fmac_f32_e32 v6, v8, v8
	v_cvt_f32_f16_sdwa v37, v31 dst_sel:DWORD dst_unused:UNUSED_PAD src0_sel:WORD_1
	v_cvt_f32_f16_e32 v36, v31
	v_add_f32_e32 v6, v7, v6
	v_pk_add_f32 v[2:3], v[2:3], v[32:33]
	v_or_b32_e32 v10, v11, v10
	v_cvt_f16_f32_e32 v11, v8
	v_add_f32_e32 v8, v12, v6
	v_cvt_f16_f32_e32 v6, v2
	v_cvt_f16_f32_sdwa v7, v3 dst_sel:WORD_1 dst_unused:UNUSED_PAD src0_sel:DWORD
	v_cvt_f16_f32_sdwa v22, v17 dst_sel:WORD_1 dst_unused:UNUSED_PAD src0_sel:DWORD
	v_pk_add_f32 v[4:5], v[4:5], v[36:37]
	s_mov_b64 s[22:23], 0xb0
	v_cvt_f16_f32_sdwa v17, v13 dst_sel:WORD_1 dst_unused:UNUSED_PAD src0_sel:DWORD
	v_cvt_f16_f32_sdwa v13, v9 dst_sel:WORD_1 dst_unused:UNUSED_PAD src0_sel:DWORD
	v_or_b32_e32 v6, v7, v6
	v_cvt_f16_f32_e32 v7, v4
	v_cvt_f16_f32_sdwa v9, v5 dst_sel:WORD_1 dst_unused:UNUSED_PAD src0_sel:DWORD
	s_waitcnt lgkmcnt(0)
	v_lshl_add_u64 v[18:19], v[140:141], 0, s[22:23]
	v_mul_f32_e32 v3, v3, v3
	v_or_b32_e32 v21, v22, v21
	v_lshlrev_b64 v[22:23], 11, v[18:19]
	v_fmac_f32_e32 v3, v2, v2
	v_mul_f32_e32 v2, v5, v5
	v_lshl_add_u64 v[22:23], s[24:25], 0, v[22:23]
	v_fmac_f32_e32 v2, v4, v4
	v_lshl_add_u64 v[22:23], v[138:139], 1, v[22:23]
	v_or_b32_e32 v15, v17, v15
	v_or_b32_e32 v11, v13, v11
	v_or_b32_e32 v7, v9, v7
	v_add_f32_e32 v2, v3, v2
	v_mov_b32_e32 v3, v1
	global_store_dwordx2 v[22:23], v[20:21], off sc1
	global_store_dwordx2 v[22:23], v[14:15], off offset:32 sc1
	global_store_dwordx2 v[22:23], v[10:11], off offset:256 sc1
	global_store_dwordx2 v[22:23], v[6:7], off offset:288 sc1
	v_add_f32_e32 v2, v8, v2
	v_mbcnt_lo_u32_b32 v3, -1, v3
	v_mbcnt_hi_u32_b32 v3, -1, v3
	v_lshlrev_b32_e32 v3, 2, v3
	v_xor_b32_e32 v3, 64, v3
	ds_bpermute_b32 v3, v3, v2
	s_waitcnt lgkmcnt(0)
	v_add_f32_e32 v2, v2, v3
	v_mov_b32_e32 v3, v1
	s_nop 0
	v_mbcnt_lo_u32_b32 v3, -1, v3
	v_mbcnt_hi_u32_b32 v3, -1, v3
	v_lshlrev_b32_e32 v3, 2, v3
	v_xor_b32_e32 v3, 0x80, v3
	ds_bpermute_b32 v3, v3, v2
	s_and_saveexec_b64 s[22:23], s[0:1]
	s_cbranch_execz .LBB0_2006
	v_lshlrev_b64 v[4:5], 6, v[18:19]
	v_lshl_add_u64 v[4:5], s[20:21], 0, v[4:5]
	s_waitcnt lgkmcnt(0)
	v_add_f32_e32 v2, v2, v3
	global_store_dword v[4:5], v2, off

.LBB0_2078:
	s_mov_b32 s13, s33
	v_lshl_or_b32 v190, s21, 7, v175
	v_mov_b32_e32 v130, s13
	ds_read2_b32 v[130:131], v130 offset1:1
	s_ashr_i32 s21, s20, 31
	s_lshl_b64 s[20:21], s[20:21], 8
	v_lshl_add_u64 v[170:171], s[20:21], 0, v[158:159]
	v_lshlrev_b64 v[132:133], 6, v[170:171]
	s_waitcnt lgkmcnt(0)
	v_readfirstlane_b32 s13, v130
	v_readfirstlane_b32 s15, v131
	v_mov_b32_e32 v174, v1
	v_mov_b32_e32 v186, s13
	s_mov_b32 s13, s33
	v_mov_b32_e32 v187, s15
	v_mov_b32_e32 v130, s13
	ds_read2_b32 v[130:131], v130 offset1:1
	v_ashrrev_i32_e32 v191, 31, v190
	v_mov_b64_e32 v[226:227], v[240:241]
	s_waitcnt lgkmcnt(0)
	v_readfirstlane_b32 s22, v130
	v_readfirstlane_b32 s23, v131
	s_nop 1
	v_lshl_add_u64 v[130:131], s[22:23], 0, v[0:1]
	v_lshl_add_u64 v[130:131], v[130:131], 0, v[132:133]
	v_add_co_u32_e32 v134, vcc, s58, v130
	s_mov_b64 s[22:23], 0x10380000
	s_nop 0
	v_addc_co_u32_e32 v135, vcc, 0, v131, vcc
	v_lshl_add_u64 v[132:133], v[130:131], 0, s[22:23]
	global_load_dwordx4 v[176:179], v[134:135], off
	global_load_dwordx4 v[180:183], v[132:133], off offset:1024
	global_load_dwordx4 v[192:195], v[132:133], off offset:2048
	global_load_dwordx4 v[146:149], v[132:133], off offset:3072
	v_add_co_u32_e32 v130, vcc, s59, v130
	s_mov_b64 s[22:23], 0xaa00000
	s_nop 0
	v_addc_co_u32_e32 v131, vcc, 0, v131, vcc
	global_load_dwordx4 v[142:145], v[130:131], off
	global_load_dwordx4 v[138:141], v[130:131], off offset:1024
	global_load_dwordx4 v[134:137], v[130:131], off offset:2048
	s_nop 0
	global_load_dwordx4 v[130:133], v[130:131], off offset:3072
	s_andn2_b64 vcc, exec, s[0:1]
	v_mbcnt_lo_u32_b32 v174, -1, v174
	v_mbcnt_hi_u32_b32 v174, -1, v174
	v_lshlrev_b32_e32 v174, 2, v174
	v_xor_b32_e32 v174, 64, v174
	s_waitcnt vmcnt(0)
	v_mov_b32_e32 v188, v177
	v_mov_b32_e32 v189, v178
	v_mov_b32_e32 v177, v179
	v_pk_add_f32 v[176:177], v[188:189], v[176:177]
	s_nop 0
	v_add_f32_e32 v172, v176, v177
	ds_bpermute_b32 v174, v174, v172
	v_mov_b32_e32 v176, v181
	v_mov_b32_e32 v177, v182
	v_mov_b32_e32 v181, v183
	v_pk_add_f32 v[176:177], v[176:177], v[180:181]
	s_waitcnt lgkmcnt(0)
	v_add_f32_e32 v172, v172, v174
	v_mov_b32_e32 v174, v1
	s_nop 0
	v_mbcnt_lo_u32_b32 v174, -1, v174
	v_mbcnt_hi_u32_b32 v174, -1, v174
	v_lshlrev_b32_e32 v174, 2, v174
	v_xor_b32_e32 v174, 0x80, v174
	ds_bpermute_b32 v174, v174, v172
	s_waitcnt lgkmcnt(0)
	v_add_f32_e32 v172, v172, v174
	v_mov_b32_e32 v174, v1
	v_fmamk_f32 v172, v172, 0x3a800000, v228
	v_mbcnt_lo_u32_b32 v174, -1, v174
	v_mbcnt_hi_u32_b32 v174, -1, v174
	v_lshlrev_b32_e32 v174, 2, v174
	v_rsq_f32_e32 v188, v172
	v_add_f32_e32 v172, v176, v177
	v_xor_b32_e32 v174, 64, v174
	ds_bpermute_b32 v174, v174, v172
	v_mov_b32_e32 v176, v193
	v_mov_b32_e32 v177, v194
	v_mov_b32_e32 v193, v195
	v_pk_add_f32 v[176:177], v[176:177], v[192:193]
	s_waitcnt lgkmcnt(0)
	v_add_f32_e32 v172, v172, v174
	v_mov_b32_e32 v174, v1
	v_pk_mul_f32 v[126:127], v[126:127], v[188:189] op_sel_hi:[1,0]
	v_mbcnt_lo_u32_b32 v174, -1, v174
	v_mbcnt_hi_u32_b32 v174, -1, v174
	v_lshlrev_b32_e32 v174, 2, v174
	v_xor_b32_e32 v174, 0x80, v174
	ds_bpermute_b32 v174, v174, v172
	v_pk_mul_f32 v[122:123], v[122:123], v[188:189] op_sel_hi:[1,0]
	v_pk_mul_f32 v[124:125], v[124:125], v[188:189] op_sel_hi:[1,0]
	v_pk_mul_f32 v[118:119], v[118:119], v[188:189] op_sel_hi:[1,0]
	v_pk_mul_f32 v[114:115], v[114:115], v[188:189] op_sel_hi:[1,0]
	s_waitcnt lgkmcnt(0)
	v_add_f32_e32 v172, v172, v174
	v_fmamk_f32 v172, v172, 0x3a800000, v228
	v_rsq_f32_e32 v174, v172
	v_add_f32_e32 v172, v176, v177
	v_mov_b32_e32 v176, v1
	v_mov_b32_e32 v177, v148
	v_mbcnt_lo_u32_b32 v176, -1, v176
	v_mbcnt_hi_u32_b32 v176, -1, v176
	v_lshlrev_b32_e32 v176, 2, v176
	v_xor_b32_e32 v176, 64, v176
	ds_bpermute_b32 v176, v176, v172
	v_mov_b32_e32 v148, v143
	v_mov_b32_e32 v143, v145
	v_mov_b32_e32 v145, v140
	v_mov_b32_e32 v140, v135
	s_waitcnt lgkmcnt(0)
	v_add_f32_e32 v172, v172, v176
	v_mov_b32_e32 v176, v1
	v_mov_b32_e32 v135, v137
	v_mbcnt_lo_u32_b32 v176, -1, v176
	v_mbcnt_hi_u32_b32 v176, -1, v176
	v_lshlrev_b32_e32 v176, 2, v176
	v_xor_b32_e32 v176, 0x80, v176
	ds_bpermute_b32 v176, v176, v172
	v_mov_b32_e32 v137, v132
	v_pk_mul_f32 v[116:117], v[116:117], v[188:189] op_sel_hi:[1,0]
	v_pk_mul_f32 v[110:111], v[110:111], v[174:175] op_sel_hi:[1,0]
	v_pk_mul_f32 v[106:107], v[106:107], v[174:175] op_sel_hi:[1,0]
	s_waitcnt lgkmcnt(0)
	v_add_f32_e32 v172, v172, v176
	v_mov_b32_e32 v176, v147
	v_mov_b32_e32 v147, v149
	v_pk_add_f32 v[146:147], v[176:177], v[146:147]
	v_mov_b32_e32 v149, v144
	v_add_f32_e32 v146, v146, v147
	v_mov_b32_e32 v147, v1
	v_pk_add_f32 v[142:143], v[148:149], v[142:143]
	v_mbcnt_lo_u32_b32 v147, -1, v147
	v_mbcnt_hi_u32_b32 v147, -1, v147
	v_lshlrev_b32_e32 v147, 2, v147
	v_xor_b32_e32 v147, 64, v147
	ds_bpermute_b32 v147, v147, v146
	v_add_f32_e32 v142, v142, v143
	v_mov_b32_e32 v143, v1
	v_mov_b32_e32 v144, v139
	v_mov_b32_e32 v139, v141
	s_waitcnt lgkmcnt(0)
	v_add_f32_e32 v146, v146, v147
	v_mov_b32_e32 v147, v1
	v_mov_b32_e32 v141, v136
	v_mbcnt_lo_u32_b32 v143, -1, v143
	v_mbcnt_hi_u32_b32 v143, -1, v143
	v_lshlrev_b32_e32 v143, 2, v143
	v_xor_b32_e32 v143, 64, v143
	ds_bpermute_b32 v143, v143, v142
	v_mov_b32_e32 v136, v131
	v_mov_b32_e32 v131, v133
	v_mul_f32_e32 v133, 0xbfb8aa3b, v126
	v_exp_f32_e32 v133, v133
	v_pk_add_f32 v[138:139], v[144:145], v[138:139]
	s_waitcnt lgkmcnt(0)
	v_add_f32_e32 v142, v142, v143
	v_mov_b32_e32 v143, v1
	v_add_f32_e32 v138, v138, v139
	v_mov_b32_e32 v139, v1
	v_add_f32_e32 v133, 1.0, v133
	v_mbcnt_lo_u32_b32 v139, -1, v139
	v_pk_add_f32 v[130:131], v[136:137], v[130:131]
	v_rcp_f32_e32 v136, v133
	v_mul_f32_e32 v133, 0xbfb8aa3b, v127
	v_mbcnt_hi_u32_b32 v139, -1, v139
	v_exp_f32_e32 v133, v133
	v_lshlrev_b32_e32 v139, 2, v139
	v_xor_b32_e32 v139, 64, v139
	ds_bpermute_b32 v139, v139, v138
	v_add_f32_e32 v133, 1.0, v133
	v_rcp_f32_e32 v137, v133
	v_pk_add_f32 v[134:135], v[140:141], v[134:135]
	v_add_f32_e32 v130, v130, v131
	s_waitcnt lgkmcnt(0)
	v_add_f32_e32 v138, v138, v139
	v_mov_b32_e32 v139, v1
	v_add_f32_e32 v134, v134, v135
	v_mov_b32_e32 v135, v1
	v_pk_mul_f32 v[126:127], v[126:127], v[136:137]
	v_mbcnt_lo_u32_b32 v135, -1, v135
	v_pk_mul_f32 v[122:123], v[122:123], v[126:127]
	v_pk_mul_f32 v[126:127], v[128:129], v[188:189] op_sel_hi:[1,0]
	v_mbcnt_hi_u32_b32 v135, -1, v135
	v_mul_f32_e32 v128, 0xbfb8aa3b, v126
	v_mul_f32_e32 v129, 0xbfb8aa3b, v127
	v_lshlrev_b32_e32 v135, 2, v135
	v_exp_f32_e32 v128, v128
	v_exp_f32_e32 v129, v129
	v_xor_b32_e32 v135, 64, v135
	ds_bpermute_b32 v135, v135, v134
	v_add_f32_e32 v128, 1.0, v128
	v_add_f32_e32 v129, 1.0, v129
	v_rcp_f32_e32 v128, v128
	v_rcp_f32_e32 v129, v129
	s_waitcnt lgkmcnt(0)
	v_add_f32_e32 v134, v134, v135
	v_mov_b32_e32 v135, v1
	v_mov_b32_e32 v131, v1
	v_pk_mul_f32 v[126:127], v[126:127], v[128:129]
	v_mbcnt_lo_u32_b32 v131, -1, v131
	v_mbcnt_hi_u32_b32 v131, -1, v131
	v_pk_mul_f32 v[124:125], v[124:125], v[126:127]
	v_mul_f32_e32 v126, 0xbfb8aa3b, v118
	v_mul_f32_e32 v127, 0xbfb8aa3b, v119
	v_lshlrev_b32_e32 v131, 2, v131
	v_exp_f32_e32 v126, v126
	v_exp_f32_e32 v127, v127
	v_xor_b32_e32 v131, 64, v131
	ds_bpermute_b32 v131, v131, v130
	v_add_f32_e32 v126, 1.0, v126
	v_add_f32_e32 v127, 1.0, v127
	v_rcp_f32_e32 v126, v126
	v_rcp_f32_e32 v127, v127
	s_waitcnt lgkmcnt(0)
	v_add_f32_e32 v130, v130, v131
	v_mov_b32_e32 v131, v1
	v_pk_mul_f32 v[118:119], v[118:119], v[126:127]
	v_mbcnt_lo_u32_b32 v131, -1, v131
	v_mbcnt_hi_u32_b32 v131, -1, v131
	v_pk_mul_f32 v[118:119], v[114:115], v[118:119]
	v_pk_mul_f32 v[114:115], v[120:121], v[188:189] op_sel_hi:[1,0]
	v_lshlrev_b32_e32 v131, 2, v131
	v_mul_f32_e32 v120, 0xbfb8aa3b, v114
	v_mul_f32_e32 v121, 0xbfb8aa3b, v115
	v_xor_b32_e32 v131, 0x80, v131
	v_exp_f32_e32 v120, v120
	v_exp_f32_e32 v121, v121
	ds_bpermute_b32 v131, v131, v130
	v_pk_mul_f32 v[108:109], v[108:109], v[174:175] op_sel_hi:[1,0]
	v_add_f32_e32 v120, 1.0, v120
	v_add_f32_e32 v121, 1.0, v121
	v_rcp_f32_e32 v120, v120
	v_rcp_f32_e32 v121, v121
	s_waitcnt lgkmcnt(0)
	v_add_f32_e32 v130, v130, v131
	v_fmamk_f32 v130, v130, 0x3a800000, v228
	v_rsq_f32_e32 v132, v130
	v_lshl_add_u64 v[130:131], v[190:191], 1, v[186:187]
	v_lshl_add_u64 v[130:131], v[130:131], 0, s[22:23]
	v_pk_mul_f32 v[114:115], v[114:115], v[120:121]
	v_pk_mul_f32 v[102:103], v[102:103], v[174:175] op_sel_hi:[1,0]
	v_pk_mul_f32 v[120:121], v[116:117], v[114:115]
	v_cvt_pk_bf16_f32 v116, v118, v119
	v_mad_u64_u32 v[118:119], s[22:23], v170, s89, v[130:131]
	v_cvt_pk_bf16_f32 v117, v120, v121
	v_mov_b32_e32 v120, v119
	v_mad_u64_u32 v[120:121], s[22:23], v171, s89, v[120:121]
	v_cvt_pk_bf16_f32 v114, v122, v123
	v_cvt_pk_bf16_f32 v115, v124, v125
	v_mov_b32_e32 v119, v120
	global_store_dwordx4 v[118:119], v[114:117], off sc1
	v_pk_mul_f32 v[98:99], v[98:99], v[174:175] op_sel_hi:[1,0]
	v_fmamk_f32 v172, v172, 0x3a800000, v228
	v_mul_f32_e32 v114, 0xbfb8aa3b, v110
	v_mul_f32_e32 v115, 0xbfb8aa3b, v111
	v_exp_f32_e32 v114, v114
	v_exp_f32_e32 v115, v115
	v_rsq_f32_e32 v172, v172
	v_pk_mul_f32 v[100:101], v[100:101], v[174:175] op_sel_hi:[1,0]
	v_add_f32_e32 v114, 1.0, v114
	v_add_f32_e32 v115, 1.0, v115
	v_rcp_f32_e32 v114, v114
	v_rcp_f32_e32 v115, v115
	v_pk_mul_f32 v[94:95], v[94:95], v[172:173] op_sel_hi:[1,0]
	v_pk_mul_f32 v[90:91], v[90:91], v[172:173] op_sel_hi:[1,0]
	v_pk_mul_f32 v[92:93], v[92:93], v[172:173] op_sel_hi:[1,0]
	v_pk_mul_f32 v[110:111], v[110:111], v[114:115]
	v_pk_mul_f32 v[86:87], v[86:87], v[172:173] op_sel_hi:[1,0]
	v_pk_mul_f32 v[106:107], v[106:107], v[110:111]
	v_pk_mul_f32 v[110:111], v[112:113], v[174:175] op_sel_hi:[1,0]
	v_pk_mul_f32 v[82:83], v[82:83], v[172:173] op_sel_hi:[1,0]
	v_mul_f32_e32 v112, 0xbfb8aa3b, v110
	v_mul_f32_e32 v113, 0xbfb8aa3b, v111
	v_exp_f32_e32 v112, v112
	v_exp_f32_e32 v113, v113
	v_mbcnt_lo_u32_b32 v147, -1, v147
	v_mbcnt_hi_u32_b32 v147, -1, v147
	v_add_f32_e32 v112, 1.0, v112
	v_add_f32_e32 v113, 1.0, v113
	v_rcp_f32_e32 v112, v112
	v_rcp_f32_e32 v113, v113
	v_lshlrev_b32_e32 v147, 2, v147
	v_xor_b32_e32 v147, 0x80, v147
	ds_bpermute_b32 v147, v147, v146
	v_pk_mul_f32 v[110:111], v[110:111], v[112:113]
	v_pk_mul_f32 v[84:85], v[84:85], v[172:173] op_sel_hi:[1,0]
	v_pk_mul_f32 v[108:109], v[108:109], v[110:111]
	v_mul_f32_e32 v110, 0xbfb8aa3b, v102
	v_mul_f32_e32 v111, 0xbfb8aa3b, v103
	v_exp_f32_e32 v110, v110
	v_exp_f32_e32 v111, v111
	s_waitcnt lgkmcnt(0)
	v_add_f32_e32 v146, v146, v147
	v_fmamk_f32 v146, v146, 0x3a800000, v228
	v_add_f32_e32 v110, 1.0, v110
	v_add_f32_e32 v111, 1.0, v111
	v_rcp_f32_e32 v110, v110
	v_rcp_f32_e32 v111, v111
	v_rsq_f32_e32 v146, v146
	v_mbcnt_lo_u32_b32 v143, -1, v143
	v_mbcnt_hi_u32_b32 v143, -1, v143
	v_pk_mul_f32 v[102:103], v[102:103], v[110:111]
	v_lshl_add_u64 v[110:111], v[160:161], 0, s[20:21]
	v_pk_mul_f32 v[102:103], v[98:99], v[102:103]
	v_pk_mul_f32 v[98:99], v[104:105], v[174:175] op_sel_hi:[1,0]
	v_pk_mul_f32 v[78:79], v[78:79], v[146:147] op_sel_hi:[1,0]
	v_mul_f32_e32 v104, 0xbfb8aa3b, v98
	v_mul_f32_e32 v105, 0xbfb8aa3b, v99
	v_exp_f32_e32 v104, v104
	v_exp_f32_e32 v105, v105
	v_pk_mul_f32 v[74:75], v[74:75], v[146:147] op_sel_hi:[1,0]
	v_pk_mul_f32 v[76:77], v[76:77], v[146:147] op_sel_hi:[1,0]
	v_add_f32_e32 v104, 1.0, v104
	v_add_f32_e32 v105, 1.0, v105
	v_rcp_f32_e32 v104, v104
	v_rcp_f32_e32 v105, v105
	v_pk_mul_f32 v[70:71], v[70:71], v[146:147] op_sel_hi:[1,0]
	v_pk_mul_f32 v[66:67], v[66:67], v[146:147] op_sel_hi:[1,0]
	v_lshlrev_b32_e32 v143, 2, v143
	v_pk_mul_f32 v[98:99], v[98:99], v[104:105]
	v_xor_b32_e32 v143, 0x80, v143
	v_pk_mul_f32 v[104:105], v[100:101], v[98:99]
	v_cvt_pk_bf16_f32 v100, v102, v103
	v_mad_u64_u32 v[102:103], s[22:23], v110, s89, v[130:131]
	v_cvt_pk_bf16_f32 v101, v104, v105
	v_mov_b32_e32 v104, v103
	v_mad_u64_u32 v[104:105], s[22:23], v111, s89, v[104:105]
	v_cvt_pk_bf16_f32 v98, v106, v107
	v_cvt_pk_bf16_f32 v99, v108, v109
	v_mov_b32_e32 v103, v104
	global_store_dwordx4 v[102:103], v[98:101], off sc1
	ds_bpermute_b32 v143, v143, v142
	v_pk_mul_f32 v[68:69], v[68:69], v[146:147] op_sel_hi:[1,0]
	v_mul_f32_e32 v98, 0xbfb8aa3b, v94
	v_mul_f32_e32 v99, 0xbfb8aa3b, v95
	v_exp_f32_e32 v98, v98
	v_exp_f32_e32 v99, v99
	s_waitcnt lgkmcnt(0)
	v_add_f32_e32 v142, v142, v143
	v_fmamk_f32 v142, v142, 0x3a800000, v228
	v_add_f32_e32 v98, 1.0, v98
	v_add_f32_e32 v99, 1.0, v99
	v_rcp_f32_e32 v98, v98
	v_rcp_f32_e32 v99, v99
	v_rsq_f32_e32 v142, v142
	v_mbcnt_lo_u32_b32 v139, -1, v139
	v_mbcnt_hi_u32_b32 v139, -1, v139
	v_pk_mul_f32 v[94:95], v[94:95], v[98:99]
	v_pk_mul_f32 v[62:63], v[62:63], v[142:143] op_sel_hi:[1,0]
	v_pk_mul_f32 v[90:91], v[90:91], v[94:95]
	v_pk_mul_f32 v[94:95], v[96:97], v[172:173] op_sel_hi:[1,0]
	v_pk_mul_f32 v[58:59], v[58:59], v[142:143] op_sel_hi:[1,0]
	v_mul_f32_e32 v96, 0xbfb8aa3b, v94
	v_mul_f32_e32 v97, 0xbfb8aa3b, v95
	v_exp_f32_e32 v96, v96
	v_exp_f32_e32 v97, v97
	v_pk_mul_f32 v[60:61], v[60:61], v[142:143] op_sel_hi:[1,0]
	v_pk_mul_f32 v[54:55], v[54:55], v[142:143] op_sel_hi:[1,0]
	v_add_f32_e32 v96, 1.0, v96
	v_add_f32_e32 v97, 1.0, v97
	v_rcp_f32_e32 v96, v96
	v_rcp_f32_e32 v97, v97
	v_pk_mul_f32 v[50:51], v[50:51], v[142:143] op_sel_hi:[1,0]
	v_lshlrev_b32_e32 v139, 2, v139
	v_xor_b32_e32 v139, 0x80, v139
	v_pk_mul_f32 v[94:95], v[94:95], v[96:97]
	ds_bpermute_b32 v139, v139, v138
	v_pk_mul_f32 v[92:93], v[92:93], v[94:95]
	v_mul_f32_e32 v94, 0xbfb8aa3b, v86
	v_mul_f32_e32 v95, 0xbfb8aa3b, v87
	v_exp_f32_e32 v94, v94
	v_exp_f32_e32 v95, v95
	s_waitcnt lgkmcnt(0)
	v_add_f32_e32 v138, v138, v139
	v_fmamk_f32 v138, v138, 0x3a800000, v228
	v_add_f32_e32 v94, 1.0, v94
	v_add_f32_e32 v95, 1.0, v95
	v_rcp_f32_e32 v94, v94
	v_rcp_f32_e32 v95, v95
	v_rsq_f32_e32 v138, v138
	v_pk_mul_f32 v[52:53], v[52:53], v[142:143] op_sel_hi:[1,0]
	v_mbcnt_lo_u32_b32 v135, -1, v135
	v_pk_mul_f32 v[86:87], v[86:87], v[94:95]
	v_lshl_add_u64 v[94:95], v[162:163], 0, s[20:21]
	v_pk_mul_f32 v[86:87], v[82:83], v[86:87]
	v_pk_mul_f32 v[82:83], v[88:89], v[172:173] op_sel_hi:[1,0]
	v_pk_mul_f32 v[46:47], v[46:47], v[138:139] op_sel_hi:[1,0]
	v_mul_f32_e32 v88, 0xbfb8aa3b, v82
	v_mul_f32_e32 v89, 0xbfb8aa3b, v83
	v_exp_f32_e32 v88, v88
	v_exp_f32_e32 v89, v89
	v_pk_mul_f32 v[42:43], v[42:43], v[138:139] op_sel_hi:[1,0]
	v_pk_mul_f32 v[44:45], v[44:45], v[138:139] op_sel_hi:[1,0]
	v_add_f32_e32 v88, 1.0, v88
	v_add_f32_e32 v89, 1.0, v89
	v_rcp_f32_e32 v88, v88
	v_rcp_f32_e32 v89, v89
	v_pk_mul_f32 v[38:39], v[38:39], v[138:139] op_sel_hi:[1,0]
	v_pk_mul_f32 v[34:35], v[34:35], v[138:139] op_sel_hi:[1,0]
	v_mbcnt_hi_u32_b32 v135, -1, v135
	v_pk_mul_f32 v[82:83], v[82:83], v[88:89]
	v_lshlrev_b32_e32 v135, 2, v135
	v_pk_mul_f32 v[88:89], v[84:85], v[82:83]
	v_cvt_pk_bf16_f32 v84, v86, v87
	v_mad_u64_u32 v[86:87], s[22:23], v94, s89, v[130:131]
	v_cvt_pk_bf16_f32 v85, v88, v89
	v_mov_b32_e32 v88, v87
	v_mad_u64_u32 v[88:89], s[22:23], v95, s89, v[88:89]
	v_cvt_pk_bf16_f32 v82, v90, v91
	v_cvt_pk_bf16_f32 v83, v92, v93
	v_mov_b32_e32 v87, v88
	global_store_dwordx4 v[86:87], v[82:85], off sc1
	v_xor_b32_e32 v135, 0x80, v135
	ds_bpermute_b32 v135, v135, v134
	v_mul_f32_e32 v82, 0xbfb8aa3b, v78
	v_mul_f32_e32 v83, 0xbfb8aa3b, v79
	v_exp_f32_e32 v82, v82
	v_exp_f32_e32 v83, v83
	s_waitcnt lgkmcnt(0)
	v_add_f32_e32 v134, v134, v135
	v_fmamk_f32 v134, v134, 0x3a800000, v228
	v_add_f32_e32 v82, 1.0, v82
	v_add_f32_e32 v83, 1.0, v83
	v_rcp_f32_e32 v82, v82
	v_rcp_f32_e32 v83, v83
	v_rsq_f32_e32 v134, v134
	v_pk_mul_f32 v[36:37], v[36:37], v[138:139] op_sel_hi:[1,0]
	v_pk_mul_f32 v[14:15], v[14:15], v[132:133] op_sel_hi:[1,0]
	v_pk_mul_f32 v[78:79], v[78:79], v[82:83]
	v_pk_mul_f32 v[30:31], v[30:31], v[134:135] op_sel_hi:[1,0]
	v_pk_mul_f32 v[74:75], v[74:75], v[78:79]
	v_pk_mul_f32 v[78:79], v[80:81], v[146:147] op_sel_hi:[1,0]
	v_pk_mul_f32 v[26:27], v[26:27], v[134:135] op_sel_hi:[1,0]
	v_mul_f32_e32 v80, 0xbfb8aa3b, v78
	v_mul_f32_e32 v81, 0xbfb8aa3b, v79
	v_exp_f32_e32 v80, v80
	v_exp_f32_e32 v81, v81
	v_pk_mul_f32 v[28:29], v[28:29], v[134:135] op_sel_hi:[1,0]
	v_pk_mul_f32 v[22:23], v[22:23], v[134:135] op_sel_hi:[1,0]
	v_add_f32_e32 v80, 1.0, v80
	v_add_f32_e32 v81, 1.0, v81
	v_rcp_f32_e32 v80, v80
	v_rcp_f32_e32 v81, v81
	v_pk_mul_f32 v[18:19], v[18:19], v[134:135] op_sel_hi:[1,0]
	v_pk_mul_f32 v[20:21], v[20:21], v[134:135] op_sel_hi:[1,0]
	v_pk_mul_f32 v[10:11], v[10:11], v[132:133] op_sel_hi:[1,0]
	v_pk_mul_f32 v[78:79], v[78:79], v[80:81]
	v_pk_mul_f32 v[12:13], v[12:13], v[132:133] op_sel_hi:[1,0]
	v_pk_mul_f32 v[76:77], v[76:77], v[78:79]
	v_mul_f32_e32 v78, 0xbfb8aa3b, v70
	v_mul_f32_e32 v79, 0xbfb8aa3b, v71
	v_exp_f32_e32 v78, v78
	v_exp_f32_e32 v79, v79
	v_pk_mul_f32 v[6:7], v[6:7], v[132:133] op_sel_hi:[1,0]
	v_pk_mul_f32 v[2:3], v[2:3], v[132:133] op_sel_hi:[1,0]
	v_add_f32_e32 v78, 1.0, v78
	v_add_f32_e32 v79, 1.0, v79
	v_rcp_f32_e32 v78, v78
	v_rcp_f32_e32 v79, v79
	v_pk_mul_f32 v[4:5], v[4:5], v[132:133] op_sel_hi:[1,0]
	v_pk_mul_f32 v[70:71], v[70:71], v[78:79]
	s_nop 0
	v_pk_mul_f32 v[70:71], v[66:67], v[70:71]
	v_pk_mul_f32 v[66:67], v[72:73], v[146:147] op_sel_hi:[1,0]
	v_lshl_add_u64 v[78:79], v[164:165], 0, s[20:21]
	v_mul_f32_e32 v72, 0xbfb8aa3b, v66
	v_mul_f32_e32 v73, 0xbfb8aa3b, v67
	v_exp_f32_e32 v72, v72
	v_exp_f32_e32 v73, v73
	v_add_f32_e32 v72, 1.0, v72
	v_add_f32_e32 v73, 1.0, v73
	v_rcp_f32_e32 v72, v72
	v_rcp_f32_e32 v73, v73
	s_nop 0
	v_pk_mul_f32 v[66:67], v[66:67], v[72:73]
	s_nop 0
	v_pk_mul_f32 v[72:73], v[68:69], v[66:67]
	v_cvt_pk_bf16_f32 v68, v70, v71
	v_mad_u64_u32 v[70:71], s[20:21], v78, s89, v[130:131]
	v_cvt_pk_bf16_f32 v69, v72, v73
	v_mov_b32_e32 v72, v71
	v_mad_u64_u32 v[72:73], s[20:21], v79, s89, v[72:73]
	v_cvt_pk_bf16_f32 v66, v74, v75
	v_cvt_pk_bf16_f32 v67, v76, v77
	v_mov_b32_e32 v71, v72
	global_store_dwordx4 v[70:71], v[66:69], off sc1
	s_nop 1
	v_mul_f32_e32 v66, 0xbfb8aa3b, v62
	v_mul_f32_e32 v67, 0xbfb8aa3b, v63
	v_exp_f32_e32 v66, v66
	v_exp_f32_e32 v67, v67
	v_add_f32_e32 v66, 1.0, v66
	v_add_f32_e32 v67, 1.0, v67
	v_rcp_f32_e32 v66, v66
	v_rcp_f32_e32 v67, v67
	s_nop 0
	v_pk_mul_f32 v[62:63], v[62:63], v[66:67]
	s_nop 0
	v_pk_mul_f32 v[58:59], v[58:59], v[62:63]
	v_pk_mul_f32 v[62:63], v[64:65], v[142:143] op_sel_hi:[1,0]
	s_nop 0
	v_mul_f32_e32 v64, 0xbfb8aa3b, v62
	v_mul_f32_e32 v65, 0xbfb8aa3b, v63
	v_exp_f32_e32 v64, v64
	v_exp_f32_e32 v65, v65
	v_add_f32_e32 v64, 1.0, v64
	v_add_f32_e32 v65, 1.0, v65
	v_rcp_f32_e32 v64, v64
	v_rcp_f32_e32 v65, v65
	s_nop 0
	v_pk_mul_f32 v[62:63], v[62:63], v[64:65]
	s_nop 0
	v_pk_mul_f32 v[60:61], v[60:61], v[62:63]
	v_mul_f32_e32 v62, 0xbfb8aa3b, v54
	v_mul_f32_e32 v63, 0xbfb8aa3b, v55
	v_exp_f32_e32 v62, v62
	v_exp_f32_e32 v63, v63
	v_add_f32_e32 v62, 1.0, v62
	v_add_f32_e32 v63, 1.0, v63
	v_rcp_f32_e32 v62, v62
	v_rcp_f32_e32 v63, v63
	s_nop 0
	v_pk_mul_f32 v[54:55], v[54:55], v[62:63]
	s_nop 0
	v_pk_mul_f32 v[54:55], v[50:51], v[54:55]
	v_pk_mul_f32 v[50:51], v[56:57], v[142:143] op_sel_hi:[1,0]
	v_lshl_add_u64 v[62:63], v[170:171], 0, s[96:97]
	v_mul_f32_e32 v56, 0xbfb8aa3b, v50
	v_mul_f32_e32 v57, 0xbfb8aa3b, v51
	v_exp_f32_e32 v56, v56
	v_exp_f32_e32 v57, v57
	v_add_f32_e32 v56, 1.0, v56
	v_add_f32_e32 v57, 1.0, v57
	v_rcp_f32_e32 v56, v56
	v_rcp_f32_e32 v57, v57
	s_nop 0
	v_pk_mul_f32 v[50:51], v[50:51], v[56:57]
	s_nop 0
	v_pk_mul_f32 v[56:57], v[52:53], v[50:51]
	v_cvt_pk_bf16_f32 v52, v54, v55
	v_mad_u64_u32 v[54:55], s[20:21], v62, s89, v[130:131]
	v_cvt_pk_bf16_f32 v53, v56, v57
	v_mov_b32_e32 v56, v55
	v_mad_u64_u32 v[56:57], s[20:21], v63, s89, v[56:57]
	v_cvt_pk_bf16_f32 v50, v58, v59
	v_cvt_pk_bf16_f32 v51, v60, v61
	v_mov_b32_e32 v55, v56
	global_store_dwordx4 v[54:55], v[50:53], off sc1
	s_mov_b64 s[20:21], 0x90
	s_nop 0
	v_mul_f32_e32 v50, 0xbfb8aa3b, v46
	v_mul_f32_e32 v51, 0xbfb8aa3b, v47
	v_exp_f32_e32 v50, v50
	v_exp_f32_e32 v51, v51
	v_add_f32_e32 v50, 1.0, v50
	v_add_f32_e32 v51, 1.0, v51
	v_rcp_f32_e32 v50, v50
	v_rcp_f32_e32 v51, v51
	s_nop 0
	v_pk_mul_f32 v[46:47], v[46:47], v[50:51]
	s_nop 0
	v_pk_mul_f32 v[42:43], v[42:43], v[46:47]
	v_pk_mul_f32 v[46:47], v[48:49], v[138:139] op_sel_hi:[1,0]
	s_nop 0
	v_mul_f32_e32 v48, 0xbfb8aa3b, v46
	v_mul_f32_e32 v49, 0xbfb8aa3b, v47
	v_exp_f32_e32 v48, v48
	v_exp_f32_e32 v49, v49
	v_add_f32_e32 v48, 1.0, v48
	v_add_f32_e32 v49, 1.0, v49
	v_rcp_f32_e32 v48, v48
	v_rcp_f32_e32 v49, v49
	s_nop 0
	v_pk_mul_f32 v[46:47], v[46:47], v[48:49]
	s_nop 0
	v_pk_mul_f32 v[44:45], v[44:45], v[46:47]
	v_mul_f32_e32 v46, 0xbfb8aa3b, v38
	v_mul_f32_e32 v47, 0xbfb8aa3b, v39
	v_exp_f32_e32 v46, v46
	v_exp_f32_e32 v47, v47
	v_add_f32_e32 v46, 1.0, v46
	v_add_f32_e32 v47, 1.0, v47
	v_rcp_f32_e32 v46, v46
	v_rcp_f32_e32 v47, v47
	s_nop 0
	v_pk_mul_f32 v[38:39], v[38:39], v[46:47]
	s_nop 0
	v_pk_mul_f32 v[38:39], v[34:35], v[38:39]
	v_pk_mul_f32 v[34:35], v[40:41], v[138:139] op_sel_hi:[1,0]
	v_lshl_add_u64 v[46:47], v[170:171], 0, s[20:21]
	v_mul_f32_e32 v40, 0xbfb8aa3b, v34
	v_mul_f32_e32 v41, 0xbfb8aa3b, v35
	v_exp_f32_e32 v40, v40
	v_exp_f32_e32 v41, v41
	v_add_f32_e32 v40, 1.0, v40
	v_add_f32_e32 v41, 1.0, v41
	v_rcp_f32_e32 v40, v40
	v_rcp_f32_e32 v41, v41
	s_nop 0
	v_pk_mul_f32 v[34:35], v[34:35], v[40:41]
	s_nop 0
	v_pk_mul_f32 v[40:41], v[36:37], v[34:35]
	v_cvt_pk_bf16_f32 v36, v38, v39
	v_mad_u64_u32 v[38:39], s[20:21], v46, s89, v[130:131]
	v_cvt_pk_bf16_f32 v37, v40, v41
	v_mov_b32_e32 v40, v39
	v_mad_u64_u32 v[40:41], s[20:21], v47, s89, v[40:41]
	v_cvt_pk_bf16_f32 v34, v42, v43
	v_cvt_pk_bf16_f32 v35, v44, v45
	v_mov_b32_e32 v39, v40
	global_store_dwordx4 v[38:39], v[34:37], off sc1
	s_mov_b64 s[20:21], 0xa0
	s_nop 0
	v_mul_f32_e32 v34, 0xbfb8aa3b, v30
	v_mul_f32_e32 v35, 0xbfb8aa3b, v31
	v_exp_f32_e32 v34, v34
	v_exp_f32_e32 v35, v35
	v_add_f32_e32 v34, 1.0, v34
	v_add_f32_e32 v35, 1.0, v35
	v_rcp_f32_e32 v34, v34
	v_rcp_f32_e32 v35, v35
	s_nop 0
	v_pk_mul_f32 v[30:31], v[30:31], v[34:35]
	s_nop 0
	v_pk_mul_f32 v[26:27], v[26:27], v[30:31]
	v_pk_mul_f32 v[30:31], v[32:33], v[134:135] op_sel_hi:[1,0]
	s_nop 0
	v_mul_f32_e32 v32, 0xbfb8aa3b, v30
	v_mul_f32_e32 v33, 0xbfb8aa3b, v31
	v_exp_f32_e32 v32, v32
	v_exp_f32_e32 v33, v33
	v_add_f32_e32 v32, 1.0, v32
	v_add_f32_e32 v33, 1.0, v33
	v_rcp_f32_e32 v32, v32
	v_rcp_f32_e32 v33, v33
	s_nop 0
	v_pk_mul_f32 v[30:31], v[30:31], v[32:33]
	s_nop 0
	v_pk_mul_f32 v[28:29], v[28:29], v[30:31]
	v_mul_f32_e32 v30, 0xbfb8aa3b, v22
	v_mul_f32_e32 v31, 0xbfb8aa3b, v23
	v_exp_f32_e32 v30, v30
	v_exp_f32_e32 v31, v31
	v_add_f32_e32 v30, 1.0, v30
	v_add_f32_e32 v31, 1.0, v31
	v_rcp_f32_e32 v30, v30
	v_rcp_f32_e32 v31, v31
	s_nop 0
	v_pk_mul_f32 v[22:23], v[22:23], v[30:31]
	s_nop 0
	v_pk_mul_f32 v[22:23], v[18:19], v[22:23]
	v_pk_mul_f32 v[18:19], v[24:25], v[134:135] op_sel_hi:[1,0]
	v_lshl_add_u64 v[30:31], v[170:171], 0, s[20:21]
	v_mul_f32_e32 v24, 0xbfb8aa3b, v18
	v_mul_f32_e32 v25, 0xbfb8aa3b, v19
	v_exp_f32_e32 v24, v24
	v_exp_f32_e32 v25, v25
	v_add_f32_e32 v24, 1.0, v24
	v_add_f32_e32 v25, 1.0, v25
	v_rcp_f32_e32 v24, v24
	v_rcp_f32_e32 v25, v25
	s_nop 0
	v_pk_mul_f32 v[18:19], v[18:19], v[24:25]
	s_nop 0
	v_pk_mul_f32 v[24:25], v[20:21], v[18:19]
	v_cvt_pk_bf16_f32 v20, v22, v23
	v_mad_u64_u32 v[22:23], s[20:21], v30, s89, v[130:131]
	v_cvt_pk_bf16_f32 v21, v24, v25
	v_mov_b32_e32 v24, v23
	v_mad_u64_u32 v[24:25], s[20:21], v31, s89, v[24:25]
	v_cvt_pk_bf16_f32 v18, v26, v27
	v_cvt_pk_bf16_f32 v19, v28, v29
	v_mov_b32_e32 v23, v24
	global_store_dwordx4 v[22:23], v[18:21], off sc1
	s_mov_b64 s[20:21], 0xb0
	s_nop 0
	v_mul_f32_e32 v18, 0xbfb8aa3b, v14
	v_mul_f32_e32 v19, 0xbfb8aa3b, v15
	v_exp_f32_e32 v18, v18
	v_exp_f32_e32 v19, v19
	v_add_f32_e32 v18, 1.0, v18
	v_add_f32_e32 v19, 1.0, v19
	v_rcp_f32_e32 v18, v18
	v_rcp_f32_e32 v19, v19
	s_nop 0
	v_pk_mul_f32 v[14:15], v[14:15], v[18:19]
	s_nop 0
	v_pk_mul_f32 v[10:11], v[10:11], v[14:15]
	v_pk_mul_f32 v[14:15], v[16:17], v[132:133] op_sel_hi:[1,0]
	s_nop 0
	v_mul_f32_e32 v16, 0xbfb8aa3b, v14
	v_mul_f32_e32 v17, 0xbfb8aa3b, v15
	v_exp_f32_e32 v16, v16
	v_exp_f32_e32 v17, v17
	v_add_f32_e32 v16, 1.0, v16
	v_add_f32_e32 v17, 1.0, v17
	v_rcp_f32_e32 v16, v16
	v_rcp_f32_e32 v17, v17
	s_nop 0
	v_pk_mul_f32 v[14:15], v[14:15], v[16:17]
	s_nop 0
	v_pk_mul_f32 v[12:13], v[12:13], v[14:15]
	v_mul_f32_e32 v14, 0xbfb8aa3b, v6
	v_mul_f32_e32 v15, 0xbfb8aa3b, v7
	v_exp_f32_e32 v14, v14
	v_exp_f32_e32 v15, v15
	v_add_f32_e32 v14, 1.0, v14
	v_add_f32_e32 v15, 1.0, v15
	v_rcp_f32_e32 v14, v14
	v_rcp_f32_e32 v15, v15
	s_nop 0
	v_pk_mul_f32 v[6:7], v[6:7], v[14:15]
	s_nop 0
	v_pk_mul_f32 v[6:7], v[2:3], v[6:7]
	v_pk_mul_f32 v[2:3], v[8:9], v[132:133] op_sel_hi:[1,0]
	v_lshl_add_u64 v[14:15], v[170:171], 0, s[20:21]
	v_mul_f32_e32 v8, 0xbfb8aa3b, v2
	v_mul_f32_e32 v9, 0xbfb8aa3b, v3
	v_exp_f32_e32 v8, v8
	v_exp_f32_e32 v9, v9
	v_add_f32_e32 v8, 1.0, v8
	v_add_f32_e32 v9, 1.0, v9
	v_rcp_f32_e32 v8, v8
	v_rcp_f32_e32 v9, v9
	s_nop 0
	v_pk_mul_f32 v[2:3], v[2:3], v[8:9]
	s_nop 0
	v_pk_mul_f32 v[8:9], v[4:5], v[2:3]
	v_cvt_pk_bf16_f32 v4, v6, v7
	v_mad_u64_u32 v[6:7], s[20:21], v14, s89, v[130:131]
	v_cvt_pk_bf16_f32 v5, v8, v9
	v_mov_b32_e32 v8, v7
	v_mad_u64_u32 v[8:9], s[20:21], v15, s89, v[8:9]
	v_cvt_pk_bf16_f32 v2, v10, v11
	v_cvt_pk_bf16_f32 v3, v12, v13
	v_mov_b32_e32 v7, v8
	s_mov_b64 s[20:21], -1
	global_store_dwordx4 v[6:7], v[2:5], off sc1
	s_cbranch_vccnz .LBB0_2071
	s_andn2_b64 vcc, exec, s[4:5]
	s_cbranch_vccnz .LBB0_2070
	s_barrier
	s_branch .LBB0_2070

.LBB0_2163:
	v_add_u32_e32 v0, 24, v0
	s_waitcnt lgkmcnt(0)
	v_mad_u64_u32 v[40:41], s[2:3], v0, s25, 0
	v_ashrrev_i32_e32 v42, 31, v0
	v_mov_b32_e32 v0, v41
	v_mad_u64_u32 v[42:43], s[2:3], v42, s25, v[0:1]
	v_mov_b32_e32 v41, v42
	v_lshl_add_u64 v[38:39], v[40:41], 1, v[38:39]
	global_store_dwordx4 v[38:39], v[34:37], off sc1
	s_waitcnt lgkmcnt(0)
	s_add_i32 s31, s31, s34
	s_add_i32 s36, s36, s37
	s_add_i32 s39, s39, s40
	s_andn2_b64 vcc, exec, s[18:19]
	s_mov_b32 s22, s41
	v_mov_b32_e32 v62, v6
	v_mov_b32_e32 v63, v7
	v_mov_b32_e32 v64, v8
	v_mov_b32_e32 v65, v9
	v_mov_b32_e32 v58, v2
	v_mov_b32_e32 v59, v3
	v_mov_b32_e32 v60, v4
	v_mov_b32_e32 v61, v5
	v_mov_b32_e32 v54, v14
	v_mov_b32_e32 v55, v15
	v_mov_b32_e32 v56, v16
	v_mov_b32_e32 v57, v17
	v_mov_b32_e32 v50, v10
	v_mov_b32_e32 v51, v11
	v_mov_b32_e32 v52, v12
	v_mov_b32_e32 v53, v13
	v_mov_b32_e32 v46, v22
	v_mov_b32_e32 v47, v23
	v_mov_b32_e32 v48, v24
	v_mov_b32_e32 v49, v25
	v_mov_b32_e32 v42, v18
	v_mov_b32_e32 v43, v19
	v_mov_b32_e32 v44, v20
	v_mov_b32_e32 v45, v21
	v_mov_b32_e32 v38, v30
	v_mov_b32_e32 v39, v31
	v_mov_b32_e32 v40, v32
	v_mov_b32_e32 v41, v33
	v_mov_b32_e32 v34, v26
	v_mov_b32_e32 v35, v27
	v_mov_b32_e32 v36, v28
	v_mov_b32_e32 v37, v29
	s_cbranch_vccz .LBB0_2086

.LBB0_2223:
	s_mul_i32 s2, s30, s42
	s_add_i32 s2, s2, s31
	v_add_u32_e32 v0, s2, v70
	v_mad_u64_u32 v[40:41], s[2:3], v0, s25, 0
	v_ashrrev_i32_e32 v43, 31, v0
	v_mov_b32_e32 v42, v41
	s_ashr_i32 s21, s20, 31
	v_mad_u64_u32 v[42:43], s[2:3], v43, s25, v[42:43]
	s_waitcnt lgkmcnt(0)
	v_lshl_add_u64 v[38:39], s[20:21], 1, v[66:67]
	v_mov_b32_e32 v41, v42
	v_lshl_add_u64 v[40:41], v[40:41], 1, v[38:39]
	global_store_dwordx4 v[40:41], v[34:37], off sc1
	ds_read2_b32 v[40:41], v72 offset0:8 offset1:41
	s_andn2_b64 vcc, exec, s[14:15]
	v_cndmask_b32_e64 v34, 0, 1, s[14:15]
	v_cmp_ne_u32_e64 s[2:3], 1, v34
	s_mov_b64 s[20:21], -1
	s_cbranch_vccnz .LBB0_2225
	ds_read2_b32 v[36:37], v72 offset0:74 offset1:107
	ds_read2_b32 v[42:43], v72 offset0:206 offset1:239
	s_waitcnt lgkmcnt(2)
	v_cvt_pk_bf16_f32 v34, v40, v41
	s_mov_b64 s[20:21], 0
	s_waitcnt lgkmcnt(1)
	v_cvt_pk_bf16_f32 v35, v36, v37
	ds_read2_b32 v[36:37], v72 offset0:140 offset1:173
	s_waitcnt lgkmcnt(0)
	v_cvt_pk_bf16_f32 v36, v36, v37
	v_cvt_pk_bf16_f32 v37, v42, v43

.LBB0_2227:
	s_waitcnt lgkmcnt(0)
	v_add_u32_e32 v40, 8, v0
	v_ashrrev_i32_e32 v43, 31, v40
	v_mad_u64_u32 v[40:41], s[20:21], v40, s25, 0
	v_mov_b32_e32 v42, v41
	v_mad_u64_u32 v[42:43], s[20:21], v43, s25, v[42:43]
	v_mov_b32_e32 v41, v42
	v_lshl_add_u64 v[40:41], v[40:41], 1, v[38:39]
	global_store_dwordx4 v[40:41], v[34:37], off sc1
	ds_read2_b32 v[40:41], v72 offset0:16 offset1:49
	s_mov_b64 s[20:21], -1
	s_and_b64 vcc, exec, s[2:3]
	s_cbranch_vccnz .LBB0_2229
	ds_read2_b32 v[36:37], v72 offset0:82 offset1:115
	ds_read2_b32 v[42:43], v72 offset0:214 offset1:247
	s_waitcnt lgkmcnt(2)
	v_cvt_pk_bf16_f32 v34, v40, v41
	s_mov_b64 s[20:21], 0
	s_waitcnt lgkmcnt(1)
	v_cvt_pk_bf16_f32 v35, v36, v37
	ds_read2_b32 v[36:37], v72 offset0:148 offset1:181
	s_waitcnt lgkmcnt(0)
	v_cvt_pk_bf16_f32 v36, v36, v37
	v_cvt_pk_bf16_f32 v37, v42, v43

.LBB0_2231:
	s_waitcnt lgkmcnt(0)
	v_add_u32_e32 v40, 16, v0
	v_ashrrev_i32_e32 v43, 31, v40
	v_mad_u64_u32 v[40:41], s[20:21], v40, s25, 0
	v_mov_b32_e32 v42, v41
	v_mad_u64_u32 v[42:43], s[20:21], v43, s25, v[42:43]
	v_mov_b32_e32 v41, v42
	v_lshl_add_u64 v[40:41], v[40:41], 1, v[38:39]
	global_store_dwordx4 v[40:41], v[34:37], off sc1
	ds_read2_b32 v[40:41], v72 offset0:24 offset1:57
	s_mov_b64 s[20:21], -1
	s_and_b64 vcc, exec, s[2:3]
	s_cbranch_vccnz .LBB0_2233
	ds_read2_b32 v[36:37], v72 offset0:90 offset1:123
	ds_read2_b32 v[42:43], v72 offset0:222 offset1:255
	s_waitcnt lgkmcnt(2)
	v_cvt_pk_bf16_f32 v34, v40, v41
	s_mov_b64 s[20:21], 0
	s_waitcnt lgkmcnt(1)
	v_cvt_pk_bf16_f32 v35, v36, v37
	ds_read2_b32 v[36:37], v72 offset0:156 offset1:189
	s_waitcnt lgkmcnt(0)
	v_cvt_pk_bf16_f32 v36, v36, v37
	v_cvt_pk_bf16_f32 v37, v42, v43

.LBB0_2319:
	v_add_u32_e32 v0, 0xffff8018, v0
	s_waitcnt lgkmcnt(0)
	v_mad_u64_u32 v[40:41], s[2:3], v0, s25, 0
	v_ashrrev_i32_e32 v42, 31, v0
	v_mov_b32_e32 v0, v41
	v_mad_u64_u32 v[42:43], s[2:3], v42, s25, v[0:1]
	v_mov_b32_e32 v41, v42
	v_lshl_add_u64 v[38:39], v[40:41], 1, v[38:39]
	global_store_dwordx4 v[38:39], v[34:37], off sc1
	s_waitcnt lgkmcnt(0)
	s_add_i32 s31, s31, 0x8000
	s_add_i32 s35, s35, 0x10000
	s_addk_i32 s37, 0x4000
	s_andn2_b64 vcc, exec, s[18:19]
	s_mov_b32 s22, s38
	v_mov_b32_e32 v62, v6
	v_mov_b32_e32 v63, v7
	v_mov_b32_e32 v64, v8
	v_mov_b32_e32 v65, v9
	v_mov_b32_e32 v58, v2
	v_mov_b32_e32 v59, v3
	v_mov_b32_e32 v60, v4
	v_mov_b32_e32 v61, v5
	v_mov_b32_e32 v54, v14
	v_mov_b32_e32 v55, v15
	v_mov_b32_e32 v56, v16
	v_mov_b32_e32 v57, v17
	v_mov_b32_e32 v50, v10
	v_mov_b32_e32 v51, v11
	v_mov_b32_e32 v52, v12
	v_mov_b32_e32 v53, v13
	v_mov_b32_e32 v46, v22
	v_mov_b32_e32 v47, v23
	v_mov_b32_e32 v48, v24
	v_mov_b32_e32 v49, v25
	v_mov_b32_e32 v42, v18
	v_mov_b32_e32 v43, v19
	v_mov_b32_e32 v44, v20
	v_mov_b32_e32 v45, v21
	v_mov_b32_e32 v38, v30
	v_mov_b32_e32 v39, v31
	v_mov_b32_e32 v40, v32
	v_mov_b32_e32 v41, v33
	v_mov_b32_e32 v34, v26
	v_mov_b32_e32 v35, v27
	v_mov_b32_e32 v36, v28
	v_mov_b32_e32 v37, v29
	s_cbranch_vccz .LBB0_2242

.LBB0_2379:
	s_mul_i32 s2, s30, s39
	s_add_i32 s2, s2, s31
	v_add_u32_e32 v0, s2, v70
	v_add_u32_e32 v40, 0xffff8000, v0
	v_ashrrev_i32_e32 v43, 31, v40
	v_mad_u64_u32 v[40:41], s[2:3], v40, s25, 0
	v_mov_b32_e32 v42, v41
	s_ashr_i32 s21, s20, 31
	v_mad_u64_u32 v[42:43], s[2:3], v43, s25, v[42:43]
	s_waitcnt lgkmcnt(0)
	v_lshl_add_u64 v[38:39], s[20:21], 1, v[66:67]
	v_mov_b32_e32 v41, v42
	v_lshl_add_u64 v[40:41], v[40:41], 1, v[38:39]
	global_store_dwordx4 v[40:41], v[34:37], off sc1
	ds_read2_b32 v[40:41], v72 offset0:8 offset1:41
	s_andn2_b64 vcc, exec, s[14:15]
	v_cndmask_b32_e64 v34, 0, 1, s[14:15]
	v_cmp_ne_u32_e64 s[2:3], 1, v34
	s_mov_b64 s[20:21], -1
	s_cbranch_vccnz .LBB0_2381
	ds_read2_b32 v[36:37], v72 offset0:74 offset1:107
	ds_read2_b32 v[42:43], v72 offset0:206 offset1:239
	s_waitcnt lgkmcnt(2)
	v_cvt_pk_bf16_f32 v34, v40, v41
	s_mov_b64 s[20:21], 0
	s_waitcnt lgkmcnt(1)
	v_cvt_pk_bf16_f32 v35, v36, v37
	ds_read2_b32 v[36:37], v72 offset0:140 offset1:173
	s_waitcnt lgkmcnt(0)
	v_cvt_pk_bf16_f32 v36, v36, v37
	v_cvt_pk_bf16_f32 v37, v42, v43

.LBB0_2383:
	s_waitcnt lgkmcnt(0)
	v_add_u32_e32 v40, 0xffff8008, v0
	v_ashrrev_i32_e32 v43, 31, v40
	v_mad_u64_u32 v[40:41], s[20:21], v40, s25, 0
	v_mov_b32_e32 v42, v41
	v_mad_u64_u32 v[42:43], s[20:21], v43, s25, v[42:43]
	v_mov_b32_e32 v41, v42
	v_lshl_add_u64 v[40:41], v[40:41], 1, v[38:39]
	global_store_dwordx4 v[40:41], v[34:37], off sc1
	ds_read2_b32 v[40:41], v72 offset0:16 offset1:49
	s_mov_b64 s[20:21], -1
	s_and_b64 vcc, exec, s[2:3]
	s_cbranch_vccnz .LBB0_2385
	ds_read2_b32 v[36:37], v72 offset0:82 offset1:115
	ds_read2_b32 v[42:43], v72 offset0:214 offset1:247
	s_waitcnt lgkmcnt(2)
	v_cvt_pk_bf16_f32 v34, v40, v41
	s_mov_b64 s[20:21], 0
	s_waitcnt lgkmcnt(1)
	v_cvt_pk_bf16_f32 v35, v36, v37
	ds_read2_b32 v[36:37], v72 offset0:148 offset1:181
	s_waitcnt lgkmcnt(0)
	v_cvt_pk_bf16_f32 v36, v36, v37
	v_cvt_pk_bf16_f32 v37, v42, v43

.LBB0_2387:
	s_waitcnt lgkmcnt(0)
	v_add_u32_e32 v40, 0xffff8010, v0
	v_ashrrev_i32_e32 v43, 31, v40
	v_mad_u64_u32 v[40:41], s[20:21], v40, s25, 0
	v_mov_b32_e32 v42, v41
	v_mad_u64_u32 v[42:43], s[20:21], v43, s25, v[42:43]
	v_mov_b32_e32 v41, v42
	v_lshl_add_u64 v[40:41], v[40:41], 1, v[38:39]
	global_store_dwordx4 v[40:41], v[34:37], off sc1
	ds_read2_b32 v[40:41], v72 offset0:24 offset1:57
	s_mov_b64 s[20:21], -1
	s_and_b64 vcc, exec, s[2:3]
	s_cbranch_vccnz .LBB0_2389
	ds_read2_b32 v[36:37], v72 offset0:90 offset1:123
	ds_read2_b32 v[42:43], v72 offset0:222 offset1:255
	s_waitcnt lgkmcnt(2)
	v_cvt_pk_bf16_f32 v34, v40, v41
	s_mov_b64 s[20:21], 0
	s_waitcnt lgkmcnt(1)
	v_cvt_pk_bf16_f32 v35, v36, v37
	ds_read2_b32 v[36:37], v72 offset0:156 offset1:189
	s_waitcnt lgkmcnt(0)
	v_cvt_pk_bf16_f32 v36, v36, v37
	v_cvt_pk_bf16_f32 v37, v42, v43

.LBB0_2476:
	s_mov_b32 s23, s33
	s_ashr_i32 s23, s22, 31
	s_lshl_b64 s[22:23], s[22:23], 8
	v_lshl_or_b32 v138, s47, 8, v165
	v_lshl_add_u64 v[140:141], s[22:23], 0, v[132:133]
	v_ashrrev_i32_e32 v139, 31, v138
	v_lshlrev_b64 v[144:145], 11, v[140:141]
	v_lshl_add_u64 v[142:143], s[6:7], 0, v[144:145]
	v_lshlrev_b64 v[146:147], 1, v[138:139]
	s_mov_b32 s24, s33
	v_lshl_add_u64 v[142:143], v[142:143], 0, v[146:147]
	global_load_dwordx2 v[168:169], v[142:143], off
	global_load_dwordx2 v[162:163], v[142:143], off offset:32
	global_load_dwordx2 v[160:161], v[142:143], off offset:256
	global_load_dwordx2 v[156:157], v[142:143], off offset:288
	v_lshl_add_u64 v[142:143], s[6:7], 0, v[146:147]
	v_lshl_add_u64 v[144:145], v[142:143], 0, v[144:145]
	v_add_co_u32_e32 v146, vcc, s54, v144
	v_mov_b32_e32 v154, s24
	s_nop 0
	v_addc_co_u32_e32 v147, vcc, 0, v145, vcc
	global_load_dwordx2 v[152:153], v[146:147], off
	global_load_dwordx2 v[150:151], v[146:147], off offset:32
	global_load_dwordx2 v[148:149], v[146:147], off offset:256
	s_nop 0
	global_load_dwordx2 v[146:147], v[146:147], off offset:288
	ds_read2_b32 v[170:171], v154 offset1:1
	v_lshlrev_b64 v[154:155], 10, v[140:141]
	v_lshl_add_u64 v[158:159], v[154:155], 0, v[138:139]
	s_mov_b64 s[6:7], -1
	s_and_b64 vcc, exec, s[10:11]
	v_lshl_add_u64 v[154:155], v[158:159], 1, s[20:21]
	s_waitcnt lgkmcnt(0)
	v_readfirstlane_b32 s24, v170
	v_readfirstlane_b32 s25, v171
	s_waitcnt vmcnt(0)
	v_cvt_f32_f16_e32 v172, v168
	v_cvt_f32_f16_e32 v174, v169
	v_cvt_f32_f16_sdwa v175, v169 dst_sel:DWORD dst_unused:UNUSED_PAD src0_sel:WORD_1
	v_cvt_f32_f16_sdwa v173, v168 dst_sel:DWORD dst_unused:UNUSED_PAD src0_sel:WORD_1
	v_pk_fma_f32 v[128:129], v[128:129], 0.5, v[174:175] op_sel_hi:[1,0,1]
	v_pk_fma_f32 v[126:127], v[126:127], 0.5, v[172:173] op_sel_hi:[1,0,1]
	s_cbranch_vccz .LBB0_2478
	v_cvt_f16_f32_e32 v167, v126
	v_cvt_f16_f32_sdwa v168, v127 dst_sel:WORD_1 dst_unused:UNUSED_PAD src0_sel:DWORD
	v_cvt_f16_f32_e32 v169, v128
	v_cvt_f16_f32_sdwa v170, v129 dst_sel:WORD_1 dst_unused:UNUSED_PAD src0_sel:DWORD
	s_mov_b64 s[6:7], 0
	v_or_b32_e32 v168, v168, v167
	v_or_b32_e32 v169, v170, v169
	global_store_dwordx2 v[154:155], v[168:169], off sc1
	v_pk_mul_f32 v[168:169], v[128:129], v[128:129]
	v_pk_mul_f32 v[170:171], v[126:127], v[126:127]
	s_nop 0
	v_pk_mov_b32 v[172:173], v[170:171], v[168:169] op_sel:[1,0]
	v_mov_b32_e32 v171, v169
	v_pk_add_f32 v[168:169], v[172:173], v[170:171]
	s_nop 0
	v_add_f32_e32 v167, v168, v169

.LBB0_2480:
	s_nop 1
	v_cvt_f32_f16_sdwa v127, v162 dst_sel:DWORD dst_unused:UNUSED_PAD src0_sel:WORD_1
	v_cvt_f32_f16_e32 v126, v162
	v_cvt_f32_f16_sdwa v129, v163 dst_sel:DWORD dst_unused:UNUSED_PAD src0_sel:WORD_1
	v_cvt_f32_f16_e32 v128, v163
	s_andn2_b64 vcc, exec, s[10:11]
	v_pk_fma_f32 v[122:123], v[122:123], 0.5, v[126:127] op_sel_hi:[1,0,1]
	v_cndmask_b32_e64 v126, 0, 1, s[10:11]
	v_pk_fma_f32 v[124:125], v[124:125], 0.5, v[128:129] op_sel_hi:[1,0,1]
	v_cmp_ne_u32_e64 s[6:7], 1, v126
	s_mov_b64 s[22:23], -1
	s_cbranch_vccnz .LBB0_2482
	v_cvt_f16_f32_e32 v126, v122
	v_cvt_f16_f32_sdwa v127, v123 dst_sel:WORD_1 dst_unused:UNUSED_PAD src0_sel:DWORD
	v_cvt_f16_f32_e32 v128, v124
	v_cvt_f16_f32_sdwa v129, v125 dst_sel:WORD_1 dst_unused:UNUSED_PAD src0_sel:DWORD
	s_mov_b64 s[22:23], 0
	v_or_b32_e32 v126, v127, v126
	v_or_b32_e32 v127, v129, v128
	global_store_dwordx2 v[154:155], v[126:127], off offset:32 sc1
	v_pk_mul_f32 v[126:127], v[124:125], v[124:125]
	v_pk_mul_f32 v[128:129], v[122:123], v[122:123]
	s_nop 0
	v_pk_mov_b32 v[162:163], v[128:129], v[126:127] op_sel:[1,0]
	v_mov_b32_e32 v129, v127
	v_pk_add_f32 v[126:127], v[162:163], v[128:129]
	s_nop 0
	v_add_f32_e32 v126, v126, v127
	v_add_f32_e32 v126, v126, v167

.LBB0_2484:
	s_nop 1
	v_cvt_f32_f16_sdwa v123, v160 dst_sel:DWORD dst_unused:UNUSED_PAD src0_sel:WORD_1
	v_cvt_f32_f16_sdwa v125, v161 dst_sel:DWORD dst_unused:UNUSED_PAD src0_sel:WORD_1
	v_cvt_f32_f16_e32 v124, v161
	v_cvt_f32_f16_e32 v122, v160
	s_and_b64 vcc, exec, s[6:7]
	s_mov_b64 s[22:23], -1
	v_pk_fma_f32 v[120:121], v[120:121], 0.5, v[124:125] op_sel_hi:[1,0,1]
	v_pk_fma_f32 v[118:119], v[118:119], 0.5, v[122:123] op_sel_hi:[1,0,1]
	s_cbranch_vccnz .LBB0_2486
	v_cvt_f16_f32_e32 v122, v118
	v_cvt_f16_f32_sdwa v123, v119 dst_sel:WORD_1 dst_unused:UNUSED_PAD src0_sel:DWORD
	v_cvt_f16_f32_e32 v124, v120
	v_cvt_f16_f32_sdwa v125, v121 dst_sel:WORD_1 dst_unused:UNUSED_PAD src0_sel:DWORD
	s_mov_b64 s[22:23], 0
	v_or_b32_e32 v122, v123, v122
	v_or_b32_e32 v123, v125, v124
	global_store_dwordx2 v[154:155], v[122:123], off offset:256 sc1
	v_pk_mul_f32 v[122:123], v[120:121], v[120:121]
	v_pk_mul_f32 v[124:125], v[118:119], v[118:119]
	s_nop 0
	v_pk_mov_b32 v[128:129], v[124:125], v[122:123] op_sel:[1,0]
	v_mov_b32_e32 v125, v123
	v_pk_add_f32 v[122:123], v[128:129], v[124:125]
	s_nop 0
	v_add_f32_e32 v122, v122, v123
	v_add_f32_e32 v122, v122, v126

.LBB0_2488:
	s_nop 1
	v_cvt_f32_f16_sdwa v119, v156 dst_sel:DWORD dst_unused:UNUSED_PAD src0_sel:WORD_1
	v_cvt_f32_f16_sdwa v121, v157 dst_sel:DWORD dst_unused:UNUSED_PAD src0_sel:WORD_1
	v_cvt_f32_f16_e32 v120, v157
	v_cvt_f32_f16_e32 v118, v156
	s_and_b64 vcc, exec, s[6:7]
	s_mov_b64 s[22:23], -1
	v_pk_fma_f32 v[116:117], v[116:117], 0.5, v[120:121] op_sel_hi:[1,0,1]
	v_pk_fma_f32 v[114:115], v[114:115], 0.5, v[118:119] op_sel_hi:[1,0,1]
	s_cbranch_vccnz .LBB0_2490
	v_cvt_f16_f32_e32 v118, v114
	v_cvt_f16_f32_sdwa v119, v115 dst_sel:WORD_1 dst_unused:UNUSED_PAD src0_sel:DWORD
	v_cvt_f16_f32_sdwa v120, v117 dst_sel:WORD_1 dst_unused:UNUSED_PAD src0_sel:DWORD
	s_mov_b64 s[22:23], 0
	v_or_b32_e32 v118, v119, v118
	v_cvt_f16_f32_e32 v119, v116
	v_or_b32_e32 v119, v120, v119
	global_store_dwordx2 v[154:155], v[118:119], off offset:288 sc1
	v_pk_mul_f32 v[118:119], v[116:117], v[116:117]
	v_pk_mul_f32 v[120:121], v[114:115], v[114:115]
	s_nop 0
	v_pk_mov_b32 v[124:125], v[120:121], v[118:119] op_sel:[1,0]
	v_mov_b32_e32 v121, v119
	v_pk_add_f32 v[118:119], v[124:125], v[120:121]
	s_nop 0
	v_add_f32_e32 v118, v118, v119
	v_add_f32_e32 v118, v118, v122

.LBB0_2496:
	v_add_co_u32_e32 v114, vcc, 0x10000, v144
	v_cvt_f32_f16_sdwa v125, v152 dst_sel:DWORD dst_unused:UNUSED_PAD src0_sel:WORD_1
	s_waitcnt lgkmcnt(0)
	v_addc_co_u32_e32 v115, vcc, 0, v145, vcc
	global_load_dwordx2 v[120:121], v[114:115], off
	global_load_dwordx2 v[118:119], v[114:115], off offset:32
	global_load_dwordx2 v[116:117], v[114:115], off offset:256
	s_nop 0
	global_load_dwordx2 v[114:115], v[114:115], off offset:288
	v_cvt_f32_f16_e32 v124, v152
	v_cvt_f32_f16_sdwa v129, v153 dst_sel:DWORD dst_unused:UNUSED_PAD src0_sel:WORD_1
	v_cvt_f32_f16_e32 v128, v153
	v_or_b32_e32 v122, 16, v140
	v_mov_b32_e32 v123, v141
	v_lshlrev_b64 v[126:127], 10, v[122:123]
	v_lshl_add_u64 v[126:127], v[126:127], 0, v[138:139]
	v_pk_fma_f32 v[112:113], v[112:113], 0.5, v[128:129] op_sel_hi:[1,0,1]
	v_pk_fma_f32 v[110:111], v[110:111], 0.5, v[124:125] op_sel_hi:[1,0,1]
	s_mov_b64 s[24:25], -1
	s_and_b64 vcc, exec, s[6:7]
	v_lshl_add_u64 v[124:125], v[126:127], 1, s[20:21]
	s_cbranch_vccnz .LBB0_2498
	v_cvt_f16_f32_e32 v128, v110
	v_cvt_f16_f32_sdwa v129, v111 dst_sel:WORD_1 dst_unused:UNUSED_PAD src0_sel:DWORD
	v_cvt_f16_f32_e32 v152, v112
	v_cvt_f16_f32_sdwa v153, v113 dst_sel:WORD_1 dst_unused:UNUSED_PAD src0_sel:DWORD
	s_mov_b64 s[24:25], 0
	v_or_b32_e32 v128, v129, v128
	v_or_b32_e32 v129, v153, v152
	global_store_dwordx2 v[124:125], v[128:129], off sc1
	v_pk_mul_f32 v[128:129], v[112:113], v[112:113]
	v_pk_mul_f32 v[152:153], v[110:111], v[110:111]
	s_nop 0
	v_pk_mov_b32 v[154:155], v[152:153], v[128:129] op_sel:[1,0]
	v_mov_b32_e32 v153, v129
	v_pk_add_f32 v[128:129], v[154:155], v[152:153]
	s_nop 0
	v_add_f32_e32 v128, v128, v129

.LBB0_2500:
	s_nop 1
	v_cvt_f32_f16_sdwa v111, v150 dst_sel:DWORD dst_unused:UNUSED_PAD src0_sel:WORD_1
	v_cvt_f32_f16_sdwa v113, v151 dst_sel:DWORD dst_unused:UNUSED_PAD src0_sel:WORD_1
	v_cvt_f32_f16_e32 v112, v151
	v_cvt_f32_f16_e32 v110, v150
	s_and_b64 vcc, exec, s[6:7]
	s_mov_b64 s[24:25], -1
	v_pk_fma_f32 v[108:109], v[108:109], 0.5, v[112:113] op_sel_hi:[1,0,1]
	v_pk_fma_f32 v[106:107], v[106:107], 0.5, v[110:111] op_sel_hi:[1,0,1]
	s_cbranch_vccnz .LBB0_2502
	v_cvt_f16_f32_e32 v110, v106
	v_cvt_f16_f32_sdwa v111, v107 dst_sel:WORD_1 dst_unused:UNUSED_PAD src0_sel:DWORD
	v_cvt_f16_f32_e32 v112, v108
	v_cvt_f16_f32_sdwa v113, v109 dst_sel:WORD_1 dst_unused:UNUSED_PAD src0_sel:DWORD
	s_mov_b64 s[24:25], 0
	v_or_b32_e32 v110, v111, v110
	v_or_b32_e32 v111, v113, v112
	global_store_dwordx2 v[124:125], v[110:111], off offset:32 sc1
	v_pk_mul_f32 v[110:111], v[108:109], v[108:109]
	v_pk_mul_f32 v[112:113], v[106:107], v[106:107]
	s_nop 0
	v_pk_mov_b32 v[150:151], v[112:113], v[110:111] op_sel:[1,0]
	v_mov_b32_e32 v113, v111
	v_pk_add_f32 v[110:111], v[150:151], v[112:113]
	s_nop 0
	v_add_f32_e32 v110, v110, v111
	v_add_f32_e32 v110, v110, v128

.LBB0_2504:
	s_nop 1
	v_cvt_f32_f16_sdwa v107, v148 dst_sel:DWORD dst_unused:UNUSED_PAD src0_sel:WORD_1
	v_cvt_f32_f16_sdwa v109, v149 dst_sel:DWORD dst_unused:UNUSED_PAD src0_sel:WORD_1
	v_cvt_f32_f16_e32 v108, v149
	v_cvt_f32_f16_e32 v106, v148
	s_and_b64 vcc, exec, s[6:7]
	s_mov_b64 s[24:25], -1
	v_pk_fma_f32 v[104:105], v[104:105], 0.5, v[108:109] op_sel_hi:[1,0,1]
	v_pk_fma_f32 v[102:103], v[102:103], 0.5, v[106:107] op_sel_hi:[1,0,1]
	s_cbranch_vccnz .LBB0_2506
	v_cvt_f16_f32_e32 v106, v102
	v_cvt_f16_f32_sdwa v107, v103 dst_sel:WORD_1 dst_unused:UNUSED_PAD src0_sel:DWORD
	v_cvt_f16_f32_e32 v108, v104
	v_cvt_f16_f32_sdwa v109, v105 dst_sel:WORD_1 dst_unused:UNUSED_PAD src0_sel:DWORD
	s_mov_b64 s[24:25], 0
	v_or_b32_e32 v106, v107, v106
	v_or_b32_e32 v107, v109, v108
	global_store_dwordx2 v[124:125], v[106:107], off offset:256 sc1
	v_pk_mul_f32 v[106:107], v[104:105], v[104:105]
	v_pk_mul_f32 v[108:109], v[102:103], v[102:103]
	s_nop 0
	v_pk_mov_b32 v[112:113], v[108:109], v[106:107] op_sel:[1,0]
	v_mov_b32_e32 v109, v107
	v_pk_add_f32 v[106:107], v[112:113], v[108:109]
	s_nop 0
	v_add_f32_e32 v106, v106, v107
	v_add_f32_e32 v106, v106, v110

.LBB0_2508:
	s_nop 1
	v_cvt_f32_f16_sdwa v103, v146 dst_sel:DWORD dst_unused:UNUSED_PAD src0_sel:WORD_1
	v_cvt_f32_f16_sdwa v105, v147 dst_sel:DWORD dst_unused:UNUSED_PAD src0_sel:WORD_1
	v_cvt_f32_f16_e32 v104, v147
	v_cvt_f32_f16_e32 v102, v146
	s_and_b64 vcc, exec, s[6:7]
	s_mov_b64 s[24:25], -1
	v_pk_fma_f32 v[100:101], v[100:101], 0.5, v[104:105] op_sel_hi:[1,0,1]
	v_pk_fma_f32 v[98:99], v[98:99], 0.5, v[102:103] op_sel_hi:[1,0,1]
	s_cbranch_vccnz .LBB0_2511
	v_cvt_f16_f32_e32 v102, v98
	v_cvt_f16_f32_sdwa v103, v99 dst_sel:WORD_1 dst_unused:UNUSED_PAD src0_sel:DWORD
	v_cvt_f16_f32_sdwa v104, v101 dst_sel:WORD_1 dst_unused:UNUSED_PAD src0_sel:DWORD
	v_or_b32_e32 v102, v103, v102
	v_cvt_f16_f32_e32 v103, v100
	v_or_b32_e32 v103, v104, v103
	global_store_dwordx2 v[124:125], v[102:103], off offset:288 sc1
	v_pk_mul_f32 v[102:103], v[100:101], v[100:101]
	v_pk_mul_f32 v[104:105], v[98:99], v[98:99]
	s_nop 0
	v_pk_mov_b32 v[108:109], v[104:105], v[102:103] op_sel:[1,0]
	v_mov_b32_e32 v105, v103
	v_pk_add_f32 v[102:103], v[108:109], v[104:105]
	s_nop 0
	v_add_f32_e32 v102, v102, v103
	v_add_f32_e32 v102, v102, v106
	s_cbranch_execz .LBB0_2512

.LBB0_2516:
	v_add_co_u32_e32 v98, vcc, 0x18000, v144
	s_waitcnt vmcnt(3)
	v_cvt_f32_f16_sdwa v109, v120 dst_sel:DWORD dst_unused:UNUSED_PAD src0_sel:WORD_1
	s_waitcnt lgkmcnt(0)
	v_addc_co_u32_e32 v99, vcc, 0, v145, vcc
	global_load_dwordx2 v[104:105], v[98:99], off
	global_load_dwordx2 v[102:103], v[98:99], off offset:32
	global_load_dwordx2 v[100:101], v[98:99], off offset:256
	s_nop 0
	global_load_dwordx2 v[98:99], v[98:99], off offset:288
	v_cvt_f32_f16_e32 v108, v120
	v_cvt_f32_f16_sdwa v113, v121 dst_sel:DWORD dst_unused:UNUSED_PAD src0_sel:WORD_1
	v_cvt_f32_f16_e32 v112, v121
	v_or_b32_e32 v106, 32, v140
	v_mov_b32_e32 v107, v141
	v_lshlrev_b64 v[110:111], 10, v[106:107]
	v_lshl_add_u64 v[110:111], v[110:111], 0, v[138:139]
	v_pk_fma_f32 v[96:97], v[96:97], 0.5, v[112:113] op_sel_hi:[1,0,1]
	v_pk_fma_f32 v[94:95], v[94:95], 0.5, v[108:109] op_sel_hi:[1,0,1]
	s_mov_b64 s[24:25], -1
	s_and_b64 vcc, exec, s[6:7]
	v_lshl_add_u64 v[108:109], v[110:111], 1, s[20:21]
	s_cbranch_vccnz .LBB0_2518
	v_cvt_f16_f32_e32 v112, v94
	v_cvt_f16_f32_sdwa v113, v95 dst_sel:WORD_1 dst_unused:UNUSED_PAD src0_sel:DWORD
	v_cvt_f16_f32_e32 v120, v96
	v_cvt_f16_f32_sdwa v121, v97 dst_sel:WORD_1 dst_unused:UNUSED_PAD src0_sel:DWORD
	s_mov_b64 s[24:25], 0
	v_or_b32_e32 v112, v113, v112
	v_or_b32_e32 v113, v121, v120
	global_store_dwordx2 v[108:109], v[112:113], off sc1
	v_pk_mul_f32 v[112:113], v[96:97], v[96:97]
	v_pk_mul_f32 v[120:121], v[94:95], v[94:95]
	s_nop 0
	v_pk_mov_b32 v[122:123], v[120:121], v[112:113] op_sel:[1,0]
	v_mov_b32_e32 v121, v113
	v_pk_add_f32 v[112:113], v[122:123], v[120:121]
	s_nop 0
	v_add_f32_e32 v112, v112, v113

.LBB0_2520:
	s_waitcnt vmcnt(6)
	s_nop 0
	v_cvt_f32_f16_sdwa v95, v118 dst_sel:DWORD dst_unused:UNUSED_PAD src0_sel:WORD_1
	v_cvt_f32_f16_sdwa v97, v119 dst_sel:DWORD dst_unused:UNUSED_PAD src0_sel:WORD_1
	v_cvt_f32_f16_e32 v96, v119
	v_cvt_f32_f16_e32 v94, v118
	s_and_b64 vcc, exec, s[6:7]
	s_mov_b64 s[24:25], -1
	v_pk_fma_f32 v[92:93], v[92:93], 0.5, v[96:97] op_sel_hi:[1,0,1]
	v_pk_fma_f32 v[90:91], v[90:91], 0.5, v[94:95] op_sel_hi:[1,0,1]
	s_cbranch_vccnz .LBB0_2522
	v_cvt_f16_f32_e32 v94, v90
	v_cvt_f16_f32_sdwa v95, v91 dst_sel:WORD_1 dst_unused:UNUSED_PAD src0_sel:DWORD
	v_cvt_f16_f32_e32 v96, v92
	v_cvt_f16_f32_sdwa v97, v93 dst_sel:WORD_1 dst_unused:UNUSED_PAD src0_sel:DWORD
	s_mov_b64 s[24:25], 0
	v_or_b32_e32 v94, v95, v94
	v_or_b32_e32 v95, v97, v96
	global_store_dwordx2 v[108:109], v[94:95], off offset:32 sc1
	v_pk_mul_f32 v[94:95], v[92:93], v[92:93]
	v_pk_mul_f32 v[96:97], v[90:91], v[90:91]
	s_nop 0
	v_pk_mov_b32 v[118:119], v[96:97], v[94:95] op_sel:[1,0]
	v_mov_b32_e32 v97, v95
	v_pk_add_f32 v[94:95], v[118:119], v[96:97]
	s_nop 0
	v_add_f32_e32 v94, v94, v95
	v_add_f32_e32 v94, v94, v112

.LBB0_2524:
	s_waitcnt vmcnt(5)
	s_nop 0
	v_cvt_f32_f16_sdwa v91, v116 dst_sel:DWORD dst_unused:UNUSED_PAD src0_sel:WORD_1
	v_cvt_f32_f16_sdwa v93, v117 dst_sel:DWORD dst_unused:UNUSED_PAD src0_sel:WORD_1
	v_cvt_f32_f16_e32 v92, v117
	v_cvt_f32_f16_e32 v90, v116
	s_and_b64 vcc, exec, s[6:7]
	s_mov_b64 s[24:25], -1
	v_pk_fma_f32 v[88:89], v[88:89], 0.5, v[92:93] op_sel_hi:[1,0,1]
	v_pk_fma_f32 v[86:87], v[86:87], 0.5, v[90:91] op_sel_hi:[1,0,1]
	s_cbranch_vccnz .LBB0_2526
	v_cvt_f16_f32_e32 v90, v86
	v_cvt_f16_f32_sdwa v91, v87 dst_sel:WORD_1 dst_unused:UNUSED_PAD src0_sel:DWORD
	v_cvt_f16_f32_e32 v92, v88
	v_cvt_f16_f32_sdwa v93, v89 dst_sel:WORD_1 dst_unused:UNUSED_PAD src0_sel:DWORD
	s_mov_b64 s[24:25], 0
	v_or_b32_e32 v90, v91, v90
	v_or_b32_e32 v91, v93, v92
	global_store_dwordx2 v[108:109], v[90:91], off offset:256 sc1
	v_pk_mul_f32 v[90:91], v[88:89], v[88:89]
	v_pk_mul_f32 v[92:93], v[86:87], v[86:87]
	s_nop 0
	v_pk_mov_b32 v[96:97], v[92:93], v[90:91] op_sel:[1,0]
	v_mov_b32_e32 v93, v91
	v_pk_add_f32 v[90:91], v[96:97], v[92:93]
	s_nop 0
	v_add_f32_e32 v90, v90, v91
	v_add_f32_e32 v90, v90, v94

.LBB0_2528:
	s_waitcnt vmcnt(4)
	s_nop 0
	v_cvt_f32_f16_sdwa v87, v114 dst_sel:DWORD dst_unused:UNUSED_PAD src0_sel:WORD_1
	v_cvt_f32_f16_sdwa v89, v115 dst_sel:DWORD dst_unused:UNUSED_PAD src0_sel:WORD_1
	v_cvt_f32_f16_e32 v88, v115
	v_cvt_f32_f16_e32 v86, v114
	s_and_b64 vcc, exec, s[6:7]
	s_mov_b64 s[24:25], -1
	v_pk_fma_f32 v[84:85], v[84:85], 0.5, v[88:89] op_sel_hi:[1,0,1]
	v_pk_fma_f32 v[82:83], v[82:83], 0.5, v[86:87] op_sel_hi:[1,0,1]
	s_cbranch_vccnz .LBB0_2531
	v_cvt_f16_f32_e32 v86, v82
	v_cvt_f16_f32_sdwa v87, v83 dst_sel:WORD_1 dst_unused:UNUSED_PAD src0_sel:DWORD
	v_cvt_f16_f32_sdwa v88, v85 dst_sel:WORD_1 dst_unused:UNUSED_PAD src0_sel:DWORD
	v_or_b32_e32 v86, v87, v86
	v_cvt_f16_f32_e32 v87, v84
	v_or_b32_e32 v87, v88, v87
	global_store_dwordx2 v[108:109], v[86:87], off offset:288 sc1
	v_pk_mul_f32 v[86:87], v[84:85], v[84:85]
	v_pk_mul_f32 v[88:89], v[82:83], v[82:83]
	s_nop 0
	v_pk_mov_b32 v[92:93], v[88:89], v[86:87] op_sel:[1,0]
	v_mov_b32_e32 v89, v87
	v_pk_add_f32 v[86:87], v[92:93], v[88:89]
	s_nop 0
	v_add_f32_e32 v86, v86, v87
	v_add_f32_e32 v86, v86, v90
	s_cbranch_execz .LBB0_2532

.LBB0_2536:
	v_add_co_u32_e32 v82, vcc, 0x40000, v144
	s_waitcnt vmcnt(3)
	v_cvt_f32_f16_sdwa v93, v104 dst_sel:DWORD dst_unused:UNUSED_PAD src0_sel:WORD_1
	s_waitcnt lgkmcnt(0)
	v_addc_co_u32_e32 v83, vcc, 0, v145, vcc
	global_load_dwordx2 v[88:89], v[82:83], off
	global_load_dwordx2 v[86:87], v[82:83], off offset:32
	global_load_dwordx2 v[84:85], v[82:83], off offset:256
	s_nop 0
	global_load_dwordx2 v[82:83], v[82:83], off offset:288
	v_cvt_f32_f16_e32 v92, v104
	v_cvt_f32_f16_sdwa v97, v105 dst_sel:DWORD dst_unused:UNUSED_PAD src0_sel:WORD_1
	v_cvt_f32_f16_e32 v96, v105
	v_or_b32_e32 v90, 48, v140
	v_mov_b32_e32 v91, v141
	v_lshlrev_b64 v[94:95], 10, v[90:91]
	v_lshl_add_u64 v[94:95], v[94:95], 0, v[138:139]
	v_pk_fma_f32 v[80:81], v[80:81], 0.5, v[96:97] op_sel_hi:[1,0,1]
	v_pk_fma_f32 v[78:79], v[78:79], 0.5, v[92:93] op_sel_hi:[1,0,1]
	s_mov_b64 s[24:25], -1
	s_and_b64 vcc, exec, s[6:7]
	v_lshl_add_u64 v[92:93], v[94:95], 1, s[20:21]
	s_cbranch_vccnz .LBB0_2538
	v_cvt_f16_f32_e32 v96, v78
	v_cvt_f16_f32_sdwa v97, v79 dst_sel:WORD_1 dst_unused:UNUSED_PAD src0_sel:DWORD
	v_cvt_f16_f32_e32 v104, v80
	v_cvt_f16_f32_sdwa v105, v81 dst_sel:WORD_1 dst_unused:UNUSED_PAD src0_sel:DWORD
	s_mov_b64 s[24:25], 0
	v_or_b32_e32 v96, v97, v96
	v_or_b32_e32 v97, v105, v104
	global_store_dwordx2 v[92:93], v[96:97], off sc1
	v_pk_mul_f32 v[96:97], v[80:81], v[80:81]
	v_pk_mul_f32 v[104:105], v[78:79], v[78:79]
	s_nop 0
	v_pk_mov_b32 v[106:107], v[104:105], v[96:97] op_sel:[1,0]
	v_mov_b32_e32 v105, v97
	v_pk_add_f32 v[96:97], v[106:107], v[104:105]
	s_nop 0
	v_add_f32_e32 v96, v96, v97

.LBB0_2540:
	s_waitcnt vmcnt(6)
	s_nop 0
	v_cvt_f32_f16_sdwa v79, v102 dst_sel:DWORD dst_unused:UNUSED_PAD src0_sel:WORD_1
	v_cvt_f32_f16_sdwa v81, v103 dst_sel:DWORD dst_unused:UNUSED_PAD src0_sel:WORD_1
	v_cvt_f32_f16_e32 v80, v103
	v_cvt_f32_f16_e32 v78, v102
	s_and_b64 vcc, exec, s[6:7]
	s_mov_b64 s[24:25], -1
	v_pk_fma_f32 v[76:77], v[76:77], 0.5, v[80:81] op_sel_hi:[1,0,1]
	v_pk_fma_f32 v[74:75], v[74:75], 0.5, v[78:79] op_sel_hi:[1,0,1]
	s_cbranch_vccnz .LBB0_2542
	v_cvt_f16_f32_e32 v78, v74
	v_cvt_f16_f32_sdwa v79, v75 dst_sel:WORD_1 dst_unused:UNUSED_PAD src0_sel:DWORD
	v_cvt_f16_f32_e32 v80, v76
	v_cvt_f16_f32_sdwa v81, v77 dst_sel:WORD_1 dst_unused:UNUSED_PAD src0_sel:DWORD
	s_mov_b64 s[24:25], 0
	v_or_b32_e32 v78, v79, v78
	v_or_b32_e32 v79, v81, v80
	global_store_dwordx2 v[92:93], v[78:79], off offset:32 sc1
	v_pk_mul_f32 v[78:79], v[76:77], v[76:77]
	v_pk_mul_f32 v[80:81], v[74:75], v[74:75]
	s_nop 0
	v_pk_mov_b32 v[102:103], v[80:81], v[78:79] op_sel:[1,0]
	v_mov_b32_e32 v81, v79
	v_pk_add_f32 v[78:79], v[102:103], v[80:81]
	s_nop 0
	v_add_f32_e32 v78, v78, v79
	v_add_f32_e32 v78, v78, v96

.LBB0_2544:
	s_waitcnt vmcnt(5)
	s_nop 0
	v_cvt_f32_f16_sdwa v75, v100 dst_sel:DWORD dst_unused:UNUSED_PAD src0_sel:WORD_1
	v_cvt_f32_f16_sdwa v77, v101 dst_sel:DWORD dst_unused:UNUSED_PAD src0_sel:WORD_1
	v_cvt_f32_f16_e32 v76, v101
	v_cvt_f32_f16_e32 v74, v100
	s_and_b64 vcc, exec, s[6:7]
	s_mov_b64 s[24:25], -1
	v_pk_fma_f32 v[72:73], v[72:73], 0.5, v[76:77] op_sel_hi:[1,0,1]
	v_pk_fma_f32 v[70:71], v[70:71], 0.5, v[74:75] op_sel_hi:[1,0,1]
	s_cbranch_vccnz .LBB0_2546
	v_cvt_f16_f32_e32 v74, v70
	v_cvt_f16_f32_sdwa v75, v71 dst_sel:WORD_1 dst_unused:UNUSED_PAD src0_sel:DWORD
	v_cvt_f16_f32_e32 v76, v72
	v_cvt_f16_f32_sdwa v77, v73 dst_sel:WORD_1 dst_unused:UNUSED_PAD src0_sel:DWORD
	s_mov_b64 s[24:25], 0
	v_or_b32_e32 v74, v75, v74
	v_or_b32_e32 v75, v77, v76
	global_store_dwordx2 v[92:93], v[74:75], off offset:256 sc1
	v_pk_mul_f32 v[74:75], v[72:73], v[72:73]
	v_pk_mul_f32 v[76:77], v[70:71], v[70:71]
	s_nop 0
	v_pk_mov_b32 v[80:81], v[76:77], v[74:75] op_sel:[1,0]
	v_mov_b32_e32 v77, v75
	v_pk_add_f32 v[74:75], v[80:81], v[76:77]
	s_nop 0
	v_add_f32_e32 v74, v74, v75
	v_add_f32_e32 v74, v74, v78

.LBB0_2548:
	s_waitcnt vmcnt(4)
	s_nop 0
	v_cvt_f32_f16_sdwa v71, v98 dst_sel:DWORD dst_unused:UNUSED_PAD src0_sel:WORD_1
	v_cvt_f32_f16_sdwa v73, v99 dst_sel:DWORD dst_unused:UNUSED_PAD src0_sel:WORD_1
	v_cvt_f32_f16_e32 v72, v99
	v_cvt_f32_f16_e32 v70, v98
	s_and_b64 vcc, exec, s[6:7]
	s_mov_b64 s[24:25], -1
	v_pk_fma_f32 v[68:69], v[68:69], 0.5, v[72:73] op_sel_hi:[1,0,1]
	v_pk_fma_f32 v[66:67], v[66:67], 0.5, v[70:71] op_sel_hi:[1,0,1]
	s_cbranch_vccnz .LBB0_2551
	v_cvt_f16_f32_e32 v70, v66
	v_cvt_f16_f32_sdwa v71, v67 dst_sel:WORD_1 dst_unused:UNUSED_PAD src0_sel:DWORD
	v_cvt_f16_f32_sdwa v72, v69 dst_sel:WORD_1 dst_unused:UNUSED_PAD src0_sel:DWORD
	v_or_b32_e32 v70, v71, v70
	v_cvt_f16_f32_e32 v71, v68
	v_or_b32_e32 v71, v72, v71
	global_store_dwordx2 v[92:93], v[70:71], off offset:288 sc1
	v_pk_mul_f32 v[70:71], v[68:69], v[68:69]
	v_pk_mul_f32 v[72:73], v[66:67], v[66:67]
	s_nop 0
	v_pk_mov_b32 v[76:77], v[72:73], v[70:71] op_sel:[1,0]
	v_mov_b32_e32 v73, v71
	v_pk_add_f32 v[70:71], v[76:77], v[72:73]
	s_nop 0
	v_add_f32_e32 v70, v70, v71
	v_add_f32_e32 v70, v70, v74
	s_cbranch_execz .LBB0_2552

.LBB0_2556:
	v_lshl_add_u64 v[76:77], v[140:141], 0, s[96:97]
	s_waitcnt lgkmcnt(0)
	v_lshlrev_b64 v[66:67], 11, v[76:77]
	v_or_b32_e32 v68, 0x8000, v66
	v_mov_b32_e32 v69, v67
	v_lshl_add_u64 v[68:69], v[142:143], 0, v[68:69]
	global_load_dwordx2 v[74:75], v[68:69], off
	global_load_dwordx2 v[72:73], v[68:69], off offset:32
	global_load_dwordx2 v[70:71], v[68:69], off offset:256
	s_nop 0
	global_load_dwordx2 v[68:69], v[68:69], off offset:288
	s_waitcnt vmcnt(7)
	v_cvt_f32_f16_sdwa v79, v88 dst_sel:DWORD dst_unused:UNUSED_PAD src0_sel:WORD_1
	v_cvt_f32_f16_sdwa v91, v89 dst_sel:DWORD dst_unused:UNUSED_PAD src0_sel:WORD_1
	v_cvt_f32_f16_e32 v90, v89
	v_cvt_f32_f16_e32 v78, v88
	v_lshlrev_b64 v[80:81], 10, v[76:77]
	v_lshl_add_u64 v[80:81], v[80:81], 0, v[138:139]
	v_pk_fma_f32 v[64:65], v[64:65], 0.5, v[90:91] op_sel_hi:[1,0,1]
	v_pk_fma_f32 v[62:63], v[62:63], 0.5, v[78:79] op_sel_hi:[1,0,1]
	s_mov_b64 s[24:25], -1
	s_and_b64 vcc, exec, s[6:7]
	v_lshl_add_u64 v[78:79], v[80:81], 1, s[20:21]
	s_cbranch_vccnz .LBB0_2558
	v_cvt_f16_f32_e32 v88, v62
	v_cvt_f16_f32_sdwa v89, v63 dst_sel:WORD_1 dst_unused:UNUSED_PAD src0_sel:DWORD
	v_cvt_f16_f32_e32 v90, v64
	v_cvt_f16_f32_sdwa v91, v65 dst_sel:WORD_1 dst_unused:UNUSED_PAD src0_sel:DWORD
	s_mov_b64 s[24:25], 0
	v_or_b32_e32 v88, v89, v88
	v_or_b32_e32 v89, v91, v90
	global_store_dwordx2 v[78:79], v[88:89], off sc1
	v_pk_mul_f32 v[88:89], v[64:65], v[64:65]
	v_pk_mul_f32 v[90:91], v[62:63], v[62:63]
	s_nop 0
	v_pk_mov_b32 v[92:93], v[90:91], v[88:89] op_sel:[1,0]
	v_mov_b32_e32 v91, v89
	v_pk_add_f32 v[88:89], v[92:93], v[90:91]
	s_nop 0
	v_add_f32_e32 v88, v88, v89

.LBB0_2560:
	s_waitcnt vmcnt(6)
	s_nop 0
	v_cvt_f32_f16_sdwa v63, v86 dst_sel:DWORD dst_unused:UNUSED_PAD src0_sel:WORD_1
	v_cvt_f32_f16_sdwa v65, v87 dst_sel:DWORD dst_unused:UNUSED_PAD src0_sel:WORD_1
	v_cvt_f32_f16_e32 v64, v87
	v_cvt_f32_f16_e32 v62, v86
	s_and_b64 vcc, exec, s[6:7]
	s_mov_b64 s[24:25], -1
	v_pk_fma_f32 v[60:61], v[60:61], 0.5, v[64:65] op_sel_hi:[1,0,1]
	v_pk_fma_f32 v[58:59], v[58:59], 0.5, v[62:63] op_sel_hi:[1,0,1]
	s_cbranch_vccnz .LBB0_2562
	v_cvt_f16_f32_e32 v62, v58
	v_cvt_f16_f32_sdwa v63, v59 dst_sel:WORD_1 dst_unused:UNUSED_PAD src0_sel:DWORD
	v_cvt_f16_f32_e32 v64, v60
	v_cvt_f16_f32_sdwa v65, v61 dst_sel:WORD_1 dst_unused:UNUSED_PAD src0_sel:DWORD
	s_mov_b64 s[24:25], 0
	v_or_b32_e32 v62, v63, v62
	v_or_b32_e32 v63, v65, v64
	global_store_dwordx2 v[78:79], v[62:63], off offset:32 sc1
	v_pk_mul_f32 v[62:63], v[60:61], v[60:61]
	v_pk_mul_f32 v[64:65], v[58:59], v[58:59]
	s_nop 0
	v_pk_mov_b32 v[86:87], v[64:65], v[62:63] op_sel:[1,0]
	v_mov_b32_e32 v65, v63
	v_pk_add_f32 v[62:63], v[86:87], v[64:65]
	s_nop 0
	v_add_f32_e32 v62, v62, v63
	v_add_f32_e32 v62, v62, v88

.LBB0_2564:
	s_waitcnt vmcnt(5)
	s_nop 0
	v_cvt_f32_f16_sdwa v59, v84 dst_sel:DWORD dst_unused:UNUSED_PAD src0_sel:WORD_1
	v_cvt_f32_f16_sdwa v61, v85 dst_sel:DWORD dst_unused:UNUSED_PAD src0_sel:WORD_1
	v_cvt_f32_f16_e32 v60, v85
	v_cvt_f32_f16_e32 v58, v84
	s_and_b64 vcc, exec, s[6:7]
	s_mov_b64 s[24:25], -1
	v_pk_fma_f32 v[56:57], v[56:57], 0.5, v[60:61] op_sel_hi:[1,0,1]
	v_pk_fma_f32 v[54:55], v[54:55], 0.5, v[58:59] op_sel_hi:[1,0,1]
	s_cbranch_vccnz .LBB0_2566
	v_cvt_f16_f32_e32 v58, v54
	v_cvt_f16_f32_sdwa v59, v55 dst_sel:WORD_1 dst_unused:UNUSED_PAD src0_sel:DWORD
	v_cvt_f16_f32_e32 v60, v56
	v_cvt_f16_f32_sdwa v61, v57 dst_sel:WORD_1 dst_unused:UNUSED_PAD src0_sel:DWORD
	s_mov_b64 s[24:25], 0
	v_or_b32_e32 v58, v59, v58
	v_or_b32_e32 v59, v61, v60
	global_store_dwordx2 v[78:79], v[58:59], off offset:256 sc1
	v_pk_mul_f32 v[58:59], v[56:57], v[56:57]
	v_pk_mul_f32 v[60:61], v[54:55], v[54:55]
	s_nop 0
	v_pk_mov_b32 v[64:65], v[60:61], v[58:59] op_sel:[1,0]
	v_mov_b32_e32 v61, v59
	v_pk_add_f32 v[58:59], v[64:65], v[60:61]
	s_nop 0
	v_add_f32_e32 v58, v58, v59
	v_add_f32_e32 v58, v58, v62

.LBB0_2568:
	s_waitcnt vmcnt(4)
	s_nop 0
	v_cvt_f32_f16_sdwa v55, v82 dst_sel:DWORD dst_unused:UNUSED_PAD src0_sel:WORD_1
	v_cvt_f32_f16_sdwa v57, v83 dst_sel:DWORD dst_unused:UNUSED_PAD src0_sel:WORD_1
	v_cvt_f32_f16_e32 v56, v83
	v_cvt_f32_f16_e32 v54, v82
	s_and_b64 vcc, exec, s[6:7]
	s_mov_b64 s[24:25], -1
	v_pk_fma_f32 v[52:53], v[52:53], 0.5, v[56:57] op_sel_hi:[1,0,1]
	v_pk_fma_f32 v[50:51], v[50:51], 0.5, v[54:55] op_sel_hi:[1,0,1]
	s_cbranch_vccnz .LBB0_2571
	v_cvt_f16_f32_e32 v54, v50
	v_cvt_f16_f32_sdwa v55, v51 dst_sel:WORD_1 dst_unused:UNUSED_PAD src0_sel:DWORD
	v_cvt_f16_f32_sdwa v56, v53 dst_sel:WORD_1 dst_unused:UNUSED_PAD src0_sel:DWORD
	v_or_b32_e32 v54, v55, v54
	v_cvt_f16_f32_e32 v55, v52
	v_or_b32_e32 v55, v56, v55
	global_store_dwordx2 v[78:79], v[54:55], off offset:288 sc1
	v_pk_mul_f32 v[54:55], v[52:53], v[52:53]
	v_pk_mul_f32 v[56:57], v[50:51], v[50:51]
	s_nop 0
	v_pk_mov_b32 v[60:61], v[56:57], v[54:55] op_sel:[1,0]
	v_mov_b32_e32 v57, v55
	v_pk_add_f32 v[54:55], v[60:61], v[56:57]
	s_nop 0
	v_add_f32_e32 v54, v54, v55
	v_add_f32_e32 v54, v54, v58
	s_cbranch_execz .LBB0_2572

.LBB0_2576:
	v_or_b32_e32 v50, 0x10000, v66
	s_waitcnt lgkmcnt(0)
	v_mov_b32_e32 v51, v67
	v_lshl_add_u64 v[50:51], v[142:143], 0, v[50:51]
	global_load_dwordx2 v[56:57], v[50:51], off
	global_load_dwordx2 v[54:55], v[50:51], off offset:32
	global_load_dwordx2 v[52:53], v[50:51], off offset:256
	s_nop 0
	global_load_dwordx2 v[50:51], v[50:51], off offset:288
	s_waitcnt vmcnt(7)
	v_cvt_f32_f16_sdwa v61, v74 dst_sel:DWORD dst_unused:UNUSED_PAD src0_sel:WORD_1
	v_cvt_f32_f16_e32 v60, v74
	v_cvt_f32_f16_sdwa v65, v75 dst_sel:DWORD dst_unused:UNUSED_PAD src0_sel:WORD_1
	v_cvt_f32_f16_e32 v64, v75
	s_mov_b64 s[24:25], 0x90
	v_lshl_add_u64 v[58:59], v[140:141], 0, s[24:25]
	v_lshlrev_b64 v[62:63], 10, v[58:59]
	v_lshl_add_u64 v[62:63], v[62:63], 0, v[138:139]
	v_pk_fma_f32 v[48:49], v[48:49], 0.5, v[64:65] op_sel_hi:[1,0,1]
	v_pk_fma_f32 v[46:47], v[46:47], 0.5, v[60:61] op_sel_hi:[1,0,1]
	s_mov_b64 s[24:25], -1
	s_and_b64 vcc, exec, s[6:7]
	v_lshl_add_u64 v[60:61], v[62:63], 1, s[20:21]
	s_cbranch_vccnz .LBB0_2578
	v_cvt_f16_f32_e32 v64, v46
	v_cvt_f16_f32_sdwa v65, v47 dst_sel:WORD_1 dst_unused:UNUSED_PAD src0_sel:DWORD
	v_cvt_f16_f32_e32 v74, v48
	v_cvt_f16_f32_sdwa v75, v49 dst_sel:WORD_1 dst_unused:UNUSED_PAD src0_sel:DWORD
	s_mov_b64 s[24:25], 0
	v_or_b32_e32 v64, v65, v64
	v_or_b32_e32 v65, v75, v74
	global_store_dwordx2 v[60:61], v[64:65], off sc1
	v_pk_mul_f32 v[64:65], v[48:49], v[48:49]
	v_pk_mul_f32 v[74:75], v[46:47], v[46:47]
	s_nop 0
	v_pk_mov_b32 v[76:77], v[74:75], v[64:65] op_sel:[1,0]
	v_mov_b32_e32 v75, v65
	v_pk_add_f32 v[64:65], v[76:77], v[74:75]
	s_nop 0
	v_add_f32_e32 v64, v64, v65

.LBB0_2580:
	s_waitcnt vmcnt(6)
	s_nop 0
	v_cvt_f32_f16_sdwa v47, v72 dst_sel:DWORD dst_unused:UNUSED_PAD src0_sel:WORD_1
	v_cvt_f32_f16_sdwa v49, v73 dst_sel:DWORD dst_unused:UNUSED_PAD src0_sel:WORD_1
	v_cvt_f32_f16_e32 v48, v73
	v_cvt_f32_f16_e32 v46, v72
	s_and_b64 vcc, exec, s[6:7]
	s_mov_b64 s[24:25], -1
	v_pk_fma_f32 v[44:45], v[44:45], 0.5, v[48:49] op_sel_hi:[1,0,1]
	v_pk_fma_f32 v[42:43], v[42:43], 0.5, v[46:47] op_sel_hi:[1,0,1]
	s_cbranch_vccnz .LBB0_2582
	v_cvt_f16_f32_e32 v46, v42
	v_cvt_f16_f32_sdwa v47, v43 dst_sel:WORD_1 dst_unused:UNUSED_PAD src0_sel:DWORD
	v_cvt_f16_f32_e32 v48, v44
	v_cvt_f16_f32_sdwa v49, v45 dst_sel:WORD_1 dst_unused:UNUSED_PAD src0_sel:DWORD
	s_mov_b64 s[24:25], 0
	v_or_b32_e32 v46, v47, v46
	v_or_b32_e32 v47, v49, v48
	global_store_dwordx2 v[60:61], v[46:47], off offset:32 sc1
	v_pk_mul_f32 v[46:47], v[44:45], v[44:45]
	v_pk_mul_f32 v[48:49], v[42:43], v[42:43]
	s_nop 0
	v_pk_mov_b32 v[72:73], v[48:49], v[46:47] op_sel:[1,0]
	v_mov_b32_e32 v49, v47
	v_pk_add_f32 v[46:47], v[72:73], v[48:49]
	s_nop 0
	v_add_f32_e32 v46, v46, v47
	v_add_f32_e32 v46, v46, v64

.LBB0_2584:
	s_waitcnt vmcnt(5)
	s_nop 0
	v_cvt_f32_f16_sdwa v43, v70 dst_sel:DWORD dst_unused:UNUSED_PAD src0_sel:WORD_1
	v_cvt_f32_f16_sdwa v45, v71 dst_sel:DWORD dst_unused:UNUSED_PAD src0_sel:WORD_1
	v_cvt_f32_f16_e32 v44, v71
	v_cvt_f32_f16_e32 v42, v70
	s_and_b64 vcc, exec, s[6:7]
	s_mov_b64 s[24:25], -1
	v_pk_fma_f32 v[40:41], v[40:41], 0.5, v[44:45] op_sel_hi:[1,0,1]
	v_pk_fma_f32 v[38:39], v[38:39], 0.5, v[42:43] op_sel_hi:[1,0,1]
	s_cbranch_vccnz .LBB0_2586
	v_cvt_f16_f32_e32 v42, v38
	v_cvt_f16_f32_sdwa v43, v39 dst_sel:WORD_1 dst_unused:UNUSED_PAD src0_sel:DWORD
	v_cvt_f16_f32_e32 v44, v40
	v_cvt_f16_f32_sdwa v45, v41 dst_sel:WORD_1 dst_unused:UNUSED_PAD src0_sel:DWORD
	s_mov_b64 s[24:25], 0
	v_or_b32_e32 v42, v43, v42
	v_or_b32_e32 v43, v45, v44
	global_store_dwordx2 v[60:61], v[42:43], off offset:256 sc1
	v_pk_mul_f32 v[42:43], v[40:41], v[40:41]
	v_pk_mul_f32 v[44:45], v[38:39], v[38:39]
	s_nop 0
	v_pk_mov_b32 v[48:49], v[44:45], v[42:43] op_sel:[1,0]
	v_mov_b32_e32 v45, v43
	v_pk_add_f32 v[42:43], v[48:49], v[44:45]
	s_nop 0
	v_add_f32_e32 v42, v42, v43
	v_add_f32_e32 v42, v42, v46

.LBB0_2588:
	s_waitcnt vmcnt(4)
	s_nop 0
	v_cvt_f32_f16_sdwa v39, v68 dst_sel:DWORD dst_unused:UNUSED_PAD src0_sel:WORD_1
	v_cvt_f32_f16_sdwa v41, v69 dst_sel:DWORD dst_unused:UNUSED_PAD src0_sel:WORD_1
	v_cvt_f32_f16_e32 v40, v69
	v_cvt_f32_f16_e32 v38, v68
	s_and_b64 vcc, exec, s[6:7]
	s_mov_b64 s[24:25], -1
	v_pk_fma_f32 v[36:37], v[36:37], 0.5, v[40:41] op_sel_hi:[1,0,1]
	v_pk_fma_f32 v[34:35], v[34:35], 0.5, v[38:39] op_sel_hi:[1,0,1]
	s_cbranch_vccnz .LBB0_2591
	v_cvt_f16_f32_e32 v38, v34
	v_cvt_f16_f32_sdwa v39, v35 dst_sel:WORD_1 dst_unused:UNUSED_PAD src0_sel:DWORD
	v_cvt_f16_f32_sdwa v40, v37 dst_sel:WORD_1 dst_unused:UNUSED_PAD src0_sel:DWORD
	v_or_b32_e32 v38, v39, v38
	v_cvt_f16_f32_e32 v39, v36
	v_or_b32_e32 v39, v40, v39
	global_store_dwordx2 v[60:61], v[38:39], off offset:288 sc1
	v_pk_mul_f32 v[38:39], v[36:37], v[36:37]
	v_pk_mul_f32 v[40:41], v[34:35], v[34:35]
	s_nop 0
	v_pk_mov_b32 v[44:45], v[40:41], v[38:39] op_sel:[1,0]
	v_mov_b32_e32 v41, v39
	v_pk_add_f32 v[38:39], v[44:45], v[40:41]
	s_nop 0
	v_add_f32_e32 v38, v38, v39
	v_add_f32_e32 v38, v38, v42
	s_cbranch_execz .LBB0_2592

.LBB0_2596:
	v_or_b32_e32 v66, 0x18000, v66
	s_waitcnt lgkmcnt(0)
	v_lshl_add_u64 v[34:35], v[142:143], 0, v[66:67]
	global_load_dwordx2 v[40:41], v[34:35], off
	global_load_dwordx2 v[38:39], v[34:35], off offset:32
	global_load_dwordx2 v[36:37], v[34:35], off offset:256
	s_nop 0
	global_load_dwordx2 v[34:35], v[34:35], off offset:288
	s_waitcnt vmcnt(7)
	v_cvt_f32_f16_sdwa v45, v56 dst_sel:DWORD dst_unused:UNUSED_PAD src0_sel:WORD_1
	v_cvt_f32_f16_e32 v44, v56
	v_cvt_f32_f16_sdwa v49, v57 dst_sel:DWORD dst_unused:UNUSED_PAD src0_sel:WORD_1
	v_cvt_f32_f16_e32 v48, v57
	s_mov_b64 s[24:25], 0xa0
	v_lshl_add_u64 v[42:43], v[140:141], 0, s[24:25]
	v_lshlrev_b64 v[46:47], 10, v[42:43]
	v_lshl_add_u64 v[46:47], v[46:47], 0, v[138:139]
	v_pk_fma_f32 v[32:33], v[32:33], 0.5, v[48:49] op_sel_hi:[1,0,1]
	v_pk_fma_f32 v[30:31], v[30:31], 0.5, v[44:45] op_sel_hi:[1,0,1]
	s_mov_b64 s[24:25], -1
	s_and_b64 vcc, exec, s[6:7]
	v_lshl_add_u64 v[44:45], v[46:47], 1, s[20:21]
	s_cbranch_vccnz .LBB0_2598
	v_cvt_f16_f32_e32 v48, v30
	v_cvt_f16_f32_sdwa v49, v31 dst_sel:WORD_1 dst_unused:UNUSED_PAD src0_sel:DWORD
	v_cvt_f16_f32_e32 v56, v32
	v_cvt_f16_f32_sdwa v57, v33 dst_sel:WORD_1 dst_unused:UNUSED_PAD src0_sel:DWORD
	s_mov_b64 s[24:25], 0
	v_or_b32_e32 v48, v49, v48
	v_or_b32_e32 v49, v57, v56
	global_store_dwordx2 v[44:45], v[48:49], off sc1
	v_pk_mul_f32 v[48:49], v[32:33], v[32:33]
	v_pk_mul_f32 v[56:57], v[30:31], v[30:31]
	s_nop 0
	v_pk_mov_b32 v[58:59], v[56:57], v[48:49] op_sel:[1,0]
	v_mov_b32_e32 v57, v49
	v_pk_add_f32 v[48:49], v[58:59], v[56:57]
	s_nop 0
	v_add_f32_e32 v48, v48, v49

.LBB0_2600:
	s_waitcnt vmcnt(6)
	s_nop 0
	v_cvt_f32_f16_sdwa v31, v54 dst_sel:DWORD dst_unused:UNUSED_PAD src0_sel:WORD_1
	v_cvt_f32_f16_sdwa v33, v55 dst_sel:DWORD dst_unused:UNUSED_PAD src0_sel:WORD_1
	v_cvt_f32_f16_e32 v32, v55
	v_cvt_f32_f16_e32 v30, v54
	s_and_b64 vcc, exec, s[6:7]
	s_mov_b64 s[24:25], -1
	v_pk_fma_f32 v[28:29], v[28:29], 0.5, v[32:33] op_sel_hi:[1,0,1]
	v_pk_fma_f32 v[26:27], v[26:27], 0.5, v[30:31] op_sel_hi:[1,0,1]
	s_cbranch_vccnz .LBB0_2602
	v_cvt_f16_f32_e32 v30, v26
	v_cvt_f16_f32_sdwa v31, v27 dst_sel:WORD_1 dst_unused:UNUSED_PAD src0_sel:DWORD
	v_cvt_f16_f32_e32 v32, v28
	v_cvt_f16_f32_sdwa v33, v29 dst_sel:WORD_1 dst_unused:UNUSED_PAD src0_sel:DWORD
	s_mov_b64 s[24:25], 0
	v_or_b32_e32 v30, v31, v30
	v_or_b32_e32 v31, v33, v32
	global_store_dwordx2 v[44:45], v[30:31], off offset:32 sc1
	v_pk_mul_f32 v[30:31], v[28:29], v[28:29]
	v_pk_mul_f32 v[32:33], v[26:27], v[26:27]
	s_nop 0
	v_pk_mov_b32 v[54:55], v[32:33], v[30:31] op_sel:[1,0]
	v_mov_b32_e32 v33, v31
	v_pk_add_f32 v[30:31], v[54:55], v[32:33]
	s_nop 0
	v_add_f32_e32 v30, v30, v31
	v_add_f32_e32 v30, v30, v48

.LBB0_2604:
	s_waitcnt vmcnt(5)
	s_nop 0
	v_cvt_f32_f16_sdwa v27, v52 dst_sel:DWORD dst_unused:UNUSED_PAD src0_sel:WORD_1
	v_cvt_f32_f16_sdwa v29, v53 dst_sel:DWORD dst_unused:UNUSED_PAD src0_sel:WORD_1
	v_cvt_f32_f16_e32 v28, v53
	v_cvt_f32_f16_e32 v26, v52
	s_and_b64 vcc, exec, s[6:7]
	s_mov_b64 s[24:25], -1
	v_pk_fma_f32 v[24:25], v[24:25], 0.5, v[28:29] op_sel_hi:[1,0,1]
	v_pk_fma_f32 v[22:23], v[22:23], 0.5, v[26:27] op_sel_hi:[1,0,1]
	s_cbranch_vccnz .LBB0_2606
	v_cvt_f16_f32_e32 v26, v22
	v_cvt_f16_f32_sdwa v27, v23 dst_sel:WORD_1 dst_unused:UNUSED_PAD src0_sel:DWORD
	v_cvt_f16_f32_e32 v28, v24
	v_cvt_f16_f32_sdwa v29, v25 dst_sel:WORD_1 dst_unused:UNUSED_PAD src0_sel:DWORD
	s_mov_b64 s[24:25], 0
	v_or_b32_e32 v26, v27, v26
	v_or_b32_e32 v27, v29, v28
	global_store_dwordx2 v[44:45], v[26:27], off offset:256 sc1
	v_pk_mul_f32 v[26:27], v[24:25], v[24:25]
	v_pk_mul_f32 v[28:29], v[22:23], v[22:23]
	s_nop 0
	v_pk_mov_b32 v[32:33], v[28:29], v[26:27] op_sel:[1,0]
	v_mov_b32_e32 v29, v27
	v_pk_add_f32 v[26:27], v[32:33], v[28:29]
	s_nop 0
	v_add_f32_e32 v26, v26, v27
	v_add_f32_e32 v26, v26, v30

.LBB0_2608:
	s_waitcnt vmcnt(4)
	s_nop 0
	v_cvt_f32_f16_sdwa v23, v50 dst_sel:DWORD dst_unused:UNUSED_PAD src0_sel:WORD_1
	v_cvt_f32_f16_sdwa v25, v51 dst_sel:DWORD dst_unused:UNUSED_PAD src0_sel:WORD_1
	v_cvt_f32_f16_e32 v24, v51
	v_cvt_f32_f16_e32 v22, v50
	s_and_b64 vcc, exec, s[6:7]
	s_mov_b64 s[24:25], -1
	v_pk_fma_f32 v[20:21], v[20:21], 0.5, v[24:25] op_sel_hi:[1,0,1]
	v_pk_fma_f32 v[18:19], v[18:19], 0.5, v[22:23] op_sel_hi:[1,0,1]
	s_cbranch_vccnz .LBB0_2611
	v_cvt_f16_f32_e32 v22, v18
	v_cvt_f16_f32_sdwa v23, v19 dst_sel:WORD_1 dst_unused:UNUSED_PAD src0_sel:DWORD
	v_cvt_f16_f32_sdwa v24, v21 dst_sel:WORD_1 dst_unused:UNUSED_PAD src0_sel:DWORD
	v_or_b32_e32 v22, v23, v22
	v_cvt_f16_f32_e32 v23, v20
	v_or_b32_e32 v23, v24, v23
	global_store_dwordx2 v[44:45], v[22:23], off offset:288 sc1
	v_pk_mul_f32 v[22:23], v[20:21], v[20:21]
	v_pk_mul_f32 v[24:25], v[18:19], v[18:19]
	s_nop 0
	v_pk_mov_b32 v[28:29], v[24:25], v[22:23] op_sel:[1,0]
	v_mov_b32_e32 v25, v23
	v_pk_add_f32 v[22:23], v[28:29], v[24:25]
	s_nop 0
	v_add_f32_e32 v22, v22, v23
	v_add_f32_e32 v22, v22, v26
	s_cbranch_execz .LBB0_2612

.LBB0_2616:
	s_waitcnt vmcnt(3)
	v_cvt_f32_f16_sdwa v21, v40 dst_sel:DWORD dst_unused:UNUSED_PAD src0_sel:WORD_1
	v_cvt_f32_f16_e32 v20, v40
	v_cvt_f32_f16_sdwa v25, v41 dst_sel:DWORD dst_unused:UNUSED_PAD src0_sel:WORD_1
	v_cvt_f32_f16_e32 v24, v41
	s_mov_b64 s[24:25], 0xb0
	s_waitcnt lgkmcnt(0)
	v_lshl_add_u64 v[18:19], v[140:141], 0, s[24:25]
	v_lshlrev_b64 v[22:23], 10, v[18:19]
	v_lshl_add_u64 v[22:23], v[22:23], 0, v[138:139]
	v_pk_fma_f32 v[16:17], v[16:17], 0.5, v[24:25] op_sel_hi:[1,0,1]
	v_pk_fma_f32 v[14:15], v[14:15], 0.5, v[20:21] op_sel_hi:[1,0,1]
	s_mov_b64 s[24:25], -1
	s_and_b64 vcc, exec, s[6:7]
	v_lshl_add_u64 v[20:21], v[22:23], 1, s[20:21]
	s_cbranch_vccnz .LBB0_2618
	v_cvt_f16_f32_e32 v24, v14
	v_cvt_f16_f32_sdwa v25, v15 dst_sel:WORD_1 dst_unused:UNUSED_PAD src0_sel:DWORD
	v_cvt_f16_f32_e32 v26, v16
	v_cvt_f16_f32_sdwa v27, v17 dst_sel:WORD_1 dst_unused:UNUSED_PAD src0_sel:DWORD
	s_mov_b64 s[24:25], 0
	v_or_b32_e32 v24, v25, v24
	v_or_b32_e32 v25, v27, v26
	global_store_dwordx2 v[20:21], v[24:25], off sc1
	v_pk_mul_f32 v[24:25], v[16:17], v[16:17]
	v_pk_mul_f32 v[26:27], v[14:15], v[14:15]
	s_nop 0
	v_pk_mov_b32 v[28:29], v[26:27], v[24:25] op_sel:[1,0]
	v_mov_b32_e32 v27, v25
	v_pk_add_f32 v[24:25], v[28:29], v[26:27]
	s_nop 0
	v_add_f32_e32 v24, v24, v25

.LBB0_2620:
	s_waitcnt vmcnt(2)
	s_nop 0
	v_cvt_f32_f16_sdwa v15, v38 dst_sel:DWORD dst_unused:UNUSED_PAD src0_sel:WORD_1
	v_cvt_f32_f16_sdwa v17, v39 dst_sel:DWORD dst_unused:UNUSED_PAD src0_sel:WORD_1
	v_cvt_f32_f16_e32 v16, v39
	v_cvt_f32_f16_e32 v14, v38
	s_and_b64 vcc, exec, s[6:7]
	s_mov_b64 s[20:21], -1
	v_pk_fma_f32 v[12:13], v[12:13], 0.5, v[16:17] op_sel_hi:[1,0,1]
	v_pk_fma_f32 v[10:11], v[10:11], 0.5, v[14:15] op_sel_hi:[1,0,1]
	s_cbranch_vccnz .LBB0_2622
	v_cvt_f16_f32_e32 v14, v10
	v_cvt_f16_f32_sdwa v15, v11 dst_sel:WORD_1 dst_unused:UNUSED_PAD src0_sel:DWORD
	v_cvt_f16_f32_e32 v16, v12
	v_cvt_f16_f32_sdwa v17, v13 dst_sel:WORD_1 dst_unused:UNUSED_PAD src0_sel:DWORD
	s_mov_b64 s[20:21], 0
	v_or_b32_e32 v14, v15, v14
	v_or_b32_e32 v15, v17, v16
	global_store_dwordx2 v[20:21], v[14:15], off offset:32 sc1
	v_pk_mul_f32 v[14:15], v[12:13], v[12:13]
	v_pk_mul_f32 v[16:17], v[10:11], v[10:11]
	s_nop 0
	v_pk_mov_b32 v[26:27], v[16:17], v[14:15] op_sel:[1,0]
	v_mov_b32_e32 v17, v15
	v_pk_add_f32 v[14:15], v[26:27], v[16:17]
	s_nop 0
	v_add_f32_e32 v14, v14, v15
	v_add_f32_e32 v14, v14, v24

.LBB0_2624:
	s_waitcnt vmcnt(1)
	s_nop 0
	v_cvt_f32_f16_sdwa v11, v36 dst_sel:DWORD dst_unused:UNUSED_PAD src0_sel:WORD_1
	v_cvt_f32_f16_sdwa v13, v37 dst_sel:DWORD dst_unused:UNUSED_PAD src0_sel:WORD_1
	v_cvt_f32_f16_e32 v12, v37
	v_cvt_f32_f16_e32 v10, v36
	s_and_b64 vcc, exec, s[6:7]
	s_mov_b64 s[20:21], -1
	v_pk_fma_f32 v[8:9], v[8:9], 0.5, v[12:13] op_sel_hi:[1,0,1]
	v_pk_fma_f32 v[6:7], v[6:7], 0.5, v[10:11] op_sel_hi:[1,0,1]
	s_cbranch_vccnz .LBB0_2626
	v_cvt_f16_f32_e32 v10, v6
	v_cvt_f16_f32_sdwa v11, v7 dst_sel:WORD_1 dst_unused:UNUSED_PAD src0_sel:DWORD
	v_cvt_f16_f32_e32 v12, v8
	v_cvt_f16_f32_sdwa v13, v9 dst_sel:WORD_1 dst_unused:UNUSED_PAD src0_sel:DWORD
	s_mov_b64 s[20:21], 0
	v_or_b32_e32 v10, v11, v10
	v_or_b32_e32 v11, v13, v12
	global_store_dwordx2 v[20:21], v[10:11], off offset:256 sc1
	v_pk_mul_f32 v[10:11], v[8:9], v[8:9]
	v_pk_mul_f32 v[12:13], v[6:7], v[6:7]
	s_nop 0
	v_pk_mov_b32 v[16:17], v[12:13], v[10:11] op_sel:[1,0]
	v_mov_b32_e32 v13, v11
	v_pk_add_f32 v[10:11], v[16:17], v[12:13]
	s_nop 0
	v_add_f32_e32 v10, v10, v11
	v_add_f32_e32 v10, v10, v14

.LBB0_2628:
	s_waitcnt vmcnt(0)
	s_nop 0
	v_cvt_f32_f16_sdwa v7, v34 dst_sel:DWORD dst_unused:UNUSED_PAD src0_sel:WORD_1
	v_cvt_f32_f16_sdwa v9, v35 dst_sel:DWORD dst_unused:UNUSED_PAD src0_sel:WORD_1
	v_cvt_f32_f16_e32 v8, v35
	v_cvt_f32_f16_e32 v6, v34
	s_and_b64 vcc, exec, s[6:7]
	s_mov_b64 s[20:21], -1
	v_pk_fma_f32 v[4:5], v[4:5], 0.5, v[8:9] op_sel_hi:[1,0,1]
	v_pk_fma_f32 v[2:3], v[2:3], 0.5, v[6:7] op_sel_hi:[1,0,1]
	s_cbranch_vccnz .LBB0_2634
	v_cvt_f16_f32_e32 v6, v2
	v_cvt_f16_f32_sdwa v7, v3 dst_sel:WORD_1 dst_unused:UNUSED_PAD src0_sel:DWORD
	v_cvt_f16_f32_sdwa v8, v5 dst_sel:WORD_1 dst_unused:UNUSED_PAD src0_sel:DWORD
	v_or_b32_e32 v6, v7, v6
	v_cvt_f16_f32_e32 v7, v4
	v_or_b32_e32 v7, v8, v7
	global_store_dwordx2 v[20:21], v[6:7], off offset:288 sc1
	v_pk_mul_f32 v[6:7], v[4:5], v[4:5]
	v_pk_mul_f32 v[8:9], v[2:3], v[2:3]
	s_nop 0
	v_pk_mov_b32 v[12:13], v[8:9], v[6:7] op_sel:[1,0]
	v_mov_b32_e32 v9, v7
	v_pk_add_f32 v[6:7], v[12:13], v[8:9]
	s_nop 0
	v_add_f32_e32 v6, v6, v7
	v_add_f32_e32 v6, v6, v10
	s_cbranch_execz .LBB0_2635
